# de-serialized epilogue/mid gate and residual loads (P5 mid+final, P6/P9 residual), R3 state-fragment prefetch, NA dwordx4 V loads
# speedup vs baseline: 1.0542x; 1.0542x over previous
; #define LAS __attribute__((address_space(3)))
; __device__ __forceinline__ unsigned cvt_pk_bf16(float lo, float hi) { const f32v2_t v = {lo, hi}; const bf16v2_t r = __builtin_convertvector(v, bf16v2_t); return __builtin_bit_cast(unsigned, r); }
; __device__ __forceinline__ void unpack8(const u32x4 w, float* f) { f[0] = bf_lo(w.x); f[1] = bf_hi(w.x); f[2] = bf_lo(w.y); f[3] = bf_hi(w.y); f[4] = bf_lo(w.z); f[5] = bf_hi(w.z); f[6] = bf_lo(w.w); f[7] = bf_hi(w.w); }
; __device__ __forceinline__ void r3_item(const bf16_t* __restrict__ proj, const bf16_t* __restrict__ projT, const bf16_t* __restrict__ st, bf16_t* ro, ...
;     ...
;     for (int q = 0; q < 4; ++q) { float s1 = 0.f, s2 = 0.f; const int n = 32 * q + c;
; #pragma unroll
;         for (int k = 0; k < 8; ++k) { s1 += stat[(k * 128 + n) * 2]; s2 += stat[(k * 128 + n) * 2 + 1]; }
;         const float mu = s1 * (1.0f / 256.0f); float var = s2 * (1.0f / 256.0f) - mu * mu; var = var < 0.f ? 0.f : var; const float rs = rsqrtf(var + EPS);
; #pragma unroll
;         for (int g4 = 0; g4 < 4; ++g4) { u32x2 pw; pw.x = cvt_pk_bf16((acc[q][4 * g4] - mu) * rs, (acc[q][4 * g4 + 1] - mu) * rs); pw.y = cvt_pk_bf16((acc[q][4 * g4 + 2] - mu) * rs, (acc[q][4 * g4 + 3] - mu) * rs);
;             *(LAS u32x2*)(Ol + n * OL_STRIDE + 32 * w + 8 * g4 + 4 * hh) = pw; } }
;     __syncthreads();
; #pragma unroll
;     for (int it = 0; it < 8; ++it) { const int id = tid + NTHREADS * it, tq = id >> 5, d8 = (id & 31) * 8;
;         float y[8], rg[8], o[8]; unpack8(*(const LAS u32x4*)(Ol + tq * OL_STRIDE + d8), y);
;         unpack8(__builtin_nontemporal_load((const u32x4*)(proj + (size_t)(tok0 + tq) * NPROJ + 2048 + h * 256 + d8)), rg);
.LBB0_484:
	s_or_b64 exec, exec, s[4:5]
	v_and_b32_e32 v72, 0xf8, v249
	v_lshlrev_b32_e32 v72, 1, v72
	v_mov_b32_e32 v73, 0
	v_ashrrev_i32_e32 v74, 5, v247
	v_add_u32_e32 v74, s6, v74
	v_mov_b64_e32 v[76:77], s[40:41]
	s_lshl_b32 s96, s58, 1
	s_add_u32 s96, s96, s23
	s_mov_b32 s97, 0
	v_mad_i64_i32 v[76:77], s[98:99], v74, s18, v[76:77]
	v_lshl_add_u64 v[76:77], v[76:77], 0, s[96:97]
	v_lshl_add_u64 v[76:77], v[76:77], 0, v[72:73]
	s_mov_b32 s96, 0x28000
	global_load_dwordx4 v[80:83], v[76:77], off nt
	v_lshl_add_u64 v[76:77], v[76:77], 0, s[96:97]
	global_load_dwordx4 v[84:87], v[76:77], off nt
	v_lshl_add_u64 v[76:77], v[76:77], 0, s[96:97]
	global_load_dwordx4 v[88:91], v[76:77], off nt
	v_lshl_add_u64 v[76:77], v[76:77], 0, s[96:97]
	global_load_dwordx4 v[92:95], v[76:77], off nt
	v_lshl_add_u64 v[76:77], v[76:77], 0, s[96:97]
	global_load_dwordx4 v[96:99], v[76:77], off nt
	v_lshl_add_u64 v[76:77], v[76:77], 0, s[96:97]
	global_load_dwordx4 v[100:103], v[76:77], off nt
	v_lshl_add_u64 v[76:77], v[76:77], 0, s[96:97]
	global_load_dwordx4 v[104:107], v[76:77], off nt
	v_lshl_add_u64 v[76:77], v[76:77], 0, s[96:97]
	global_load_dwordx4 v[108:111], v[76:77], off nt
	s_add_u32 s4, s30, s42
	s_addc_u32 s5, s31, s43
	s_add_u32 s4, s4, 0x1c240000
	s_addc_u32 s5, s5, 0
	s_lshl_b32 s7, s44, 1
	s_add_i32 s10, s7, 0
	s_add_i32 s7, 0, 0x19800
	v_add_u32_e32 v0, s7, v0
	s_waitcnt lgkmcnt(0)
	s_barrier
	ds_read2st64_b64 v[66:69], v0 offset1:2
	s_waitcnt lgkmcnt(0)
	v_pk_add_f32 v[66:67], v[66:67], 0 op_sel_hi:[1,0]
	s_nop 0
	v_pk_add_f32 v[70:71], v[66:67], v[68:69]
	ds_read2st64_b64 v[66:69], v0 offset0:4 offset1:6
	s_waitcnt lgkmcnt(0)
	v_pk_add_f32 v[66:67], v[70:71], v[66:67]
	s_nop 0
	v_pk_add_f32 v[70:71], v[66:67], v[68:69]
	ds_read2st64_b64 v[66:69], v0 offset0:8 offset1:10
	s_waitcnt lgkmcnt(0)
	v_pk_add_f32 v[66:67], v[70:71], v[66:67]
	s_nop 0
	v_pk_add_f32 v[70:71], v[66:67], v[68:69]
	ds_read2st64_b64 v[66:69], v0 offset0:12 offset1:14
	s_waitcnt lgkmcnt(0)
	v_pk_add_f32 v[66:67], v[70:71], v[66:67]
	s_nop 0
	v_pk_add_f32 v[66:67], v[66:67], v[68:69]
	s_nop 0
	v_pk_mul_f32 v[66:67], v[66:67], s[66:67] op_sel_hi:[1,0]
	s_nop 0
	v_fma_f32 v0, -v66, v66, v67
	v_cmp_ngt_f32_e32 vcc, 0, v0
	v_pk_add_f32 v[50:51], v[50:51], v[66:67] op_sel_hi:[1,0] neg_lo:[0,1] neg_hi:[0,1]
	v_pk_add_f32 v[52:53], v[52:53], v[66:67] op_sel_hi:[1,0] neg_lo:[0,1] neg_hi:[0,1]
	v_cndmask_b32_e32 v0, 0, v0, vcc
	v_add_f32_e32 v0, 0x358637bd, v0
	v_cmp_gt_f32_e32 vcc, s65, v0
	v_mul_f32_e32 v68, 0x4b800000, v0
	s_nop 0
	v_cndmask_b32_e32 v0, v0, v68, vcc
	v_rsq_f32_e32 v0, v0
	s_nop 0
	v_mul_f32_e32 v68, 0x45800000, v0
	v_cndmask_b32_e32 v0, v0, v68, vcc
	v_pk_mul_f32 v[50:51], v[50:51], v[0:1] op_sel_hi:[1,0]
	v_pk_mul_f32 v[52:53], v[52:53], v[0:1] op_sel_hi:[1,0]
	v_cvt_pk_bf16_f32 v50, v50, v51
	v_cvt_pk_bf16_f32 v51, v52, v53
	v_pk_add_f32 v[52:53], v[54:55], v[66:67] op_sel_hi:[1,0] neg_lo:[0,1] neg_hi:[0,1]
	v_pk_add_f32 v[54:55], v[56:57], v[66:67] op_sel_hi:[1,0] neg_lo:[0,1] neg_hi:[0,1]
	v_mul_u32_u24_e32 v68, 0x210, v250
	v_pk_mul_f32 v[52:53], v[52:53], v[0:1] op_sel_hi:[1,0]
	v_pk_mul_f32 v[54:55], v[54:55], v[0:1] op_sel_hi:[1,0]
	v_add3_u32 v68, s10, v252, v68
	v_cvt_pk_bf16_f32 v52, v52, v53
	v_cvt_pk_bf16_f32 v53, v54, v55
	ds_write2_b64 v68, v[50:51], v[52:53] offset1:2
	v_pk_add_f32 v[50:51], v[58:59], v[66:67] op_sel_hi:[1,0] neg_lo:[0,1] neg_hi:[0,1]
	v_pk_add_f32 v[52:53], v[60:61], v[66:67] op_sel_hi:[1,0] neg_lo:[0,1] neg_hi:[0,1]
	v_pk_mul_f32 v[50:51], v[50:51], v[0:1] op_sel_hi:[1,0]
	v_pk_mul_f32 v[52:53], v[52:53], v[0:1] op_sel_hi:[1,0]
	v_cvt_pk_bf16_f32 v50, v50, v51
	v_cvt_pk_bf16_f32 v51, v52, v53
	v_pk_add_f32 v[52:53], v[62:63], v[66:67] op_sel_hi:[1,0] neg_lo:[0,1] neg_hi:[0,1]
	v_pk_add_f32 v[54:55], v[64:65], v[66:67] op_sel_hi:[1,0] neg_lo:[0,1] neg_hi:[0,1]
	v_pk_mul_f32 v[52:53], v[52:53], v[0:1] op_sel_hi:[1,0]
	v_pk_mul_f32 v[54:55], v[54:55], v[0:1] op_sel_hi:[1,0]
	v_cvt_pk_bf16_f32 v52, v52, v53
	v_cvt_pk_bf16_f32 v53, v54, v55
	ds_write2_b64 v68, v[50:51], v[52:53] offset0:4 offset1:6
	v_lshl_add_u32 v0, v229, 3, s7
	ds_read2st64_b64 v[50:53], v0 offset1:2
	s_waitcnt lgkmcnt(0)
	v_pk_add_f32 v[50:51], v[50:51], 0 op_sel_hi:[1,0]
	s_nop 0
	v_pk_add_f32 v[54:55], v[50:51], v[52:53]
	ds_read2st64_b64 v[50:53], v0 offset0:4 offset1:6
	s_waitcnt lgkmcnt(0)
	v_pk_add_f32 v[50:51], v[54:55], v[50:51]
	s_nop 0
	v_pk_add_f32 v[54:55], v[50:51], v[52:53]
	ds_read2st64_b64 v[50:53], v0 offset0:8 offset1:10
	s_waitcnt lgkmcnt(0)
	v_pk_add_f32 v[50:51], v[54:55], v[50:51]
	s_nop 0
	v_pk_add_f32 v[54:55], v[50:51], v[52:53]
	ds_read2st64_b64 v[50:53], v0 offset0:12 offset1:14
	s_waitcnt lgkmcnt(0)
; #define LAS __attribute__((address_space(3)))
; __device__ __forceinline__ unsigned cvt_pk_bf16(float lo, float hi) { const f32v2_t v = {lo, hi}; const bf16v2_t r = __builtin_convertvector(v, bf16v2_t); return __builtin_bit_cast(unsigned, r); }
; __device__ __forceinline__ void r3_item(const bf16_t* __restrict__ proj, const bf16_t* __restrict__ projT, const bf16_t* __restrict__ st, bf16_t* ro, ...
;     ...
;     for (int q = 0; q < 4; ++q) { float s1 = 0.f, s2 = 0.f; const int n = 32 * q + c;
; #pragma unroll
;         for (int k = 0; k < 8; ++k) { s1 += stat[(k * 128 + n) * 2]; s2 += stat[(k * 128 + n) * 2 + 1]; }
;         const float mu = s1 * (1.0f / 256.0f); float var = s2 * (1.0f / 256.0f) - mu * mu; var = var < 0.f ? 0.f : var; const float rs = rsqrtf(var + EPS);
; #pragma unroll
;         for (int g4 = 0; g4 < 4; ++g4) { u32x2 pw; pw.x = cvt_pk_bf16((acc[q][4 * g4] - mu) * rs, (acc[q][4 * g4 + 1] - mu) * rs); pw.y = cvt_pk_bf16((acc[q][4 * g4 + 2] - mu) * rs, (acc[q][4 * g4 + 3] - mu) * rs);
;             *(LAS u32x2*)(Ol + n * OL_STRIDE + 32 * w + 8 * g4 + 4 * hh) = pw; } }
	v_pk_add_f32 v[50:51], v[54:55], v[50:51]
	s_nop 0
	v_pk_add_f32 v[50:51], v[50:51], v[52:53]
	s_nop 0
	v_pk_mul_f32 v[50:51], v[50:51], s[66:67] op_sel_hi:[1,0]
	s_nop 0
	v_fma_f32 v0, -v50, v50, v51
	v_cmp_ngt_f32_e32 vcc, 0, v0
	v_pk_add_f32 v[34:35], v[34:35], v[50:51] op_sel_hi:[1,0] neg_lo:[0,1] neg_hi:[0,1]
	v_pk_add_f32 v[36:37], v[36:37], v[50:51] op_sel_hi:[1,0] neg_lo:[0,1] neg_hi:[0,1]
	v_cndmask_b32_e32 v0, 0, v0, vcc
	v_add_f32_e32 v0, 0x358637bd, v0
	v_cmp_gt_f32_e32 vcc, s65, v0
	v_mul_f32_e32 v52, 0x4b800000, v0
	s_nop 0
	v_cndmask_b32_e32 v0, v0, v52, vcc
	v_rsq_f32_e32 v0, v0
	s_nop 0
	v_mul_f32_e32 v52, 0x45800000, v0
	v_cndmask_b32_e32 v0, v0, v52, vcc
	v_pk_mul_f32 v[34:35], v[34:35], v[0:1] op_sel_hi:[1,0]
	v_pk_mul_f32 v[36:37], v[36:37], v[0:1] op_sel_hi:[1,0]
	v_cvt_pk_bf16_f32 v34, v34, v35
	v_cvt_pk_bf16_f32 v35, v36, v37
	v_pk_add_f32 v[36:37], v[38:39], v[50:51] op_sel_hi:[1,0] neg_lo:[0,1] neg_hi:[0,1]
	v_pk_add_f32 v[38:39], v[40:41], v[50:51] op_sel_hi:[1,0] neg_lo:[0,1] neg_hi:[0,1]
	v_pk_mul_f32 v[36:37], v[36:37], v[0:1] op_sel_hi:[1,0]
	v_pk_mul_f32 v[38:39], v[38:39], v[0:1] op_sel_hi:[1,0]
	v_cvt_pk_bf16_f32 v36, v36, v37
	v_cvt_pk_bf16_f32 v37, v38, v39
	v_add_u32_e32 v40, 0x4000, v68
	ds_write2_b64 v40, v[34:35], v[36:37] offset0:64 offset1:66
	v_pk_add_f32 v[34:35], v[42:43], v[50:51] op_sel_hi:[1,0] neg_lo:[0,1] neg_hi:[0,1]
	v_pk_add_f32 v[36:37], v[44:45], v[50:51] op_sel_hi:[1,0] neg_lo:[0,1] neg_hi:[0,1]
	v_pk_mul_f32 v[34:35], v[34:35], v[0:1] op_sel_hi:[1,0]
	v_pk_mul_f32 v[36:37], v[36:37], v[0:1] op_sel_hi:[1,0]
	v_cvt_pk_bf16_f32 v34, v34, v35
	v_cvt_pk_bf16_f32 v35, v36, v37
	v_pk_add_f32 v[36:37], v[46:47], v[50:51] op_sel_hi:[1,0] neg_lo:[0,1] neg_hi:[0,1]
	v_pk_add_f32 v[38:39], v[48:49], v[50:51] op_sel_hi:[1,0] neg_lo:[0,1] neg_hi:[0,1]
	v_pk_mul_f32 v[36:37], v[36:37], v[0:1] op_sel_hi:[1,0]
	v_pk_mul_f32 v[38:39], v[38:39], v[0:1] op_sel_hi:[1,0]
	v_cvt_pk_bf16_f32 v36, v36, v37
	v_cvt_pk_bf16_f32 v37, v38, v39
	ds_write2_b64 v40, v[34:35], v[36:37] offset0:68 offset1:70
	v_lshl_add_u32 v0, v227, 3, s7
	ds_read2st64_b64 v[34:37], v0 offset1:2
	s_waitcnt lgkmcnt(0)
	v_pk_add_f32 v[34:35], v[34:35], 0 op_sel_hi:[1,0]
	s_nop 0
	v_pk_add_f32 v[38:39], v[34:35], v[36:37]
	ds_read2st64_b64 v[34:37], v0 offset0:4 offset1:6
	s_waitcnt lgkmcnt(0)
	v_pk_add_f32 v[34:35], v[38:39], v[34:35]
	s_nop 0
	v_pk_add_f32 v[38:39], v[34:35], v[36:37]
	ds_read2st64_b64 v[34:37], v0 offset0:8 offset1:10
	s_waitcnt lgkmcnt(0)
	v_pk_add_f32 v[34:35], v[38:39], v[34:35]
	s_nop 0
	v_pk_add_f32 v[38:39], v[34:35], v[36:37]
	ds_read2st64_b64 v[34:37], v0 offset0:12 offset1:14
	s_waitcnt lgkmcnt(0)
	v_pk_add_f32 v[34:35], v[38:39], v[34:35]
	s_nop 0
	v_pk_add_f32 v[34:35], v[34:35], v[36:37]
	s_nop 0
	v_pk_mul_f32 v[34:35], v[34:35], s[66:67] op_sel_hi:[1,0]
	s_nop 0
	v_fma_f32 v0, -v34, v34, v35
	v_cmp_ngt_f32_e32 vcc, 0, v0
	v_pk_add_f32 v[18:19], v[18:19], v[34:35] op_sel_hi:[1,0] neg_lo:[0,1] neg_hi:[0,1]
	v_pk_add_f32 v[20:21], v[20:21], v[34:35] op_sel_hi:[1,0] neg_lo:[0,1] neg_hi:[0,1]
	v_cndmask_b32_e32 v0, 0, v0, vcc
	v_add_f32_e32 v0, 0x358637bd, v0
	v_cmp_gt_f32_e32 vcc, s65, v0
	v_mul_f32_e32 v36, 0x4b800000, v0
	s_nop 0
	v_cndmask_b32_e32 v0, v0, v36, vcc
	v_rsq_f32_e32 v0, v0
	s_nop 0
	v_mul_f32_e32 v36, 0x45800000, v0
	v_cndmask_b32_e32 v0, v0, v36, vcc
	v_pk_mul_f32 v[18:19], v[18:19], v[0:1] op_sel_hi:[1,0]
	v_pk_mul_f32 v[20:21], v[20:21], v[0:1] op_sel_hi:[1,0]
	v_cvt_pk_bf16_f32 v18, v18, v19
	v_cvt_pk_bf16_f32 v19, v20, v21
	v_pk_add_f32 v[20:21], v[22:23], v[34:35] op_sel_hi:[1,0] neg_lo:[0,1] neg_hi:[0,1]
	v_pk_add_f32 v[22:23], v[24:25], v[34:35] op_sel_hi:[1,0] neg_lo:[0,1] neg_hi:[0,1]
	v_pk_mul_f32 v[20:21], v[20:21], v[0:1] op_sel_hi:[1,0]
	v_pk_mul_f32 v[22:23], v[22:23], v[0:1] op_sel_hi:[1,0]
	v_cvt_pk_bf16_f32 v20, v20, v21
	v_cvt_pk_bf16_f32 v21, v22, v23
	v_add_u32_e32 v24, 0x8000, v68
	ds_write2_b64 v24, v[18:19], v[20:21] offset0:128 offset1:130
	v_pk_add_f32 v[18:19], v[26:27], v[34:35] op_sel_hi:[1,0] neg_lo:[0,1] neg_hi:[0,1]
	v_pk_add_f32 v[20:21], v[28:29], v[34:35] op_sel_hi:[1,0] neg_lo:[0,1] neg_hi:[0,1]
	v_pk_mul_f32 v[18:19], v[18:19], v[0:1] op_sel_hi:[1,0]
	v_pk_mul_f32 v[20:21], v[20:21], v[0:1] op_sel_hi:[1,0]
	v_cvt_pk_bf16_f32 v18, v18, v19
	v_cvt_pk_bf16_f32 v19, v20, v21
	v_pk_add_f32 v[20:21], v[30:31], v[34:35] op_sel_hi:[1,0] neg_lo:[0,1] neg_hi:[0,1]
	v_pk_add_f32 v[22:23], v[32:33], v[34:35] op_sel_hi:[1,0] neg_lo:[0,1] neg_hi:[0,1]
	v_pk_mul_f32 v[20:21], v[20:21], v[0:1] op_sel_hi:[1,0]
	v_pk_mul_f32 v[22:23], v[22:23], v[0:1] op_sel_hi:[1,0]
	v_cvt_pk_bf16_f32 v20, v20, v21
	v_cvt_pk_bf16_f32 v21, v22, v23
	ds_write2_b64 v24, v[18:19], v[20:21] offset0:132 offset1:134
	v_lshl_add_u32 v0, v210, 3, s7
	ds_read2st64_b64 v[18:21], v0 offset1:2
	s_lshl_b32 s7, s58, 2
	s_add_u32 s10, s14, s7
	s_addc_u32 s11, s46, 0
	s_lshl_b32 s58, s58, 1
	s_waitcnt lgkmcnt(0)
	v_pk_add_f32 v[18:19], v[18:19], 0 op_sel_hi:[1,0]
	s_add_i32 s27, s27, s52
	v_pk_add_f32 v[22:23], v[18:19], v[20:21]
	ds_read2st64_b64 v[18:21], v0 offset0:4 offset1:6
	s_add_i32 s25, s25, s22
	s_add_u32 s0, s0, s54
	s_addc_u32 s1, s1, s55
	s_cmpk_gt_i32 s27, 0x1ff
	s_waitcnt lgkmcnt(0)
	v_pk_add_f32 v[18:19], v[22:23], v[18:19]
	s_nop 0
	v_pk_add_f32 v[22:23], v[18:19], v[20:21]
	ds_read2st64_b64 v[18:21], v0 offset0:8 offset1:10
	s_waitcnt lgkmcnt(0)
	v_pk_add_f32 v[18:19], v[22:23], v[18:19]
	s_nop 0
	v_pk_add_f32 v[22:23], v[18:19], v[20:21]
	ds_read2st64_b64 v[18:21], v0 offset0:12 offset1:14
	s_waitcnt lgkmcnt(0)
; #define LAS __attribute__((address_space(3)))
; __device__ __forceinline__ unsigned cvt_pk_bf16(float lo, float hi) { const f32v2_t v = {lo, hi}; const bf16v2_t r = __builtin_convertvector(v, bf16v2_t); return __builtin_bit_cast(unsigned, r); }
; __device__ __forceinline__ float sigmoidf_(float x) { return __builtin_amdgcn_rcpf(1.0f + __expf(-x)); }
; __device__ __forceinline__ void unpack8(const u32x4 w, float* f) { f[0] = bf_lo(w.x); f[1] = bf_hi(w.x); f[2] = bf_lo(w.y); f[3] = bf_hi(w.y); f[4] = bf_lo(w.z); f[5] = bf_hi(w.z); f[6] = bf_lo(w.w); f[7] = bf_hi(w.w); }
; __device__ __forceinline__ u32x4 pack8(const float* f) { u32x4 w; w.x = cvt_pk_bf16(f[0], f[1]); w.y = cvt_pk_bf16(f[2], f[3]); w.z = cvt_pk_bf16(f[4], f[5]); w.w = cvt_pk_bf16(f[6], f[7]); return w; }
; __device__ __forceinline__ void r3_item(const bf16_t* __restrict__ proj, const bf16_t* __restrict__ projT, const bf16_t* __restrict__ st, bf16_t* ro, ...
;     ...
;     for (int q = 0; q < 4; ++q) { float s1 = 0.f, s2 = 0.f; const int n = 32 * q + c;
; #pragma unroll
;         for (int k = 0; k < 8; ++k) { s1 += stat[(k * 128 + n) * 2]; s2 += stat[(k * 128 + n) * 2 + 1]; }
;         const float mu = s1 * (1.0f / 256.0f); float var = s2 * (1.0f / 256.0f) - mu * mu; var = var < 0.f ? 0.f : var; const float rs = rsqrtf(var + EPS);
; #pragma unroll
;         for (int g4 = 0; g4 < 4; ++g4) { u32x2 pw; pw.x = cvt_pk_bf16((acc[q][4 * g4] - mu) * rs, (acc[q][4 * g4 + 1] - mu) * rs); pw.y = cvt_pk_bf16((acc[q][4 * g4 + 2] - mu) * rs, (acc[q][4 * g4 + 3] - mu) * rs);
;             *(LAS u32x2*)(Ol + n * OL_STRIDE + 32 * w + 8 * g4 + 4 * hh) = pw; } }
;     __syncthreads();
; #pragma unroll
;     for (int it = 0; it < 8; ++it) { const int id = tid + NTHREADS * it, tq = id >> 5, d8 = (id & 31) * 8;
;         float y[8], rg[8], o[8]; unpack8(*(const LAS u32x4*)(Ol + tq * OL_STRIDE + d8), y);
;         unpack8(__builtin_nontemporal_load((const u32x4*)(proj + (size_t)(tok0 + tq) * NPROJ + 2048 + h * 256 + d8)), rg);
;         const f32x4 g0 = *(const f32x4*)(gn + h * 256 + d8), g1 = *(const f32x4*)(gn + h * 256 + d8 + 4);
; #pragma unroll
;         for (int j = 0; j < 8; ++j) { const float gv = j < 4 ? g0[j & 3] : g1[j & 3]; o[j] = rg[j] * sigmoidf_(rg[j]) * y[j] * gv; }
;         *(u32x4*)(ro + (size_t)(tok0 + tq) * 1536 + 512 + h * 256 + d8) = pack8(o); }
	v_pk_add_f32 v[18:19], v[22:23], v[18:19]
	s_nop 0
	v_pk_add_f32 v[18:19], v[18:19], v[20:21]
	v_mov_b64_e32 v[22:23], s[40:41]
	v_pk_mul_f32 v[18:19], v[18:19], s[66:67] op_sel_hi:[1,0]
	s_nop 0
	v_fma_f32 v0, -v18, v18, v19
	v_cmp_ngt_f32_e32 vcc, 0, v0
	v_pk_add_f32 v[2:3], v[2:3], v[18:19] op_sel_hi:[1,0] neg_lo:[0,1] neg_hi:[0,1]
	v_pk_add_f32 v[4:5], v[4:5], v[18:19] op_sel_hi:[1,0] neg_lo:[0,1] neg_hi:[0,1]
	v_cndmask_b32_e32 v0, 0, v0, vcc
	v_add_f32_e32 v0, 0x358637bd, v0
	v_cmp_gt_f32_e32 vcc, s65, v0
	v_mul_f32_e32 v20, 0x4b800000, v0
	s_nop 0
	v_cndmask_b32_e32 v0, v0, v20, vcc
	v_rsq_f32_e32 v0, v0
	s_nop 0
	v_mul_f32_e32 v20, 0x45800000, v0
	v_cndmask_b32_e32 v0, v0, v20, vcc
	v_pk_mul_f32 v[2:3], v[2:3], v[0:1] op_sel_hi:[1,0]
	v_pk_mul_f32 v[4:5], v[4:5], v[0:1] op_sel_hi:[1,0]
	v_cvt_pk_bf16_f32 v2, v2, v3
	v_cvt_pk_bf16_f32 v3, v4, v5
	v_pk_add_f32 v[4:5], v[6:7], v[18:19] op_sel_hi:[1,0] neg_lo:[0,1] neg_hi:[0,1]
	v_pk_add_f32 v[6:7], v[8:9], v[18:19] op_sel_hi:[1,0] neg_lo:[0,1] neg_hi:[0,1]
	v_pk_mul_f32 v[4:5], v[4:5], v[0:1] op_sel_hi:[1,0]
	v_pk_mul_f32 v[6:7], v[6:7], v[0:1] op_sel_hi:[1,0]
	v_cvt_pk_bf16_f32 v4, v4, v5
	v_cvt_pk_bf16_f32 v5, v6, v7
	v_add_u32_e32 v8, 0xc000, v68
	ds_write2_b64 v8, v[2:3], v[4:5] offset0:192 offset1:194
	v_pk_add_f32 v[2:3], v[10:11], v[18:19] op_sel_hi:[1,0] neg_lo:[0,1] neg_hi:[0,1]
	v_pk_add_f32 v[4:5], v[12:13], v[18:19] op_sel_hi:[1,0] neg_lo:[0,1] neg_hi:[0,1]
	v_pk_mul_f32 v[2:3], v[2:3], v[0:1] op_sel_hi:[1,0]
	v_pk_mul_f32 v[4:5], v[4:5], v[0:1] op_sel_hi:[1,0]
	v_cvt_pk_bf16_f32 v2, v2, v3
	v_cvt_pk_bf16_f32 v3, v4, v5
	v_pk_add_f32 v[4:5], v[14:15], v[18:19] op_sel_hi:[1,0] neg_lo:[0,1] neg_hi:[0,1]
	v_pk_add_f32 v[6:7], v[16:17], v[18:19] op_sel_hi:[1,0] neg_lo:[0,1] neg_hi:[0,1]
	v_pk_mul_f32 v[4:5], v[4:5], v[0:1] op_sel_hi:[1,0]
	v_pk_mul_f32 v[6:7], v[6:7], v[0:1] op_sel_hi:[1,0]
	v_cvt_pk_bf16_f32 v4, v4, v5
	v_cvt_pk_bf16_f32 v5, v6, v7
	ds_write2_b64 v8, v[2:3], v[4:5] offset0:196 offset1:198
	v_and_b32_e32 v2, 0xf8, v249
	v_lshlrev_b32_e32 v0, 1, v2
	v_add_u32_e32 v20, 0, v0
	v_lshlrev_b32_e32 v6, 2, v2
	v_ashrrev_i32_e32 v14, 5, v247
	s_waitcnt lgkmcnt(0)
	s_barrier
	global_load_dwordx4 v[2:5], v6, s[10:11] offset:16
	s_nop 0
	global_load_dwordx4 v[6:9], v6, s[10:11]
	v_mad_u64_u32 v[10:11], s[10:11], v14, s56, v[20:21]
	v_add_u32_e32 v21, s6, v14
	v_mad_i64_i32 v[14:15], s[10:11], v21, s18, v[22:23]
	v_lshl_add_u64 v[14:15], v[14:15], 0, s[58:59]
	v_lshl_add_u64 v[14:15], v[14:15], 0, v[0:1]
	v_add_co_u32_e32 v14, vcc, s23, v14
	ds_read_b128 v[10:13], v10
	s_nop 0
	v_addc_co_u32_e32 v15, vcc, 0, v15, vcc
	s_waitcnt vmcnt(0)
	v_mov_b64_e32 v[14:15], v[80:81]
	v_mov_b64_e32 v[16:17], v[82:83]
	s_waitcnt lgkmcnt(0)
	v_lshlrev_b32_e32 v18, 16, v10
	v_and_b32_e32 v19, 0xffff0000, v10
	s_waitcnt vmcnt(0)
	v_lshlrev_b32_e32 v24, 16, v14
	v_mul_f32_e32 v10, 0xbfb8aa3b, v24
	v_exp_f32_e32 v10, v10
	v_and_b32_e32 v25, 0xffff0000, v14
	v_lshlrev_b32_e32 v14, 16, v15
	v_and_b32_e32 v15, 0xffff0000, v15
	v_add_f32_e32 v10, 1.0, v10
	v_rcp_f32_e32 v26, v10
	v_mul_f32_e32 v10, 0xbfb8aa3b, v25
	v_exp_f32_e32 v10, v10
	s_nop 0
	v_add_f32_e32 v10, 1.0, v10
	v_rcp_f32_e32 v27, v10
	v_lshlrev_b32_e32 v10, 16, v11
	v_and_b32_e32 v11, 0xffff0000, v11
	v_pk_mul_f32 v[24:25], v[26:27], v[24:25]
	s_nop 0
	v_pk_mul_f32 v[18:19], v[24:25], v[18:19]
	v_mul_f32_e32 v24, 0xbfb8aa3b, v14
	v_mul_f32_e32 v25, 0xbfb8aa3b, v15
	v_exp_f32_e32 v24, v24
	v_exp_f32_e32 v25, v25
	v_pk_mul_f32 v[18:19], v[6:7], v[18:19]
	v_add_f32_e32 v24, 1.0, v24
	v_add_f32_e32 v25, 1.0, v25
	v_rcp_f32_e32 v24, v24
	v_rcp_f32_e32 v25, v25
	s_nop 0
	v_pk_mul_f32 v[14:15], v[24:25], v[14:15]
	s_nop 0
	v_pk_mul_f32 v[10:11], v[14:15], v[10:11]
	v_lshlrev_b32_e32 v24, 16, v16
	v_pk_mul_f32 v[14:15], v[8:9], v[10:11]
	v_lshlrev_b32_e32 v10, 16, v12
	v_and_b32_e32 v11, 0xffff0000, v12
	v_mul_f32_e32 v12, 0xbfb8aa3b, v24
	v_exp_f32_e32 v12, v12
	v_and_b32_e32 v25, 0xffff0000, v16
	v_add_f32_e32 v12, 1.0, v12
	v_rcp_f32_e32 v26, v12
	v_mul_f32_e32 v12, 0xbfb8aa3b, v25
	v_exp_f32_e32 v12, v12
	s_nop 0
	v_add_f32_e32 v12, 1.0, v12
	v_rcp_f32_e32 v27, v12
	v_lshlrev_b32_e32 v12, 16, v17
	v_mul_f32_e32 v16, 0xbfb8aa3b, v12
	v_exp_f32_e32 v16, v16
	v_pk_mul_f32 v[24:25], v[26:27], v[24:25]
	v_add_f32_e32 v16, 1.0, v16
	v_pk_mul_f32 v[10:11], v[24:25], v[10:11]
	v_rcp_f32_e32 v16, v16
	v_pk_mul_f32 v[24:25], v[2:3], v[10:11]
	v_lshlrev_b32_e32 v10, 16, v13
	v_and_b32_e32 v11, 0xffff0000, v13
	v_and_b32_e32 v13, 0xffff0000, v17
	v_mul_f32_e32 v17, 0xbfb8aa3b, v13
	v_exp_f32_e32 v17, v17
	s_nop 0
	v_add_f32_e32 v17, 1.0, v17
	v_rcp_f32_e32 v17, v17
	s_nop 0
	v_pk_mul_f32 v[12:13], v[16:17], v[12:13]
	s_nop 0
	v_pk_mul_f32 v[10:11], v[12:13], v[10:11]
	v_cvt_pk_bf16_f32 v12, v24, v25
	v_pk_mul_f32 v[16:17], v[4:5], v[10:11]
	v_cvt_pk_bf16_f32 v10, v18, v19
	v_mov_b64_e32 v[18:19], s[4:5]
	v_cvt_pk_bf16_f32 v11, v14, v15
	v_mad_i64_i32 v[14:15], s[4:5], v21, s24, v[18:19]
	v_lshl_add_u64 v[14:15], v[14:15], 0, s[58:59]
	v_cvt_pk_bf16_f32 v13, v16, v17
	v_lshl_add_u64 v[14:15], v[14:15], 0, v[0:1]
	global_store_dwordx4 v[14:15], v[10:13], off offset:1024
	v_ashrrev_i32_e32 v14, 5, v248
	s_nop 0
	v_mad_u64_u32 v[10:11], s[4:5], v14, s56, v[20:21]
	v_add_u32_e32 v21, s6, v14
	v_mad_i64_i32 v[14:15], s[4:5], v21, s18, v[22:23]
	v_lshl_add_u64 v[14:15], v[14:15], 0, s[58:59]
	v_lshl_add_u64 v[14:15], v[14:15], 0, v[0:1]
	v_add_co_u32_e32 v14, vcc, s23, v14
	ds_read_b128 v[10:13], v10
	s_nop 0
	v_addc_co_u32_e32 v15, vcc, 0, v15, vcc
	v_mov_b64_e32 v[14:15], v[84:85]
	v_mov_b64_e32 v[16:17], v[86:87]
	s_waitcnt lgkmcnt(0)
; #define LAS __attribute__((address_space(3)))
; __device__ __forceinline__ float sigmoidf_(float x) { return __builtin_amdgcn_rcpf(1.0f + __expf(-x)); }
; __device__ __forceinline__ void unpack8(const u32x4 w, float* f) { f[0] = bf_lo(w.x); f[1] = bf_hi(w.x); f[2] = bf_lo(w.y); f[3] = bf_hi(w.y); f[4] = bf_lo(w.z); f[5] = bf_hi(w.z); f[6] = bf_lo(w.w); f[7] = bf_hi(w.w); }
; __device__ __forceinline__ u32x4 pack8(const float* f) { u32x4 w; w.x = cvt_pk_bf16(f[0], f[1]); w.y = cvt_pk_bf16(f[2], f[3]); w.z = cvt_pk_bf16(f[4], f[5]); w.w = cvt_pk_bf16(f[6], f[7]); return w; }
; __device__ __forceinline__ void r3_item(const bf16_t* __restrict__ proj, const bf16_t* __restrict__ projT, const bf16_t* __restrict__ st, bf16_t* ro, ...
;     ...
;     for (int it = 0; it < 8; ++it) { const int id = tid + NTHREADS * it, tq = id >> 5, d8 = (id & 31) * 8;
;         float y[8], rg[8], o[8]; unpack8(*(const LAS u32x4*)(Ol + tq * OL_STRIDE + d8), y);
;         unpack8(__builtin_nontemporal_load((const u32x4*)(proj + (size_t)(tok0 + tq) * NPROJ + 2048 + h * 256 + d8)), rg);
;         const f32x4 g0 = *(const f32x4*)(gn + h * 256 + d8), g1 = *(const f32x4*)(gn + h * 256 + d8 + 4);
; #pragma unroll
;         for (int j = 0; j < 8; ++j) { const float gv = j < 4 ? g0[j & 3] : g1[j & 3]; o[j] = rg[j] * sigmoidf_(rg[j]) * y[j] * gv; }
;         *(u32x4*)(ro + (size_t)(tok0 + tq) * 1536 + 512 + h * 256 + d8) = pack8(o); }
	v_lshlrev_b32_e32 v24, 16, v10
	v_and_b32_e32 v25, 0xffff0000, v10
	v_lshlrev_b32_e32 v26, 16, v14
	v_mul_f32_e32 v10, 0xbfb8aa3b, v26
	v_exp_f32_e32 v10, v10
	v_and_b32_e32 v27, 0xffff0000, v14
	v_lshlrev_b32_e32 v14, 16, v15
	v_and_b32_e32 v15, 0xffff0000, v15
	v_add_f32_e32 v10, 1.0, v10
	v_rcp_f32_e32 v28, v10
	v_mul_f32_e32 v10, 0xbfb8aa3b, v27
	v_exp_f32_e32 v10, v10
	s_nop 0
	v_add_f32_e32 v10, 1.0, v10
	v_rcp_f32_e32 v29, v10
	v_lshlrev_b32_e32 v10, 16, v11
	v_and_b32_e32 v11, 0xffff0000, v11
	v_pk_mul_f32 v[26:27], v[28:29], v[26:27]
	s_nop 0
	v_pk_mul_f32 v[24:25], v[26:27], v[24:25]
	v_mul_f32_e32 v26, 0xbfb8aa3b, v14
	v_mul_f32_e32 v27, 0xbfb8aa3b, v15
	v_exp_f32_e32 v26, v26
	v_exp_f32_e32 v27, v27
	v_pk_mul_f32 v[24:25], v[6:7], v[24:25]
	v_add_f32_e32 v26, 1.0, v26
	v_add_f32_e32 v27, 1.0, v27
	v_rcp_f32_e32 v26, v26
	v_rcp_f32_e32 v27, v27
	s_nop 0
	v_pk_mul_f32 v[14:15], v[26:27], v[14:15]
	s_nop 0
	v_pk_mul_f32 v[10:11], v[14:15], v[10:11]
	v_lshlrev_b32_e32 v26, 16, v16
	v_pk_mul_f32 v[14:15], v[8:9], v[10:11]
	v_lshlrev_b32_e32 v10, 16, v12
	v_and_b32_e32 v11, 0xffff0000, v12
	v_mul_f32_e32 v12, 0xbfb8aa3b, v26
	v_exp_f32_e32 v12, v12
	v_and_b32_e32 v27, 0xffff0000, v16
	v_add_f32_e32 v12, 1.0, v12
	v_rcp_f32_e32 v28, v12
	v_mul_f32_e32 v12, 0xbfb8aa3b, v27
	v_exp_f32_e32 v12, v12
	s_nop 0
	v_add_f32_e32 v12, 1.0, v12
	v_rcp_f32_e32 v29, v12
	v_lshlrev_b32_e32 v12, 16, v17
	v_mul_f32_e32 v16, 0xbfb8aa3b, v12
	v_exp_f32_e32 v16, v16
	v_pk_mul_f32 v[26:27], v[28:29], v[26:27]
	v_add_f32_e32 v16, 1.0, v16
	v_pk_mul_f32 v[10:11], v[26:27], v[10:11]
	v_rcp_f32_e32 v16, v16
	v_pk_mul_f32 v[26:27], v[2:3], v[10:11]
	v_lshlrev_b32_e32 v10, 16, v13
	v_and_b32_e32 v11, 0xffff0000, v13
	v_and_b32_e32 v13, 0xffff0000, v17
	v_mul_f32_e32 v17, 0xbfb8aa3b, v13
	v_exp_f32_e32 v17, v17
	s_nop 0
	v_add_f32_e32 v17, 1.0, v17
	v_rcp_f32_e32 v17, v17
	s_nop 0
	v_pk_mul_f32 v[12:13], v[16:17], v[12:13]
	s_nop 0
	v_pk_mul_f32 v[10:11], v[12:13], v[10:11]
	v_cvt_pk_bf16_f32 v12, v26, v27
	v_pk_mul_f32 v[16:17], v[4:5], v[10:11]
	v_cvt_pk_bf16_f32 v11, v14, v15
	v_mad_i64_i32 v[14:15], s[4:5], v21, s24, v[18:19]
	v_lshl_add_u64 v[14:15], v[14:15], 0, s[58:59]
	v_cvt_pk_bf16_f32 v10, v24, v25
	v_cvt_pk_bf16_f32 v13, v16, v17
	v_lshl_add_u64 v[14:15], v[14:15], 0, v[0:1]
	global_store_dwordx4 v[14:15], v[10:13], off offset:1024
	s_nop 1
	v_add_u32_e32 v10, 0x400, v247
	v_ashrrev_i32_e32 v14, 5, v10
	v_mad_u64_u32 v[10:11], s[4:5], v14, s56, v[20:21]
	v_add_u32_e32 v21, s6, v14
	v_mad_i64_i32 v[14:15], s[4:5], v21, s18, v[22:23]
	v_lshl_add_u64 v[14:15], v[14:15], 0, s[58:59]
	v_lshl_add_u64 v[14:15], v[14:15], 0, v[0:1]
	v_add_co_u32_e32 v14, vcc, s23, v14
	ds_read_b128 v[10:13], v10
	s_nop 0
	v_addc_co_u32_e32 v15, vcc, 0, v15, vcc
	v_mov_b64_e32 v[14:15], v[88:89]
	v_mov_b64_e32 v[16:17], v[90:91]
	s_waitcnt lgkmcnt(0)
	v_lshlrev_b32_e32 v24, 16, v10
	v_and_b32_e32 v25, 0xffff0000, v10
	v_lshlrev_b32_e32 v26, 16, v14
	v_mul_f32_e32 v10, 0xbfb8aa3b, v26
	v_exp_f32_e32 v10, v10
	v_and_b32_e32 v27, 0xffff0000, v14
	v_lshlrev_b32_e32 v14, 16, v15
	v_and_b32_e32 v15, 0xffff0000, v15
	v_add_f32_e32 v10, 1.0, v10
	v_rcp_f32_e32 v28, v10
	v_mul_f32_e32 v10, 0xbfb8aa3b, v27
	v_exp_f32_e32 v10, v10
	s_nop 0
	v_add_f32_e32 v10, 1.0, v10
	v_rcp_f32_e32 v29, v10
	v_lshlrev_b32_e32 v10, 16, v11
	v_and_b32_e32 v11, 0xffff0000, v11
	v_pk_mul_f32 v[26:27], v[28:29], v[26:27]
	s_nop 0
	v_pk_mul_f32 v[24:25], v[26:27], v[24:25]
	v_mul_f32_e32 v26, 0xbfb8aa3b, v14
	v_mul_f32_e32 v27, 0xbfb8aa3b, v15
	v_exp_f32_e32 v26, v26
	v_exp_f32_e32 v27, v27
	v_pk_mul_f32 v[24:25], v[6:7], v[24:25]
	v_add_f32_e32 v26, 1.0, v26
	v_add_f32_e32 v27, 1.0, v27
	v_rcp_f32_e32 v26, v26
	v_rcp_f32_e32 v27, v27
	s_nop 0
	v_pk_mul_f32 v[14:15], v[26:27], v[14:15]
	s_nop 0
	v_pk_mul_f32 v[10:11], v[14:15], v[10:11]
	v_lshlrev_b32_e32 v26, 16, v16
	v_pk_mul_f32 v[14:15], v[8:9], v[10:11]
	v_lshlrev_b32_e32 v10, 16, v12
	v_and_b32_e32 v11, 0xffff0000, v12
	v_mul_f32_e32 v12, 0xbfb8aa3b, v26
	v_exp_f32_e32 v12, v12
	v_and_b32_e32 v27, 0xffff0000, v16
	v_add_f32_e32 v12, 1.0, v12
	v_rcp_f32_e32 v28, v12
	v_mul_f32_e32 v12, 0xbfb8aa3b, v27
	v_exp_f32_e32 v12, v12
	s_nop 0
	v_add_f32_e32 v12, 1.0, v12
	v_rcp_f32_e32 v29, v12
	v_lshlrev_b32_e32 v12, 16, v17
	v_mul_f32_e32 v16, 0xbfb8aa3b, v12
	v_exp_f32_e32 v16, v16
	v_pk_mul_f32 v[26:27], v[28:29], v[26:27]
	v_add_f32_e32 v16, 1.0, v16
	v_pk_mul_f32 v[10:11], v[26:27], v[10:11]
	v_rcp_f32_e32 v16, v16
	v_pk_mul_f32 v[26:27], v[2:3], v[10:11]
	v_lshlrev_b32_e32 v10, 16, v13
	v_and_b32_e32 v11, 0xffff0000, v13
	v_and_b32_e32 v13, 0xffff0000, v17
	v_mul_f32_e32 v17, 0xbfb8aa3b, v13
	v_exp_f32_e32 v17, v17
	s_nop 0
	v_add_f32_e32 v17, 1.0, v17
	v_rcp_f32_e32 v17, v17
	s_nop 0
	v_pk_mul_f32 v[12:13], v[16:17], v[12:13]
	s_nop 0
	v_pk_mul_f32 v[10:11], v[12:13], v[10:11]
	v_cvt_pk_bf16_f32 v12, v26, v27
	v_pk_mul_f32 v[16:17], v[4:5], v[10:11]
	v_cvt_pk_bf16_f32 v11, v14, v15
	v_mad_i64_i32 v[14:15], s[4:5], v21, s24, v[18:19]
	v_lshl_add_u64 v[14:15], v[14:15], 0, s[58:59]
	v_cvt_pk_bf16_f32 v10, v24, v25
	v_cvt_pk_bf16_f32 v13, v16, v17
	v_lshl_add_u64 v[14:15], v[14:15], 0, v[0:1]
	global_store_dwordx4 v[14:15], v[10:13], off offset:1024
	s_nop 1
	v_add_u32_e32 v10, 0x600, v247
	v_ashrrev_i32_e32 v14, 5, v10
	v_mad_u64_u32 v[10:11], s[4:5], v14, s56, v[20:21]
	v_add_u32_e32 v21, s6, v14
	v_mad_i64_i32 v[14:15], s[4:5], v21, s18, v[22:23]
	v_lshl_add_u64 v[14:15], v[14:15], 0, s[58:59]
	v_lshl_add_u64 v[14:15], v[14:15], 0, v[0:1]
	v_add_co_u32_e32 v14, vcc, s23, v14
	ds_read_b128 v[10:13], v10
	s_nop 0
	v_addc_co_u32_e32 v15, vcc, 0, v15, vcc
	v_mov_b64_e32 v[14:15], v[92:93]
	v_mov_b64_e32 v[16:17], v[94:95]
	s_waitcnt lgkmcnt(0)
; #define LAS __attribute__((address_space(3)))
; __device__ __forceinline__ float sigmoidf_(float x) { return __builtin_amdgcn_rcpf(1.0f + __expf(-x)); }
; __device__ __forceinline__ void unpack8(const u32x4 w, float* f) { f[0] = bf_lo(w.x); f[1] = bf_hi(w.x); f[2] = bf_lo(w.y); f[3] = bf_hi(w.y); f[4] = bf_lo(w.z); f[5] = bf_hi(w.z); f[6] = bf_lo(w.w); f[7] = bf_hi(w.w); }
; __device__ __forceinline__ u32x4 pack8(const float* f) { u32x4 w; w.x = cvt_pk_bf16(f[0], f[1]); w.y = cvt_pk_bf16(f[2], f[3]); w.z = cvt_pk_bf16(f[4], f[5]); w.w = cvt_pk_bf16(f[6], f[7]); return w; }
; __device__ __forceinline__ void r3_item(const bf16_t* __restrict__ proj, const bf16_t* __restrict__ projT, const bf16_t* __restrict__ st, bf16_t* ro, ...
;     ...
;     for (int it = 0; it < 8; ++it) { const int id = tid + NTHREADS * it, tq = id >> 5, d8 = (id & 31) * 8;
;         float y[8], rg[8], o[8]; unpack8(*(const LAS u32x4*)(Ol + tq * OL_STRIDE + d8), y);
;         unpack8(__builtin_nontemporal_load((const u32x4*)(proj + (size_t)(tok0 + tq) * NPROJ + 2048 + h * 256 + d8)), rg);
;         const f32x4 g0 = *(const f32x4*)(gn + h * 256 + d8), g1 = *(const f32x4*)(gn + h * 256 + d8 + 4);
; #pragma unroll
;         for (int j = 0; j < 8; ++j) { const float gv = j < 4 ? g0[j & 3] : g1[j & 3]; o[j] = rg[j] * sigmoidf_(rg[j]) * y[j] * gv; }
;         *(u32x4*)(ro + (size_t)(tok0 + tq) * 1536 + 512 + h * 256 + d8) = pack8(o); }
	v_lshlrev_b32_e32 v24, 16, v10
	v_and_b32_e32 v25, 0xffff0000, v10
	v_lshlrev_b32_e32 v26, 16, v14
	v_mul_f32_e32 v10, 0xbfb8aa3b, v26
	v_exp_f32_e32 v10, v10
	v_and_b32_e32 v27, 0xffff0000, v14
	v_lshlrev_b32_e32 v14, 16, v15
	v_and_b32_e32 v15, 0xffff0000, v15
	v_add_f32_e32 v10, 1.0, v10
	v_rcp_f32_e32 v28, v10
	v_mul_f32_e32 v10, 0xbfb8aa3b, v27
	v_exp_f32_e32 v10, v10
	s_nop 0
	v_add_f32_e32 v10, 1.0, v10
	v_rcp_f32_e32 v29, v10
	v_lshlrev_b32_e32 v10, 16, v11
	v_and_b32_e32 v11, 0xffff0000, v11
	v_pk_mul_f32 v[26:27], v[28:29], v[26:27]
	s_nop 0
	v_pk_mul_f32 v[24:25], v[26:27], v[24:25]
	v_mul_f32_e32 v26, 0xbfb8aa3b, v14
	v_mul_f32_e32 v27, 0xbfb8aa3b, v15
	v_exp_f32_e32 v26, v26
	v_exp_f32_e32 v27, v27
	v_pk_mul_f32 v[24:25], v[6:7], v[24:25]
	v_add_f32_e32 v26, 1.0, v26
	v_add_f32_e32 v27, 1.0, v27
	v_rcp_f32_e32 v26, v26
	v_rcp_f32_e32 v27, v27
	s_nop 0
	v_pk_mul_f32 v[14:15], v[26:27], v[14:15]
	s_nop 0
	v_pk_mul_f32 v[10:11], v[14:15], v[10:11]
	v_lshlrev_b32_e32 v26, 16, v16
	v_pk_mul_f32 v[14:15], v[8:9], v[10:11]
	v_lshlrev_b32_e32 v10, 16, v12
	v_and_b32_e32 v11, 0xffff0000, v12
	v_mul_f32_e32 v12, 0xbfb8aa3b, v26
	v_exp_f32_e32 v12, v12
	v_and_b32_e32 v27, 0xffff0000, v16
	v_add_f32_e32 v12, 1.0, v12
	v_rcp_f32_e32 v28, v12
	v_mul_f32_e32 v12, 0xbfb8aa3b, v27
	v_exp_f32_e32 v12, v12
	s_nop 0
	v_add_f32_e32 v12, 1.0, v12
	v_rcp_f32_e32 v29, v12
	v_lshlrev_b32_e32 v12, 16, v17
	v_mul_f32_e32 v16, 0xbfb8aa3b, v12
	v_exp_f32_e32 v16, v16
	v_pk_mul_f32 v[26:27], v[28:29], v[26:27]
	v_add_f32_e32 v16, 1.0, v16
	v_pk_mul_f32 v[10:11], v[26:27], v[10:11]
	v_rcp_f32_e32 v16, v16
	v_pk_mul_f32 v[26:27], v[2:3], v[10:11]
	v_lshlrev_b32_e32 v10, 16, v13
	v_and_b32_e32 v11, 0xffff0000, v13
	v_and_b32_e32 v13, 0xffff0000, v17
	v_mul_f32_e32 v17, 0xbfb8aa3b, v13
	v_exp_f32_e32 v17, v17
	s_nop 0
	v_add_f32_e32 v17, 1.0, v17
	v_rcp_f32_e32 v17, v17
	s_nop 0
	v_pk_mul_f32 v[12:13], v[16:17], v[12:13]
	s_nop 0
	v_pk_mul_f32 v[10:11], v[12:13], v[10:11]
	v_cvt_pk_bf16_f32 v12, v26, v27
	v_pk_mul_f32 v[16:17], v[4:5], v[10:11]
	v_cvt_pk_bf16_f32 v11, v14, v15
	v_mad_i64_i32 v[14:15], s[4:5], v21, s24, v[18:19]
	v_lshl_add_u64 v[14:15], v[14:15], 0, s[58:59]
	v_cvt_pk_bf16_f32 v10, v24, v25
	v_cvt_pk_bf16_f32 v13, v16, v17
	v_lshl_add_u64 v[14:15], v[14:15], 0, v[0:1]
	global_store_dwordx4 v[14:15], v[10:13], off offset:1024
	s_nop 1
	v_add_u32_e32 v10, 0x800, v247
	v_ashrrev_i32_e32 v14, 5, v10
	v_mad_u64_u32 v[10:11], s[4:5], v14, s56, v[20:21]
	v_add_u32_e32 v21, s6, v14
	v_mad_i64_i32 v[14:15], s[4:5], v21, s18, v[22:23]
	v_lshl_add_u64 v[14:15], v[14:15], 0, s[58:59]
	v_lshl_add_u64 v[14:15], v[14:15], 0, v[0:1]
	v_add_co_u32_e32 v14, vcc, s23, v14
	ds_read_b128 v[10:13], v10
	s_nop 0
	v_addc_co_u32_e32 v15, vcc, 0, v15, vcc
	v_mov_b64_e32 v[14:15], v[96:97]
	v_mov_b64_e32 v[16:17], v[98:99]
	s_waitcnt lgkmcnt(0)
	v_lshlrev_b32_e32 v24, 16, v10
	v_and_b32_e32 v25, 0xffff0000, v10
	v_lshlrev_b32_e32 v26, 16, v14
	v_mul_f32_e32 v10, 0xbfb8aa3b, v26
	v_exp_f32_e32 v10, v10
	v_and_b32_e32 v27, 0xffff0000, v14
	v_lshlrev_b32_e32 v14, 16, v15
	v_and_b32_e32 v15, 0xffff0000, v15
	v_add_f32_e32 v10, 1.0, v10
	v_rcp_f32_e32 v28, v10
	v_mul_f32_e32 v10, 0xbfb8aa3b, v27
	v_exp_f32_e32 v10, v10
	s_nop 0
	v_add_f32_e32 v10, 1.0, v10
	v_rcp_f32_e32 v29, v10
	v_lshlrev_b32_e32 v10, 16, v11
	v_and_b32_e32 v11, 0xffff0000, v11
	v_pk_mul_f32 v[26:27], v[28:29], v[26:27]
	s_nop 0
	v_pk_mul_f32 v[24:25], v[26:27], v[24:25]
	v_mul_f32_e32 v26, 0xbfb8aa3b, v14
	v_mul_f32_e32 v27, 0xbfb8aa3b, v15
	v_exp_f32_e32 v26, v26
	v_exp_f32_e32 v27, v27
	v_pk_mul_f32 v[24:25], v[6:7], v[24:25]
	v_add_f32_e32 v26, 1.0, v26
	v_add_f32_e32 v27, 1.0, v27
	v_rcp_f32_e32 v26, v26
	v_rcp_f32_e32 v27, v27
	s_nop 0
	v_pk_mul_f32 v[14:15], v[26:27], v[14:15]
	s_nop 0
	v_pk_mul_f32 v[10:11], v[14:15], v[10:11]
	v_lshlrev_b32_e32 v26, 16, v16
	v_pk_mul_f32 v[14:15], v[8:9], v[10:11]
	v_lshlrev_b32_e32 v10, 16, v12
	v_and_b32_e32 v11, 0xffff0000, v12
	v_mul_f32_e32 v12, 0xbfb8aa3b, v26
	v_exp_f32_e32 v12, v12
	v_and_b32_e32 v27, 0xffff0000, v16
	v_add_f32_e32 v12, 1.0, v12
	v_rcp_f32_e32 v28, v12
	v_mul_f32_e32 v12, 0xbfb8aa3b, v27
	v_exp_f32_e32 v12, v12
	s_nop 0
	v_add_f32_e32 v12, 1.0, v12
	v_rcp_f32_e32 v29, v12
	v_lshlrev_b32_e32 v12, 16, v17
	v_mul_f32_e32 v16, 0xbfb8aa3b, v12
	v_exp_f32_e32 v16, v16
	v_pk_mul_f32 v[26:27], v[28:29], v[26:27]
	v_add_f32_e32 v16, 1.0, v16
	v_pk_mul_f32 v[10:11], v[26:27], v[10:11]
	v_rcp_f32_e32 v16, v16
	v_pk_mul_f32 v[26:27], v[2:3], v[10:11]
	v_lshlrev_b32_e32 v10, 16, v13
	v_and_b32_e32 v11, 0xffff0000, v13
	v_and_b32_e32 v13, 0xffff0000, v17
	v_mul_f32_e32 v17, 0xbfb8aa3b, v13
	v_exp_f32_e32 v17, v17
	s_nop 0
	v_add_f32_e32 v17, 1.0, v17
	v_rcp_f32_e32 v17, v17
	s_nop 0
	v_pk_mul_f32 v[12:13], v[16:17], v[12:13]
	s_nop 0
	v_pk_mul_f32 v[10:11], v[12:13], v[10:11]
	v_cvt_pk_bf16_f32 v12, v26, v27
	v_pk_mul_f32 v[16:17], v[4:5], v[10:11]
	v_cvt_pk_bf16_f32 v11, v14, v15
	v_mad_i64_i32 v[14:15], s[4:5], v21, s24, v[18:19]
	v_lshl_add_u64 v[14:15], v[14:15], 0, s[58:59]
	v_cvt_pk_bf16_f32 v10, v24, v25
	v_cvt_pk_bf16_f32 v13, v16, v17
	v_lshl_add_u64 v[14:15], v[14:15], 0, v[0:1]
	global_store_dwordx4 v[14:15], v[10:13], off offset:1024
	s_nop 1
	v_add_u32_e32 v10, 0xa00, v247
	v_ashrrev_i32_e32 v14, 5, v10
	v_mad_u64_u32 v[10:11], s[4:5], v14, s56, v[20:21]
	v_add_u32_e32 v21, s6, v14
	v_mad_i64_i32 v[14:15], s[4:5], v21, s18, v[22:23]
	v_lshl_add_u64 v[14:15], v[14:15], 0, s[58:59]
	v_lshl_add_u64 v[14:15], v[14:15], 0, v[0:1]
	v_add_co_u32_e32 v14, vcc, s23, v14
	ds_read_b128 v[10:13], v10
	s_nop 0
	v_addc_co_u32_e32 v15, vcc, 0, v15, vcc
	v_mov_b64_e32 v[14:15], v[100:101]
	v_mov_b64_e32 v[16:17], v[102:103]
	s_waitcnt lgkmcnt(0)
; #define LAS __attribute__((address_space(3)))
; __device__ __forceinline__ float sigmoidf_(float x) { return __builtin_amdgcn_rcpf(1.0f + __expf(-x)); }
; __device__ __forceinline__ void unpack8(const u32x4 w, float* f) { f[0] = bf_lo(w.x); f[1] = bf_hi(w.x); f[2] = bf_lo(w.y); f[3] = bf_hi(w.y); f[4] = bf_lo(w.z); f[5] = bf_hi(w.z); f[6] = bf_lo(w.w); f[7] = bf_hi(w.w); }
; __device__ __forceinline__ u32x4 pack8(const float* f) { u32x4 w; w.x = cvt_pk_bf16(f[0], f[1]); w.y = cvt_pk_bf16(f[2], f[3]); w.z = cvt_pk_bf16(f[4], f[5]); w.w = cvt_pk_bf16(f[6], f[7]); return w; }
; __device__ __forceinline__ void r3_item(const bf16_t* __restrict__ proj, const bf16_t* __restrict__ projT, const bf16_t* __restrict__ st, bf16_t* ro, ...
;     ...
;     for (int it = 0; it < 8; ++it) { const int id = tid + NTHREADS * it, tq = id >> 5, d8 = (id & 31) * 8;
;         float y[8], rg[8], o[8]; unpack8(*(const LAS u32x4*)(Ol + tq * OL_STRIDE + d8), y);
;         unpack8(__builtin_nontemporal_load((const u32x4*)(proj + (size_t)(tok0 + tq) * NPROJ + 2048 + h * 256 + d8)), rg);
;         const f32x4 g0 = *(const f32x4*)(gn + h * 256 + d8), g1 = *(const f32x4*)(gn + h * 256 + d8 + 4);
; #pragma unroll
;         for (int j = 0; j < 8; ++j) { const float gv = j < 4 ? g0[j & 3] : g1[j & 3]; o[j] = rg[j] * sigmoidf_(rg[j]) * y[j] * gv; }
;         *(u32x4*)(ro + (size_t)(tok0 + tq) * 1536 + 512 + h * 256 + d8) = pack8(o); }
	v_lshlrev_b32_e32 v24, 16, v10
	v_and_b32_e32 v25, 0xffff0000, v10
	v_lshlrev_b32_e32 v26, 16, v14
	v_mul_f32_e32 v10, 0xbfb8aa3b, v26
	v_exp_f32_e32 v10, v10
	v_and_b32_e32 v27, 0xffff0000, v14
	v_lshlrev_b32_e32 v14, 16, v15
	v_and_b32_e32 v15, 0xffff0000, v15
	v_add_f32_e32 v10, 1.0, v10
	v_rcp_f32_e32 v28, v10
	v_mul_f32_e32 v10, 0xbfb8aa3b, v27
	v_exp_f32_e32 v10, v10
	s_nop 0
	v_add_f32_e32 v10, 1.0, v10
	v_rcp_f32_e32 v29, v10
	v_lshlrev_b32_e32 v10, 16, v11
	v_and_b32_e32 v11, 0xffff0000, v11
	v_pk_mul_f32 v[26:27], v[28:29], v[26:27]
	s_nop 0
	v_pk_mul_f32 v[24:25], v[26:27], v[24:25]
	v_mul_f32_e32 v26, 0xbfb8aa3b, v14
	v_mul_f32_e32 v27, 0xbfb8aa3b, v15
	v_exp_f32_e32 v26, v26
	v_exp_f32_e32 v27, v27
	v_pk_mul_f32 v[24:25], v[6:7], v[24:25]
	v_add_f32_e32 v26, 1.0, v26
	v_add_f32_e32 v27, 1.0, v27
	v_rcp_f32_e32 v26, v26
	v_rcp_f32_e32 v27, v27
	s_nop 0
	v_pk_mul_f32 v[14:15], v[26:27], v[14:15]
	s_nop 0
	v_pk_mul_f32 v[10:11], v[14:15], v[10:11]
	v_lshlrev_b32_e32 v26, 16, v16
	v_pk_mul_f32 v[14:15], v[8:9], v[10:11]
	v_lshlrev_b32_e32 v10, 16, v12
	v_and_b32_e32 v11, 0xffff0000, v12
	v_mul_f32_e32 v12, 0xbfb8aa3b, v26
	v_exp_f32_e32 v12, v12
	v_and_b32_e32 v27, 0xffff0000, v16
	v_add_f32_e32 v12, 1.0, v12
	v_rcp_f32_e32 v28, v12
	v_mul_f32_e32 v12, 0xbfb8aa3b, v27
	v_exp_f32_e32 v12, v12
	s_nop 0
	v_add_f32_e32 v12, 1.0, v12
	v_rcp_f32_e32 v29, v12
	v_lshlrev_b32_e32 v12, 16, v17
	v_mul_f32_e32 v16, 0xbfb8aa3b, v12
	v_exp_f32_e32 v16, v16
	v_pk_mul_f32 v[26:27], v[28:29], v[26:27]
	v_add_f32_e32 v16, 1.0, v16
	v_pk_mul_f32 v[10:11], v[26:27], v[10:11]
	v_rcp_f32_e32 v16, v16
	v_pk_mul_f32 v[26:27], v[2:3], v[10:11]
	v_lshlrev_b32_e32 v10, 16, v13
	v_and_b32_e32 v11, 0xffff0000, v13
	v_and_b32_e32 v13, 0xffff0000, v17
	v_mul_f32_e32 v17, 0xbfb8aa3b, v13
	v_exp_f32_e32 v17, v17
	s_nop 0
	v_add_f32_e32 v17, 1.0, v17
	v_rcp_f32_e32 v17, v17
	s_nop 0
	v_pk_mul_f32 v[12:13], v[16:17], v[12:13]
	s_nop 0
	v_pk_mul_f32 v[10:11], v[12:13], v[10:11]
	v_cvt_pk_bf16_f32 v12, v26, v27
	v_pk_mul_f32 v[16:17], v[4:5], v[10:11]
	v_cvt_pk_bf16_f32 v11, v14, v15
	v_mad_i64_i32 v[14:15], s[4:5], v21, s24, v[18:19]
	v_lshl_add_u64 v[14:15], v[14:15], 0, s[58:59]
	v_cvt_pk_bf16_f32 v10, v24, v25
	v_cvt_pk_bf16_f32 v13, v16, v17
	v_lshl_add_u64 v[14:15], v[14:15], 0, v[0:1]
	global_store_dwordx4 v[14:15], v[10:13], off offset:1024
	s_nop 1
	v_add_u32_e32 v10, 0xc00, v247
	v_ashrrev_i32_e32 v14, 5, v10
	v_mad_u64_u32 v[10:11], s[4:5], v14, s56, v[20:21]
	v_add_u32_e32 v21, s6, v14
	v_mad_i64_i32 v[14:15], s[4:5], v21, s18, v[22:23]
	v_lshl_add_u64 v[14:15], v[14:15], 0, s[58:59]
	v_lshl_add_u64 v[14:15], v[14:15], 0, v[0:1]
	v_add_co_u32_e32 v14, vcc, s23, v14
	ds_read_b128 v[10:13], v10
	s_nop 0
	v_addc_co_u32_e32 v15, vcc, 0, v15, vcc
	v_mov_b64_e32 v[14:15], v[104:105]
	v_mov_b64_e32 v[16:17], v[106:107]
	s_waitcnt lgkmcnt(0)
	v_lshlrev_b32_e32 v24, 16, v10
	v_and_b32_e32 v25, 0xffff0000, v10
	v_lshlrev_b32_e32 v26, 16, v14
	v_mul_f32_e32 v10, 0xbfb8aa3b, v26
	v_exp_f32_e32 v10, v10
	v_and_b32_e32 v27, 0xffff0000, v14
	v_lshlrev_b32_e32 v14, 16, v15
	v_and_b32_e32 v15, 0xffff0000, v15
	v_add_f32_e32 v10, 1.0, v10
	v_rcp_f32_e32 v28, v10
	v_mul_f32_e32 v10, 0xbfb8aa3b, v27
	v_exp_f32_e32 v10, v10
	s_nop 0
	v_add_f32_e32 v10, 1.0, v10
	v_rcp_f32_e32 v29, v10
	v_lshlrev_b32_e32 v10, 16, v11
	v_and_b32_e32 v11, 0xffff0000, v11
	v_pk_mul_f32 v[26:27], v[28:29], v[26:27]
	s_nop 0
	v_pk_mul_f32 v[24:25], v[26:27], v[24:25]
	v_mul_f32_e32 v26, 0xbfb8aa3b, v14
	v_mul_f32_e32 v27, 0xbfb8aa3b, v15
	v_exp_f32_e32 v26, v26
	v_exp_f32_e32 v27, v27
	v_pk_mul_f32 v[24:25], v[6:7], v[24:25]
	v_add_f32_e32 v26, 1.0, v26
	v_add_f32_e32 v27, 1.0, v27
	v_rcp_f32_e32 v26, v26
	v_rcp_f32_e32 v27, v27
	s_nop 0
	v_pk_mul_f32 v[14:15], v[26:27], v[14:15]
	s_nop 0
	v_pk_mul_f32 v[10:11], v[14:15], v[10:11]
	v_lshlrev_b32_e32 v26, 16, v16
	v_pk_mul_f32 v[14:15], v[8:9], v[10:11]
	v_lshlrev_b32_e32 v10, 16, v12
	v_and_b32_e32 v11, 0xffff0000, v12
	v_mul_f32_e32 v12, 0xbfb8aa3b, v26
	v_exp_f32_e32 v12, v12
	v_and_b32_e32 v27, 0xffff0000, v16
	v_add_f32_e32 v12, 1.0, v12
	v_rcp_f32_e32 v28, v12
	v_mul_f32_e32 v12, 0xbfb8aa3b, v27
	v_exp_f32_e32 v12, v12
	s_nop 0
	v_add_f32_e32 v12, 1.0, v12
	v_rcp_f32_e32 v29, v12
	v_lshlrev_b32_e32 v12, 16, v17
	v_mul_f32_e32 v16, 0xbfb8aa3b, v12
	v_exp_f32_e32 v16, v16
	v_pk_mul_f32 v[26:27], v[28:29], v[26:27]
	v_add_f32_e32 v16, 1.0, v16
	v_pk_mul_f32 v[10:11], v[26:27], v[10:11]
	v_rcp_f32_e32 v16, v16
	v_pk_mul_f32 v[26:27], v[2:3], v[10:11]
	v_lshlrev_b32_e32 v10, 16, v13
	v_and_b32_e32 v11, 0xffff0000, v13
	v_and_b32_e32 v13, 0xffff0000, v17
	v_mul_f32_e32 v17, 0xbfb8aa3b, v13
	v_exp_f32_e32 v17, v17
	s_nop 0
	v_add_f32_e32 v17, 1.0, v17
	v_rcp_f32_e32 v17, v17
	s_nop 0
	v_pk_mul_f32 v[12:13], v[16:17], v[12:13]
	s_nop 0
	v_pk_mul_f32 v[10:11], v[12:13], v[10:11]
	v_cvt_pk_bf16_f32 v12, v26, v27
	v_pk_mul_f32 v[16:17], v[4:5], v[10:11]
	v_cvt_pk_bf16_f32 v11, v14, v15
	v_mad_i64_i32 v[14:15], s[4:5], v21, s24, v[18:19]
	v_lshl_add_u64 v[14:15], v[14:15], 0, s[58:59]
	v_cvt_pk_bf16_f32 v10, v24, v25
	v_cvt_pk_bf16_f32 v13, v16, v17
	v_lshl_add_u64 v[14:15], v[14:15], 0, v[0:1]
	global_store_dwordx4 v[14:15], v[10:13], off offset:1024
	s_nop 1
	v_add_u32_e32 v10, 0xe00, v247
	v_ashrrev_i32_e32 v14, 5, v10
	v_mad_u64_u32 v[10:11], s[4:5], v14, s56, v[20:21]
	v_add_u32_e32 v20, s6, v14
	v_mad_i64_i32 v[14:15], s[4:5], v20, s18, v[22:23]
	v_lshl_add_u64 v[14:15], v[14:15], 0, s[58:59]
	v_lshl_add_u64 v[14:15], v[14:15], 0, v[0:1]
	v_add_co_u32_e32 v14, vcc, s23, v14
	ds_read_b128 v[10:13], v10
	s_nop 0
	v_addc_co_u32_e32 v15, vcc, 0, v15, vcc
	v_mov_b64_e32 v[14:15], v[108:109]
	v_mov_b64_e32 v[16:17], v[110:111]
	v_and_b32_e32 v23, 0xffff0000, v16
	v_lshlrev_b32_e32 v22, 16, v16
	v_mul_f32_e32 v16, 0xbfb8aa3b, v23
	v_exp_f32_e32 v16, v16
	s_nop 0
	v_add_f32_e32 v16, 1.0, v16
	v_rcp_f32_e32 v25, v16
	v_mul_f32_e32 v16, 0xbfb8aa3b, v22
	v_exp_f32_e32 v16, v16
	s_nop 0
	v_add_f32_e32 v16, 1.0, v16
	v_rcp_f32_e32 v24, v16
	s_nop 0
	v_pk_mul_f32 v[22:23], v[24:25], v[22:23]
	s_waitcnt lgkmcnt(0)
; #define LAS __attribute__((address_space(3)))
; __device__ __forceinline__ float sigmoidf_(float x) { return __builtin_amdgcn_rcpf(1.0f + __expf(-x)); }
; __device__ __forceinline__ void r3_item(const bf16_t* __restrict__ proj, const bf16_t* __restrict__ projT, const bf16_t* __restrict__ st, bf16_t* ro, ...
;     const int tid = otid(), w = __builtin_amdgcn_readfirstlane(tid >> 6), lane = tid & 63, c = lane & 31, hh = lane >> 5;
;     const int ch = item >> 2, h = item & 3, tok0 = ch * 128, pos0 = tok0 % seqlen;
;     LAS bf16_t* Ql = (LAS bf16_t*)lds; LAS bf16_t* Kl = (LAS bf16_t*)(lds + 34816); LAS bf16_t* Pl = (LAS bf16_t*)(lds + 69632);
;     LAS float* stat = (LAS float*)(lds + 104448);
;     LAS bf16_t* Ol = (LAS bf16_t*)lds;
;     const float scale = 0.08838834764831845f;
;     bf16x8 asb[8], asf[8], avt[8];
;     const size_t stb0 = ((size_t)(ch * 4 + h) * 2) * 32768 + (size_t)(32 * w + c) * 128 + 8 * hh;
; #pragma unroll
;     for (int s = 0; s < 8; ++s) asb[s] = *(const bf16x8*)(st + stb0 + 32768 + 16 * s);
; #pragma unroll
;     for (int it = 0; it < 2; ++it) {
;         const int id = tid + NTHREADS * it, t = id >> 3, d8 = (id & 7) * 8;
;         const f32x4 c0 = *(const f32x4*)(cosN + (size_t)(pos0 + t) * 64 + d8), c1 = *(const f32x4*)(cosN + (size_t)(pos0 + t) * 64 + d8 + 4);
;         const f32x4 s0 = *(const f32x4*)(sinN + (size_t)(pos0 + t) * 64 + d8), s1 = *(const f32x4*)(sinN + (size_t)(pos0 + t) * 64 + d8 + 4);
;         float a[8], b[8], o1[8], o2[8];
;         const bf16_t* qp = proj + (size_t)(tok0 + t) * NPROJ + 1024 + h * 128 + d8;
;         unpack8(__builtin_nontemporal_load((const u32x4*)qp), a); unpack8(__builtin_nontemporal_load((const u32x4*)(qp + 64)), b);
;     ...
;     for (int it = 0; it < 8; ++it) { const int id = tid + NTHREADS * it, tq = id >> 5, d8 = (id & 31) * 8;
;         float y[8], rg[8], o[8]; unpack8(*(const LAS u32x4*)(Ol + tq * OL_STRIDE + d8), y);
;         unpack8(__builtin_nontemporal_load((const u32x4*)(proj + (size_t)(tok0 + tq) * NPROJ + 2048 + h * 256 + d8)), rg);
;         const f32x4 g0 = *(const f32x4*)(gn + h * 256 + d8), g1 = *(const f32x4*)(gn + h * 256 + d8 + 4);
; #pragma unroll
;         for (int j = 0; j < 8; ++j) { const float gv = j < 4 ? g0[j & 3] : g1[j & 3]; o[j] = rg[j] * sigmoidf_(rg[j]) * y[j] * gv; }
;         *(u32x4*)(ro + (size_t)(tok0 + tq) * 1536 + 512 + h * 256 + d8) = pack8(o); }
	v_lshlrev_b32_e32 v24, 16, v12
	v_and_b32_e32 v25, 0xffff0000, v12
	v_pk_mul_f32 v[22:23], v[22:23], v[24:25]
	s_nop 0
	v_pk_mul_f32 v[22:23], v[2:3], v[22:23]
	v_and_b32_e32 v3, 0xffff0000, v15
	v_mul_f32_e32 v12, 0xbfb8aa3b, v3
	v_exp_f32_e32 v12, v12
	v_lshlrev_b32_e32 v2, 16, v15
	v_add_f32_e32 v12, 1.0, v12
	v_rcp_f32_e32 v25, v12
	v_mul_f32_e32 v12, 0xbfb8aa3b, v2
	v_exp_f32_e32 v12, v12
	s_nop 0
	v_add_f32_e32 v12, 1.0, v12
	v_rcp_f32_e32 v24, v12
	v_lshlrev_b32_e32 v12, 16, v13
	v_and_b32_e32 v13, 0xffff0000, v13
	v_pk_mul_f32 v[2:3], v[24:25], v[2:3]
	v_lshlrev_b32_e32 v24, 16, v11
	v_and_b32_e32 v25, 0xffff0000, v11
	v_pk_mul_f32 v[2:3], v[2:3], v[24:25]
	s_nop 0
	v_pk_mul_f32 v[8:9], v[8:9], v[2:3]
	v_and_b32_e32 v3, 0xffff0000, v14
	v_mul_f32_e32 v11, 0xbfb8aa3b, v3
	v_exp_f32_e32 v11, v11
	v_lshlrev_b32_e32 v2, 16, v14
	v_add_f32_e32 v11, 1.0, v11
	v_rcp_f32_e32 v15, v11
	v_mul_f32_e32 v11, 0xbfb8aa3b, v2
	v_exp_f32_e32 v11, v11
	s_nop 0
	v_add_f32_e32 v11, 1.0, v11
	v_rcp_f32_e32 v14, v11
	s_nop 0
	v_pk_mul_f32 v[2:3], v[14:15], v[2:3]
	v_lshlrev_b32_e32 v14, 16, v10
	v_and_b32_e32 v15, 0xffff0000, v10
	v_pk_mul_f32 v[2:3], v[2:3], v[14:15]
	s_nop 0
	v_pk_mul_f32 v[2:3], v[6:7], v[2:3]
	v_lshlrev_b32_e32 v6, 16, v17
	v_and_b32_e32 v7, 0xffff0000, v17
	v_mul_f32_e32 v10, 0xbfb8aa3b, v6
	v_mul_f32_e32 v11, 0xbfb8aa3b, v7
	v_exp_f32_e32 v10, v10
	v_exp_f32_e32 v11, v11
	v_cvt_pk_bf16_f32 v2, v2, v3
	v_cvt_pk_bf16_f32 v3, v8, v9
	v_add_f32_e32 v10, 1.0, v10
	v_add_f32_e32 v11, 1.0, v11
	v_rcp_f32_e32 v10, v10
	v_rcp_f32_e32 v11, v11
	s_nop 0
	v_pk_mul_f32 v[6:7], v[10:11], v[6:7]
	s_nop 0
	v_pk_mul_f32 v[6:7], v[6:7], v[12:13]
	s_nop 0
	v_pk_mul_f32 v[6:7], v[4:5], v[6:7]
	v_cvt_pk_bf16_f32 v4, v22, v23
	v_cvt_pk_bf16_f32 v5, v6, v7
	v_mad_i64_i32 v[6:7], s[4:5], v20, s24, v[18:19]
	v_lshl_add_u64 v[6:7], v[6:7], 0, s[58:59]
	v_lshl_add_u64 v[6:7], v[6:7], 0, v[0:1]
	global_store_dwordx4 v[6:7], v[2:5], off offset:1024
	s_barrier
	s_cbranch_scc1 .LBB0_481
.LBB0_485:
	s_and_b32 s7, s27, 3
	s_mov_b64 s[4:5], 0
	s_add_u32 s6, s30, s4
	s_addc_u32 s10, s31, s5
	s_or_b32 s4, s7, s90
	s_lshl_b32 s58, s4, 1
	s_lshl_b64 s[4:5], s[58:59], 2
	s_add_u32 s4, s6, s4
	s_addc_u32 s5, s10, s5
	s_and_b32 s6, s25, 0xffffff80
	global_load_dwordx2 v[224:225], v244, s[4:5]
	s_mov_b64 s[4:5], 0
	s_lshl_b32 s58, s7, 8
	s_ashr_i32 s7, s6, 31
	s_add_u32 s4, s30, s4
	s_addc_u32 s5, s31, s5
	s_add_u32 s40, s4, 0xe240000
	s_addc_u32 s41, s5, 0
	s_mov_b64 s[4:5], 0
	s_add_u32 s4, s30, s4
	s_addc_u32 s5, s31, s5
	s_mov_b64 s[28:29], 0
	s_mov_b64 s[42:43], 0
	s_mov_b64 s[10:11], 0
	s_add_u32 s16, s30, s10
	s_addc_u32 s17, s31, s11
	s_mov_b64 s[10:11], 0
	s_add_u32 s38, s30, s10
	s_addc_u32 s39, s31, s11
	s_ashr_i32 s11, s25, 31
	s_add_i32 s33, s6, s11
	s_xor_b32 s33, s33, s11
	v_mov_b32_e32 v247, v232
	s_mul_hi_u32 s34, s33, s67
	s_mul_i32 s34, s34, s71
	v_readfirstlane_b32 s10, v247
	s_ashr_i32 s45, s10, 6
	s_sub_i32 s33, s33, s34
	s_lshl_b32 s44, s45, 5
	s_sub_i32 s34, s33, s71
	s_cmp_ge_u32 s33, s71
	v_lshlrev_b32_e32 v249, 3, v247
	s_cselect_b32 s33, s34, s33
	v_and_b32_e32 v0, 56, v249
	s_sub_i32 s34, s33, s71
	v_lshlrev_b32_e32 v2, 2, v0
	v_mov_b32_e32 v3, v1
	s_cmp_ge_u32 s33, s71
	v_lshl_add_u64 v[4:5], s[16:17], 0, v[2:3]
	s_mov_b64 s[16:17], 0x440000
	v_ashrrev_i32_e32 v106, 3, v247
	s_cselect_b32 s33, s34, s33
	v_lshl_add_u64 v[26:27], v[4:5], 0, s[16:17]
	v_add_u32_e32 v4, s6, v106
	v_mov_b64_e32 v[28:29], s[40:41]
	s_xor_b32 s33, s33, s11
	v_mad_i64_i32 v[4:5], s[16:17], v4, s18, v[28:29]
	s_sub_i32 s11, s33, s11
	v_lshl_add_u64 v[2:3], s[38:39], 0, v[2:3]
	s_mov_b64 s[16:17], 0x840000
	v_lshl_add_u64 v[32:33], v[2:3], 0, s[16:17]
	v_add_u32_e32 v2, s11, v106
	v_lshl_add_u64 v[4:5], v[4:5], 0, s[58:59]
	v_lshlrev_b32_e32 v30, 1, v0
	v_mov_b32_e32 v31, v1
	v_ashrrev_i32_e32 v3, 31, v2
	v_lshl_add_u64 v[18:19], v[4:5], 0, v[30:31]
	v_lshlrev_b64 v[2:3], 8, v[2:3]
	global_load_dwordx4 v[42:45], v[18:19], off offset:2176 nt
	v_lshl_add_u64 v[4:5], v[26:27], 0, v[2:3]
	global_load_dwordx4 v[38:41], v[18:19], off offset:2048 nt
	global_load_dwordx4 v[10:13], v[4:5], off
	v_lshl_add_u64 v[6:7], v[32:33], 0, v[2:3]
	global_load_dwordx4 v[14:17], v[6:7], off
	s_nop 0
	global_load_dwordx4 v[2:5], v[4:5], off offset:16
	s_nop 0
	global_load_dwordx4 v[6:9], v[6:7], off offset:16
	s_nop 0
	global_load_dwordx4 v[22:25], v[18:19], off offset:3072 nt
	s_nop 0
	global_load_dwordx4 v[18:21], v[18:19], off offset:3200 nt
	v_and_b32_e32 v250, 31, v247
	v_or_b32_e32 v34, s44, v250
	v_ashrrev_i32_e32 v35, 31, v34
	v_bfe_u32 v251, v247, 5, 1
	v_lshlrev_b64 v[34:35], 8, v[34:35]
	v_lshlrev_b32_e32 v0, 4, v251
	v_lshl_add_u64 v[34:35], s[28:29], 0, v[34:35]
	v_lshl_add_u64 v[34:35], v[34:35], 0, v[0:1]
	v_lshl_add_u64 v[222:223], s[0:1], 0, v[34:35]
	v_add_co_u32_e32 v46, vcc, s26, v222
	v_add_u32_e32 v248, 0x200, v247
	s_nop 0
	v_addc_co_u32_e32 v47, vcc, 0, v223, vcc
	global_load_dwordx4 v[34:37], v[46:47], off
	global_load_dwordx4 v[90:93], v[46:47], off offset:32
	global_load_dwordx4 v[86:89], v[46:47], off offset:64
	global_load_dwordx4 v[82:85], v[46:47], off offset:96
	global_load_dwordx4 v[78:81], v[46:47], off offset:128
	global_load_dwordx4 v[74:77], v[46:47], off offset:160
	global_load_dwordx4 v[70:73], v[46:47], off offset:192
	global_load_dwordx4 v[66:69], v[46:47], off offset:224
	v_ashrrev_i32_e32 v107, 3, v248
	v_lshlrev_b32_e32 v252, 3, v251
	v_mad_u32_u24 v233, v250, s12, v246
	v_mov_b32_e32 v234, 0x358637bd
	s_waitcnt vmcnt(15)
	v_lshlrev_b32_e32 v48, 16, v42
	v_and_b32_e32 v49, 0xffff0000, v42
	s_waitcnt vmcnt(14)
; #define LAS __attribute__((address_space(3)))
; __device__ __forceinline__ void unpack8(const u32x4 w, float* f) { f[0] = bf_lo(w.x); f[1] = bf_hi(w.x); f[2] = bf_lo(w.y); f[3] = bf_hi(w.y); f[4] = bf_lo(w.z); f[5] = bf_hi(w.z); f[6] = bf_lo(w.w); f[7] = bf_hi(w.w); }
; __device__ __forceinline__ u32x4 pack8(const float* f) { u32x4 w; w.x = cvt_pk_bf16(f[0], f[1]); w.y = cvt_pk_bf16(f[2], f[3]); w.z = cvt_pk_bf16(f[4], f[5]); w.w = cvt_pk_bf16(f[6], f[7]); return w; }
; __device__ __forceinline__ void r3_item(const bf16_t* __restrict__ proj, const bf16_t* __restrict__ projT, const bf16_t* __restrict__ st, bf16_t* ro, ...
;     ...
;     for (int it = 0; it < 2; ++it) {
;         const int id = tid + NTHREADS * it, t = id >> 3, d8 = (id & 7) * 8;
;         const f32x4 c0 = *(const f32x4*)(cosN + (size_t)(pos0 + t) * 64 + d8), c1 = *(const f32x4*)(cosN + (size_t)(pos0 + t) * 64 + d8 + 4);
;         const f32x4 s0 = *(const f32x4*)(sinN + (size_t)(pos0 + t) * 64 + d8), s1 = *(const f32x4*)(sinN + (size_t)(pos0 + t) * 64 + d8 + 4);
;         float a[8], b[8], o1[8], o2[8];
;         const bf16_t* qp = proj + (size_t)(tok0 + t) * NPROJ + 1024 + h * 128 + d8;
;         unpack8(__builtin_nontemporal_load((const u32x4*)qp), a); unpack8(__builtin_nontemporal_load((const u32x4*)(qp + 64)), b);
; #pragma unroll
;         for (int j = 0; j < 8; ++j) { const float cv = j < 4 ? c0[j & 3] : c1[j & 3], sv = j < 4 ? s0[j & 3] : s1[j & 3]; o1[j] = a[j] * cv - b[j] * sv; o2[j] = a[j] * sv + b[j] * cv; }
;         *(LAS u32x4*)(Ql + t * KT_STRIDE + d8) = pack8(o1); *(LAS u32x4*)(Ql + t * KT_STRIDE + 64 + d8) = pack8(o2);
;         const bf16_t* kp = proj + (size_t)(tok0 + t) * NPROJ + 1536 + h * 128 + d8;
;         unpack8(__builtin_nontemporal_load((const u32x4*)kp), a); unpack8(__builtin_nontemporal_load((const u32x4*)(kp + 64)), b);
; #pragma unroll
;         for (int j = 0; j < 8; ++j) { const float cv = j < 4 ? c0[j & 3] : c1[j & 3], sv = j < 4 ? s0[j & 3] : s1[j & 3]; o1[j] = (a[j] * cv - b[j] * sv) * scale; o2[j] = (a[j] * sv + b[j] * cv) * scale; }
;         *(LAS u32x4*)(Kl + t * KT_STRIDE + d8) = pack8(o1); *(LAS u32x4*)(Kl + t * KT_STRIDE + 64 + d8) = pack8(o2);
;     }
	v_lshlrev_b32_e32 v46, 16, v38
	v_and_b32_e32 v47, 0xffff0000, v38
	v_lshlrev_b32_e32 v42, 16, v43
	v_and_b32_e32 v43, 0xffff0000, v43
	s_waitcnt vmcnt(13)
	v_pk_mul_f32 v[50:51], v[10:11], v[48:49]
	s_waitcnt vmcnt(12)
	v_pk_mul_f32 v[48:49], v[14:15], v[48:49]
	v_lshlrev_b32_e32 v38, 16, v39
	v_and_b32_e32 v39, 0xffff0000, v39
	v_pk_fma_f32 v[94:95], v[14:15], v[46:47], v[50:51]
	v_pk_fma_f32 v[96:97], v[10:11], v[46:47], v[48:49] neg_lo:[0,0,1] neg_hi:[0,0,1]
	v_pk_mul_f32 v[46:47], v[12:13], v[42:43]
	v_pk_mul_f32 v[42:43], v[16:17], v[42:43]
	v_lshlrev_b32_e32 v100, 16, v44
	v_and_b32_e32 v101, 0xffff0000, v44
	v_pk_fma_f32 v[98:99], v[16:17], v[38:39], v[46:47]
	v_pk_fma_f32 v[42:43], v[12:13], v[38:39], v[42:43] neg_lo:[0,0,1] neg_hi:[0,0,1]
	v_lshlrev_b32_e32 v38, 16, v40
	v_and_b32_e32 v39, 0xffff0000, v40
	s_waitcnt vmcnt(11)
	v_pk_mul_f32 v[46:47], v[2:3], v[100:101]
	v_lshlrev_b32_e32 v40, 16, v45
	s_waitcnt vmcnt(10)
	v_pk_fma_f32 v[102:103], v[6:7], v[38:39], v[46:47]
	v_add_u32_e32 v46, s11, v107
	v_ashrrev_i32_e32 v47, 31, v46
	v_lshlrev_b64 v[58:59], 8, v[46:47]
	v_lshl_add_u64 v[50:51], v[26:27], 0, v[58:59]
	v_add_u32_e32 v26, s6, v107
	v_mad_i64_i32 v[26:27], s[16:17], v26, s18, v[28:29]
	v_lshl_add_u64 v[26:27], v[26:27], 0, s[58:59]
	v_lshl_add_u64 v[104:105], v[26:27], 0, v[30:31]
	v_lshl_add_u64 v[32:33], v[32:33], 0, v[58:59]
	global_load_dwordx4 v[46:49], v[104:105], off offset:2048 nt
	global_load_dwordx4 v[26:29], v[50:51], off offset:16
	s_nop 0
	global_load_dwordx4 v[50:53], v[50:51], off
	s_nop 0
	global_load_dwordx4 v[54:57], v[104:105], off offset:2176 nt
	global_load_dwordx4 v[58:61], v[32:33], off offset:16
	global_load_dwordx4 v[62:65], v[32:33], off
	v_pk_mul_f32 v[32:33], v[6:7], v[100:101]
	v_mul_lo_u32 v31, v106, s12
	v_pk_fma_f32 v[32:33], v[2:3], v[38:39], v[32:33] neg_lo:[0,0,1] neg_hi:[0,0,1]
	v_lshlrev_b32_e32 v38, 16, v41
	v_and_b32_e32 v39, 0xffff0000, v41
	v_and_b32_e32 v41, 0xffff0000, v45
	v_pk_mul_f32 v[44:45], v[4:5], v[40:41]
	v_pk_mul_f32 v[40:41], v[8:9], v[40:41]
	v_pk_fma_f32 v[44:45], v[8:9], v[38:39], v[44:45]
	v_pk_fma_f32 v[100:101], v[4:5], v[38:39], v[40:41] neg_lo:[0,0,1] neg_hi:[0,0,1]
	v_cvt_pk_bf16_f32 v38, v96, v97
	v_cvt_pk_bf16_f32 v39, v42, v43
	v_cvt_pk_bf16_f32 v40, v32, v33
	v_cvt_pk_bf16_f32 v41, v100, v101
	v_add3_u32 v31, 0, v31, v30
	ds_write_b128 v31, v[38:41]
	v_cvt_pk_bf16_f32 v38, v94, v95
	v_cvt_pk_bf16_f32 v39, v98, v99
	v_cvt_pk_bf16_f32 v40, v102, v103
	v_cvt_pk_bf16_f32 v41, v44, v45
	ds_write_b128 v31, v[38:41] offset:128
	s_waitcnt vmcnt(14)
	v_lshlrev_b32_e32 v38, 16, v18
	v_and_b32_e32 v39, 0xffff0000, v18
	v_lshlrev_b32_e32 v32, 16, v22
	v_and_b32_e32 v33, 0xffff0000, v22
	v_pk_mul_f32 v[40:41], v[10:11], v[38:39]
	global_load_dwordx4 v[42:45], v[104:105], off offset:3200 nt
	v_pk_fma_f32 v[40:41], v[14:15], v[32:33], v[40:41]
	v_pk_mul_f32 v[14:15], v[14:15], v[38:39]
	v_pk_mul_f32 v[94:95], v[40:41], s[64:65] op_sel_hi:[1,0]
	global_load_dwordx4 v[38:41], v[104:105], off offset:3072 nt
	v_lshlrev_b32_e32 v18, 16, v19
	v_and_b32_e32 v19, 0xffff0000, v19
	v_pk_fma_f32 v[10:11], v[10:11], v[32:33], v[14:15] neg_lo:[0,0,1] neg_hi:[0,0,1]
	v_lshlrev_b32_e32 v14, 16, v23
	v_and_b32_e32 v15, 0xffff0000, v23
	v_pk_mul_f32 v[22:23], v[12:13], v[18:19]
	v_pk_mul_f32 v[10:11], v[10:11], s[64:65] op_sel_hi:[1,0]
	v_pk_fma_f32 v[22:23], v[16:17], v[14:15], v[22:23]
	v_pk_mul_f32 v[16:17], v[16:17], v[18:19]
	v_pk_mul_f32 v[22:23], v[22:23], s[64:65] op_sel_hi:[1,0]
	v_pk_fma_f32 v[12:13], v[12:13], v[14:15], v[16:17] neg_lo:[0,0,1] neg_hi:[0,0,1]
	v_lshlrev_b32_e32 v16, 16, v20
	v_and_b32_e32 v17, 0xffff0000, v20
	v_lshlrev_b32_e32 v14, 16, v24
	v_and_b32_e32 v15, 0xffff0000, v24
	v_pk_mul_f32 v[18:19], v[2:3], v[16:17]
	v_pk_mul_f32 v[12:13], v[12:13], s[64:65] op_sel_hi:[1,0]
	v_pk_fma_f32 v[18:19], v[6:7], v[14:15], v[18:19]
	v_pk_mul_f32 v[6:7], v[6:7], v[16:17]
	v_pk_mul_f32 v[18:19], v[18:19], s[64:65] op_sel_hi:[1,0]
	v_pk_fma_f32 v[2:3], v[2:3], v[14:15], v[6:7] neg_lo:[0,0,1] neg_hi:[0,0,1]
	v_lshlrev_b32_e32 v14, 16, v21
	v_and_b32_e32 v15, 0xffff0000, v21
	v_pk_mul_f32 v[6:7], v[2:3], s[64:65] op_sel_hi:[1,0]
	v_lshlrev_b32_e32 v2, 16, v25
	v_and_b32_e32 v3, 0xffff0000, v25
	v_pk_mul_f32 v[16:17], v[4:5], v[14:15]
	s_ashr_i32 s11, s10, 7
	v_pk_fma_f32 v[16:17], v[8:9], v[2:3], v[16:17]
	v_pk_mul_f32 v[8:9], v[8:9], v[14:15]
	v_pk_mul_f32 v[16:17], v[16:17], s[64:65] op_sel_hi:[1,0]
	v_pk_fma_f32 v[2:3], v[4:5], v[2:3], v[8:9] neg_lo:[0,0,1] neg_hi:[0,0,1]
	v_cvt_pk_bf16_f32 v4, v6, v7
	v_pk_mul_f32 v[8:9], v[2:3], s[64:65] op_sel_hi:[1,0]
	v_cvt_pk_bf16_f32 v2, v10, v11
	v_cvt_pk_bf16_f32 v3, v12, v13
	v_cvt_pk_bf16_f32 v5, v8, v9
	ds_write_b128 v31, v[2:5] offset:34816
	v_cvt_pk_bf16_f32 v2, v94, v95
	v_cvt_pk_bf16_f32 v3, v22, v23
	v_cvt_pk_bf16_f32 v4, v18, v19
	v_cvt_pk_bf16_f32 v5, v16, v17
	ds_write_b128 v31, v[2:5] offset:34944
	s_lshl_b32 s28, s11, 5
	s_waitcnt vmcnt(7)
	v_lshlrev_b32_e32 v2, 16, v46
	v_and_b32_e32 v3, 0xffff0000, v46
	s_waitcnt vmcnt(4)
	v_lshlrev_b32_e32 v4, 16, v54
	v_and_b32_e32 v5, 0xffff0000, v54
	v_pk_mul_f32 v[6:7], v[50:51], v[4:5]
	s_waitcnt vmcnt(2)
; #define LAS __attribute__((address_space(3)))
; __device__ __forceinline__ void unpack8(const u32x4 w, float* f) { f[0] = bf_lo(w.x); f[1] = bf_hi(w.x); f[2] = bf_lo(w.y); f[3] = bf_hi(w.y); f[4] = bf_lo(w.z); f[5] = bf_hi(w.z); f[6] = bf_lo(w.w); f[7] = bf_hi(w.w); }
; __device__ __forceinline__ u32x4 pack8(const float* f) { u32x4 w; w.x = cvt_pk_bf16(f[0], f[1]); w.y = cvt_pk_bf16(f[2], f[3]); w.z = cvt_pk_bf16(f[4], f[5]); w.w = cvt_pk_bf16(f[6], f[7]); return w; }
; __device__ __forceinline__ f32x16 mfma32(bf16x8 a, bf16x8 b, f32x16 c) { return __builtin_amdgcn_mfma_f32_32x32x16_bf16(a, b, c, 0, 0, 0); }
; __device__ __forceinline__ f32x16 zero16() { return (f32x16){0.f, 0.f, 0.f, 0.f, 0.f, 0.f, 0.f, 0.f, 0.f, 0.f, 0.f, 0.f, 0.f, 0.f, 0.f, 0.f}; }
; __device__ __forceinline__ void r3_item(const bf16_t* __restrict__ proj, const bf16_t* __restrict__ projT, const bf16_t* __restrict__ st, bf16_t* ro, ...
;     ...
;         *(LAS u32x4*)(Ql + t * KT_STRIDE + d8) = pack8(o1); *(LAS u32x4*)(Ql + t * KT_STRIDE + 64 + d8) = pack8(o2);
;         const bf16_t* kp = proj + (size_t)(tok0 + t) * NPROJ + 1536 + h * 128 + d8;
;         unpack8(__builtin_nontemporal_load((const u32x4*)kp), a); unpack8(__builtin_nontemporal_load((const u32x4*)(kp + 64)), b);
; #pragma unroll
;         for (int j = 0; j < 8; ++j) { const float cv = j < 4 ? c0[j & 3] : c1[j & 3], sv = j < 4 ? s0[j & 3] : s1[j & 3]; o1[j] = (a[j] * cv - b[j] * sv) * scale; o2[j] = (a[j] * sv + b[j] * cv) * scale; }
;         *(LAS u32x4*)(Kl + t * KT_STRIDE + d8) = pack8(o1); *(LAS u32x4*)(Kl + t * KT_STRIDE + 64 + d8) = pack8(o2);
;     }
;     __syncthreads();
;     { const int kt = w >> 1;
; #pragma unroll
;       for (int q2 = 0; q2 < 2; ++q2) { const int tqt = 2 * (w & 1) + q2;
;           f32x16 x = zero16();
; #pragma unroll
;           for (int s = 0; s < 8; ++s) { const bf16x8 kf = *(const LAS bf16x8*)(Kl + (32 * kt + c) * KT_STRIDE + 16 * s + 8 * hh);
;               const bf16x8 qf = *(const LAS bf16x8*)(Ql + (32 * tqt + c) * KT_STRIDE + 16 * s + 8 * hh); x = mfma32(kf, qf, x); }
	v_pk_mul_f32 v[4:5], v[62:63], v[4:5]
	v_lshlrev_b32_e32 v8, 16, v55
	v_and_b32_e32 v9, 0xffff0000, v55
	v_pk_fma_f32 v[6:7], v[62:63], v[2:3], v[6:7]
	v_pk_fma_f32 v[2:3], v[50:51], v[2:3], v[4:5] neg_lo:[0,0,1] neg_hi:[0,0,1]
	v_lshlrev_b32_e32 v4, 16, v47
	v_and_b32_e32 v5, 0xffff0000, v47
	v_pk_mul_f32 v[10:11], v[52:53], v[8:9]
	v_pk_mul_f32 v[8:9], v[64:65], v[8:9]
	v_lshlrev_b32_e32 v12, 16, v56
	v_and_b32_e32 v13, 0xffff0000, v56
	v_pk_fma_f32 v[10:11], v[64:65], v[4:5], v[10:11]
	v_pk_fma_f32 v[4:5], v[52:53], v[4:5], v[8:9] neg_lo:[0,0,1] neg_hi:[0,0,1]
	v_lshlrev_b32_e32 v8, 16, v48
	v_and_b32_e32 v9, 0xffff0000, v48
	v_pk_mul_f32 v[14:15], v[26:27], v[12:13]
	v_pk_mul_f32 v[12:13], v[58:59], v[12:13]
	v_lshlrev_b32_e32 v16, 16, v57
	v_and_b32_e32 v17, 0xffff0000, v57
	v_pk_fma_f32 v[14:15], v[58:59], v[8:9], v[14:15]
	v_pk_fma_f32 v[8:9], v[26:27], v[8:9], v[12:13] neg_lo:[0,0,1] neg_hi:[0,0,1]
	v_lshlrev_b32_e32 v12, 16, v49
	v_and_b32_e32 v13, 0xffff0000, v49
	v_pk_mul_f32 v[18:19], v[28:29], v[16:17]
	v_pk_mul_f32 v[16:17], v[60:61], v[16:17]
	v_pk_fma_f32 v[18:19], v[60:61], v[12:13], v[18:19]
	v_pk_fma_f32 v[12:13], v[28:29], v[12:13], v[16:17] neg_lo:[0,0,1] neg_hi:[0,0,1]
	v_cvt_pk_bf16_f32 v2, v2, v3
	v_cvt_pk_bf16_f32 v3, v4, v5
	v_cvt_pk_bf16_f32 v4, v8, v9
	v_mul_lo_u32 v8, v107, s12
	v_cvt_pk_bf16_f32 v5, v12, v13
	v_add3_u32 v20, 0, v8, v30
	ds_write_b128 v20, v[2:5]
	v_cvt_pk_bf16_f32 v2, v6, v7
	v_cvt_pk_bf16_f32 v3, v10, v11
	v_cvt_pk_bf16_f32 v4, v14, v15
	v_cvt_pk_bf16_f32 v5, v18, v19
	ds_write_b128 v20, v[2:5] offset:128
	s_waitcnt vmcnt(1)
	v_lshlrev_b32_e32 v4, 16, v42
	v_and_b32_e32 v5, 0xffff0000, v42
	s_waitcnt vmcnt(0)
	v_lshlrev_b32_e32 v2, 16, v38
	v_and_b32_e32 v3, 0xffff0000, v38
	v_pk_mul_f32 v[6:7], v[50:51], v[4:5]
	v_pk_mul_f32 v[4:5], v[62:63], v[4:5]
	v_lshlrev_b32_e32 v8, 16, v43
	v_and_b32_e32 v9, 0xffff0000, v43
	v_pk_fma_f32 v[6:7], v[62:63], v[2:3], v[6:7]
	v_pk_fma_f32 v[2:3], v[50:51], v[2:3], v[4:5] neg_lo:[0,0,1] neg_hi:[0,0,1]
	v_lshlrev_b32_e32 v4, 16, v39
	v_and_b32_e32 v5, 0xffff0000, v39
	v_pk_mul_f32 v[10:11], v[52:53], v[8:9]
	v_pk_mul_f32 v[8:9], v[64:65], v[8:9]
	v_lshlrev_b32_e32 v12, 16, v44
	v_and_b32_e32 v13, 0xffff0000, v44
	v_pk_fma_f32 v[10:11], v[64:65], v[4:5], v[10:11]
	v_pk_fma_f32 v[4:5], v[52:53], v[4:5], v[8:9] neg_lo:[0,0,1] neg_hi:[0,0,1]
	v_lshlrev_b32_e32 v8, 16, v40
	v_and_b32_e32 v9, 0xffff0000, v40
	v_pk_mul_f32 v[14:15], v[26:27], v[12:13]
	v_pk_mul_f32 v[12:13], v[58:59], v[12:13]
	v_lshlrev_b32_e32 v16, 16, v45
	v_and_b32_e32 v17, 0xffff0000, v45
	v_pk_fma_f32 v[14:15], v[58:59], v[8:9], v[14:15]
	v_pk_fma_f32 v[8:9], v[26:27], v[8:9], v[12:13] neg_lo:[0,0,1] neg_hi:[0,0,1]
	v_lshlrev_b32_e32 v12, 16, v41
	v_and_b32_e32 v13, 0xffff0000, v41
	v_pk_mul_f32 v[18:19], v[28:29], v[16:17]
	v_pk_mul_f32 v[16:17], v[60:61], v[16:17]
	v_pk_fma_f32 v[18:19], v[60:61], v[12:13], v[18:19]
	v_pk_fma_f32 v[12:13], v[28:29], v[12:13], v[16:17] neg_lo:[0,0,1] neg_hi:[0,0,1]
	v_pk_mul_f32 v[2:3], v[2:3], s[64:65] op_sel_hi:[1,0]
	v_pk_mul_f32 v[4:5], v[4:5], s[64:65] op_sel_hi:[1,0]
	v_pk_mul_f32 v[8:9], v[8:9], s[64:65] op_sel_hi:[1,0]
	v_pk_mul_f32 v[12:13], v[12:13], s[64:65] op_sel_hi:[1,0]
	v_pk_mul_f32 v[6:7], v[6:7], s[64:65] op_sel_hi:[1,0]
	v_pk_mul_f32 v[10:11], v[10:11], s[64:65] op_sel_hi:[1,0]
	v_pk_mul_f32 v[14:15], v[14:15], s[64:65] op_sel_hi:[1,0]
	v_pk_mul_f32 v[18:19], v[18:19], s[64:65] op_sel_hi:[1,0]
	v_cvt_pk_bf16_f32 v2, v2, v3
	v_cvt_pk_bf16_f32 v3, v4, v5
	v_cvt_pk_bf16_f32 v4, v8, v9
	v_cvt_pk_bf16_f32 v5, v12, v13
	ds_write_b128 v20, v[2:5] offset:34816
	v_cvt_pk_bf16_f32 v2, v6, v7
	v_cvt_pk_bf16_f32 v3, v10, v11
	v_cvt_pk_bf16_f32 v4, v14, v15
	v_cvt_pk_bf16_f32 v5, v18, v19
	ds_write_b128 v20, v[2:5] offset:34944
	v_or_b32_e32 v2, s28, v250
	v_add_u32_e32 v38, 0, v0
	v_mad_u64_u32 v[18:19], s[16:17], v2, s12, v[38:39]
	s_waitcnt lgkmcnt(0)
	s_barrier
	ds_read_b128 v[2:5], v18 offset:34816
	v_and_or_b32 v28, s10, 64, v250
	v_mad_u32_u24 v19, v28, s12, v38
	ds_read_b128 v[6:9], v19
	s_waitcnt lgkmcnt(0)
	v_mfma_f32_32x32x16_bf16 v[2:17], v[2:5], v[6:9], 0
	ds_read_b128 v[20:23], v18 offset:34848
	ds_read_b128 v[24:27], v19 offset:32
	v_lshl_or_b32 v30, v251, 2, s28
	v_or_b32_e32 v31, 1, v30
	v_or_b32_e32 v32, 2, v30
	v_or_b32_e32 v33, 3, v30
	v_or_b32_e32 v39, 8, v30
	v_or_b32_e32 v40, 9, v30
	s_waitcnt lgkmcnt(0)
	v_mfma_f32_32x32x16_bf16 v[2:17], v[20:23], v[24:27], v[2:17]
	ds_read_b128 v[20:23], v18 offset:34880
	ds_read_b128 v[24:27], v19 offset:64
	v_or_b32_e32 v41, 10, v30
	v_or_b32_e32 v42, 11, v30
	s_lshl_b32 s10, s11, 6
	s_add_i32 s10, s20, s10
	v_add_u32_e32 v29, s10, v252
	v_or_b32_e32 v44, 17, v30
	s_waitcnt lgkmcnt(0)
	v_mfma_f32_32x32x16_bf16 v[2:17], v[20:23], v[24:27], v[2:17]
	ds_read_b128 v[20:23], v18 offset:34912
	ds_read_b128 v[24:27], v19 offset:96
	v_or_b32_e32 v43, 16, v30
	v_or_b32_e32 v45, 18, v30
	v_or_b32_e32 v46, 19, v30
	v_or_b32_e32 v47, 24, v30
	v_or_b32_e32 v48, 25, v30
	v_or_b32_e32 v49, 26, v30
	s_waitcnt lgkmcnt(0)
	v_mfma_f32_32x32x16_bf16 v[2:17], v[20:23], v[24:27], v[2:17]
	ds_read_b128 v[20:23], v18 offset:34944
	ds_read_b128 v[24:27], v19 offset:128
	v_or_b32_e32 v50, 27, v30
	v_mad_u32_u24 v51, v28, s12, v246
	v_add_u32_e32 v52, v38, v51
	v_mad_u32_u24 v190, v250, s12, v38
	v_add_u32_e32 v191, v38, v233
	s_waitcnt lgkmcnt(0)
	v_mfma_f32_32x32x16_bf16 v[2:17], v[20:23], v[24:27], v[2:17]
	ds_read_b128 v[20:23], v18 offset:34976
	ds_read_b128 v[24:27], v19 offset:160
	s_waitcnt lgkmcnt(0)
	v_mfma_f32_32x32x16_bf16 v[2:17], v[20:23], v[24:27], v[2:17]
	ds_read_b128 v[20:23], v18 offset:35008
	ds_read_b128 v[24:27], v19 offset:192
	s_waitcnt lgkmcnt(0)
; #define LAS __attribute__((address_space(3)))
; __device__ __forceinline__ unsigned cvt_pk_bf16(float lo, float hi) { const f32v2_t v = {lo, hi}; const bf16v2_t r = __builtin_convertvector(v, bf16v2_t); return __builtin_bit_cast(unsigned, r); }
; __device__ __forceinline__ f32x16 mfma32(bf16x8 a, bf16x8 b, f32x16 c) { return __builtin_amdgcn_mfma_f32_32x32x16_bf16(a, b, c, 0, 0, 0); }
; __device__ __forceinline__ f32x16 zero16() { return (f32x16){0.f, 0.f, 0.f, 0.f, 0.f, 0.f, 0.f, 0.f, 0.f, 0.f, 0.f, 0.f, 0.f, 0.f, 0.f, 0.f}; }
; __device__ __forceinline__ void r3_item(const bf16_t* __restrict__ proj, const bf16_t* __restrict__ projT, const bf16_t* __restrict__ st, bf16_t* ro, ...
;     ...
;     { const int kt = w >> 1;
; #pragma unroll
;       for (int q2 = 0; q2 < 2; ++q2) { const int tqt = 2 * (w & 1) + q2;
;           f32x16 x = zero16();
; #pragma unroll
;           for (int s = 0; s < 8; ++s) { const bf16x8 kf = *(const LAS bf16x8*)(Kl + (32 * kt + c) * KT_STRIDE + 16 * s + 8 * hh);
;               const bf16x8 qf = *(const LAS bf16x8*)(Ql + (32 * tqt + c) * KT_STRIDE + 16 * s + 8 * hh); x = mfma32(kf, qf, x); }
;           const int n = 32 * tqt + c;
; #pragma unroll
;           for (int g4 = 0; g4 < 4; ++g4) { float pv[4];
; #pragma unroll
;               for (int j = 0; j < 4; ++j) { const int mk = 32 * kt + 8 * g4 + 4 * hh + j; const int diff = n - mk;
;                   const float dec = __builtin_amdgcn_exp2f(diff >= 0 ? (float)diff * lgf2 : (float)(-diff) * lgb2); pv[j] = x[4 * g4 + j] * dec; }
;               u32x2 pw; pw.x = cvt_pk_bf16(pv[0], pv[1]); pw.y = cvt_pk_bf16(pv[2], pv[3]);
;               *(LAS u32x2*)(Pl + n * KT_STRIDE + 32 * kt + 8 * g4 + 4 * hh) = pw; } } }
	v_mfma_f32_32x32x16_bf16 v[2:17], v[20:23], v[24:27], v[2:17]
	ds_read_b128 v[20:23], v18 offset:35040
	ds_read_b128 v[24:27], v19 offset:224
	v_sub_u32_e32 v19, v28, v30
	v_cmp_gt_i32_e32 vcc, 0, v19
	s_waitcnt lgkmcnt(0)
	v_mfma_f32_32x32x16_bf16 v[2:17], v[20:23], v[24:27], v[2:17]
	v_sub_u32_e32 v20, 0, v19
	v_max_i32_e32 v20, v19, v20
	v_cvt_f32_u32_e32 v20, v20
	v_cndmask_b32_e32 v19, v224, v225, vcc
	v_sub_u32_e32 v21, v28, v31
	v_cmp_gt_i32_e32 vcc, 0, v21
	v_mul_f32_e32 v19, v19, v20
	v_sub_u32_e32 v20, 0, v21
	v_max_i32_e32 v20, v21, v20
	v_cvt_f32_u32_e32 v22, v20
	v_exp_f32_e32 v20, v19
	v_cndmask_b32_e32 v19, v224, v225, vcc
	v_mad_u32_u24 v24, v28, s12, v29
	v_mul_f32_e32 v19, v19, v22
	v_exp_f32_e32 v21, v19
	v_sub_u32_e32 v19, v28, v32
	v_sub_u32_e32 v22, 0, v19
	v_max_i32_e32 v22, v19, v22
	v_cvt_f32_u32_e32 v22, v22
	v_pk_mul_f32 v[2:3], v[20:21], v[2:3]
	v_sub_u32_e32 v21, v28, v33
	v_cmp_gt_i32_e32 vcc, 0, v19
	v_sub_u32_e32 v20, 0, v21
	v_max_i32_e32 v20, v21, v20
	v_cndmask_b32_e32 v19, v224, v225, vcc
	v_mul_f32_e32 v19, v19, v22
	v_cvt_f32_u32_e32 v22, v20
	v_cmp_gt_i32_e32 vcc, 0, v21
	v_exp_f32_e32 v20, v19
	v_cvt_pk_bf16_f32 v2, v2, v3
	v_cndmask_b32_e32 v19, v224, v225, vcc
	v_mul_f32_e32 v19, v19, v22
	v_exp_f32_e32 v21, v19
	v_sub_u32_e32 v19, v28, v39
	v_sub_u32_e32 v22, 0, v19
	v_max_i32_e32 v22, v19, v22
	v_cvt_f32_u32_e32 v22, v22
	v_pk_mul_f32 v[4:5], v[20:21], v[4:5]
	v_sub_u32_e32 v21, v28, v40
	v_cmp_gt_i32_e32 vcc, 0, v19
	v_sub_u32_e32 v20, 0, v21
	v_max_i32_e32 v20, v21, v20
	v_cndmask_b32_e32 v19, v224, v225, vcc
	v_mul_f32_e32 v19, v19, v22
	v_cvt_f32_u32_e32 v22, v20
	v_cmp_gt_i32_e32 vcc, 0, v21
	v_exp_f32_e32 v20, v19
	v_cvt_pk_bf16_f32 v3, v4, v5
	v_cndmask_b32_e32 v19, v224, v225, vcc
	v_mul_f32_e32 v19, v19, v22
	v_sub_u32_e32 v22, v28, v41
	v_sub_u32_e32 v21, 0, v22
	v_max_i32_e32 v21, v22, v21
	v_cvt_f32_u32_e32 v23, v21
	v_cmp_gt_i32_e32 vcc, 0, v22
	v_exp_f32_e32 v21, v19
	s_nop 0
	v_cndmask_b32_e32 v19, v224, v225, vcc
	v_mul_f32_e32 v19, v19, v23
	v_sub_u32_e32 v23, v28, v42
	v_sub_u32_e32 v22, 0, v23
	v_max_i32_e32 v22, v23, v22
	v_cvt_f32_u32_e32 v25, v22
	v_cmp_gt_i32_e32 vcc, 0, v23
	v_exp_f32_e32 v22, v19
	v_pk_mul_f32 v[4:5], v[20:21], v[6:7]
	v_cndmask_b32_e32 v19, v224, v225, vcc
	v_mul_f32_e32 v19, v19, v25
	v_exp_f32_e32 v23, v19
	v_cvt_pk_bf16_f32 v4, v4, v5
	v_pk_mul_f32 v[6:7], v[22:23], v[8:9]
	s_nop 0
	v_cvt_pk_bf16_f32 v5, v6, v7
	ds_write2_b64 v24, v[2:3], v[4:5] offset1:2
	v_sub_u32_e32 v3, v28, v44
	v_sub_u32_e32 v4, 0, v3
	v_max_i32_e32 v4, v3, v4
	v_sub_u32_e32 v6, v28, v43
	v_cvt_f32_u32_e32 v4, v4
	v_cmp_gt_i32_e32 vcc, 0, v6
	v_sub_u32_e32 v7, 0, v6
	v_max_i32_e32 v7, v6, v7
	v_cndmask_b32_e32 v2, v224, v225, vcc
	v_cmp_gt_i32_e32 vcc, 0, v3
	v_cvt_f32_u32_e32 v7, v7
	v_mul_f32_e32 v2, v2, v7
	v_cndmask_b32_e32 v3, v224, v225, vcc
	v_mul_f32_e32 v3, v3, v4
	v_sub_u32_e32 v4, v28, v45
	v_sub_u32_e32 v5, 0, v4
	v_max_i32_e32 v5, v4, v5
	v_cvt_f32_u32_e32 v5, v5
	v_cmp_gt_i32_e32 vcc, 0, v4
	v_exp_f32_e32 v2, v2
	v_exp_f32_e32 v3, v3
	v_cndmask_b32_e32 v4, v224, v225, vcc
	v_mul_f32_e32 v4, v4, v5
	v_sub_u32_e32 v5, v28, v46
	v_sub_u32_e32 v6, 0, v5
	v_max_i32_e32 v6, v5, v6
	v_cvt_f32_u32_e32 v6, v6
	v_cmp_gt_i32_e32 vcc, 0, v5
	v_pk_mul_f32 v[2:3], v[2:3], v[10:11]
	v_exp_f32_e32 v4, v4
	v_cndmask_b32_e32 v5, v224, v225, vcc
	v_mul_f32_e32 v5, v5, v6
	v_sub_u32_e32 v6, v28, v47
	v_sub_u32_e32 v7, 0, v6
	v_max_i32_e32 v7, v6, v7
	v_cvt_f32_u32_e32 v7, v7
	v_cmp_gt_i32_e32 vcc, 0, v6
	v_exp_f32_e32 v5, v5
	v_cvt_pk_bf16_f32 v2, v2, v3
	v_cndmask_b32_e32 v6, v224, v225, vcc
	v_mul_f32_e32 v6, v6, v7
	v_sub_u32_e32 v7, v28, v48
	v_sub_u32_e32 v8, 0, v7
	v_max_i32_e32 v8, v7, v8
	v_cvt_f32_u32_e32 v8, v8
	v_cmp_gt_i32_e32 vcc, 0, v7
	v_exp_f32_e32 v6, v6
	v_pk_mul_f32 v[4:5], v[4:5], v[12:13]
	v_cndmask_b32_e32 v7, v224, v225, vcc
	v_mul_f32_e32 v7, v7, v8
	v_sub_u32_e32 v8, v28, v49
	v_sub_u32_e32 v9, 0, v8
	v_max_i32_e32 v9, v8, v9
	v_cvt_f32_u32_e32 v9, v9
	v_cmp_gt_i32_e32 vcc, 0, v8
	v_exp_f32_e32 v7, v7
	v_cvt_pk_bf16_f32 v3, v4, v5
	v_cndmask_b32_e32 v8, v224, v225, vcc
	v_mul_f32_e32 v8, v8, v9
	v_sub_u32_e32 v9, v28, v50
	v_sub_u32_e32 v10, 0, v9
	v_max_i32_e32 v10, v9, v10
	v_cvt_f32_u32_e32 v10, v10
	v_cmp_gt_i32_e32 vcc, 0, v9
	v_exp_f32_e32 v8, v8
	v_pk_mul_f32 v[4:5], v[6:7], v[14:15]
	v_cndmask_b32_e32 v9, v224, v225, vcc
	v_mul_f32_e32 v9, v9, v10
	v_exp_f32_e32 v9, v9
	v_cvt_pk_bf16_f32 v4, v4, v5
	v_pk_mul_f32 v[6:7], v[8:9], v[16:17]
	s_nop 0
	v_cvt_pk_bf16_f32 v5, v6, v7
	ds_write2_b64 v24, v[2:3], v[4:5] offset0:4 offset1:6
	ds_read_b128 v[2:5], v18 offset:34816
	ds_read_b128 v[6:9], v52
	s_waitcnt lgkmcnt(0)
	v_mfma_f32_32x32x16_bf16 v[2:17], v[2:5], v[6:9], 0
	ds_read_b128 v[20:23], v18 offset:34848
	ds_read_b128 v[24:27], v52 offset:32
	s_waitcnt lgkmcnt(0)
	v_mfma_f32_32x32x16_bf16 v[2:17], v[20:23], v[24:27], v[2:17]
	ds_read_b128 v[20:23], v18 offset:34880
	ds_read_b128 v[24:27], v52 offset:64
	s_waitcnt lgkmcnt(0)
	v_mfma_f32_32x32x16_bf16 v[2:17], v[20:23], v[24:27], v[2:17]
	ds_read_b128 v[20:23], v18 offset:34912
	ds_read_b128 v[24:27], v52 offset:96
	s_waitcnt lgkmcnt(0)
	v_mfma_f32_32x32x16_bf16 v[2:17], v[20:23], v[24:27], v[2:17]
	ds_read_b128 v[20:23], v18 offset:34944
	ds_read_b128 v[24:27], v52 offset:128
	s_waitcnt lgkmcnt(0)
	v_mfma_f32_32x32x16_bf16 v[2:17], v[20:23], v[24:27], v[2:17]
	ds_read_b128 v[20:23], v18 offset:34976
	ds_read_b128 v[24:27], v52 offset:160
	s_waitcnt lgkmcnt(0)
	v_mfma_f32_32x32x16_bf16 v[2:17], v[20:23], v[24:27], v[2:17]
	ds_read_b128 v[20:23], v18 offset:35008
	ds_read_b128 v[24:27], v52 offset:192
	s_waitcnt lgkmcnt(0)
; #define LAS __attribute__((address_space(3)))
; __device__ __forceinline__ unsigned cvt_pk_bf16(float lo, float hi) { const f32v2_t v = {lo, hi}; const bf16v2_t r = __builtin_convertvector(v, bf16v2_t); return __builtin_bit_cast(unsigned, r); }
; __device__ __forceinline__ void r3_item(const bf16_t* __restrict__ proj, const bf16_t* __restrict__ projT, const bf16_t* __restrict__ st, bf16_t* ro, ...
;     ...
;           const int n = 32 * tqt + c;
; #pragma unroll
;           for (int g4 = 0; g4 < 4; ++g4) { float pv[4];
; #pragma unroll
;               for (int j = 0; j < 4; ++j) { const int mk = 32 * kt + 8 * g4 + 4 * hh + j; const int diff = n - mk;
;                   const float dec = __builtin_amdgcn_exp2f(diff >= 0 ? (float)diff * lgf2 : (float)(-diff) * lgb2); pv[j] = x[4 * g4 + j] * dec; }
;               u32x2 pw; pw.x = cvt_pk_bf16(pv[0], pv[1]); pw.y = cvt_pk_bf16(pv[2], pv[3]);
;               *(LAS u32x2*)(Pl + n * KT_STRIDE + 32 * kt + 8 * g4 + 4 * hh) = pw; } } }
	v_mfma_f32_32x32x16_bf16 v[2:17], v[20:23], v[24:27], v[2:17]
	ds_read_b128 v[18:21], v18 offset:35040
	ds_read_b128 v[22:25], v52 offset:224
	v_or_b32_e32 v26, 32, v28
	s_waitcnt lgkmcnt(0)
	v_mfma_f32_32x32x16_bf16 v[2:17], v[18:21], v[22:25], v[2:17]
	v_sub_u32_e32 v18, v26, v30
	v_sub_u32_e32 v19, 0, v18
	v_max_i32_e32 v19, v18, v19
	v_cvt_f32_u32_e32 v19, v19
	v_cmp_gt_i32_e32 vcc, 0, v18
	v_add_u32_e32 v22, v29, v51
	s_nop 0
	v_cndmask_b32_e32 v18, v224, v225, vcc
	v_mul_f32_e32 v18, v18, v19
	v_sub_u32_e32 v19, v26, v31
	v_sub_u32_e32 v20, 0, v19
	v_max_i32_e32 v20, v19, v20
	v_cvt_f32_u32_e32 v20, v20
	v_cmp_gt_i32_e32 vcc, 0, v19
	v_exp_f32_e32 v18, v18
	s_nop 0
	v_cndmask_b32_e32 v19, v224, v225, vcc
	v_mul_f32_e32 v19, v19, v20
	v_exp_f32_e32 v19, v19
	v_sub_u32_e32 v20, v26, v32
	v_sub_u32_e32 v21, 0, v20
	v_max_i32_e32 v21, v20, v21
	v_pk_mul_f32 v[2:3], v[18:19], v[2:3]
	v_sub_u32_e32 v19, v26, v33
	v_cmp_gt_i32_e32 vcc, 0, v20
	v_sub_u32_e32 v20, 0, v19
	v_max_i32_e32 v20, v19, v20
	v_cvt_f32_u32_e32 v21, v21
	v_cvt_f32_u32_e32 v20, v20
	v_cndmask_b32_e32 v18, v224, v225, vcc
	v_cmp_gt_i32_e32 vcc, 0, v19
	v_mul_f32_e32 v18, v18, v21
	v_exp_f32_e32 v18, v18
	v_cndmask_b32_e32 v19, v224, v225, vcc
	v_mul_f32_e32 v19, v19, v20
	v_exp_f32_e32 v19, v19
	v_sub_u32_e32 v20, v26, v39
	v_sub_u32_e32 v21, 0, v20
	v_max_i32_e32 v21, v20, v21
	v_pk_mul_f32 v[4:5], v[18:19], v[4:5]
	v_sub_u32_e32 v19, v26, v40
	v_cmp_gt_i32_e32 vcc, 0, v20
	v_sub_u32_e32 v20, 0, v19
	v_max_i32_e32 v20, v19, v20
	v_cvt_f32_u32_e32 v20, v20
	v_cvt_f32_u32_e32 v21, v21
	v_cndmask_b32_e32 v18, v224, v225, vcc
	v_cmp_gt_i32_e32 vcc, 0, v19
	v_cvt_pk_bf16_f32 v2, v2, v3
	v_mul_f32_e32 v18, v18, v21
	v_cndmask_b32_e32 v19, v224, v225, vcc
	v_mul_f32_e32 v19, v19, v20
	v_sub_u32_e32 v20, v26, v41
	v_sub_u32_e32 v21, 0, v20
	v_max_i32_e32 v21, v20, v21
	v_cvt_f32_u32_e32 v21, v21
	v_cmp_gt_i32_e32 vcc, 0, v20
	v_exp_f32_e32 v18, v18
	v_exp_f32_e32 v19, v19
	v_cndmask_b32_e32 v20, v224, v225, vcc
	v_mul_f32_e32 v20, v20, v21
	v_sub_u32_e32 v21, v26, v42
	v_sub_u32_e32 v23, 0, v21
	v_max_i32_e32 v23, v21, v23
	v_cvt_f32_u32_e32 v23, v23
	v_cmp_gt_i32_e32 vcc, 0, v21
	v_exp_f32_e32 v20, v20
	v_cvt_pk_bf16_f32 v3, v4, v5
	v_cndmask_b32_e32 v21, v224, v225, vcc
	v_mul_f32_e32 v21, v21, v23
	v_exp_f32_e32 v21, v21
	v_pk_mul_f32 v[4:5], v[18:19], v[6:7]
	v_mov_b32_e32 v39, 0x4400
	v_cvt_pk_bf16_f32 v4, v4, v5
	v_pk_mul_f32 v[6:7], v[20:21], v[8:9]
	v_mad_u32_u24 v235, v250, s12, v39
	v_cvt_pk_bf16_f32 v5, v6, v7
	ds_write2_b64 v22, v[2:3], v[4:5] offset1:2
	v_sub_u32_e32 v3, v26, v44
	v_sub_u32_e32 v4, 0, v3
	v_max_i32_e32 v4, v3, v4
	v_sub_u32_e32 v6, v26, v43
	v_cvt_f32_u32_e32 v4, v4
	v_cmp_gt_i32_e32 vcc, 0, v6
	v_sub_u32_e32 v7, 0, v6
	v_max_i32_e32 v7, v6, v7
	v_cndmask_b32_e32 v2, v224, v225, vcc
	v_cmp_gt_i32_e32 vcc, 0, v3
	v_cvt_f32_u32_e32 v7, v7
	v_mov_b32_e32 v39, 0x6600
	v_cndmask_b32_e32 v3, v224, v225, vcc
	v_mul_f32_e32 v3, v3, v4
	v_sub_u32_e32 v4, v26, v45
	v_sub_u32_e32 v5, 0, v4
	v_max_i32_e32 v5, v4, v5
	v_cvt_f32_u32_e32 v5, v5
	v_cmp_gt_i32_e32 vcc, 0, v4
	v_mul_f32_e32 v2, v2, v7
	v_exp_f32_e32 v2, v2
	v_cndmask_b32_e32 v4, v224, v225, vcc
	v_mul_f32_e32 v4, v4, v5
	v_sub_u32_e32 v5, v26, v46
	v_sub_u32_e32 v6, 0, v5
	v_max_i32_e32 v6, v5, v6
	v_cvt_f32_u32_e32 v6, v6
	v_cmp_gt_i32_e32 vcc, 0, v5
	v_exp_f32_e32 v3, v3
	v_exp_f32_e32 v4, v4
	v_cndmask_b32_e32 v5, v224, v225, vcc
	v_mul_f32_e32 v5, v5, v6
	v_sub_u32_e32 v6, v26, v47
	v_sub_u32_e32 v7, 0, v6
	v_max_i32_e32 v7, v6, v7
	v_cvt_f32_u32_e32 v7, v7
	v_cmp_gt_i32_e32 vcc, 0, v6
	v_pk_mul_f32 v[2:3], v[2:3], v[10:11]
	v_exp_f32_e32 v5, v5
	v_cndmask_b32_e32 v6, v224, v225, vcc
	v_mul_f32_e32 v6, v6, v7
	v_sub_u32_e32 v7, v26, v48
	v_sub_u32_e32 v8, 0, v7
	v_max_i32_e32 v8, v7, v8
	v_cvt_f32_u32_e32 v8, v8
	v_cmp_gt_i32_e32 vcc, 0, v7
	v_exp_f32_e32 v6, v6
	v_pk_mul_f32 v[4:5], v[4:5], v[12:13]
	v_cndmask_b32_e32 v7, v224, v225, vcc
	v_mul_f32_e32 v7, v7, v8
	v_sub_u32_e32 v8, v26, v49
	v_sub_u32_e32 v9, 0, v8
	v_max_i32_e32 v9, v8, v9
	v_cvt_f32_u32_e32 v9, v9
	v_cmp_gt_i32_e32 vcc, 0, v8
	v_exp_f32_e32 v7, v7
	v_cvt_pk_bf16_f32 v2, v2, v3
	v_cndmask_b32_e32 v8, v224, v225, vcc
	v_mul_f32_e32 v8, v8, v9
	v_sub_u32_e32 v9, v26, v50
	v_sub_u32_e32 v10, 0, v9
	v_max_i32_e32 v10, v9, v10
	v_cvt_f32_u32_e32 v10, v10
	v_cmp_gt_i32_e32 vcc, 0, v9
	v_exp_f32_e32 v8, v8
	v_cvt_pk_bf16_f32 v3, v4, v5
	v_cndmask_b32_e32 v9, v224, v225, vcc
	v_mul_f32_e32 v9, v9, v10
	v_exp_f32_e32 v9, v9
	v_pk_mul_f32 v[4:5], v[6:7], v[14:15]
	v_mad_u32_u24 v253, v250, s12, v39
	v_cvt_pk_bf16_f32 v4, v4, v5
	v_pk_mul_f32 v[6:7], v[8:9], v[16:17]
	v_add_u32_e32 v214, v38, v235
	v_cvt_pk_bf16_f32 v5, v6, v7
	v_add_u32_e32 v218, v38, v253
	ds_write2_b64 v22, v[2:3], v[4:5] offset0:4 offset1:6
	s_waitcnt lgkmcnt(0)
	s_barrier
; #define LAS __attribute__((address_space(3)))
; __device__ __forceinline__ f32x16 mfma32(bf16x8 a, bf16x8 b, f32x16 c) { return __builtin_amdgcn_mfma_f32_32x32x16_bf16(a, b, c, 0, 0, 0); }
; __device__ __forceinline__ void r3_item(const bf16_t* __restrict__ proj, const bf16_t* __restrict__ projT, const bf16_t* __restrict__ st, bf16_t* ro, ...
;     ...
;     { const bf16_t* vp0 = projT + (size_t)(1024 + h * 256 + 32 * w + c) * MG + tok0 + 8 * hh;
; #pragma unroll
;       for (int s = 0; s < 8; ++s) { asf[s] = *(const bf16x8*)(st + stb0 + 16 * s); avt[s] = *(const bf16x8*)(vp0 + 16 * s); } }
; #pragma unroll
;     for (int s = 0; s < 8; ++s) { const bf16x8 a = asb[s];
; #pragma unroll
;         for (int q = 0; q < 4; ++q) { const bf16x8 b = *(const LAS bf16x8*)(Ql + (32 * q + c) * KT_STRIDE + 16 * s + 8 * hh); acc[q] = mfma32(a, b, acc[q]); } }
; #pragma unroll
;     for (int q = 0; q < 4; ++q) { const int n = 32 * q + c; const float f = __builtin_amdgcn_exp2f((float)(128 - n) * lgb2 - (float)(n + 1) * lgf2); acc[q] *= f; }
; #pragma unroll
;     for (int s = 0; s < 8; ++s) { const bf16x8 a = asf[s];
; #pragma unroll
;         for (int q = 0; q < 4; ++q) { const bf16x8 b = *(const LAS bf16x8*)(Ql + (32 * q + c) * KT_STRIDE + 16 * s + 8 * hh); acc[q] = mfma32(a, b, acc[q]); } }
	ds_read_b128 v[210:213], v190
	ds_read_b128 v[98:101], v190 offset:32
	ds_read_b128 v[206:209], v191
	ds_read_b128 v[178:181], v190 offset:192
	ds_read_b128 v[94:97], v214
	ds_read_b128 v[106:109], v214 offset:32
	ds_read_b128 v[202:205], v218
	ds_read_b128 v[186:189], v214 offset:192
	ds_read_b128 v[102:105], v191 offset:32
	ds_read_b128 v[118:121], v191 offset:64
	ds_read_b128 v[110:113], v218 offset:32
	ds_read_b128 v[126:129], v218 offset:64
	ds_read_b128 v[114:117], v190 offset:64
	ds_read_b128 v[130:133], v190 offset:96
	ds_read_b128 v[122:125], v214 offset:64
	ds_read_b128 v[138:141], v214 offset:96
	ds_read_b128 v[134:137], v191 offset:96
	ds_read_b128 v[150:153], v191 offset:128
	ds_read_b128 v[142:145], v218 offset:96
	ds_read_b128 v[158:161], v218 offset:128
	ds_read_b128 v[146:149], v190 offset:128
	ds_read_b128 v[162:165], v190 offset:160
	ds_read_b128 v[154:157], v214 offset:128
	ds_read_b128 v[170:173], v214 offset:160
	ds_read_b128 v[166:169], v191 offset:160
	ds_read_b128 v[182:185], v191 offset:192
	ds_read_b128 v[174:177], v218 offset:160
	ds_read_b128 v[194:197], v190 offset:224
	ds_read_b128 v[190:193], v191 offset:224
	global_load_dwordx4 v[236:239], v[222:223], off
	s_waitcnt lgkmcnt(14)
	v_mfma_f32_32x32x16_bf16 v[18:33], v[34:37], v[210:213], 0
	ds_read_b128 v[198:201], v218 offset:192
	ds_read_b128 v[214:217], v214 offset:224
	ds_read_b128 v[218:221], v218 offset:224
	v_mfma_f32_32x32x16_bf16 v[18:33], v[90:93], v[98:101], v[18:33]
	v_mfma_f32_32x32x16_bf16 v[2:17], v[34:37], v[206:209], 0
	v_mfma_f32_32x32x16_bf16 v[50:65], v[34:37], v[94:97], 0
	v_mfma_f32_32x32x16_bf16 v[34:49], v[34:37], v[202:205], 0
	v_mfma_f32_32x32x16_bf16 v[18:33], v[86:89], v[114:117], v[18:33]
	v_mfma_f32_32x32x16_bf16 v[2:17], v[90:93], v[102:105], v[2:17]
	v_mfma_f32_32x32x16_bf16 v[50:65], v[90:93], v[106:109], v[50:65]
	v_mfma_f32_32x32x16_bf16 v[34:49], v[90:93], v[110:113], v[34:49]
	v_mfma_f32_32x32x16_bf16 v[18:33], v[82:85], v[130:133], v[18:33]
	v_mfma_f32_32x32x16_bf16 v[2:17], v[86:89], v[118:121], v[2:17]
	v_mfma_f32_32x32x16_bf16 v[50:65], v[86:89], v[122:125], v[50:65]
	v_mfma_f32_32x32x16_bf16 v[34:49], v[86:89], v[126:129], v[34:49]
	s_waitcnt lgkmcnt(11)
	v_mfma_f32_32x32x16_bf16 v[18:33], v[78:81], v[146:149], v[18:33]
	v_mfma_f32_32x32x16_bf16 v[2:17], v[82:85], v[134:137], v[2:17]
	v_mfma_f32_32x32x16_bf16 v[50:65], v[82:85], v[138:141], v[50:65]
	v_mfma_f32_32x32x16_bf16 v[34:49], v[82:85], v[142:145], v[34:49]
	s_waitcnt lgkmcnt(10)
	v_mfma_f32_32x32x16_bf16 v[18:33], v[74:77], v[162:165], v[18:33]
	v_mfma_f32_32x32x16_bf16 v[2:17], v[78:81], v[150:153], v[2:17]
	s_waitcnt lgkmcnt(9)
	v_mfma_f32_32x32x16_bf16 v[50:65], v[78:81], v[154:157], v[50:65]
	v_mfma_f32_32x32x16_bf16 v[34:49], v[78:81], v[158:161], v[34:49]
	v_mfma_f32_32x32x16_bf16 v[18:33], v[70:73], v[178:181], v[18:33]
	s_waitcnt lgkmcnt(7)
	v_mfma_f32_32x32x16_bf16 v[2:17], v[74:77], v[166:169], v[2:17]
	v_mfma_f32_32x32x16_bf16 v[50:65], v[74:77], v[170:173], v[50:65]
	s_waitcnt lgkmcnt(5)
	v_mfma_f32_32x32x16_bf16 v[34:49], v[74:77], v[174:177], v[34:49]
	v_add_u32_e32 v74, 1, v250
	v_sub_u32_e32 v75, 0x80, v250
	v_cvt_f32_ubyte0_e32 v75, v75
	v_cvt_f32_ubyte0_e32 v74, v74
	v_mul_f32_e64 v228, v224, v74
	v_mul_f32_e64 v229, v225, v75
	v_sub_f32_e32 v74, v229, v228
	s_waitcnt lgkmcnt(4)
	v_mfma_f32_32x32x16_bf16 v[18:33], v[66:69], v[194:197], v[18:33]
	v_exp_f32_e32 v74, v74
	v_or_b32_e32 v229, 32, v250
	v_mfma_f32_32x32x16_bf16 v[2:17], v[70:73], v[182:185], v[2:17]
	s_nop 8
	v_mul_f32_e64 v32, v74, v32
	v_mul_f32_e64 v33, v74, v33
	v_mul_f32_e64 v30, v74, v30
	v_mul_f32_e64 v31, v74, v31
	v_mul_f32_e64 v28, v74, v28
	v_mul_f32_e64 v29, v74, v29
	v_pk_mul_f32 v[26:27], v[74:75], v[26:27] op_sel_hi:[0,1]
	v_pk_mul_f32 v[24:25], v[74:75], v[24:25] op_sel_hi:[0,1]
	v_pk_mul_f32 v[22:23], v[74:75], v[22:23] op_sel_hi:[0,1]
	v_pk_mul_f32 v[20:21], v[74:75], v[20:21] op_sel_hi:[0,1]
	v_mfma_f32_32x32x16_bf16 v[50:65], v[70:73], v[186:189], v[50:65]
	v_mul_f32_e64 v18, v74, v18
	v_mul_f32_e64 v19, v74, v19
	v_sub_u32_e32 v75, 0x80, v229
	v_add_u32_e32 v74, 33, v250
	v_cvt_f32_ubyte0_e32 v74, v74
	v_cvt_f32_ubyte0_e32 v75, v75
	v_pk_mul_f32 v[226:227], v[224:225], v[74:75]
	s_waitcnt lgkmcnt(2)
	v_mfma_f32_32x32x16_bf16 v[34:49], v[70:73], v[198:201], v[34:49]
	v_sub_f32_e32 v74, v227, v226
	v_or_b32_e32 v227, 64, v250
	v_exp_f32_e32 v74, v74
	v_mfma_f32_32x32x16_bf16 v[2:17], v[66:69], v[190:193], v[2:17]
	s_waitcnt lgkmcnt(1)
	v_mfma_f32_32x32x16_bf16 v[50:65], v[66:69], v[214:217], v[50:65]
	s_nop 9
	v_mul_f32_e64 v16, v74, v16
	v_mul_f32_e64 v17, v74, v17
	v_mul_f32_e64 v14, v74, v14
	v_mul_f32_e64 v15, v74, v15
	v_mul_f32_e64 v12, v74, v12
	v_mul_f32_e64 v13, v74, v13
	v_pk_mul_f32 v[10:11], v[74:75], v[10:11] op_sel_hi:[0,1]
	v_pk_mul_f32 v[8:9], v[74:75], v[8:9] op_sel_hi:[0,1]
	v_pk_mul_f32 v[6:7], v[74:75], v[6:7] op_sel_hi:[0,1]
	v_pk_mul_f32 v[4:5], v[74:75], v[4:5] op_sel_hi:[0,1]
	s_waitcnt lgkmcnt(0)
	v_mfma_f32_32x32x16_bf16 v[34:49], v[66:69], v[218:221], v[34:49]
	v_sub_u32_e32 v67, 0x80, v227
	v_add_u32_e32 v66, 0x41, v250
	v_cvt_f32_ubyte0_e32 v66, v66
	v_cvt_f32_ubyte0_e32 v67, v67
	v_mul_f32_e64 v230, v224, v66
	v_mul_f32_e64 v231, v225, v67
	v_pk_mul_f32 v[2:3], v[74:75], v[2:3] op_sel_hi:[0,1]
	v_sub_f32_e32 v66, v231, v230
	v_exp_f32_e32 v66, v66
	s_waitcnt vmcnt(0)
; #define LAS __attribute__((address_space(3)))
; __device__ __forceinline__ f32x16 mfma32(bf16x8 a, bf16x8 b, f32x16 c) { return __builtin_amdgcn_mfma_f32_32x32x16_bf16(a, b, c, 0, 0, 0); }
; __device__ __forceinline__ void r3_item(const bf16_t* __restrict__ proj, const bf16_t* __restrict__ projT, const bf16_t* __restrict__ st, bf16_t* ro, ...
;     ...
;     { const bf16_t* vp0 = projT + (size_t)(1024 + h * 256 + 32 * w + c) * MG + tok0 + 8 * hh;
; #pragma unroll
;       for (int s = 0; s < 8; ++s) { asf[s] = *(const bf16x8*)(st + stb0 + 16 * s); avt[s] = *(const bf16x8*)(vp0 + 16 * s); } }
; #pragma unroll
;     for (int s = 0; s < 8; ++s) { const bf16x8 a = asb[s];
; #pragma unroll
;         for (int q = 0; q < 4; ++q) { const bf16x8 b = *(const LAS bf16x8*)(Ql + (32 * q + c) * KT_STRIDE + 16 * s + 8 * hh); acc[q] = mfma32(a, b, acc[q]); } }
; #pragma unroll
;     for (int q = 0; q < 4; ++q) { const int n = 32 * q + c; const float f = __builtin_amdgcn_exp2f((float)(128 - n) * lgb2 - (float)(n + 1) * lgf2); acc[q] *= f; }
; #pragma unroll
;     for (int s = 0; s < 8; ++s) { const bf16x8 a = asf[s];
; #pragma unroll
;         for (int q = 0; q < 4; ++q) { const bf16x8 b = *(const LAS bf16x8*)(Ql + (32 * q + c) * KT_STRIDE + 16 * s + 8 * hh); acc[q] = mfma32(a, b, acc[q]); } }
; #pragma unroll
;     for (int q = 0; q < 4; ++q) { const int n = 32 * q + c; const float f = __builtin_amdgcn_exp2f((float)(n + 1) * lgf2); acc[q] *= f; }
; #pragma unroll
;     for (int s = 0; s < 8; ++s) { const bf16x8 a = avt[s];
; #pragma unroll
;         for (int q = 0; q < 4; ++q) { const bf16x8 b = *(const LAS bf16x8*)(Pl + (32 * q + c) * KT_STRIDE + 16 * s + 8 * hh); acc[q] = mfma32(a, b, acc[q]); } }
	v_mfma_f32_32x32x16_bf16 v[18:33], v[236:239], v[210:213], v[18:33]
	v_or_b32_e32 v210, 0x60, v250
	v_mul_f32_e64 v80, v66, v64
	v_mul_f32_e64 v81, v66, v65
	v_mul_f32_e64 v78, v66, v62
	v_mul_f32_e64 v79, v66, v63
	v_pk_mul_f32 v[76:77], v[66:67], v[60:61] op_sel_hi:[0,1]
	v_pk_mul_f32 v[74:75], v[66:67], v[58:59] op_sel_hi:[0,1]
	v_pk_mul_f32 v[72:73], v[66:67], v[56:57] op_sel_hi:[0,1]
	v_pk_mul_f32 v[70:71], v[66:67], v[54:55] op_sel_hi:[0,1]
	v_pk_mul_f32 v[68:69], v[66:67], v[52:53] op_sel_hi:[0,1]
	v_pk_mul_f32 v[66:67], v[66:67], v[50:51] op_sel_hi:[0,1]
	v_sub_u32_e32 v51, 0x80, v210
	v_add_u32_e32 v50, 0x61, v250
	v_cvt_f32_ubyte0_e32 v50, v50
	v_cvt_f32_ubyte0_e32 v51, v51
	v_mfma_f32_32x32x16_bf16 v[2:17], v[236:239], v[206:209], v[2:17]
	v_mul_f32_e64 v206, v224, v50
	v_mul_f32_e64 v207, v225, v51
	v_sub_f32_e32 v50, v207, v206
	v_exp_f32_e32 v50, v50
	s_nop 0
	v_pk_mul_f32 v[84:85], v[50:51], v[36:37] op_sel_hi:[0,1]
	v_pk_mul_f32 v[82:83], v[50:51], v[34:35] op_sel_hi:[0,1]
	global_load_dwordx4 v[34:37], v[222:223], off offset:32
	v_mfma_f32_32x32x16_bf16 v[66:81], v[236:239], v[94:97], v[66:81]
	v_mul_f32_e64 v96, v50, v48
	v_mul_f32_e64 v97, v50, v49
	v_mul_f32_e64 v94, v50, v46
	v_mul_f32_e64 v95, v50, v47
	v_mul_f32_e64 v92, v50, v44
	v_mul_f32_e64 v93, v50, v45
	v_pk_mul_f32 v[90:91], v[50:51], v[42:43] op_sel_hi:[0,1]
	v_pk_mul_f32 v[88:89], v[50:51], v[40:41] op_sel_hi:[0,1]
	v_pk_mul_f32 v[86:87], v[50:51], v[38:39] op_sel_hi:[0,1]
	v_or_b32_e32 v38, s58, v250
	s_waitcnt vmcnt(0)
	v_mfma_f32_32x32x16_bf16 v[18:33], v[34:37], v[98:101], v[18:33]
	v_add_u32_e32 v38, s44, v38
	v_add_u32_e32 v38, 0x400, v38
	v_ashrrev_i32_e32 v39, 31, v38
	v_lshlrev_b64 v[38:39], 15, v[38:39]
	v_lshl_add_u64 v[38:39], s[4:5], 0, v[38:39]
	v_lshl_add_u64 v[38:39], s[6:7], 1, v[38:39]
	v_lshl_add_u64 v[38:39], v[38:39], 0, v[0:1]
	v_mfma_f32_32x32x16_bf16 v[82:97], v[236:239], v[202:205], v[82:97]
	s_mov_b32 s4, 0x18240000
	v_add_co_u32_e32 v40, vcc, s4, v38
	v_lshl_add_u64 v[98:99], v[38:39], 0, s[60:61]
	s_nop 0
	v_addc_co_u32_e32 v41, vcc, 0, v39, vcc
	v_cmp_eq_u32_e64 s[4:5], 0, v251
	v_mfma_f32_32x32x16_bf16 v[2:17], v[34:37], v[102:105], v[2:17]
	global_load_dwordx4 v[44:47], v[222:223], off offset:64
	global_load_dwordx4 v[48:51], v[222:223], off offset:96
	global_load_dwordx4 v[202:205], v[222:223], off offset:128
	global_load_dwordx4 v[236:239], v[222:223], off offset:160
	global_load_dwordx4 v[100:103], v[40:41], off
	v_exp_f32_e32 v40, v228
	v_add_u32_e32 v104, s20, v0
	v_mad_u32_u24 v105, v250, s12, v104
	v_exp_f32_e32 v0, v206
	v_mfma_f32_32x32x16_bf16 v[66:81], v[34:37], v[106:109], v[66:81]
	v_mfma_f32_32x32x16_bf16 v[82:97], v[34:37], v[110:113], v[82:97]
	global_load_dwordx4 v[106:109], v[222:223], off offset:192
	global_load_dwordx4 v[110:113], v[222:223], off offset:224
	s_waitcnt vmcnt(6)
	v_mfma_f32_32x32x16_bf16 v[18:33], v[44:47], v[114:117], v[18:33]
	v_mfma_f32_32x32x16_bf16 v[2:17], v[44:47], v[118:121], v[2:17]
	v_mfma_f32_32x32x16_bf16 v[66:81], v[44:47], v[122:125], v[66:81]
	v_mfma_f32_32x32x16_bf16 v[82:97], v[44:47], v[126:129], v[82:97]
	s_waitcnt vmcnt(5)
	v_mfma_f32_32x32x16_bf16 v[18:33], v[48:51], v[130:133], v[18:33]
	v_mfma_f32_32x32x16_bf16 v[2:17], v[48:51], v[134:137], v[2:17]
	v_mfma_f32_32x32x16_bf16 v[66:81], v[48:51], v[138:141], v[66:81]
	v_mfma_f32_32x32x16_bf16 v[82:97], v[48:51], v[142:145], v[82:97]
	s_waitcnt vmcnt(4)
	v_mfma_f32_32x32x16_bf16 v[18:33], v[202:205], v[146:149], v[18:33]
	v_mfma_f32_32x32x16_bf16 v[2:17], v[202:205], v[150:153], v[2:17]
	v_mfma_f32_32x32x16_bf16 v[66:81], v[202:205], v[154:157], v[66:81]
	v_mfma_f32_32x32x16_bf16 v[82:97], v[202:205], v[158:161], v[82:97]
	s_waitcnt vmcnt(3)
	v_mfma_f32_32x32x16_bf16 v[18:33], v[236:239], v[162:165], v[18:33]
	v_mfma_f32_32x32x16_bf16 v[2:17], v[236:239], v[166:169], v[2:17]
	v_mfma_f32_32x32x16_bf16 v[66:81], v[236:239], v[170:173], v[66:81]
	v_mfma_f32_32x32x16_bf16 v[82:97], v[236:239], v[174:177], v[82:97]
	global_load_dwordx4 v[146:149], v[98:99], off offset:32
	global_load_dwordx4 v[150:153], v[98:99], off offset:64
	global_load_dwordx4 v[154:157], v[98:99], off offset:96
	global_load_dwordx4 v[158:161], v[98:99], off offset:128
	global_load_dwordx4 v[162:165], v[98:99], off offset:160
	global_load_dwordx4 v[166:169], v[98:99], off offset:192
	global_load_dwordx4 v[170:173], v[98:99], off offset:224
	s_waitcnt vmcnt(8)
	v_mfma_f32_32x32x16_bf16 v[18:33], v[106:109], v[178:181], v[18:33]
	v_mfma_f32_32x32x16_bf16 v[2:17], v[106:109], v[182:185], v[2:17]
	v_mfma_f32_32x32x16_bf16 v[66:81], v[106:109], v[186:189], v[66:81]
	v_mfma_f32_32x32x16_bf16 v[82:97], v[106:109], v[198:201], v[82:97]
	s_waitcnt vmcnt(7)
	v_mfma_f32_32x32x16_bf16 v[18:33], v[110:113], v[194:197], v[18:33]
	s_nop 11
	v_pk_mul_f32 v[56:57], v[40:41], v[24:25] op_sel_hi:[0,1]
	v_mfma_f32_32x32x16_bf16 v[2:17], v[110:113], v[190:193], v[2:17]
	v_exp_f32_e32 v24, v226
	v_pk_mul_f32 v[60:61], v[40:41], v[28:29] op_sel_hi:[0,1]
	v_pk_mul_f32 v[64:65], v[40:41], v[32:33] op_sel_hi:[0,1]
	v_pk_mul_f32 v[62:63], v[40:41], v[30:31] op_sel_hi:[0,1]
	v_pk_mul_f32 v[58:59], v[40:41], v[26:27] op_sel_hi:[0,1]
	v_pk_mul_f32 v[54:55], v[40:41], v[22:23] op_sel_hi:[0,1]
	v_pk_mul_f32 v[52:53], v[40:41], v[20:21] op_sel_hi:[0,1]
	v_mfma_f32_32x32x16_bf16 v[66:81], v[110:113], v[214:217], v[66:81]
	s_nop 3
	v_mul_f32_e64 v42, v24, v10
	v_mul_f32_e64 v43, v24, v11
	v_exp_f32_e32 v10, v230
	v_pk_mul_f32 v[50:51], v[40:41], v[18:19] op_sel_hi:[0,1]
	v_pk_mul_f32 v[40:41], v[24:25], v[8:9] op_sel_hi:[0,1]
	v_pk_mul_f32 v[38:39], v[24:25], v[6:7] op_sel_hi:[0,1]
	ds_read_b128 v[6:9], v105
	v_pk_mul_f32 v[48:49], v[24:25], v[16:17] op_sel_hi:[0,1]
	v_pk_mul_f32 v[28:29], v[10:11], v[76:77] op_sel_hi:[0,1]
	v_add_u32_e32 v76, v104, v233
	v_mfma_f32_32x32x16_bf16 v[82:97], v[110:113], v[218:221], v[82:97]
	v_mul_f32_e64 v36, v24, v4
	v_mul_f32_e64 v37, v24, v5
	v_mul_f32_e64 v34, v24, v2
	v_mul_f32_e64 v35, v24, v3
	ds_read_b128 v[2:5], v76
	v_pk_mul_f32 v[46:47], v[24:25], v[14:15] op_sel_hi:[0,1]
	v_pk_mul_f32 v[44:45], v[24:25], v[12:13] op_sel_hi:[0,1]
	v_pk_mul_f32 v[26:27], v[10:11], v[74:75] op_sel_hi:[0,1]
	v_add_u32_e32 v74, v104, v235
	s_waitcnt lgkmcnt(0)
; #define LAS __attribute__((address_space(3)))
; __device__ __forceinline__ f32x16 mfma32(bf16x8 a, bf16x8 b, f32x16 c) { return __builtin_amdgcn_mfma_f32_32x32x16_bf16(a, b, c, 0, 0, 0); }
; __device__ __forceinline__ float xhalf_sum(float x) { const auto rr = __builtin_amdgcn_permlane32_swap(__float_as_uint(x), __float_as_uint(x), false, false); return __uint_as_float(rr[0]) + __uint_as_float(rr[1]); }
; __device__ __forceinline__ void r3_item(const bf16_t* __restrict__ proj, const bf16_t* __restrict__ projT, const bf16_t* __restrict__ st, bf16_t* ro, ...
;     ...
;     for (int s = 0; s < 8; ++s) { const bf16x8 a = avt[s];
; #pragma unroll
;         for (int q = 0; q < 4; ++q) { const bf16x8 b = *(const LAS bf16x8*)(Pl + (32 * q + c) * KT_STRIDE + 16 * s + 8 * hh); acc[q] = mfma32(a, b, acc[q]); } }
; #pragma unroll
;     for (int q = 0; q < 4; ++q) { float s1 = 0.f, s2 = 0.f;
; #pragma unroll
;         for (int i = 0; i < 16; ++i) { s1 += acc[q][i]; s2 += acc[q][i] * acc[q][i]; }
;         s1 = xhalf_sum(s1); s2 = xhalf_sum(s2);
;         if (hh == 0) { stat[(w * 128 + 32 * q + c) * 2] = s1; stat[(w * 128 + 32 * q + c) * 2 + 1] = s2; } }
	v_mfma_f32_32x32x16_bf16 v[34:49], v[100:103], v[2:5], v[34:49]
	ds_read_b128 v[2:5], v74
	v_add_u32_e32 v75, v104, v253
	v_mul_f32_e64 v20, v10, v68
	v_mul_f32_e64 v21, v10, v69
	v_mul_f32_e64 v18, v10, v66
	v_mul_f32_e64 v19, v10, v67
	ds_read_b128 v[66:69], v75
	v_pk_mul_f32 v[32:33], v[10:11], v[80:81] op_sel_hi:[0,1]
	v_pk_mul_f32 v[30:31], v[10:11], v[78:79] op_sel_hi:[0,1]
	v_pk_mul_f32 v[24:25], v[10:11], v[72:73] op_sel_hi:[0,1]
	v_pk_mul_f32 v[22:23], v[10:11], v[70:71] op_sel_hi:[0,1]
	v_mfma_f32_32x32x16_bf16 v[50:65], v[100:103], v[6:9], v[50:65]
	v_mul_f32_e64 v16, v0, v96
	v_mul_f32_e64 v17, v0, v97
	v_mul_f32_e64 v14, v0, v94
	v_mul_f32_e64 v15, v0, v95
	v_mul_f32_e64 v12, v0, v92
	v_mul_f32_e64 v13, v0, v93
	v_pk_mul_f32 v[10:11], v[0:1], v[90:91] op_sel_hi:[0,1]
	v_pk_mul_f32 v[8:9], v[0:1], v[88:89] op_sel_hi:[0,1]
	v_pk_mul_f32 v[6:7], v[0:1], v[86:87] op_sel_hi:[0,1]
	ds_read_b128 v[70:73], v105 offset:32
	s_waitcnt lgkmcnt(2)
	v_mfma_f32_32x32x16_bf16 v[18:33], v[100:103], v[2:5], v[18:33]
	v_mul_f32_e64 v4, v0, v84
	v_mul_f32_e64 v5, v0, v85
	v_mul_f32_e64 v2, v0, v82
	v_mul_f32_e64 v3, v0, v83
	v_and_b32_e32 v0, 32, v247
	v_cmp_ne_u32_e32 vcc, 0, v0
	s_waitcnt lgkmcnt(1)
	v_mfma_f32_32x32x16_bf16 v[2:17], v[100:103], v[66:69], v[2:17]
	s_waitcnt vmcnt(6) lgkmcnt(0)
	v_mfma_f32_32x32x16_bf16 v[50:65], v[146:149], v[70:73], v[50:65]
	ds_read_b128 v[70:73], v76 offset:32
	s_waitcnt lgkmcnt(0)
	v_mfma_f32_32x32x16_bf16 v[34:49], v[146:149], v[70:73], v[34:49]
	ds_read_b128 v[70:73], v74 offset:32
	s_waitcnt lgkmcnt(0)
	v_mfma_f32_32x32x16_bf16 v[18:33], v[146:149], v[70:73], v[18:33]
	ds_read_b128 v[70:73], v75 offset:32
	s_waitcnt lgkmcnt(0)
	v_mfma_f32_32x32x16_bf16 v[2:17], v[146:149], v[70:73], v[2:17]
	ds_read_b128 v[70:73], v105 offset:64
	s_waitcnt vmcnt(5) lgkmcnt(0)
	v_mfma_f32_32x32x16_bf16 v[50:65], v[150:153], v[70:73], v[50:65]
	ds_read_b128 v[70:73], v76 offset:64
	s_waitcnt lgkmcnt(0)
	v_mfma_f32_32x32x16_bf16 v[34:49], v[150:153], v[70:73], v[34:49]
	ds_read_b128 v[70:73], v74 offset:64
	s_waitcnt lgkmcnt(0)
	v_mfma_f32_32x32x16_bf16 v[18:33], v[150:153], v[70:73], v[18:33]
	ds_read_b128 v[70:73], v75 offset:64
	s_waitcnt lgkmcnt(0)
	v_mfma_f32_32x32x16_bf16 v[2:17], v[150:153], v[70:73], v[2:17]
	ds_read_b128 v[70:73], v105 offset:96
	s_waitcnt vmcnt(4) lgkmcnt(0)
	v_mfma_f32_32x32x16_bf16 v[50:65], v[154:157], v[70:73], v[50:65]
	ds_read_b128 v[70:73], v76 offset:96
	s_waitcnt lgkmcnt(0)
	v_mfma_f32_32x32x16_bf16 v[34:49], v[154:157], v[70:73], v[34:49]
	ds_read_b128 v[70:73], v74 offset:96
	s_waitcnt lgkmcnt(0)
	v_mfma_f32_32x32x16_bf16 v[18:33], v[154:157], v[70:73], v[18:33]
	ds_read_b128 v[70:73], v75 offset:96
	s_waitcnt lgkmcnt(0)
	v_mfma_f32_32x32x16_bf16 v[2:17], v[154:157], v[70:73], v[2:17]
	ds_read_b128 v[70:73], v105 offset:128
	s_waitcnt vmcnt(3) lgkmcnt(0)
	v_mfma_f32_32x32x16_bf16 v[50:65], v[158:161], v[70:73], v[50:65]
	ds_read_b128 v[70:73], v76 offset:128
	s_waitcnt lgkmcnt(0)
	v_mfma_f32_32x32x16_bf16 v[34:49], v[158:161], v[70:73], v[34:49]
	ds_read_b128 v[70:73], v74 offset:128
	s_waitcnt lgkmcnt(0)
	v_mfma_f32_32x32x16_bf16 v[18:33], v[158:161], v[70:73], v[18:33]
	ds_read_b128 v[70:73], v75 offset:128
	s_waitcnt lgkmcnt(0)
	v_mfma_f32_32x32x16_bf16 v[2:17], v[158:161], v[70:73], v[2:17]
	ds_read_b128 v[70:73], v105 offset:160
	s_waitcnt vmcnt(2) lgkmcnt(0)
	v_mfma_f32_32x32x16_bf16 v[50:65], v[162:165], v[70:73], v[50:65]
	ds_read_b128 v[70:73], v76 offset:160
	s_waitcnt lgkmcnt(0)
	v_mfma_f32_32x32x16_bf16 v[34:49], v[162:165], v[70:73], v[34:49]
	ds_read_b128 v[70:73], v74 offset:160
	s_waitcnt lgkmcnt(0)
	v_mfma_f32_32x32x16_bf16 v[18:33], v[162:165], v[70:73], v[18:33]
	ds_read_b128 v[70:73], v75 offset:160
	s_waitcnt lgkmcnt(0)
	v_mfma_f32_32x32x16_bf16 v[2:17], v[162:165], v[70:73], v[2:17]
	ds_read_b128 v[70:73], v105 offset:192
	s_waitcnt vmcnt(1) lgkmcnt(0)
	v_mfma_f32_32x32x16_bf16 v[50:65], v[166:169], v[70:73], v[50:65]
	ds_read_b128 v[70:73], v76 offset:192
	s_waitcnt lgkmcnt(0)
	v_mfma_f32_32x32x16_bf16 v[34:49], v[166:169], v[70:73], v[34:49]
	ds_read_b128 v[70:73], v74 offset:192
	s_waitcnt lgkmcnt(0)
	v_mfma_f32_32x32x16_bf16 v[18:33], v[166:169], v[70:73], v[18:33]
	ds_read_b128 v[70:73], v75 offset:192
	s_waitcnt lgkmcnt(0)
	v_mfma_f32_32x32x16_bf16 v[2:17], v[166:169], v[70:73], v[2:17]
	ds_read_b128 v[70:73], v105 offset:224
	s_waitcnt vmcnt(0) lgkmcnt(0)
	v_mfma_f32_32x32x16_bf16 v[50:65], v[170:173], v[70:73], v[50:65]
	ds_read_b128 v[70:73], v76 offset:224
	s_nop 10
	v_add_f32_e32 v0, 0, v50
	s_waitcnt lgkmcnt(0)
	v_mfma_f32_32x32x16_bf16 v[34:49], v[170:173], v[70:73], v[34:49]
	ds_read_b128 v[70:73], v74 offset:224
	v_add_f32_e32 v0, v51, v0
	v_add_f32_e32 v0, v52, v0
	v_add_f32_e32 v0, v53, v0
	v_add_f32_e32 v0, v54, v0
	v_add_f32_e32 v0, v55, v0
	v_add_f32_e32 v0, v56, v0
	s_waitcnt lgkmcnt(0)
	v_mfma_f32_32x32x16_bf16 v[18:33], v[170:173], v[70:73], v[18:33]
	ds_read_b128 v[70:73], v75 offset:224
	v_add_f32_e32 v0, v57, v0
	v_add_f32_e32 v0, v58, v0
	v_add_f32_e32 v0, v59, v0
	v_add_f32_e32 v0, v60, v0
	v_add_f32_e32 v0, v61, v0
	v_add_f32_e32 v0, v62, v0
	s_waitcnt lgkmcnt(0)
	v_mfma_f32_32x32x16_bf16 v[2:17], v[170:173], v[70:73], v[2:17]
	v_mul_f32_e32 v67, v51, v51
	v_fmac_f32_e32 v67, v50, v50
	v_fmac_f32_e32 v67, v52, v52
	v_fmac_f32_e32 v67, v53, v53
	v_fmac_f32_e32 v67, v54, v54
	v_fmac_f32_e32 v67, v55, v55
	v_fmac_f32_e32 v67, v56, v56
	v_fmac_f32_e32 v67, v57, v57
	v_fmac_f32_e32 v67, v58, v58
	v_fmac_f32_e32 v67, v59, v59
	v_fmac_f32_e32 v67, v60, v60
	v_fmac_f32_e32 v67, v61, v61
	v_fmac_f32_e32 v67, v62, v62
	v_add_f32_e32 v0, v63, v0
	v_fmac_f32_e32 v67, v63, v63
	v_add_f32_e32 v0, v64, v0
	v_fmac_f32_e32 v67, v64, v64
	v_add_f32_e32 v66, v65, v0
	v_fmac_f32_e32 v67, v65, v65
	v_mov_b32_e32 v68, v66
	v_mov_b32_e32 v69, v67
	s_nop 0
	v_permlane32_swap_b32_e32 v66, v68
	v_permlane32_swap_b32_e32 v67, v69
	s_and_saveexec_b64 s[28:29], s[4:5]
	s_cbranch_execz .LBB0_487
	s_lshl_b32 s7, s45, 10
	s_add_i32 s7, s7, 0
	v_lshl_add_u32 v0, v250, 3, s7
	v_add_u32_e32 v0, 0x19800, v0
	v_pk_add_f32 v[66:67], v[66:67], v[68:69]
	ds_write_b64 v0, v[66:67]

; __device__ __forceinline__ float sigmoidf_(float x) { return __builtin_amdgcn_rcpf(1.0f + __expf(-x)); }
; __device__ __forceinline__ void unpack8(const u32x4 w, float* f) { f[0] = bf_lo(w.x); f[1] = bf_hi(w.x); f[2] = bf_lo(w.y); f[3] = bf_hi(w.y); f[4] = bf_lo(w.z); f[5] = bf_hi(w.z); f[6] = bf_lo(w.w); f[7] = bf_hi(w.w); }
; __device__ __forceinline__ u32x4 pack8(const float* f) { u32x4 w; w.x = cvt_pk_bf16(f[0], f[1]); w.y = cvt_pk_bf16(f[2], f[3]); w.z = cvt_pk_bf16(f[4], f[5]); w.w = cvt_pk_bf16(f[6], f[7]); return w; }
;     __device__ __forceinline__ void operator()(const f32x4 (&acc)[2][2][4][2], const Unit& u, int wr, int wc, int fr, int fq) const { if (u.kind == 0) e0(acc, u, wr, wc, fr, fq); else e1(acc, u, wr, wc, fr, fq); }
;     __device__ __forceinline__ void operator()(const f32x4 (&acc)[2][2][4][2], const Unit& u, int wr, int wc, int fr, int fq) const {
;         const int row0 = u.pm * BM + wr * 64 + fr, col0 = u.pn * BM + wc * 32 + 8 * fq;
; #pragma unroll
;         for (int ai = 0; ai < 2; ++ai)
; #pragma unroll
;             for (int m = 0; m < 4; ++m) { const int row = row0 + ai * HALF + m * 16;
; #pragma unroll
;                 for (int bj = 0; bj < 2; ++bj) { const int col = col0 + bj * HALF;
;                     float gf[8], r[8]; unpack8(*(const u32x4*)(gr + (size_t)row * NPROJ + col), gf);
;                     const f32x4 v0 = acc[ai][bj][m][0], v1 = acc[ai][bj][m][1];
; #pragma unroll
;                     for (int j = 0; j < 4; ++j) { r[j] = v0[j] * sigmoidf_(gf[j]); r[4 + j] = v1[j] * sigmoidf_(gf[4 + j]); }
;                     *(u32x4*)(O + (size_t)row * D + col) = pack8(r); } }
;     }
.LBB0_548:
	v_mov_b64_e32 v[132:133], s[40:41]
	v_mad_i64_i32 v[134:135], s[10:11], v166, s18, v[132:133]
	v_lshlrev_b64 v[2:3], 1, v[164:165]
	v_ashrrev_i32_e32 v167, 31, v166
	v_lshl_add_u64 v[134:135], v[134:135], 0, v[2:3]
	v_lshlrev_b64 v[136:137], 11, v[166:167]
	v_mad_i64_i32 v[230:231], s[98:99], v166, s18, v[132:133]
	v_lshl_add_u64 v[230:231], v[230:231], 0, v[2:3]
	global_load_dwordx4 v[168:171], v[230:231], off
	global_load_dwordx4 v[190:193], v[230:231], off offset:256
	v_mad_i64_i32 v[230:231], s[98:99], v162, s18, v[132:133]
	v_lshl_add_u64 v[230:231], v[230:231], 0, v[2:3]
	global_load_dwordx4 v[194:197], v[230:231], off
	global_load_dwordx4 v[198:201], v[230:231], off offset:256
	v_mad_i64_i32 v[230:231], s[98:99], v160, s18, v[132:133]
	v_lshl_add_u64 v[230:231], v[230:231], 0, v[2:3]
	global_load_dwordx4 v[202:205], v[230:231], off
	global_load_dwordx4 v[206:209], v[230:231], off offset:256
	v_mad_i64_i32 v[230:231], s[98:99], v158, s18, v[132:133]
	v_lshl_add_u64 v[230:231], v[230:231], 0, v[2:3]
	global_load_dwordx4 v[210:213], v[230:231], off
	global_load_dwordx4 v[214:217], v[230:231], off offset:256
	v_mad_i64_i32 v[230:231], s[98:99], v156, s18, v[132:133]
	v_lshl_add_u64 v[230:231], v[230:231], 0, v[2:3]
	global_load_dwordx4 v[218:221], v[230:231], off
	global_load_dwordx4 v[222:225], v[230:231], off offset:256
	v_mad_i64_i32 v[230:231], s[98:99], v154, s18, v[132:133]
	v_lshl_add_u64 v[230:231], v[230:231], 0, v[2:3]
	global_load_dwordx4 v[226:229], v[230:231], off
	global_load_dwordx4 v[236:239], v[230:231], off offset:256
	s_waitcnt vmcnt(11)
	v_mov_b64_e32 v[164:165], v[168:169]
	v_mov_b64_e32 v[166:167], v[170:171]
	s_and_b64 vcc, exec, s[4:5]
	s_mov_b64 s[28:29], s[0:1]
	s_mov_b64 s[42:43], s[6:7]
	v_lshlrev_b32_e32 v0, 16, v164
	v_mul_f32_e32 v0, 0xbfb8aa3b, v0
	v_exp_f32_e32 v0, v0
	v_lshlrev_b32_e32 v157, 16, v166
	v_and_b32_e32 v151, 0xffff0000, v164
	v_and_b32_e32 v159, 0xffff0000, v166
	v_add_f32_e32 v0, 1.0, v0
	v_rcp_f32_e32 v164, v0
	v_mul_f32_e32 v0, 0xbfb8aa3b, v157
	v_exp_f32_e32 v0, v0
	v_lshlrev_b32_e32 v153, 16, v165
	v_and_b32_e32 v155, 0xffff0000, v165
	v_lshlrev_b32_e32 v161, 16, v167
	v_add_f32_e32 v0, 1.0, v0
	v_rcp_f32_e32 v166, v0
	v_mul_f32_e32 v0, 0xbfb8aa3b, v151
	v_exp_f32_e32 v0, v0
	v_and_b32_e32 v163, 0xffff0000, v167
	v_ashrrev_i32_e32 v157, 31, v156
	v_ashrrev_i32_e32 v151, 31, v150
	v_add_f32_e32 v0, 1.0, v0
	v_rcp_f32_e32 v165, v0
	v_mul_f32_e32 v0, 0xbfb8aa3b, v159
	v_exp_f32_e32 v0, v0
	v_ashrrev_i32_e32 v159, 31, v158
	v_pk_mul_f32 v[128:129], v[128:129], v[164:165]
	v_add_f32_e32 v0, 1.0, v0
	v_rcp_f32_e32 v167, v0
	v_mul_f32_e32 v0, 0xbfb8aa3b, v153
	v_exp_f32_e32 v0, v0
	v_ashrrev_i32_e32 v153, 31, v152
	v_pk_mul_f32 v[164:165], v[124:125], v[166:167]
	v_add_f32_e32 v0, 1.0, v0
	v_rcp_f32_e32 v124, v0
	v_mul_f32_e32 v0, 0xbfb8aa3b, v161
	v_exp_f32_e32 v0, v0
	v_ashrrev_i32_e32 v161, 31, v160
	v_add_f32_e32 v0, 1.0, v0
	v_rcp_f32_e32 v166, v0
	v_mul_f32_e32 v0, 0xbfb8aa3b, v155
	v_exp_f32_e32 v0, v0
	v_ashrrev_i32_e32 v155, 31, v154
	v_add_f32_e32 v0, 1.0, v0
	v_rcp_f32_e32 v125, v0
	v_mul_f32_e32 v0, 0xbfb8aa3b, v163
	v_exp_f32_e32 v0, v0
	v_ashrrev_i32_e32 v163, 31, v162
	v_pk_mul_f32 v[130:131], v[130:131], v[124:125]
	v_cvt_pk_bf16_f32 v124, v128, v129
	v_add_f32_e32 v0, 1.0, v0
	v_rcp_f32_e32 v167, v0
	v_lshl_add_u64 v[128:129], s[94:95], 0, v[136:137]
	v_cvt_pk_bf16_f32 v125, v130, v131
	v_lshl_add_u64 v[128:129], v[128:129], 0, v[2:3]
	v_pk_mul_f32 v[166:167], v[126:127], v[166:167]
	v_cvt_pk_bf16_f32 v126, v164, v165
	v_cvt_pk_bf16_f32 v127, v166, v167
	global_store_dwordx4 v[128:129], v[124:127], off
	s_waitcnt vmcnt(10)
	v_mov_b64_e32 v[124:125], v[190:191]
	v_mov_b64_e32 v[126:127], v[192:193]
	v_mad_i64_i32 v[230:231], s[98:99], v152, s18, v[132:133]
	v_lshl_add_u64 v[230:231], v[230:231], 0, v[2:3]
	global_load_dwordx4 v[168:171], v[230:231], off
	global_load_dwordx4 v[190:193], v[230:231], off offset:256
	v_lshlrev_b32_e32 v0, 16, v124
	v_mul_f32_e32 v0, 0xbfb8aa3b, v0
	v_exp_f32_e32 v0, v0
	v_lshlrev_b32_e32 v131, 16, v125
	v_and_b32_e32 v134, 0xffff0000, v125
	v_lshlrev_b32_e32 v125, 16, v126
	v_add_f32_e32 v0, 1.0, v0
	v_and_b32_e32 v130, 0xffff0000, v124
	v_rcp_f32_e32 v124, v0
	v_mul_f32_e32 v0, 0xbfb8aa3b, v125
	v_exp_f32_e32 v0, v0
	v_and_b32_e32 v135, 0xffff0000, v126
	v_lshlrev_b32_e32 v136, 16, v127
	v_and_b32_e32 v137, 0xffff0000, v127
	v_add_f32_e32 v0, 1.0, v0
	v_rcp_f32_e32 v126, v0
	v_mul_f32_e32 v0, 0xbfb8aa3b, v130
	v_exp_f32_e32 v0, v0
	s_nop 0
	v_add_f32_e32 v0, 1.0, v0
	v_rcp_f32_e32 v125, v0
	v_mul_f32_e32 v0, 0xbfb8aa3b, v135
	v_exp_f32_e32 v0, v0
	v_pk_mul_f32 v[120:121], v[120:121], v[124:125]
	v_add_f32_e32 v0, 1.0, v0
	v_rcp_f32_e32 v127, v0
	v_mul_f32_e32 v0, 0xbfb8aa3b, v131
	v_exp_f32_e32 v0, v0
	v_pk_mul_f32 v[124:125], v[116:117], v[126:127]
	v_add_f32_e32 v0, 1.0, v0
	v_rcp_f32_e32 v116, v0
	v_mul_f32_e32 v0, 0xbfb8aa3b, v136
	v_exp_f32_e32 v0, v0
	s_nop 0
	v_add_f32_e32 v0, 1.0, v0
	v_rcp_f32_e32 v126, v0
	v_mul_f32_e32 v0, 0xbfb8aa3b, v134
	v_exp_f32_e32 v0, v0
	s_nop 0
	v_add_f32_e32 v0, 1.0, v0
	v_rcp_f32_e32 v117, v0
	v_mul_f32_e32 v0, 0xbfb8aa3b, v137
	v_exp_f32_e32 v0, v0
	v_pk_mul_f32 v[122:123], v[122:123], v[116:117]
	v_cvt_pk_bf16_f32 v116, v120, v121
	v_add_f32_e32 v0, 1.0, v0
	v_rcp_f32_e32 v127, v0
	v_cvt_pk_bf16_f32 v117, v122, v123
	v_pk_mul_f32 v[126:127], v[118:119], v[126:127]
	v_cvt_pk_bf16_f32 v118, v124, v125
	v_cvt_pk_bf16_f32 v119, v126, v127
	global_store_dwordx4 v[128:129], v[116:119], off offset:256
	s_nop 1
	v_mad_i64_i32 v[118:119], s[10:11], v162, s18, v[132:133]
	v_lshl_add_u64 v[118:119], v[118:119], 0, v[2:3]
	s_waitcnt vmcnt(11)
; __device__ __forceinline__ float sigmoidf_(float x) { return __builtin_amdgcn_rcpf(1.0f + __expf(-x)); }
; __device__ __forceinline__ void unpack8(const u32x4 w, float* f) { f[0] = bf_lo(w.x); f[1] = bf_hi(w.x); f[2] = bf_lo(w.y); f[3] = bf_hi(w.y); f[4] = bf_lo(w.z); f[5] = bf_hi(w.z); f[6] = bf_lo(w.w); f[7] = bf_hi(w.w); }
; __device__ __forceinline__ u32x4 pack8(const float* f) { u32x4 w; w.x = cvt_pk_bf16(f[0], f[1]); w.y = cvt_pk_bf16(f[2], f[3]); w.z = cvt_pk_bf16(f[4], f[5]); w.w = cvt_pk_bf16(f[6], f[7]); return w; }
;     __device__ __forceinline__ void operator()(const f32x4 (&acc)[2][2][4][2], const Unit& u, int wr, int wc, int fr, int fq) const { if (u.kind == 0) e0(acc, u, wr, wc, fr, fq); else e1(acc, u, wr, wc, fr, fq); }
;     __device__ __forceinline__ void operator()(const f32x4 (&acc)[2][2][4][2], const Unit& u, int wr, int wc, int fr, int fq) const {
;         const int row0 = u.pm * BM + wr * 64 + fr, col0 = u.pn * BM + wc * 32 + 8 * fq;
; #pragma unroll
;         for (int ai = 0; ai < 2; ++ai)
; #pragma unroll
;             for (int m = 0; m < 4; ++m) { const int row = row0 + ai * HALF + m * 16;
; #pragma unroll
;                 for (int bj = 0; bj < 2; ++bj) { const int col = col0 + bj * HALF;
;                     float gf[8], r[8]; unpack8(*(const u32x4*)(gr + (size_t)row * NPROJ + col), gf);
;                     const f32x4 v0 = acc[ai][bj][m][0], v1 = acc[ai][bj][m][1];
; #pragma unroll
;                     for (int j = 0; j < 4; ++j) { r[j] = v0[j] * sigmoidf_(gf[j]); r[4 + j] = v1[j] * sigmoidf_(gf[4 + j]); }
;                     *(u32x4*)(O + (size_t)row * D + col) = pack8(r); } }
;     }
	v_mov_b64_e32 v[120:121], v[194:195]
	v_mov_b64_e32 v[122:123], v[196:197]
	v_lshlrev_b64 v[116:117], 11, v[162:163]
	v_lshlrev_b32_e32 v0, 16, v120
	v_mul_f32_e32 v0, 0xbfb8aa3b, v0
	v_exp_f32_e32 v0, v0
	v_lshlrev_b32_e32 v125, 16, v121
	v_and_b32_e32 v126, 0xffff0000, v121
	v_lshlrev_b32_e32 v121, 16, v122
	v_add_f32_e32 v0, 1.0, v0
	v_and_b32_e32 v124, 0xffff0000, v120
	v_rcp_f32_e32 v120, v0
	v_mul_f32_e32 v0, 0xbfb8aa3b, v121
	v_exp_f32_e32 v0, v0
	v_and_b32_e32 v127, 0xffff0000, v122
	v_lshlrev_b32_e32 v128, 16, v123
	v_and_b32_e32 v129, 0xffff0000, v123
	v_add_f32_e32 v0, 1.0, v0
	v_rcp_f32_e32 v122, v0
	v_mul_f32_e32 v0, 0xbfb8aa3b, v124
	v_exp_f32_e32 v0, v0
	s_nop 0
	v_add_f32_e32 v0, 1.0, v0
	v_rcp_f32_e32 v121, v0
	v_mul_f32_e32 v0, 0xbfb8aa3b, v127
	v_exp_f32_e32 v0, v0
	v_pk_mul_f32 v[112:113], v[112:113], v[120:121]
	v_add_f32_e32 v0, 1.0, v0
	v_rcp_f32_e32 v123, v0
	v_mul_f32_e32 v0, 0xbfb8aa3b, v125
	v_exp_f32_e32 v0, v0
	v_pk_mul_f32 v[120:121], v[108:109], v[122:123]
	v_add_f32_e32 v0, 1.0, v0
	v_rcp_f32_e32 v108, v0
	v_mul_f32_e32 v0, 0xbfb8aa3b, v128
	v_exp_f32_e32 v0, v0
	s_nop 0
	v_add_f32_e32 v0, 1.0, v0
	v_rcp_f32_e32 v122, v0
	v_mul_f32_e32 v0, 0xbfb8aa3b, v126
	v_exp_f32_e32 v0, v0
	s_nop 0
	v_add_f32_e32 v0, 1.0, v0
	v_rcp_f32_e32 v109, v0
	v_mul_f32_e32 v0, 0xbfb8aa3b, v129
	v_exp_f32_e32 v0, v0
	v_pk_mul_f32 v[114:115], v[114:115], v[108:109]
	v_cvt_pk_bf16_f32 v108, v112, v113
	v_add_f32_e32 v0, 1.0, v0
	v_rcp_f32_e32 v123, v0
	v_lshl_add_u64 v[112:113], s[94:95], 0, v[116:117]
	v_cvt_pk_bf16_f32 v109, v114, v115
	v_lshl_add_u64 v[112:113], v[112:113], 0, v[2:3]
	v_pk_mul_f32 v[122:123], v[110:111], v[122:123]
	v_cvt_pk_bf16_f32 v110, v120, v121
	v_cvt_pk_bf16_f32 v111, v122, v123
	global_store_dwordx4 v[112:113], v[108:111], off
	s_waitcnt vmcnt(10)
	v_mov_b64_e32 v[108:109], v[198:199]
	v_mov_b64_e32 v[110:111], v[200:201]
	v_mad_i64_i32 v[230:231], s[98:99], v150, s18, v[132:133]
	v_lshl_add_u64 v[230:231], v[230:231], 0, v[2:3]
	global_load_dwordx4 v[194:197], v[230:231], off
	global_load_dwordx4 v[198:201], v[230:231], off offset:256
	v_lshlrev_b32_e32 v0, 16, v108
	v_mul_f32_e32 v0, 0xbfb8aa3b, v0
	v_exp_f32_e32 v0, v0
	v_lshlrev_b32_e32 v115, 16, v109
	v_and_b32_e32 v116, 0xffff0000, v109
	v_lshlrev_b32_e32 v109, 16, v110
	v_add_f32_e32 v0, 1.0, v0
	v_and_b32_e32 v114, 0xffff0000, v108
	v_rcp_f32_e32 v108, v0
	v_mul_f32_e32 v0, 0xbfb8aa3b, v109
	v_exp_f32_e32 v0, v0
	v_and_b32_e32 v117, 0xffff0000, v110
	v_lshlrev_b32_e32 v118, 16, v111
	v_and_b32_e32 v119, 0xffff0000, v111
	v_add_f32_e32 v0, 1.0, v0
	v_rcp_f32_e32 v110, v0
	v_mul_f32_e32 v0, 0xbfb8aa3b, v114
	v_exp_f32_e32 v0, v0
	s_nop 0
	v_add_f32_e32 v0, 1.0, v0
	v_rcp_f32_e32 v109, v0
	v_mul_f32_e32 v0, 0xbfb8aa3b, v117
	v_exp_f32_e32 v0, v0
	v_pk_mul_f32 v[104:105], v[104:105], v[108:109]
	v_add_f32_e32 v0, 1.0, v0
	v_rcp_f32_e32 v111, v0
	v_mul_f32_e32 v0, 0xbfb8aa3b, v115
	v_exp_f32_e32 v0, v0
	v_pk_mul_f32 v[108:109], v[100:101], v[110:111]
	v_add_f32_e32 v0, 1.0, v0
	v_rcp_f32_e32 v100, v0
	v_mul_f32_e32 v0, 0xbfb8aa3b, v118
	v_exp_f32_e32 v0, v0
	s_nop 0
	v_add_f32_e32 v0, 1.0, v0
	v_rcp_f32_e32 v110, v0
	v_mul_f32_e32 v0, 0xbfb8aa3b, v116
	v_exp_f32_e32 v0, v0
	s_nop 0
	v_add_f32_e32 v0, 1.0, v0
	v_rcp_f32_e32 v101, v0
	v_mul_f32_e32 v0, 0xbfb8aa3b, v119
	v_exp_f32_e32 v0, v0
	v_pk_mul_f32 v[106:107], v[106:107], v[100:101]
	v_cvt_pk_bf16_f32 v100, v104, v105
	v_add_f32_e32 v0, 1.0, v0
	v_rcp_f32_e32 v111, v0
	v_cvt_pk_bf16_f32 v101, v106, v107
	v_pk_mul_f32 v[110:111], v[102:103], v[110:111]
	v_cvt_pk_bf16_f32 v102, v108, v109
	v_cvt_pk_bf16_f32 v103, v110, v111
	global_store_dwordx4 v[112:113], v[100:103], off offset:256
	s_nop 1
	v_mad_i64_i32 v[102:103], s[10:11], v160, s18, v[132:133]
	v_lshl_add_u64 v[102:103], v[102:103], 0, v[2:3]
	s_waitcnt vmcnt(11)
	v_mov_b64_e32 v[104:105], v[202:203]
	v_mov_b64_e32 v[106:107], v[204:205]
	v_lshlrev_b64 v[100:101], 11, v[160:161]
	v_lshlrev_b32_e32 v0, 16, v104
	v_mul_f32_e32 v0, 0xbfb8aa3b, v0
	v_exp_f32_e32 v0, v0
	v_lshlrev_b32_e32 v109, 16, v105
	v_and_b32_e32 v110, 0xffff0000, v105
	v_lshlrev_b32_e32 v105, 16, v106
	v_add_f32_e32 v0, 1.0, v0
	v_and_b32_e32 v108, 0xffff0000, v104
	v_rcp_f32_e32 v104, v0
	v_mul_f32_e32 v0, 0xbfb8aa3b, v105
	v_exp_f32_e32 v0, v0
	v_and_b32_e32 v111, 0xffff0000, v106
	v_lshlrev_b32_e32 v112, 16, v107
	v_and_b32_e32 v113, 0xffff0000, v107
	v_add_f32_e32 v0, 1.0, v0
	v_rcp_f32_e32 v106, v0
	v_mul_f32_e32 v0, 0xbfb8aa3b, v108
	v_exp_f32_e32 v0, v0
	s_nop 0
	v_add_f32_e32 v0, 1.0, v0
	v_rcp_f32_e32 v105, v0
	v_mul_f32_e32 v0, 0xbfb8aa3b, v111
	v_exp_f32_e32 v0, v0
	v_pk_mul_f32 v[96:97], v[96:97], v[104:105]
	v_add_f32_e32 v0, 1.0, v0
	v_rcp_f32_e32 v107, v0
	v_mul_f32_e32 v0, 0xbfb8aa3b, v109
	v_exp_f32_e32 v0, v0
	v_pk_mul_f32 v[104:105], v[92:93], v[106:107]
	v_add_f32_e32 v0, 1.0, v0
	v_rcp_f32_e32 v92, v0
	v_mul_f32_e32 v0, 0xbfb8aa3b, v112
	v_exp_f32_e32 v0, v0
	s_nop 0
	v_add_f32_e32 v0, 1.0, v0
	v_rcp_f32_e32 v106, v0
	v_mul_f32_e32 v0, 0xbfb8aa3b, v110
	v_exp_f32_e32 v0, v0
	s_nop 0
	v_add_f32_e32 v0, 1.0, v0
	v_rcp_f32_e32 v93, v0
	v_mul_f32_e32 v0, 0xbfb8aa3b, v113
	v_exp_f32_e32 v0, v0
	v_pk_mul_f32 v[98:99], v[98:99], v[92:93]
	v_cvt_pk_bf16_f32 v92, v96, v97
	v_add_f32_e32 v0, 1.0, v0
	v_rcp_f32_e32 v107, v0
	v_lshl_add_u64 v[96:97], s[94:95], 0, v[100:101]
	v_cvt_pk_bf16_f32 v93, v98, v99
	v_lshl_add_u64 v[96:97], v[96:97], 0, v[2:3]
	v_pk_mul_f32 v[106:107], v[94:95], v[106:107]
	v_cvt_pk_bf16_f32 v94, v104, v105
	v_cvt_pk_bf16_f32 v95, v106, v107
	global_store_dwordx4 v[96:97], v[92:95], off
	s_waitcnt vmcnt(10)
; __device__ __forceinline__ float sigmoidf_(float x) { return __builtin_amdgcn_rcpf(1.0f + __expf(-x)); }
; __device__ __forceinline__ void unpack8(const u32x4 w, float* f) { f[0] = bf_lo(w.x); f[1] = bf_hi(w.x); f[2] = bf_lo(w.y); f[3] = bf_hi(w.y); f[4] = bf_lo(w.z); f[5] = bf_hi(w.z); f[6] = bf_lo(w.w); f[7] = bf_hi(w.w); }
; __device__ __forceinline__ u32x4 pack8(const float* f) { u32x4 w; w.x = cvt_pk_bf16(f[0], f[1]); w.y = cvt_pk_bf16(f[2], f[3]); w.z = cvt_pk_bf16(f[4], f[5]); w.w = cvt_pk_bf16(f[6], f[7]); return w; }
;     __device__ __forceinline__ void operator()(const f32x4 (&acc)[2][2][4][2], const Unit& u, int wr, int wc, int fr, int fq) const { if (u.kind == 0) e0(acc, u, wr, wc, fr, fq); else e1(acc, u, wr, wc, fr, fq); }
;     __device__ __forceinline__ void operator()(const f32x4 (&acc)[2][2][4][2], const Unit& u, int wr, int wc, int fr, int fq) const {
;         const int row0 = u.pm * BM + wr * 64 + fr, col0 = u.pn * BM + wc * 32 + 8 * fq;
; #pragma unroll
;         for (int ai = 0; ai < 2; ++ai)
; #pragma unroll
;             for (int m = 0; m < 4; ++m) { const int row = row0 + ai * HALF + m * 16;
; #pragma unroll
;                 for (int bj = 0; bj < 2; ++bj) { const int col = col0 + bj * HALF;
;                     float gf[8], r[8]; unpack8(*(const u32x4*)(gr + (size_t)row * NPROJ + col), gf);
;                     const f32x4 v0 = acc[ai][bj][m][0], v1 = acc[ai][bj][m][1];
; #pragma unroll
;                     for (int j = 0; j < 4; ++j) { r[j] = v0[j] * sigmoidf_(gf[j]); r[4 + j] = v1[j] * sigmoidf_(gf[4 + j]); }
;                     *(u32x4*)(O + (size_t)row * D + col) = pack8(r); } }
;     }
	v_mov_b64_e32 v[92:93], v[206:207]
	v_mov_b64_e32 v[94:95], v[208:209]
	v_lshlrev_b32_e32 v0, 16, v92
	v_mul_f32_e32 v0, 0xbfb8aa3b, v0
	v_exp_f32_e32 v0, v0
	v_lshlrev_b32_e32 v99, 16, v93
	v_and_b32_e32 v100, 0xffff0000, v93
	v_lshlrev_b32_e32 v93, 16, v94
	v_add_f32_e32 v0, 1.0, v0
	v_and_b32_e32 v98, 0xffff0000, v92
	v_rcp_f32_e32 v92, v0
	v_mul_f32_e32 v0, 0xbfb8aa3b, v93
	v_exp_f32_e32 v0, v0
	v_and_b32_e32 v101, 0xffff0000, v94
	v_lshlrev_b32_e32 v102, 16, v95
	v_and_b32_e32 v103, 0xffff0000, v95
	v_add_f32_e32 v0, 1.0, v0
	v_rcp_f32_e32 v94, v0
	v_mul_f32_e32 v0, 0xbfb8aa3b, v98
	v_exp_f32_e32 v0, v0
	s_nop 0
	v_add_f32_e32 v0, 1.0, v0
	v_rcp_f32_e32 v93, v0
	v_mul_f32_e32 v0, 0xbfb8aa3b, v101
	v_exp_f32_e32 v0, v0
	v_pk_mul_f32 v[88:89], v[88:89], v[92:93]
	v_add_f32_e32 v0, 1.0, v0
	v_rcp_f32_e32 v95, v0
	v_mul_f32_e32 v0, 0xbfb8aa3b, v99
	v_exp_f32_e32 v0, v0
	v_pk_mul_f32 v[92:93], v[84:85], v[94:95]
	v_add_f32_e32 v0, 1.0, v0
	v_rcp_f32_e32 v84, v0
	v_mul_f32_e32 v0, 0xbfb8aa3b, v102
	v_exp_f32_e32 v0, v0
	s_nop 0
	v_add_f32_e32 v0, 1.0, v0
	v_rcp_f32_e32 v94, v0
	v_mul_f32_e32 v0, 0xbfb8aa3b, v100
	v_exp_f32_e32 v0, v0
	s_nop 0
	v_add_f32_e32 v0, 1.0, v0
	v_rcp_f32_e32 v85, v0
	v_mul_f32_e32 v0, 0xbfb8aa3b, v103
	v_exp_f32_e32 v0, v0
	v_pk_mul_f32 v[90:91], v[90:91], v[84:85]
	v_cvt_pk_bf16_f32 v84, v88, v89
	v_add_f32_e32 v0, 1.0, v0
	v_rcp_f32_e32 v95, v0
	v_cvt_pk_bf16_f32 v85, v90, v91
	v_pk_mul_f32 v[94:95], v[86:87], v[94:95]
	v_cvt_pk_bf16_f32 v86, v92, v93
	v_cvt_pk_bf16_f32 v87, v94, v95
	global_store_dwordx4 v[96:97], v[84:87], off offset:256
	s_nop 1
	v_mad_i64_i32 v[86:87], s[10:11], v158, s18, v[132:133]
	v_lshl_add_u64 v[86:87], v[86:87], 0, v[2:3]
	s_waitcnt vmcnt(9)
	v_mov_b64_e32 v[88:89], v[210:211]
	v_mov_b64_e32 v[90:91], v[212:213]
	v_lshlrev_b64 v[84:85], 11, v[158:159]
	v_lshlrev_b32_e32 v0, 16, v88
	v_mul_f32_e32 v0, 0xbfb8aa3b, v0
	v_exp_f32_e32 v0, v0
	v_lshlrev_b32_e32 v93, 16, v89
	v_and_b32_e32 v94, 0xffff0000, v89
	v_lshlrev_b32_e32 v89, 16, v90
	v_add_f32_e32 v0, 1.0, v0
	v_and_b32_e32 v92, 0xffff0000, v88
	v_rcp_f32_e32 v88, v0
	v_mul_f32_e32 v0, 0xbfb8aa3b, v89
	v_exp_f32_e32 v0, v0
	v_and_b32_e32 v95, 0xffff0000, v90
	v_lshlrev_b32_e32 v96, 16, v91
	v_and_b32_e32 v97, 0xffff0000, v91
	v_add_f32_e32 v0, 1.0, v0
	v_rcp_f32_e32 v90, v0
	v_mul_f32_e32 v0, 0xbfb8aa3b, v92
	v_exp_f32_e32 v0, v0
	s_nop 0
	v_add_f32_e32 v0, 1.0, v0
	v_rcp_f32_e32 v89, v0
	v_mul_f32_e32 v0, 0xbfb8aa3b, v95
	v_exp_f32_e32 v0, v0
	v_pk_mul_f32 v[80:81], v[80:81], v[88:89]
	v_add_f32_e32 v0, 1.0, v0
	v_rcp_f32_e32 v91, v0
	v_mul_f32_e32 v0, 0xbfb8aa3b, v93
	v_exp_f32_e32 v0, v0
	v_pk_mul_f32 v[88:89], v[76:77], v[90:91]
	v_add_f32_e32 v0, 1.0, v0
	v_rcp_f32_e32 v76, v0
	v_mul_f32_e32 v0, 0xbfb8aa3b, v96
	v_exp_f32_e32 v0, v0
	s_nop 0
	v_add_f32_e32 v0, 1.0, v0
	v_rcp_f32_e32 v90, v0
	v_mul_f32_e32 v0, 0xbfb8aa3b, v94
	v_exp_f32_e32 v0, v0
	s_nop 0
	v_add_f32_e32 v0, 1.0, v0
	v_rcp_f32_e32 v77, v0
	v_mul_f32_e32 v0, 0xbfb8aa3b, v97
	v_exp_f32_e32 v0, v0
	v_pk_mul_f32 v[82:83], v[82:83], v[76:77]
	v_cvt_pk_bf16_f32 v76, v80, v81
	v_add_f32_e32 v0, 1.0, v0
	v_rcp_f32_e32 v91, v0
	v_lshl_add_u64 v[80:81], s[94:95], 0, v[84:85]
	v_cvt_pk_bf16_f32 v77, v82, v83
	v_lshl_add_u64 v[80:81], v[80:81], 0, v[2:3]
	v_pk_mul_f32 v[90:91], v[78:79], v[90:91]
	v_cvt_pk_bf16_f32 v78, v88, v89
	v_cvt_pk_bf16_f32 v79, v90, v91
	global_store_dwordx4 v[80:81], v[76:79], off
	s_waitcnt vmcnt(8)
	v_mov_b64_e32 v[76:77], v[214:215]
	v_mov_b64_e32 v[78:79], v[216:217]
	v_lshlrev_b32_e32 v0, 16, v76
	v_mul_f32_e32 v0, 0xbfb8aa3b, v0
	v_exp_f32_e32 v0, v0
	v_lshlrev_b32_e32 v83, 16, v77
	v_and_b32_e32 v84, 0xffff0000, v77
	v_lshlrev_b32_e32 v77, 16, v78
	v_add_f32_e32 v0, 1.0, v0
	v_and_b32_e32 v82, 0xffff0000, v76
	v_rcp_f32_e32 v76, v0
	v_mul_f32_e32 v0, 0xbfb8aa3b, v77
	v_exp_f32_e32 v0, v0
	v_and_b32_e32 v85, 0xffff0000, v78
	v_lshlrev_b32_e32 v86, 16, v79
	v_and_b32_e32 v87, 0xffff0000, v79
	v_add_f32_e32 v0, 1.0, v0
	v_rcp_f32_e32 v78, v0
	v_mul_f32_e32 v0, 0xbfb8aa3b, v82
	v_exp_f32_e32 v0, v0
	s_nop 0
	v_add_f32_e32 v0, 1.0, v0
	v_rcp_f32_e32 v77, v0
	v_mul_f32_e32 v0, 0xbfb8aa3b, v85
	v_exp_f32_e32 v0, v0
	v_pk_mul_f32 v[72:73], v[72:73], v[76:77]
	v_add_f32_e32 v0, 1.0, v0
	v_rcp_f32_e32 v79, v0
	v_mul_f32_e32 v0, 0xbfb8aa3b, v83
	v_exp_f32_e32 v0, v0
	v_pk_mul_f32 v[76:77], v[68:69], v[78:79]
	v_add_f32_e32 v0, 1.0, v0
	v_rcp_f32_e32 v68, v0
	v_mul_f32_e32 v0, 0xbfb8aa3b, v86
	v_exp_f32_e32 v0, v0
	s_nop 0
	v_add_f32_e32 v0, 1.0, v0
	v_rcp_f32_e32 v78, v0
	v_mul_f32_e32 v0, 0xbfb8aa3b, v84
	v_exp_f32_e32 v0, v0
	s_nop 0
	v_add_f32_e32 v0, 1.0, v0
	v_rcp_f32_e32 v69, v0
	v_mul_f32_e32 v0, 0xbfb8aa3b, v87
	v_exp_f32_e32 v0, v0
	v_pk_mul_f32 v[74:75], v[74:75], v[68:69]
	v_cvt_pk_bf16_f32 v68, v72, v73
	v_add_f32_e32 v0, 1.0, v0
	v_rcp_f32_e32 v79, v0
	v_cvt_pk_bf16_f32 v69, v74, v75
	v_pk_mul_f32 v[78:79], v[70:71], v[78:79]
	v_cvt_pk_bf16_f32 v70, v76, v77
	v_cvt_pk_bf16_f32 v71, v78, v79
	global_store_dwordx4 v[80:81], v[68:71], off offset:256
	s_nop 1
	v_mad_i64_i32 v[70:71], s[10:11], v156, s18, v[132:133]
	v_lshl_add_u64 v[70:71], v[70:71], 0, v[2:3]
	s_waitcnt vmcnt(7)
; __device__ __forceinline__ float sigmoidf_(float x) { return __builtin_amdgcn_rcpf(1.0f + __expf(-x)); }
; __device__ __forceinline__ void unpack8(const u32x4 w, float* f) { f[0] = bf_lo(w.x); f[1] = bf_hi(w.x); f[2] = bf_lo(w.y); f[3] = bf_hi(w.y); f[4] = bf_lo(w.z); f[5] = bf_hi(w.z); f[6] = bf_lo(w.w); f[7] = bf_hi(w.w); }
; __device__ __forceinline__ u32x4 pack8(const float* f) { u32x4 w; w.x = cvt_pk_bf16(f[0], f[1]); w.y = cvt_pk_bf16(f[2], f[3]); w.z = cvt_pk_bf16(f[4], f[5]); w.w = cvt_pk_bf16(f[6], f[7]); return w; }
;     __device__ __forceinline__ void operator()(const f32x4 (&acc)[2][2][4][2], const Unit& u, int wr, int wc, int fr, int fq) const { if (u.kind == 0) e0(acc, u, wr, wc, fr, fq); else e1(acc, u, wr, wc, fr, fq); }
;     __device__ __forceinline__ void operator()(const f32x4 (&acc)[2][2][4][2], const Unit& u, int wr, int wc, int fr, int fq) const {
;         const int row0 = u.pm * BM + wr * 64 + fr, col0 = u.pn * BM + wc * 32 + 8 * fq;
; #pragma unroll
;         for (int ai = 0; ai < 2; ++ai)
; #pragma unroll
;             for (int m = 0; m < 4; ++m) { const int row = row0 + ai * HALF + m * 16;
; #pragma unroll
;                 for (int bj = 0; bj < 2; ++bj) { const int col = col0 + bj * HALF;
;                     float gf[8], r[8]; unpack8(*(const u32x4*)(gr + (size_t)row * NPROJ + col), gf);
;                     const f32x4 v0 = acc[ai][bj][m][0], v1 = acc[ai][bj][m][1];
; #pragma unroll
;                     for (int j = 0; j < 4; ++j) { r[j] = v0[j] * sigmoidf_(gf[j]); r[4 + j] = v1[j] * sigmoidf_(gf[4 + j]); }
;                     *(u32x4*)(O + (size_t)row * D + col) = pack8(r); } }
;     }
	v_mov_b64_e32 v[72:73], v[218:219]
	v_mov_b64_e32 v[74:75], v[220:221]
	v_lshlrev_b64 v[68:69], 11, v[156:157]
	v_lshlrev_b32_e32 v0, 16, v72
	v_mul_f32_e32 v0, 0xbfb8aa3b, v0
	v_exp_f32_e32 v0, v0
	v_lshlrev_b32_e32 v77, 16, v73
	v_and_b32_e32 v78, 0xffff0000, v73
	v_lshlrev_b32_e32 v73, 16, v74
	v_add_f32_e32 v0, 1.0, v0
	v_and_b32_e32 v76, 0xffff0000, v72
	v_rcp_f32_e32 v72, v0
	v_mul_f32_e32 v0, 0xbfb8aa3b, v73
	v_exp_f32_e32 v0, v0
	v_and_b32_e32 v79, 0xffff0000, v74
	v_lshlrev_b32_e32 v80, 16, v75
	v_and_b32_e32 v81, 0xffff0000, v75
	v_add_f32_e32 v0, 1.0, v0
	v_rcp_f32_e32 v74, v0
	v_mul_f32_e32 v0, 0xbfb8aa3b, v76
	v_exp_f32_e32 v0, v0
	s_nop 0
	v_add_f32_e32 v0, 1.0, v0
	v_rcp_f32_e32 v73, v0
	v_mul_f32_e32 v0, 0xbfb8aa3b, v79
	v_exp_f32_e32 v0, v0
	v_pk_mul_f32 v[64:65], v[64:65], v[72:73]
	v_add_f32_e32 v0, 1.0, v0
	v_rcp_f32_e32 v75, v0
	v_mul_f32_e32 v0, 0xbfb8aa3b, v77
	v_exp_f32_e32 v0, v0
	v_pk_mul_f32 v[72:73], v[60:61], v[74:75]
	v_add_f32_e32 v0, 1.0, v0
	v_rcp_f32_e32 v60, v0
	v_mul_f32_e32 v0, 0xbfb8aa3b, v80
	v_exp_f32_e32 v0, v0
	s_nop 0
	v_add_f32_e32 v0, 1.0, v0
	v_rcp_f32_e32 v74, v0
	v_mul_f32_e32 v0, 0xbfb8aa3b, v78
	v_exp_f32_e32 v0, v0
	s_nop 0
	v_add_f32_e32 v0, 1.0, v0
	v_rcp_f32_e32 v61, v0
	v_mul_f32_e32 v0, 0xbfb8aa3b, v81
	v_exp_f32_e32 v0, v0
	v_pk_mul_f32 v[66:67], v[66:67], v[60:61]
	v_cvt_pk_bf16_f32 v60, v64, v65
	v_add_f32_e32 v0, 1.0, v0
	v_rcp_f32_e32 v75, v0
	v_lshl_add_u64 v[64:65], s[94:95], 0, v[68:69]
	v_cvt_pk_bf16_f32 v61, v66, v67
	v_lshl_add_u64 v[64:65], v[64:65], 0, v[2:3]
	v_pk_mul_f32 v[74:75], v[62:63], v[74:75]
	v_cvt_pk_bf16_f32 v62, v72, v73
	v_cvt_pk_bf16_f32 v63, v74, v75
	global_store_dwordx4 v[64:65], v[60:63], off
	s_waitcnt vmcnt(6)
	v_mov_b64_e32 v[60:61], v[222:223]
	v_mov_b64_e32 v[62:63], v[224:225]
	v_lshlrev_b32_e32 v0, 16, v60
	v_mul_f32_e32 v0, 0xbfb8aa3b, v0
	v_exp_f32_e32 v0, v0
	v_lshlrev_b32_e32 v67, 16, v61
	v_and_b32_e32 v68, 0xffff0000, v61
	v_lshlrev_b32_e32 v61, 16, v62
	v_add_f32_e32 v0, 1.0, v0
	v_and_b32_e32 v66, 0xffff0000, v60
	v_rcp_f32_e32 v60, v0
	v_mul_f32_e32 v0, 0xbfb8aa3b, v61
	v_exp_f32_e32 v0, v0
	v_and_b32_e32 v69, 0xffff0000, v62
	v_lshlrev_b32_e32 v70, 16, v63
	v_and_b32_e32 v71, 0xffff0000, v63
	v_add_f32_e32 v0, 1.0, v0
	v_rcp_f32_e32 v62, v0
	v_mul_f32_e32 v0, 0xbfb8aa3b, v66
	v_exp_f32_e32 v0, v0
	s_nop 0
	v_add_f32_e32 v0, 1.0, v0
	v_rcp_f32_e32 v61, v0
	v_mul_f32_e32 v0, 0xbfb8aa3b, v69
	v_exp_f32_e32 v0, v0
	v_pk_mul_f32 v[56:57], v[56:57], v[60:61]
	v_add_f32_e32 v0, 1.0, v0
	v_rcp_f32_e32 v63, v0
	v_mul_f32_e32 v0, 0xbfb8aa3b, v67
	v_exp_f32_e32 v0, v0
	v_pk_mul_f32 v[60:61], v[52:53], v[62:63]
	v_add_f32_e32 v0, 1.0, v0
	v_rcp_f32_e32 v52, v0
	v_mul_f32_e32 v0, 0xbfb8aa3b, v70
	v_exp_f32_e32 v0, v0
	s_nop 0
	v_add_f32_e32 v0, 1.0, v0
	v_rcp_f32_e32 v62, v0
	v_mul_f32_e32 v0, 0xbfb8aa3b, v68
	v_exp_f32_e32 v0, v0
	s_nop 0
	v_add_f32_e32 v0, 1.0, v0
	v_rcp_f32_e32 v53, v0
	v_mul_f32_e32 v0, 0xbfb8aa3b, v71
	v_exp_f32_e32 v0, v0
	v_pk_mul_f32 v[58:59], v[58:59], v[52:53]
	v_cvt_pk_bf16_f32 v52, v56, v57
	v_add_f32_e32 v0, 1.0, v0
	v_rcp_f32_e32 v63, v0
	v_cvt_pk_bf16_f32 v53, v58, v59
	v_pk_mul_f32 v[62:63], v[54:55], v[62:63]
	v_cvt_pk_bf16_f32 v54, v60, v61
	v_cvt_pk_bf16_f32 v55, v62, v63
	global_store_dwordx4 v[64:65], v[52:55], off offset:256
	s_nop 1
	v_mad_i64_i32 v[54:55], s[10:11], v154, s18, v[132:133]
	v_lshl_add_u64 v[54:55], v[54:55], 0, v[2:3]
	s_waitcnt vmcnt(5)
	v_mov_b64_e32 v[56:57], v[226:227]
	v_mov_b64_e32 v[58:59], v[228:229]
	v_lshlrev_b64 v[52:53], 11, v[154:155]
	v_lshlrev_b32_e32 v0, 16, v56
	v_mul_f32_e32 v0, 0xbfb8aa3b, v0
	v_exp_f32_e32 v0, v0
	v_lshlrev_b32_e32 v61, 16, v57
	v_and_b32_e32 v62, 0xffff0000, v57
	v_lshlrev_b32_e32 v57, 16, v58
	v_add_f32_e32 v0, 1.0, v0
	v_and_b32_e32 v60, 0xffff0000, v56
	v_rcp_f32_e32 v56, v0
	v_mul_f32_e32 v0, 0xbfb8aa3b, v57
	v_exp_f32_e32 v0, v0
	v_and_b32_e32 v63, 0xffff0000, v58
	v_lshlrev_b32_e32 v64, 16, v59
	v_and_b32_e32 v65, 0xffff0000, v59
	v_add_f32_e32 v0, 1.0, v0
	v_rcp_f32_e32 v58, v0
	v_mul_f32_e32 v0, 0xbfb8aa3b, v60
	v_exp_f32_e32 v0, v0
	s_nop 0
	v_add_f32_e32 v0, 1.0, v0
	v_rcp_f32_e32 v57, v0
	v_mul_f32_e32 v0, 0xbfb8aa3b, v63
	v_exp_f32_e32 v0, v0
	v_pk_mul_f32 v[48:49], v[48:49], v[56:57]
	v_add_f32_e32 v0, 1.0, v0
	v_rcp_f32_e32 v59, v0
	v_mul_f32_e32 v0, 0xbfb8aa3b, v61
	v_exp_f32_e32 v0, v0
	v_pk_mul_f32 v[56:57], v[44:45], v[58:59]
	v_add_f32_e32 v0, 1.0, v0
	v_rcp_f32_e32 v44, v0
	v_mul_f32_e32 v0, 0xbfb8aa3b, v64
	v_exp_f32_e32 v0, v0
	s_nop 0
	v_add_f32_e32 v0, 1.0, v0
	v_rcp_f32_e32 v58, v0
	v_mul_f32_e32 v0, 0xbfb8aa3b, v62
	v_exp_f32_e32 v0, v0
	s_nop 0
	v_add_f32_e32 v0, 1.0, v0
	v_rcp_f32_e32 v45, v0
	v_mul_f32_e32 v0, 0xbfb8aa3b, v65
	v_exp_f32_e32 v0, v0
	v_pk_mul_f32 v[50:51], v[50:51], v[44:45]
	v_cvt_pk_bf16_f32 v44, v48, v49
	v_add_f32_e32 v0, 1.0, v0
	v_rcp_f32_e32 v59, v0
	v_lshl_add_u64 v[48:49], s[94:95], 0, v[52:53]
	v_cvt_pk_bf16_f32 v45, v50, v51
	v_lshl_add_u64 v[48:49], v[48:49], 0, v[2:3]
	v_pk_mul_f32 v[58:59], v[46:47], v[58:59]
	v_cvt_pk_bf16_f32 v46, v56, v57
	v_cvt_pk_bf16_f32 v47, v58, v59
	global_store_dwordx4 v[48:49], v[44:47], off
	s_waitcnt vmcnt(4)
; __device__ __forceinline__ float sigmoidf_(float x) { return __builtin_amdgcn_rcpf(1.0f + __expf(-x)); }
; __device__ __forceinline__ void unpack8(const u32x4 w, float* f) { f[0] = bf_lo(w.x); f[1] = bf_hi(w.x); f[2] = bf_lo(w.y); f[3] = bf_hi(w.y); f[4] = bf_lo(w.z); f[5] = bf_hi(w.z); f[6] = bf_lo(w.w); f[7] = bf_hi(w.w); }
; __device__ __forceinline__ u32x4 pack8(const float* f) { u32x4 w; w.x = cvt_pk_bf16(f[0], f[1]); w.y = cvt_pk_bf16(f[2], f[3]); w.z = cvt_pk_bf16(f[4], f[5]); w.w = cvt_pk_bf16(f[6], f[7]); return w; }
;     __device__ __forceinline__ void operator()(const f32x4 (&acc)[2][2][4][2], const Unit& u, int wr, int wc, int fr, int fq) const { if (u.kind == 0) e0(acc, u, wr, wc, fr, fq); else e1(acc, u, wr, wc, fr, fq); }
;     __device__ __forceinline__ void operator()(const f32x4 (&acc)[2][2][4][2], const Unit& u, int wr, int wc, int fr, int fq) const {
;         const int row0 = u.pm * BM + wr * 64 + fr, col0 = u.pn * BM + wc * 32 + 8 * fq;
; #pragma unroll
;         for (int ai = 0; ai < 2; ++ai)
; #pragma unroll
;             for (int m = 0; m < 4; ++m) { const int row = row0 + ai * HALF + m * 16;
; #pragma unroll
;                 for (int bj = 0; bj < 2; ++bj) { const int col = col0 + bj * HALF;
;                     float gf[8], r[8]; unpack8(*(const u32x4*)(gr + (size_t)row * NPROJ + col), gf);
;                     const f32x4 v0 = acc[ai][bj][m][0], v1 = acc[ai][bj][m][1];
; #pragma unroll
;                     for (int j = 0; j < 4; ++j) { r[j] = v0[j] * sigmoidf_(gf[j]); r[4 + j] = v1[j] * sigmoidf_(gf[4 + j]); }
;                     *(u32x4*)(O + (size_t)row * D + col) = pack8(r); } }
;     }
	v_mov_b64_e32 v[44:45], v[236:237]
	v_mov_b64_e32 v[46:47], v[238:239]
	v_lshlrev_b32_e32 v0, 16, v44
	v_mul_f32_e32 v0, 0xbfb8aa3b, v0
	v_exp_f32_e32 v0, v0
	v_lshlrev_b32_e32 v51, 16, v45
	v_and_b32_e32 v52, 0xffff0000, v45
	v_lshlrev_b32_e32 v45, 16, v46
	v_add_f32_e32 v0, 1.0, v0
	v_and_b32_e32 v50, 0xffff0000, v44
	v_rcp_f32_e32 v44, v0
	v_mul_f32_e32 v0, 0xbfb8aa3b, v45
	v_exp_f32_e32 v0, v0
	v_and_b32_e32 v53, 0xffff0000, v46
	v_lshlrev_b32_e32 v54, 16, v47
	v_and_b32_e32 v55, 0xffff0000, v47
	v_add_f32_e32 v0, 1.0, v0
	v_rcp_f32_e32 v46, v0
	v_mul_f32_e32 v0, 0xbfb8aa3b, v50
	v_exp_f32_e32 v0, v0
	s_nop 0
	v_add_f32_e32 v0, 1.0, v0
	v_rcp_f32_e32 v45, v0
	v_mul_f32_e32 v0, 0xbfb8aa3b, v53
	v_exp_f32_e32 v0, v0
	v_pk_mul_f32 v[40:41], v[40:41], v[44:45]
	v_add_f32_e32 v0, 1.0, v0
	v_rcp_f32_e32 v47, v0
	v_mul_f32_e32 v0, 0xbfb8aa3b, v51
	v_exp_f32_e32 v0, v0
	v_pk_mul_f32 v[44:45], v[36:37], v[46:47]
	v_add_f32_e32 v0, 1.0, v0
	v_rcp_f32_e32 v36, v0
	v_mul_f32_e32 v0, 0xbfb8aa3b, v54
	v_exp_f32_e32 v0, v0
	s_nop 0
	v_add_f32_e32 v0, 1.0, v0
	v_rcp_f32_e32 v46, v0
	v_mul_f32_e32 v0, 0xbfb8aa3b, v52
	v_exp_f32_e32 v0, v0
	s_nop 0
	v_add_f32_e32 v0, 1.0, v0
	v_rcp_f32_e32 v37, v0
	v_mul_f32_e32 v0, 0xbfb8aa3b, v55
	v_exp_f32_e32 v0, v0
	v_pk_mul_f32 v[42:43], v[42:43], v[36:37]
	v_cvt_pk_bf16_f32 v36, v40, v41
	v_add_f32_e32 v0, 1.0, v0
	v_rcp_f32_e32 v47, v0
	v_cvt_pk_bf16_f32 v37, v42, v43
	v_pk_mul_f32 v[46:47], v[38:39], v[46:47]
	v_cvt_pk_bf16_f32 v38, v44, v45
	v_cvt_pk_bf16_f32 v39, v46, v47
	global_store_dwordx4 v[48:49], v[36:39], off offset:256
	s_nop 1
	v_mad_i64_i32 v[38:39], s[10:11], v152, s18, v[132:133]
	v_lshl_add_u64 v[38:39], v[38:39], 0, v[2:3]
	s_waitcnt vmcnt(3)
	v_mov_b64_e32 v[40:41], v[168:169]
	v_mov_b64_e32 v[42:43], v[170:171]
	v_lshlrev_b64 v[36:37], 11, v[152:153]
	v_lshlrev_b32_e32 v0, 16, v40
	v_mul_f32_e32 v0, 0xbfb8aa3b, v0
	v_exp_f32_e32 v0, v0
	v_lshlrev_b32_e32 v45, 16, v41
	v_and_b32_e32 v46, 0xffff0000, v41
	v_lshlrev_b32_e32 v41, 16, v42
	v_add_f32_e32 v0, 1.0, v0
	v_and_b32_e32 v44, 0xffff0000, v40
	v_rcp_f32_e32 v40, v0
	v_mul_f32_e32 v0, 0xbfb8aa3b, v41
	v_exp_f32_e32 v0, v0
	v_and_b32_e32 v47, 0xffff0000, v42
	v_lshlrev_b32_e32 v48, 16, v43
	v_and_b32_e32 v49, 0xffff0000, v43
	v_add_f32_e32 v0, 1.0, v0
	v_rcp_f32_e32 v42, v0
	v_mul_f32_e32 v0, 0xbfb8aa3b, v44
	v_exp_f32_e32 v0, v0
	s_nop 0
	v_add_f32_e32 v0, 1.0, v0
	v_rcp_f32_e32 v41, v0
	v_mul_f32_e32 v0, 0xbfb8aa3b, v47
	v_exp_f32_e32 v0, v0
	v_pk_mul_f32 v[32:33], v[32:33], v[40:41]
	v_add_f32_e32 v0, 1.0, v0
	v_rcp_f32_e32 v43, v0
	v_mul_f32_e32 v0, 0xbfb8aa3b, v45
	v_exp_f32_e32 v0, v0
	v_pk_mul_f32 v[40:41], v[28:29], v[42:43]
	v_add_f32_e32 v0, 1.0, v0
	v_rcp_f32_e32 v28, v0
	v_mul_f32_e32 v0, 0xbfb8aa3b, v48
	v_exp_f32_e32 v0, v0
	s_nop 0
	v_add_f32_e32 v0, 1.0, v0
	v_rcp_f32_e32 v42, v0
	v_mul_f32_e32 v0, 0xbfb8aa3b, v46
	v_exp_f32_e32 v0, v0
	s_nop 0
	v_add_f32_e32 v0, 1.0, v0
	v_rcp_f32_e32 v29, v0
	v_mul_f32_e32 v0, 0xbfb8aa3b, v49
	v_exp_f32_e32 v0, v0
	v_pk_mul_f32 v[34:35], v[34:35], v[28:29]
	v_cvt_pk_bf16_f32 v28, v32, v33
	v_add_f32_e32 v0, 1.0, v0
	v_rcp_f32_e32 v43, v0
	v_lshl_add_u64 v[32:33], s[94:95], 0, v[36:37]
	v_cvt_pk_bf16_f32 v29, v34, v35
	v_lshl_add_u64 v[32:33], v[32:33], 0, v[2:3]
	v_pk_mul_f32 v[42:43], v[30:31], v[42:43]
	v_cvt_pk_bf16_f32 v30, v40, v41
	v_cvt_pk_bf16_f32 v31, v42, v43
	global_store_dwordx4 v[32:33], v[28:31], off
	s_waitcnt vmcnt(2)
; __device__ __forceinline__ float sigmoidf_(float x) { return __builtin_amdgcn_rcpf(1.0f + __expf(-x)); }
; __device__ __forceinline__ void unpack8(const u32x4 w, float* f) { f[0] = bf_lo(w.x); f[1] = bf_hi(w.x); f[2] = bf_lo(w.y); f[3] = bf_hi(w.y); f[4] = bf_lo(w.z); f[5] = bf_hi(w.z); f[6] = bf_lo(w.w); f[7] = bf_hi(w.w); }
; __device__ __forceinline__ u32x4 pack8(const float* f) { u32x4 w; w.x = cvt_pk_bf16(f[0], f[1]); w.y = cvt_pk_bf16(f[2], f[3]); w.z = cvt_pk_bf16(f[4], f[5]); w.w = cvt_pk_bf16(f[6], f[7]); return w; }
;     __device__ __forceinline__ void operator()(const f32x4 (&acc)[2][2][4][2], const Unit& u, int wr, int wc, int fr, int fq) const { if (u.kind == 0) e0(acc, u, wr, wc, fr, fq); else e1(acc, u, wr, wc, fr, fq); }
;     __device__ __forceinline__ void operator()(const f32x4 (&acc)[2][2][4][2], const Unit& u, int wr, int wc, int fr, int fq) const {
;         const int row0 = u.pm * BM + wr * 64 + fr, col0 = u.pn * BM + wc * 32 + 8 * fq;
; #pragma unroll
;         for (int ai = 0; ai < 2; ++ai)
; #pragma unroll
;             for (int m = 0; m < 4; ++m) { const int row = row0 + ai * HALF + m * 16;
; #pragma unroll
;                 for (int bj = 0; bj < 2; ++bj) { const int col = col0 + bj * HALF;
;                     float gf[8], r[8]; unpack8(*(const u32x4*)(gr + (size_t)row * NPROJ + col), gf);
;                     const f32x4 v0 = acc[ai][bj][m][0], v1 = acc[ai][bj][m][1];
; #pragma unroll
;                     for (int j = 0; j < 4; ++j) { r[j] = v0[j] * sigmoidf_(gf[j]); r[4 + j] = v1[j] * sigmoidf_(gf[4 + j]); }
;                     *(u32x4*)(O + (size_t)row * D + col) = pack8(r); } }
;     }
	v_mov_b64_e32 v[28:29], v[190:191]
	v_mov_b64_e32 v[30:31], v[192:193]
	v_lshlrev_b32_e32 v0, 16, v28
	v_mul_f32_e32 v0, 0xbfb8aa3b, v0
	v_exp_f32_e32 v0, v0
	v_lshlrev_b32_e32 v35, 16, v29
	v_and_b32_e32 v36, 0xffff0000, v29
	v_lshlrev_b32_e32 v29, 16, v30
	v_add_f32_e32 v0, 1.0, v0
	v_and_b32_e32 v34, 0xffff0000, v28
	v_rcp_f32_e32 v28, v0
	v_mul_f32_e32 v0, 0xbfb8aa3b, v29
	v_exp_f32_e32 v0, v0
	v_and_b32_e32 v37, 0xffff0000, v30
	v_lshlrev_b32_e32 v38, 16, v31
	v_and_b32_e32 v39, 0xffff0000, v31
	v_add_f32_e32 v0, 1.0, v0
	v_rcp_f32_e32 v30, v0
	v_mul_f32_e32 v0, 0xbfb8aa3b, v34
	v_exp_f32_e32 v0, v0
	s_nop 0
	v_add_f32_e32 v0, 1.0, v0
	v_rcp_f32_e32 v29, v0
	v_mul_f32_e32 v0, 0xbfb8aa3b, v37
	v_exp_f32_e32 v0, v0
	v_pk_mul_f32 v[24:25], v[24:25], v[28:29]
	v_add_f32_e32 v0, 1.0, v0
	v_rcp_f32_e32 v31, v0
	v_mul_f32_e32 v0, 0xbfb8aa3b, v35
	v_exp_f32_e32 v0, v0
	v_pk_mul_f32 v[28:29], v[20:21], v[30:31]
	v_add_f32_e32 v0, 1.0, v0
	v_rcp_f32_e32 v20, v0
	v_mul_f32_e32 v0, 0xbfb8aa3b, v38
	v_exp_f32_e32 v0, v0
	s_nop 0
	v_add_f32_e32 v0, 1.0, v0
	v_rcp_f32_e32 v30, v0
	v_mul_f32_e32 v0, 0xbfb8aa3b, v36
	v_exp_f32_e32 v0, v0
	s_nop 0
	v_add_f32_e32 v0, 1.0, v0
	v_rcp_f32_e32 v21, v0
	v_mul_f32_e32 v0, 0xbfb8aa3b, v39
	v_exp_f32_e32 v0, v0
	v_pk_mul_f32 v[26:27], v[26:27], v[20:21]
	v_cvt_pk_bf16_f32 v20, v24, v25
	v_add_f32_e32 v0, 1.0, v0
	v_rcp_f32_e32 v31, v0
	v_cvt_pk_bf16_f32 v21, v26, v27
	v_pk_mul_f32 v[30:31], v[22:23], v[30:31]
	v_cvt_pk_bf16_f32 v22, v28, v29
	v_cvt_pk_bf16_f32 v23, v30, v31
	global_store_dwordx4 v[32:33], v[20:23], off offset:256
	s_nop 1
	v_mad_i64_i32 v[22:23], s[10:11], v150, s18, v[132:133]
	v_lshl_add_u64 v[22:23], v[22:23], 0, v[2:3]
	s_waitcnt vmcnt(1)
	v_mov_b64_e32 v[24:25], v[194:195]
	v_mov_b64_e32 v[26:27], v[196:197]
	v_lshlrev_b64 v[20:21], 11, v[150:151]
	s_mov_b32 s10, s93
	s_mov_b32 s11, s72
	v_lshlrev_b32_e32 v0, 16, v24
	v_mul_f32_e32 v0, 0xbfb8aa3b, v0
	v_exp_f32_e32 v0, v0
	v_lshlrev_b32_e32 v29, 16, v25
	v_and_b32_e32 v30, 0xffff0000, v25
	v_lshlrev_b32_e32 v25, 16, v26
	v_add_f32_e32 v0, 1.0, v0
	v_and_b32_e32 v28, 0xffff0000, v24
	v_rcp_f32_e32 v24, v0
	v_mul_f32_e32 v0, 0xbfb8aa3b, v25
	v_exp_f32_e32 v0, v0
	v_and_b32_e32 v31, 0xffff0000, v26
	v_lshlrev_b32_e32 v32, 16, v27
	v_and_b32_e32 v33, 0xffff0000, v27
	v_add_f32_e32 v0, 1.0, v0
	v_rcp_f32_e32 v26, v0
	v_mul_f32_e32 v0, 0xbfb8aa3b, v28
	v_exp_f32_e32 v0, v0
	s_nop 0
	v_add_f32_e32 v0, 1.0, v0
	v_rcp_f32_e32 v25, v0
	v_mul_f32_e32 v0, 0xbfb8aa3b, v31
	v_exp_f32_e32 v0, v0
	v_pk_mul_f32 v[16:17], v[16:17], v[24:25]
	v_add_f32_e32 v0, 1.0, v0
	v_rcp_f32_e32 v27, v0
	v_mul_f32_e32 v0, 0xbfb8aa3b, v29
	v_exp_f32_e32 v0, v0
	v_pk_mul_f32 v[24:25], v[12:13], v[26:27]
	v_add_f32_e32 v0, 1.0, v0
	v_rcp_f32_e32 v12, v0
	v_mul_f32_e32 v0, 0xbfb8aa3b, v32
	v_exp_f32_e32 v0, v0
	s_nop 0
	v_add_f32_e32 v0, 1.0, v0
	v_rcp_f32_e32 v26, v0
	v_mul_f32_e32 v0, 0xbfb8aa3b, v30
	v_exp_f32_e32 v0, v0
	s_nop 0
	v_add_f32_e32 v0, 1.0, v0
	v_rcp_f32_e32 v13, v0
	v_mul_f32_e32 v0, 0xbfb8aa3b, v33
	v_exp_f32_e32 v0, v0
	v_pk_mul_f32 v[18:19], v[18:19], v[12:13]
	v_cvt_pk_bf16_f32 v12, v16, v17
	v_add_f32_e32 v0, 1.0, v0
	v_rcp_f32_e32 v27, v0
	v_lshl_add_u64 v[16:17], s[94:95], 0, v[20:21]
	v_cvt_pk_bf16_f32 v13, v18, v19
	v_lshl_add_u64 v[16:17], v[16:17], 0, v[2:3]
	v_pk_mul_f32 v[26:27], v[14:15], v[26:27]
	v_cvt_pk_bf16_f32 v14, v24, v25
	v_cvt_pk_bf16_f32 v15, v26, v27
	global_store_dwordx4 v[16:17], v[12:15], off
	s_waitcnt vmcnt(0)
	v_mov_b64_e32 v[12:13], v[198:199]
	v_mov_b64_e32 v[14:15], v[200:201]
	v_lshlrev_b32_e32 v0, 16, v12
	v_mul_f32_e32 v0, 0xbfb8aa3b, v0
	v_exp_f32_e32 v0, v0
	v_and_b32_e32 v3, 0xffff0000, v12
	v_lshlrev_b32_e32 v12, 16, v14
	v_lshlrev_b32_e32 v18, 16, v13
	v_add_f32_e32 v0, 1.0, v0
	v_rcp_f32_e32 v2, v0
	v_mul_f32_e32 v0, 0xbfb8aa3b, v12
	v_exp_f32_e32 v0, v0
	v_and_b32_e32 v19, 0xffff0000, v13
	v_and_b32_e32 v13, 0xffff0000, v14
	v_lshlrev_b32_e32 v14, 16, v15
	v_add_f32_e32 v0, 1.0, v0
	v_rcp_f32_e32 v12, v0
	v_mul_f32_e32 v0, 0xbfb8aa3b, v3
	v_exp_f32_e32 v0, v0
	v_and_b32_e32 v15, 0xffff0000, v15
	v_add_f32_e32 v0, 1.0, v0
	v_rcp_f32_e32 v3, v0
	v_mul_f32_e32 v0, 0xbfb8aa3b, v13
	v_exp_f32_e32 v0, v0
	v_pk_mul_f32 v[2:3], v[8:9], v[2:3]
	s_nop 0
	v_cvt_pk_bf16_f32 v2, v2, v3
	v_add_f32_e32 v0, 1.0, v0
	v_rcp_f32_e32 v13, v0
	v_mul_f32_e32 v0, 0xbfb8aa3b, v18
	v_exp_f32_e32 v0, v0
	v_pk_mul_f32 v[4:5], v[4:5], v[12:13]
	s_nop 0
	v_cvt_pk_bf16_f32 v4, v4, v5
	v_add_f32_e32 v0, 1.0, v0
	v_rcp_f32_e32 v8, v0
	v_mul_f32_e32 v0, 0xbfb8aa3b, v14
	v_exp_f32_e32 v0, v0
	s_nop 0
	v_add_f32_e32 v0, 1.0, v0
	v_rcp_f32_e32 v12, v0
	v_mul_f32_e32 v0, 0xbfb8aa3b, v19
	v_exp_f32_e32 v0, v0
	s_nop 0
	v_add_f32_e32 v0, 1.0, v0
	v_rcp_f32_e32 v9, v0
	v_mul_f32_e32 v0, 0xbfb8aa3b, v15
	v_exp_f32_e32 v0, v0
	v_pk_mul_f32 v[8:9], v[10:11], v[8:9]
	s_nop 0
	v_cvt_pk_bf16_f32 v3, v8, v9
	v_add_f32_e32 v0, 1.0, v0
	v_rcp_f32_e32 v13, v0
	s_nop 0
	v_pk_mul_f32 v[6:7], v[6:7], v[12:13]
	s_nop 0
	v_cvt_pk_bf16_f32 v5, v6, v7
	global_store_dwordx4 v[16:17], v[2:5], off offset:256
	s_cbranch_vccnz .LBB0_563

; __device__ __forceinline__ void unpack8(const u32x4 w, float* f) { f[0] = bf_lo(w.x); f[1] = bf_hi(w.x); f[2] = bf_lo(w.y); f[3] = bf_hi(w.y); f[4] = bf_lo(w.z); f[5] = bf_hi(w.z); f[6] = bf_lo(w.w); f[7] = bf_hi(w.w); }
;     __device__ __forceinline__ void mid(f32x4 (&acc)[2][2][4][2], const Unit& u, int wr, int wc, int fr, int fq) const {
;         const int row0 = u.pm * BM + wr * 64 + fr, col0 = u.pn * BM + wc * 32 + 8 * fq;
; #pragma unroll
;         for (int ai = 0; ai < 2; ++ai)
; #pragma unroll
;             for (int m = 0; m < 4; ++m) { int row = row0 + ai * HALF + m * 16; asm volatile("" : "+v"(row));
; #pragma unroll
;                 for (int bj = 0; bj < 2; ++bj) { const size_t off = (size_t)row * NPROJ + col0 + bj * HALF;
;                     float fa[8], fb[8]; unpack8(*(const u32x4*)(ga + off), fa); unpack8(*(const u32x4*)(gr + off), fb);
; #pragma unroll
;                     for (int j = 0; j < 8; ++j) { const float rt = (1.0f + __builtin_amdgcn_exp2f(fb[j] * -1.4426950408889634f)) * __builtin_amdgcn_rcpf(1.0f + __builtin_amdgcn_exp2f(fa[j] * -1.4426950408889634f));
;                         if (j < 4) acc[ai][bj][m][0][j] *= rt; else acc[ai][bj][m][1][j - 4] *= rt; } }
.LBB0_561:
	s_cmpk_lg_i32 vcc_lo, 0x400
	s_cbranch_scc1 .LBB0_560
	v_mad_i64_i32 v[230:231], s[98:99], v166, s57, v[164:165]
	v_lshlrev_b64 v[230:231], 1, v[230:231]
	v_lshl_add_u64 v[236:237], s[96:97], 0, v[230:231]
	v_lshl_add_u64 v[238:239], s[40:41], 0, v[230:231]
	global_load_dwordx4 v[182:185], v[236:237], off
	global_load_dwordx4 v[186:189], v[238:239], off
	global_load_dwordx4 v[190:193], v[236:237], off offset:256
	global_load_dwordx4 v[194:197], v[238:239], off offset:256
	v_mad_i64_i32 v[230:231], s[98:99], v162, s57, v[164:165]
	v_lshlrev_b64 v[230:231], 1, v[230:231]
	v_lshl_add_u64 v[236:237], s[96:97], 0, v[230:231]
	v_lshl_add_u64 v[238:239], s[40:41], 0, v[230:231]
	global_load_dwordx4 v[198:201], v[236:237], off
	global_load_dwordx4 v[202:205], v[238:239], off
	global_load_dwordx4 v[206:209], v[236:237], off offset:256
	global_load_dwordx4 v[210:213], v[238:239], off offset:256
	v_mad_i64_i32 v[230:231], s[98:99], v160, s57, v[164:165]
	v_lshlrev_b64 v[230:231], 1, v[230:231]
	v_lshl_add_u64 v[236:237], s[96:97], 0, v[230:231]
	v_lshl_add_u64 v[238:239], s[40:41], 0, v[230:231]
	global_load_dwordx4 v[214:217], v[236:237], off
	global_load_dwordx4 v[218:221], v[238:239], off
	global_load_dwordx4 v[222:225], v[236:237], off offset:256
	global_load_dwordx4 v[226:229], v[238:239], off offset:256
	v_mov_b32_e32 v0, v166
	s_nop 0
	v_mad_i64_i32 v[2:3], s[10:11], v0, s57, v[164:165]
	v_lshlrev_b64 v[2:3], 1, v[2:3]
	v_lshl_add_u64 v[132:133], s[96:97], 0, v[2:3]
	s_waitcnt vmcnt(11)
	v_mov_b64_e32 v[132:133], v[182:183]
	v_mov_b64_e32 v[134:135], v[184:185]
	v_lshlrev_b32_e32 v155, 16, v134
	v_and_b32_e32 v157, 0xffff0000, v134
	v_lshlrev_b32_e32 v159, 16, v135
	v_and_b32_e32 v161, 0xffff0000, v135
	v_lshl_add_u64 v[134:135], s[40:41], 0, v[2:3]
	s_waitcnt vmcnt(10)
	v_mov_b64_e32 v[134:135], v[186:187]
	v_mov_b64_e32 v[136:137], v[188:189]
	v_and_b32_e32 v0, 0xffff0000, v132
	v_mul_f32_e32 v0, 0xbfb8aa3b, v0
	v_exp_f32_e32 v0, v0
	v_lshlrev_b32_e32 v151, 16, v133
	v_and_b32_e32 v153, 0xffff0000, v133
	v_or_b32_e32 v2, 0x100, v2
	v_add_f32_e32 v0, 1.0, v0
	v_lshlrev_b32_e32 v163, 16, v135
	v_and_b32_e32 v167, 0xffff0000, v135
	v_lshlrev_b32_e32 v135, 16, v132
	v_and_b32_e32 v133, 0xffff0000, v134
	v_lshlrev_b32_e32 v132, 16, v134
	v_mul_f32_e32 v134, 0xbfb8aa3b, v135
	v_rcp_f32_e32 v135, v0
	v_mul_f32_e32 v0, 0xbfb8aa3b, v163
	v_lshlrev_b32_e32 v178, 16, v136
	v_and_b32_e32 v179, 0xffff0000, v136
	v_exp_f32_e32 v136, v0
	v_mul_f32_e32 v0, 0xbfb8aa3b, v151
	v_exp_f32_e32 v0, v0
	v_exp_f32_e32 v134, v134
	v_lshlrev_b32_e32 v180, 16, v137
	v_and_b32_e32 v181, 0xffff0000, v137
	v_add_f32_e32 v0, 1.0, v0
	v_rcp_f32_e32 v176, v0
	v_mul_f32_e32 v0, 0xbfb8aa3b, v167
	v_mul_f32_e32 v132, 0xbfb8aa3b, v132
	v_mul_f32_e32 v133, 0xbfb8aa3b, v133
	v_exp_f32_e32 v137, v0
	v_mul_f32_e32 v0, 0xbfb8aa3b, v153
	v_exp_f32_e32 v132, v132
	v_add_f32_e32 v134, 1.0, v134
	v_exp_f32_e32 v133, v133
	v_exp_f32_e32 v0, v0
	v_rcp_f32_e32 v134, v134
	v_pk_add_f32 v[136:137], v[136:137], 1.0 op_sel_hi:[1,0]
	v_pk_add_f32 v[132:133], v[132:133], 1.0 op_sel_hi:[1,0]
	v_add_f32_e32 v0, 1.0, v0
	v_rcp_f32_e32 v177, v0
	v_pk_mul_f32 v[132:133], v[134:135], v[132:133]
	v_mul_f32_e32 v0, 0xbfb8aa3b, v178
	v_pk_mul_f32 v[128:129], v[128:129], v[132:133]
	v_exp_f32_e32 v132, v0
	v_mul_f32_e32 v0, 0xbfb8aa3b, v155
	v_exp_f32_e32 v0, v0
	v_pk_mul_f32 v[134:135], v[176:177], v[136:137]
	v_add_f32_e32 v0, 1.0, v0
	v_pk_mul_f32 v[130:131], v[130:131], v[134:135]
	v_rcp_f32_e32 v134, v0
	v_mul_f32_e32 v0, 0xbfb8aa3b, v179
	v_exp_f32_e32 v133, v0
	v_mul_f32_e32 v0, 0xbfb8aa3b, v157
	v_exp_f32_e32 v0, v0
	v_pk_add_f32 v[132:133], v[132:133], 1.0 op_sel_hi:[1,0]
	v_add_f32_e32 v0, 1.0, v0
	v_rcp_f32_e32 v135, v0
	v_mul_f32_e32 v0, 0xbfb8aa3b, v180
	v_exp_f32_e32 v136, v0
	v_mul_f32_e32 v0, 0xbfb8aa3b, v159
	v_exp_f32_e32 v0, v0
	v_pk_mul_f32 v[132:133], v[134:135], v[132:133]
	v_add_f32_e32 v0, 1.0, v0
	v_rcp_f32_e32 v176, v0
	v_mul_f32_e32 v0, 0xbfb8aa3b, v181
	v_exp_f32_e32 v137, v0
	v_mul_f32_e32 v0, 0xbfb8aa3b, v161
	v_exp_f32_e32 v0, v0
	v_pk_mul_f32 v[124:125], v[124:125], v[132:133]
	v_pk_add_f32 v[136:137], v[136:137], 1.0 op_sel_hi:[1,0]
	v_lshl_add_u64 v[132:133], s[96:97], 0, v[2:3]
	v_add_f32_e32 v0, 1.0, v0
	v_rcp_f32_e32 v177, v0
	v_lshl_add_u64 v[2:3], s[40:41], 0, v[2:3]
	v_pk_mul_f32 v[134:135], v[176:177], v[136:137]
	s_nop 0
	v_pk_mul_f32 v[126:127], v[126:127], v[134:135]
	s_waitcnt vmcnt(9)
	v_mov_b64_e32 v[132:133], v[190:191]
	v_mov_b64_e32 v[134:135], v[192:193]
	v_lshlrev_b32_e32 v155, 16, v134
	v_and_b32_e32 v157, 0xffff0000, v134
	v_lshlrev_b32_e32 v159, 16, v135
	v_and_b32_e32 v161, 0xffff0000, v135
	s_waitcnt vmcnt(8)
; __device__ __forceinline__ void unpack8(const u32x4 w, float* f) { f[0] = bf_lo(w.x); f[1] = bf_hi(w.x); f[2] = bf_lo(w.y); f[3] = bf_hi(w.y); f[4] = bf_lo(w.z); f[5] = bf_hi(w.z); f[6] = bf_lo(w.w); f[7] = bf_hi(w.w); }
;     __device__ __forceinline__ void mid(f32x4 (&acc)[2][2][4][2], const Unit& u, int wr, int wc, int fr, int fq) const {
;         const int row0 = u.pm * BM + wr * 64 + fr, col0 = u.pn * BM + wc * 32 + 8 * fq;
; #pragma unroll
;         for (int ai = 0; ai < 2; ++ai)
; #pragma unroll
;             for (int m = 0; m < 4; ++m) { int row = row0 + ai * HALF + m * 16; asm volatile("" : "+v"(row));
; #pragma unroll
;                 for (int bj = 0; bj < 2; ++bj) { const size_t off = (size_t)row * NPROJ + col0 + bj * HALF;
;                     float fa[8], fb[8]; unpack8(*(const u32x4*)(ga + off), fa); unpack8(*(const u32x4*)(gr + off), fb);
; #pragma unroll
;                     for (int j = 0; j < 8; ++j) { const float rt = (1.0f + __builtin_amdgcn_exp2f(fb[j] * -1.4426950408889634f)) * __builtin_amdgcn_rcpf(1.0f + __builtin_amdgcn_exp2f(fa[j] * -1.4426950408889634f));
;                         if (j < 4) acc[ai][bj][m][0][j] *= rt; else acc[ai][bj][m][1][j - 4] *= rt; } }
;                 asm volatile("" ::: "memory"); }
;     }
	v_mov_b64_e32 v[134:135], v[194:195]
	v_mov_b64_e32 v[136:137], v[196:197]
	v_mad_i64_i32 v[230:231], s[98:99], v158, s57, v[164:165]
	v_lshlrev_b64 v[230:231], 1, v[230:231]
	v_lshl_add_u64 v[236:237], s[96:97], 0, v[230:231]
	v_lshl_add_u64 v[238:239], s[40:41], 0, v[230:231]
	global_load_dwordx4 v[182:185], v[236:237], off
	global_load_dwordx4 v[186:189], v[238:239], off
	global_load_dwordx4 v[190:193], v[236:237], off offset:256
	global_load_dwordx4 v[194:197], v[238:239], off offset:256
	v_and_b32_e32 v0, 0xffff0000, v132
	v_mul_f32_e32 v0, 0xbfb8aa3b, v0
	v_exp_f32_e32 v0, v0
	v_lshlrev_b32_e32 v151, 16, v133
	v_and_b32_e32 v153, 0xffff0000, v133
	v_lshlrev_b32_e32 v132, 16, v132
	v_add_f32_e32 v0, 1.0, v0
	v_rcp_f32_e32 v133, v0
	v_mul_f32_e32 v132, 0xbfb8aa3b, v132
	v_exp_f32_e32 v132, v132
	v_lshlrev_b32_e32 v163, 16, v135
	v_mul_f32_e32 v0, 0xbfb8aa3b, v163
	v_and_b32_e32 v3, 0xffff0000, v134
	v_lshlrev_b32_e32 v2, 16, v134
	v_exp_f32_e32 v134, v0
	v_mul_f32_e32 v0, 0xbfb8aa3b, v151
	v_exp_f32_e32 v0, v0
	v_and_b32_e32 v135, 0xffff0000, v135
	v_lshlrev_b32_e32 v167, 16, v136
	v_and_b32_e32 v176, 0xffff0000, v136
	v_add_f32_e32 v0, 1.0, v0
	v_rcp_f32_e32 v136, v0
	v_mul_f32_e32 v0, 0xbfb8aa3b, v135
	v_mul_f32_e32 v2, 0xbfb8aa3b, v2
	v_mul_f32_e32 v3, 0xbfb8aa3b, v3
	v_exp_f32_e32 v135, v0
	v_mul_f32_e32 v0, 0xbfb8aa3b, v153
	v_exp_f32_e32 v2, v2
	v_add_f32_e32 v132, 1.0, v132
	v_exp_f32_e32 v3, v3
	v_exp_f32_e32 v0, v0
	v_rcp_f32_e32 v132, v132
	v_lshlrev_b32_e32 v177, 16, v137
	v_pk_add_f32 v[2:3], v[2:3], 1.0 op_sel_hi:[1,0]
	v_add_f32_e32 v0, 1.0, v0
	v_and_b32_e32 v178, 0xffff0000, v137
	v_rcp_f32_e32 v137, v0
	v_pk_mul_f32 v[2:3], v[2:3], v[132:133]
	v_mul_f32_e32 v0, 0xbfb8aa3b, v167
	v_pk_mul_f32 v[120:121], v[120:121], v[2:3]
	v_exp_f32_e32 v2, v0
	v_mul_f32_e32 v0, 0xbfb8aa3b, v155
	v_exp_f32_e32 v0, v0
	v_pk_add_f32 v[134:135], v[134:135], 1.0 op_sel_hi:[1,0]
	v_add_f32_e32 v0, 1.0, v0
	v_pk_mul_f32 v[132:133], v[134:135], v[136:137]
	s_nop 0
	v_pk_mul_f32 v[122:123], v[122:123], v[132:133]
	v_rcp_f32_e32 v132, v0
	v_mul_f32_e32 v0, 0xbfb8aa3b, v176
	v_exp_f32_e32 v3, v0
	v_mul_f32_e32 v0, 0xbfb8aa3b, v157
	v_exp_f32_e32 v0, v0
	v_pk_add_f32 v[2:3], v[2:3], 1.0 op_sel_hi:[1,0]
	v_add_f32_e32 v0, 1.0, v0
	v_rcp_f32_e32 v133, v0
	v_mul_f32_e32 v0, 0xbfb8aa3b, v177
	v_exp_f32_e32 v134, v0
	v_mul_f32_e32 v0, 0xbfb8aa3b, v159
	v_exp_f32_e32 v0, v0
	v_pk_mul_f32 v[2:3], v[2:3], v[132:133]
	v_add_f32_e32 v0, 1.0, v0
	v_rcp_f32_e32 v136, v0
	v_mul_f32_e32 v0, 0xbfb8aa3b, v178
	v_exp_f32_e32 v135, v0
	v_mul_f32_e32 v0, 0xbfb8aa3b, v161
	v_exp_f32_e32 v0, v0
	v_pk_mul_f32 v[116:117], v[116:117], v[2:3]
	v_pk_add_f32 v[134:135], v[134:135], 1.0 op_sel_hi:[1,0]
	v_add_f32_e32 v0, 1.0, v0
	v_rcp_f32_e32 v137, v0
	v_mov_b32_e32 v0, v162
	v_pk_mul_f32 v[132:133], v[134:135], v[136:137]
	v_mad_i64_i32 v[2:3], s[10:11], v0, s57, v[164:165]
	v_lshlrev_b64 v[2:3], 1, v[2:3]
	v_pk_mul_f32 v[118:119], v[118:119], v[132:133]
	v_lshl_add_u64 v[132:133], s[96:97], 0, v[2:3]
	s_waitcnt vmcnt(11)
	v_mov_b64_e32 v[132:133], v[198:199]
	v_mov_b64_e32 v[134:135], v[200:201]
	v_lshlrev_b32_e32 v155, 16, v134
	v_and_b32_e32 v157, 0xffff0000, v134
	v_lshlrev_b32_e32 v159, 16, v135
	v_and_b32_e32 v161, 0xffff0000, v135
	v_lshl_add_u64 v[134:135], s[40:41], 0, v[2:3]
	s_waitcnt vmcnt(10)
	v_mov_b64_e32 v[134:135], v[202:203]
	v_mov_b64_e32 v[136:137], v[204:205]
	v_and_b32_e32 v0, 0xffff0000, v132
	v_mul_f32_e32 v0, 0xbfb8aa3b, v0
	v_exp_f32_e32 v0, v0
	v_lshlrev_b32_e32 v151, 16, v133
	v_and_b32_e32 v153, 0xffff0000, v133
	v_or_b32_e32 v2, 0x100, v2
	v_add_f32_e32 v0, 1.0, v0
	v_lshlrev_b32_e32 v163, 16, v135
	v_and_b32_e32 v167, 0xffff0000, v135
	v_lshlrev_b32_e32 v135, 16, v132
	v_and_b32_e32 v133, 0xffff0000, v134
	v_lshlrev_b32_e32 v132, 16, v134
	v_mul_f32_e32 v134, 0xbfb8aa3b, v135
	v_rcp_f32_e32 v135, v0
	v_mul_f32_e32 v0, 0xbfb8aa3b, v163
	v_lshlrev_b32_e32 v178, 16, v136
	v_and_b32_e32 v179, 0xffff0000, v136
	v_exp_f32_e32 v136, v0
	v_mul_f32_e32 v0, 0xbfb8aa3b, v151
	v_exp_f32_e32 v0, v0
	v_exp_f32_e32 v134, v134
	v_lshlrev_b32_e32 v180, 16, v137
	v_and_b32_e32 v181, 0xffff0000, v137
	v_add_f32_e32 v0, 1.0, v0
	v_rcp_f32_e32 v176, v0
	v_mul_f32_e32 v0, 0xbfb8aa3b, v167
	v_mul_f32_e32 v132, 0xbfb8aa3b, v132
	v_mul_f32_e32 v133, 0xbfb8aa3b, v133
	v_exp_f32_e32 v137, v0
	v_mul_f32_e32 v0, 0xbfb8aa3b, v153
	v_exp_f32_e32 v132, v132
	v_add_f32_e32 v134, 1.0, v134
	v_exp_f32_e32 v133, v133
	v_exp_f32_e32 v0, v0
	v_rcp_f32_e32 v134, v134
	v_pk_add_f32 v[136:137], v[136:137], 1.0 op_sel_hi:[1,0]
	v_pk_add_f32 v[132:133], v[132:133], 1.0 op_sel_hi:[1,0]
	v_add_f32_e32 v0, 1.0, v0
	v_rcp_f32_e32 v177, v0
	v_pk_mul_f32 v[132:133], v[134:135], v[132:133]
	v_mul_f32_e32 v0, 0xbfb8aa3b, v178
	v_pk_mul_f32 v[112:113], v[112:113], v[132:133]
	v_exp_f32_e32 v132, v0
	v_mul_f32_e32 v0, 0xbfb8aa3b, v155
	v_exp_f32_e32 v0, v0
	v_pk_mul_f32 v[134:135], v[176:177], v[136:137]
	v_add_f32_e32 v0, 1.0, v0
	v_pk_mul_f32 v[114:115], v[114:115], v[134:135]
	v_rcp_f32_e32 v134, v0
	v_mul_f32_e32 v0, 0xbfb8aa3b, v179
	v_exp_f32_e32 v133, v0
	v_mul_f32_e32 v0, 0xbfb8aa3b, v157
	v_exp_f32_e32 v0, v0
	v_pk_add_f32 v[132:133], v[132:133], 1.0 op_sel_hi:[1,0]
	v_add_f32_e32 v0, 1.0, v0
	v_rcp_f32_e32 v135, v0
	v_mul_f32_e32 v0, 0xbfb8aa3b, v180
	v_exp_f32_e32 v136, v0
	v_mul_f32_e32 v0, 0xbfb8aa3b, v159
	v_exp_f32_e32 v0, v0
	v_pk_mul_f32 v[132:133], v[134:135], v[132:133]
	v_add_f32_e32 v0, 1.0, v0
	v_rcp_f32_e32 v176, v0
	v_mul_f32_e32 v0, 0xbfb8aa3b, v181
	v_exp_f32_e32 v137, v0
	v_mul_f32_e32 v0, 0xbfb8aa3b, v161
	v_exp_f32_e32 v0, v0
	v_pk_mul_f32 v[108:109], v[108:109], v[132:133]
	v_pk_add_f32 v[136:137], v[136:137], 1.0 op_sel_hi:[1,0]
	v_lshl_add_u64 v[132:133], s[96:97], 0, v[2:3]
	v_add_f32_e32 v0, 1.0, v0
	v_rcp_f32_e32 v177, v0
	v_lshl_add_u64 v[2:3], s[40:41], 0, v[2:3]
	v_pk_mul_f32 v[134:135], v[176:177], v[136:137]
	s_nop 0
	v_pk_mul_f32 v[110:111], v[110:111], v[134:135]
	s_waitcnt vmcnt(9)
; __device__ __forceinline__ void unpack8(const u32x4 w, float* f) { f[0] = bf_lo(w.x); f[1] = bf_hi(w.x); f[2] = bf_lo(w.y); f[3] = bf_hi(w.y); f[4] = bf_lo(w.z); f[5] = bf_hi(w.z); f[6] = bf_lo(w.w); f[7] = bf_hi(w.w); }
;     __device__ __forceinline__ void mid(f32x4 (&acc)[2][2][4][2], const Unit& u, int wr, int wc, int fr, int fq) const {
;         const int row0 = u.pm * BM + wr * 64 + fr, col0 = u.pn * BM + wc * 32 + 8 * fq;
; #pragma unroll
;         for (int ai = 0; ai < 2; ++ai)
; #pragma unroll
;             for (int m = 0; m < 4; ++m) { int row = row0 + ai * HALF + m * 16; asm volatile("" : "+v"(row));
; #pragma unroll
;                 for (int bj = 0; bj < 2; ++bj) { const size_t off = (size_t)row * NPROJ + col0 + bj * HALF;
;                     float fa[8], fb[8]; unpack8(*(const u32x4*)(ga + off), fa); unpack8(*(const u32x4*)(gr + off), fb);
; #pragma unroll
;                     for (int j = 0; j < 8; ++j) { const float rt = (1.0f + __builtin_amdgcn_exp2f(fb[j] * -1.4426950408889634f)) * __builtin_amdgcn_rcpf(1.0f + __builtin_amdgcn_exp2f(fa[j] * -1.4426950408889634f));
;                         if (j < 4) acc[ai][bj][m][0][j] *= rt; else acc[ai][bj][m][1][j - 4] *= rt; } }
;                 asm volatile("" ::: "memory"); }
;     }
	v_mov_b64_e32 v[132:133], v[206:207]
	v_mov_b64_e32 v[134:135], v[208:209]
	v_lshlrev_b32_e32 v155, 16, v134
	v_and_b32_e32 v157, 0xffff0000, v134
	v_lshlrev_b32_e32 v159, 16, v135
	v_and_b32_e32 v161, 0xffff0000, v135
	s_waitcnt vmcnt(8)
	v_mov_b64_e32 v[134:135], v[210:211]
	v_mov_b64_e32 v[136:137], v[212:213]
	v_mad_i64_i32 v[230:231], s[98:99], v156, s57, v[164:165]
	v_lshlrev_b64 v[230:231], 1, v[230:231]
	v_lshl_add_u64 v[236:237], s[96:97], 0, v[230:231]
	v_lshl_add_u64 v[238:239], s[40:41], 0, v[230:231]
	global_load_dwordx4 v[198:201], v[236:237], off
	global_load_dwordx4 v[202:205], v[238:239], off
	global_load_dwordx4 v[206:209], v[236:237], off offset:256
	global_load_dwordx4 v[210:213], v[238:239], off offset:256
	v_and_b32_e32 v0, 0xffff0000, v132
	v_mul_f32_e32 v0, 0xbfb8aa3b, v0
	v_exp_f32_e32 v0, v0
	v_lshlrev_b32_e32 v151, 16, v133
	v_and_b32_e32 v153, 0xffff0000, v133
	v_lshlrev_b32_e32 v132, 16, v132
	v_add_f32_e32 v0, 1.0, v0
	v_rcp_f32_e32 v133, v0
	v_mul_f32_e32 v132, 0xbfb8aa3b, v132
	v_exp_f32_e32 v132, v132
	v_lshlrev_b32_e32 v163, 16, v135
	v_mul_f32_e32 v0, 0xbfb8aa3b, v163
	v_and_b32_e32 v3, 0xffff0000, v134
	v_lshlrev_b32_e32 v2, 16, v134
	v_exp_f32_e32 v134, v0
	v_mul_f32_e32 v0, 0xbfb8aa3b, v151
	v_exp_f32_e32 v0, v0
	v_and_b32_e32 v135, 0xffff0000, v135
	v_lshlrev_b32_e32 v167, 16, v136
	v_and_b32_e32 v176, 0xffff0000, v136
	v_add_f32_e32 v0, 1.0, v0
	v_rcp_f32_e32 v136, v0
	v_mul_f32_e32 v0, 0xbfb8aa3b, v135
	v_mul_f32_e32 v2, 0xbfb8aa3b, v2
	v_mul_f32_e32 v3, 0xbfb8aa3b, v3
	v_exp_f32_e32 v135, v0
	v_mul_f32_e32 v0, 0xbfb8aa3b, v153
	v_exp_f32_e32 v2, v2
	v_add_f32_e32 v132, 1.0, v132
	v_exp_f32_e32 v3, v3
	v_exp_f32_e32 v0, v0
	v_rcp_f32_e32 v132, v132
	v_lshlrev_b32_e32 v177, 16, v137
	v_pk_add_f32 v[2:3], v[2:3], 1.0 op_sel_hi:[1,0]
	v_add_f32_e32 v0, 1.0, v0
	v_and_b32_e32 v178, 0xffff0000, v137
	v_rcp_f32_e32 v137, v0
	v_pk_mul_f32 v[2:3], v[2:3], v[132:133]
	v_mul_f32_e32 v0, 0xbfb8aa3b, v167
	v_pk_mul_f32 v[104:105], v[104:105], v[2:3]
	v_exp_f32_e32 v2, v0
	v_mul_f32_e32 v0, 0xbfb8aa3b, v155
	v_exp_f32_e32 v0, v0
	v_pk_add_f32 v[134:135], v[134:135], 1.0 op_sel_hi:[1,0]
	v_add_f32_e32 v0, 1.0, v0
	v_pk_mul_f32 v[132:133], v[134:135], v[136:137]
	s_nop 0
	v_pk_mul_f32 v[106:107], v[106:107], v[132:133]
	v_rcp_f32_e32 v132, v0
	v_mul_f32_e32 v0, 0xbfb8aa3b, v176
	v_exp_f32_e32 v3, v0
	v_mul_f32_e32 v0, 0xbfb8aa3b, v157
	v_exp_f32_e32 v0, v0
	v_pk_add_f32 v[2:3], v[2:3], 1.0 op_sel_hi:[1,0]
	v_add_f32_e32 v0, 1.0, v0
	v_rcp_f32_e32 v133, v0
	v_mul_f32_e32 v0, 0xbfb8aa3b, v177
	v_exp_f32_e32 v134, v0
	v_mul_f32_e32 v0, 0xbfb8aa3b, v159
	v_exp_f32_e32 v0, v0
	v_pk_mul_f32 v[2:3], v[2:3], v[132:133]
	v_add_f32_e32 v0, 1.0, v0
	v_rcp_f32_e32 v136, v0
	v_mul_f32_e32 v0, 0xbfb8aa3b, v178
	v_exp_f32_e32 v135, v0
	v_mul_f32_e32 v0, 0xbfb8aa3b, v161
	v_exp_f32_e32 v0, v0
	v_pk_mul_f32 v[100:101], v[100:101], v[2:3]
	v_pk_add_f32 v[134:135], v[134:135], 1.0 op_sel_hi:[1,0]
	v_add_f32_e32 v0, 1.0, v0
	v_rcp_f32_e32 v137, v0
	v_mov_b32_e32 v0, v160
	v_pk_mul_f32 v[132:133], v[134:135], v[136:137]
	v_mad_i64_i32 v[2:3], s[10:11], v0, s57, v[164:165]
	v_lshlrev_b64 v[2:3], 1, v[2:3]
	v_pk_mul_f32 v[102:103], v[102:103], v[132:133]
	v_lshl_add_u64 v[132:133], s[96:97], 0, v[2:3]
	s_waitcnt vmcnt(11)
	v_mov_b64_e32 v[132:133], v[214:215]
	v_mov_b64_e32 v[134:135], v[216:217]
	v_lshlrev_b32_e32 v155, 16, v134
	v_and_b32_e32 v157, 0xffff0000, v134
	v_lshlrev_b32_e32 v159, 16, v135
	v_and_b32_e32 v161, 0xffff0000, v135
	v_lshl_add_u64 v[134:135], s[40:41], 0, v[2:3]
	s_waitcnt vmcnt(10)
	v_mov_b64_e32 v[134:135], v[218:219]
	v_mov_b64_e32 v[136:137], v[220:221]
	v_and_b32_e32 v0, 0xffff0000, v132
	v_mul_f32_e32 v0, 0xbfb8aa3b, v0
	v_exp_f32_e32 v0, v0
	v_lshlrev_b32_e32 v151, 16, v133
	v_and_b32_e32 v153, 0xffff0000, v133
	v_or_b32_e32 v2, 0x100, v2
	v_add_f32_e32 v0, 1.0, v0
	v_lshlrev_b32_e32 v163, 16, v135
	v_and_b32_e32 v167, 0xffff0000, v135
	v_lshlrev_b32_e32 v135, 16, v132
	v_and_b32_e32 v133, 0xffff0000, v134
	v_lshlrev_b32_e32 v132, 16, v134
	v_mul_f32_e32 v134, 0xbfb8aa3b, v135
	v_rcp_f32_e32 v135, v0
	v_mul_f32_e32 v0, 0xbfb8aa3b, v163
	v_lshlrev_b32_e32 v178, 16, v136
	v_and_b32_e32 v179, 0xffff0000, v136
	v_exp_f32_e32 v136, v0
	v_mul_f32_e32 v0, 0xbfb8aa3b, v151
	v_exp_f32_e32 v0, v0
	v_exp_f32_e32 v134, v134
	v_lshlrev_b32_e32 v180, 16, v137
	v_and_b32_e32 v181, 0xffff0000, v137
	v_add_f32_e32 v0, 1.0, v0
	v_rcp_f32_e32 v176, v0
	v_mul_f32_e32 v0, 0xbfb8aa3b, v167
	v_mul_f32_e32 v132, 0xbfb8aa3b, v132
	v_mul_f32_e32 v133, 0xbfb8aa3b, v133
	v_exp_f32_e32 v137, v0
	v_mul_f32_e32 v0, 0xbfb8aa3b, v153
	v_exp_f32_e32 v132, v132
	v_add_f32_e32 v134, 1.0, v134
	v_exp_f32_e32 v133, v133
	v_exp_f32_e32 v0, v0
	v_rcp_f32_e32 v134, v134
	v_pk_add_f32 v[136:137], v[136:137], 1.0 op_sel_hi:[1,0]
	v_pk_add_f32 v[132:133], v[132:133], 1.0 op_sel_hi:[1,0]
	v_add_f32_e32 v0, 1.0, v0
	v_rcp_f32_e32 v177, v0
	v_pk_mul_f32 v[132:133], v[134:135], v[132:133]
	v_mul_f32_e32 v0, 0xbfb8aa3b, v178
	v_pk_mul_f32 v[96:97], v[96:97], v[132:133]
	v_exp_f32_e32 v132, v0
	v_mul_f32_e32 v0, 0xbfb8aa3b, v155
	v_exp_f32_e32 v0, v0
	v_pk_mul_f32 v[134:135], v[176:177], v[136:137]
	v_add_f32_e32 v0, 1.0, v0
	v_pk_mul_f32 v[98:99], v[98:99], v[134:135]
	v_rcp_f32_e32 v134, v0
	v_mul_f32_e32 v0, 0xbfb8aa3b, v179
	v_exp_f32_e32 v133, v0
	v_mul_f32_e32 v0, 0xbfb8aa3b, v157
	v_exp_f32_e32 v0, v0
	v_pk_add_f32 v[132:133], v[132:133], 1.0 op_sel_hi:[1,0]
	v_add_f32_e32 v0, 1.0, v0
	v_rcp_f32_e32 v135, v0
	v_mul_f32_e32 v0, 0xbfb8aa3b, v180
	v_exp_f32_e32 v136, v0
	v_mul_f32_e32 v0, 0xbfb8aa3b, v159
	v_exp_f32_e32 v0, v0
	v_pk_mul_f32 v[132:133], v[134:135], v[132:133]
	v_add_f32_e32 v0, 1.0, v0
	v_rcp_f32_e32 v176, v0
	v_mul_f32_e32 v0, 0xbfb8aa3b, v181
	v_exp_f32_e32 v137, v0
	v_mul_f32_e32 v0, 0xbfb8aa3b, v161
	v_exp_f32_e32 v0, v0
	v_pk_mul_f32 v[92:93], v[92:93], v[132:133]
	v_pk_add_f32 v[136:137], v[136:137], 1.0 op_sel_hi:[1,0]
	v_lshl_add_u64 v[132:133], s[96:97], 0, v[2:3]
	v_add_f32_e32 v0, 1.0, v0
	v_rcp_f32_e32 v177, v0
	v_lshl_add_u64 v[2:3], s[40:41], 0, v[2:3]
	v_pk_mul_f32 v[134:135], v[176:177], v[136:137]
	s_nop 0
	v_pk_mul_f32 v[94:95], v[94:95], v[134:135]
	s_waitcnt vmcnt(9)
; __device__ __forceinline__ void unpack8(const u32x4 w, float* f) { f[0] = bf_lo(w.x); f[1] = bf_hi(w.x); f[2] = bf_lo(w.y); f[3] = bf_hi(w.y); f[4] = bf_lo(w.z); f[5] = bf_hi(w.z); f[6] = bf_lo(w.w); f[7] = bf_hi(w.w); }
;     __device__ __forceinline__ void mid(f32x4 (&acc)[2][2][4][2], const Unit& u, int wr, int wc, int fr, int fq) const {
;         const int row0 = u.pm * BM + wr * 64 + fr, col0 = u.pn * BM + wc * 32 + 8 * fq;
; #pragma unroll
;         for (int ai = 0; ai < 2; ++ai)
; #pragma unroll
;             for (int m = 0; m < 4; ++m) { int row = row0 + ai * HALF + m * 16; asm volatile("" : "+v"(row));
; #pragma unroll
;                 for (int bj = 0; bj < 2; ++bj) { const size_t off = (size_t)row * NPROJ + col0 + bj * HALF;
;                     float fa[8], fb[8]; unpack8(*(const u32x4*)(ga + off), fa); unpack8(*(const u32x4*)(gr + off), fb);
; #pragma unroll
;                     for (int j = 0; j < 8; ++j) { const float rt = (1.0f + __builtin_amdgcn_exp2f(fb[j] * -1.4426950408889634f)) * __builtin_amdgcn_rcpf(1.0f + __builtin_amdgcn_exp2f(fa[j] * -1.4426950408889634f));
;                         if (j < 4) acc[ai][bj][m][0][j] *= rt; else acc[ai][bj][m][1][j - 4] *= rt; } }
;                 asm volatile("" ::: "memory"); }
;     }
	v_mov_b64_e32 v[132:133], v[222:223]
	v_mov_b64_e32 v[134:135], v[224:225]
	v_lshlrev_b32_e32 v155, 16, v134
	v_and_b32_e32 v157, 0xffff0000, v134
	v_lshlrev_b32_e32 v159, 16, v135
	v_and_b32_e32 v161, 0xffff0000, v135
	s_waitcnt vmcnt(8)
	v_mov_b64_e32 v[134:135], v[226:227]
	v_mov_b64_e32 v[136:137], v[228:229]
	v_mad_i64_i32 v[230:231], s[98:99], v154, s57, v[164:165]
	v_lshlrev_b64 v[230:231], 1, v[230:231]
	v_lshl_add_u64 v[236:237], s[96:97], 0, v[230:231]
	v_lshl_add_u64 v[238:239], s[40:41], 0, v[230:231]
	global_load_dwordx4 v[214:217], v[236:237], off
	global_load_dwordx4 v[218:221], v[238:239], off
	global_load_dwordx4 v[222:225], v[236:237], off offset:256
	global_load_dwordx4 v[226:229], v[238:239], off offset:256
	v_and_b32_e32 v0, 0xffff0000, v132
	v_mul_f32_e32 v0, 0xbfb8aa3b, v0
	v_exp_f32_e32 v0, v0
	v_lshlrev_b32_e32 v151, 16, v133
	v_and_b32_e32 v153, 0xffff0000, v133
	v_lshlrev_b32_e32 v132, 16, v132
	v_add_f32_e32 v0, 1.0, v0
	v_rcp_f32_e32 v133, v0
	v_mul_f32_e32 v132, 0xbfb8aa3b, v132
	v_exp_f32_e32 v132, v132
	v_lshlrev_b32_e32 v163, 16, v135
	v_mul_f32_e32 v0, 0xbfb8aa3b, v163
	v_and_b32_e32 v3, 0xffff0000, v134
	v_lshlrev_b32_e32 v2, 16, v134
	v_exp_f32_e32 v134, v0
	v_mul_f32_e32 v0, 0xbfb8aa3b, v151
	v_exp_f32_e32 v0, v0
	v_and_b32_e32 v135, 0xffff0000, v135
	v_lshlrev_b32_e32 v167, 16, v136
	v_and_b32_e32 v176, 0xffff0000, v136
	v_add_f32_e32 v0, 1.0, v0
	v_rcp_f32_e32 v136, v0
	v_mul_f32_e32 v0, 0xbfb8aa3b, v135
	v_mul_f32_e32 v2, 0xbfb8aa3b, v2
	v_mul_f32_e32 v3, 0xbfb8aa3b, v3
	v_exp_f32_e32 v135, v0
	v_mul_f32_e32 v0, 0xbfb8aa3b, v153
	v_exp_f32_e32 v2, v2
	v_add_f32_e32 v132, 1.0, v132
	v_exp_f32_e32 v3, v3
	v_exp_f32_e32 v0, v0
	v_rcp_f32_e32 v132, v132
	v_lshlrev_b32_e32 v177, 16, v137
	v_pk_add_f32 v[2:3], v[2:3], 1.0 op_sel_hi:[1,0]
	v_add_f32_e32 v0, 1.0, v0
	v_and_b32_e32 v178, 0xffff0000, v137
	v_rcp_f32_e32 v137, v0
	v_pk_mul_f32 v[2:3], v[2:3], v[132:133]
	v_mul_f32_e32 v0, 0xbfb8aa3b, v167
	v_pk_mul_f32 v[88:89], v[88:89], v[2:3]
	v_exp_f32_e32 v2, v0
	v_mul_f32_e32 v0, 0xbfb8aa3b, v155
	v_exp_f32_e32 v0, v0
	v_pk_add_f32 v[134:135], v[134:135], 1.0 op_sel_hi:[1,0]
	v_add_f32_e32 v0, 1.0, v0
	v_pk_mul_f32 v[132:133], v[134:135], v[136:137]
	s_nop 0
	v_pk_mul_f32 v[90:91], v[90:91], v[132:133]
	v_rcp_f32_e32 v132, v0
	v_mul_f32_e32 v0, 0xbfb8aa3b, v176
	v_exp_f32_e32 v3, v0
	v_mul_f32_e32 v0, 0xbfb8aa3b, v157
	v_exp_f32_e32 v0, v0
	v_pk_add_f32 v[2:3], v[2:3], 1.0 op_sel_hi:[1,0]
	v_add_f32_e32 v0, 1.0, v0
	v_rcp_f32_e32 v133, v0
	v_mul_f32_e32 v0, 0xbfb8aa3b, v177
	v_exp_f32_e32 v134, v0
	v_mul_f32_e32 v0, 0xbfb8aa3b, v159
	v_exp_f32_e32 v0, v0
	v_pk_mul_f32 v[2:3], v[2:3], v[132:133]
	v_add_f32_e32 v0, 1.0, v0
	v_rcp_f32_e32 v136, v0
	v_mul_f32_e32 v0, 0xbfb8aa3b, v178
	v_exp_f32_e32 v135, v0
	v_mul_f32_e32 v0, 0xbfb8aa3b, v161
	v_exp_f32_e32 v0, v0
	v_pk_mul_f32 v[84:85], v[84:85], v[2:3]
	v_pk_add_f32 v[134:135], v[134:135], 1.0 op_sel_hi:[1,0]
	v_add_f32_e32 v0, 1.0, v0
	v_rcp_f32_e32 v137, v0
	v_mov_b32_e32 v0, v158
	v_pk_mul_f32 v[132:133], v[134:135], v[136:137]
	v_mad_i64_i32 v[2:3], s[10:11], v0, s57, v[164:165]
	v_lshlrev_b64 v[2:3], 1, v[2:3]
	v_pk_mul_f32 v[86:87], v[86:87], v[132:133]
	v_lshl_add_u64 v[132:133], s[96:97], 0, v[2:3]
	s_waitcnt vmcnt(11)
	v_mov_b64_e32 v[132:133], v[182:183]
	v_mov_b64_e32 v[134:135], v[184:185]
	v_lshlrev_b32_e32 v155, 16, v134
	v_and_b32_e32 v157, 0xffff0000, v134
	v_lshlrev_b32_e32 v159, 16, v135
	v_and_b32_e32 v161, 0xffff0000, v135
	v_lshl_add_u64 v[134:135], s[40:41], 0, v[2:3]
	s_waitcnt vmcnt(10)
	v_mov_b64_e32 v[134:135], v[186:187]
	v_mov_b64_e32 v[136:137], v[188:189]
	v_and_b32_e32 v0, 0xffff0000, v132
	v_mul_f32_e32 v0, 0xbfb8aa3b, v0
	v_exp_f32_e32 v0, v0
	v_lshlrev_b32_e32 v151, 16, v133
	v_and_b32_e32 v153, 0xffff0000, v133
	v_or_b32_e32 v2, 0x100, v2
	v_add_f32_e32 v0, 1.0, v0
	v_lshlrev_b32_e32 v163, 16, v135
	v_and_b32_e32 v167, 0xffff0000, v135
	v_lshlrev_b32_e32 v135, 16, v132
	v_and_b32_e32 v133, 0xffff0000, v134
	v_lshlrev_b32_e32 v132, 16, v134
	v_mul_f32_e32 v134, 0xbfb8aa3b, v135
	v_rcp_f32_e32 v135, v0
	v_mul_f32_e32 v0, 0xbfb8aa3b, v163
	v_lshlrev_b32_e32 v178, 16, v136
	v_and_b32_e32 v179, 0xffff0000, v136
	v_exp_f32_e32 v136, v0
	v_mul_f32_e32 v0, 0xbfb8aa3b, v151
	v_exp_f32_e32 v0, v0
	v_exp_f32_e32 v134, v134
	v_lshlrev_b32_e32 v180, 16, v137
	v_and_b32_e32 v181, 0xffff0000, v137
	v_add_f32_e32 v0, 1.0, v0
	v_rcp_f32_e32 v176, v0
	v_mul_f32_e32 v0, 0xbfb8aa3b, v167
	v_mul_f32_e32 v132, 0xbfb8aa3b, v132
	v_mul_f32_e32 v133, 0xbfb8aa3b, v133
	v_exp_f32_e32 v137, v0
	v_mul_f32_e32 v0, 0xbfb8aa3b, v153
	v_exp_f32_e32 v132, v132
	v_add_f32_e32 v134, 1.0, v134
	v_exp_f32_e32 v133, v133
	v_exp_f32_e32 v0, v0
	v_rcp_f32_e32 v134, v134
	v_pk_add_f32 v[136:137], v[136:137], 1.0 op_sel_hi:[1,0]
	v_pk_add_f32 v[132:133], v[132:133], 1.0 op_sel_hi:[1,0]
	v_add_f32_e32 v0, 1.0, v0
	v_rcp_f32_e32 v177, v0
	v_pk_mul_f32 v[132:133], v[134:135], v[132:133]
	v_mul_f32_e32 v0, 0xbfb8aa3b, v178
	v_pk_mul_f32 v[80:81], v[80:81], v[132:133]
	v_exp_f32_e32 v132, v0
	v_mul_f32_e32 v0, 0xbfb8aa3b, v155
	v_exp_f32_e32 v0, v0
	v_pk_mul_f32 v[134:135], v[176:177], v[136:137]
	v_add_f32_e32 v0, 1.0, v0
	v_pk_mul_f32 v[82:83], v[82:83], v[134:135]
	v_rcp_f32_e32 v134, v0
	v_mul_f32_e32 v0, 0xbfb8aa3b, v179
	v_exp_f32_e32 v133, v0
	v_mul_f32_e32 v0, 0xbfb8aa3b, v157
	v_exp_f32_e32 v0, v0
	v_pk_add_f32 v[132:133], v[132:133], 1.0 op_sel_hi:[1,0]
	v_add_f32_e32 v0, 1.0, v0
	v_rcp_f32_e32 v135, v0
	v_mul_f32_e32 v0, 0xbfb8aa3b, v180
	v_exp_f32_e32 v136, v0
	v_mul_f32_e32 v0, 0xbfb8aa3b, v159
	v_exp_f32_e32 v0, v0
	v_pk_mul_f32 v[132:133], v[134:135], v[132:133]
	v_add_f32_e32 v0, 1.0, v0
	v_rcp_f32_e32 v176, v0
	v_mul_f32_e32 v0, 0xbfb8aa3b, v181
	v_exp_f32_e32 v137, v0
	v_mul_f32_e32 v0, 0xbfb8aa3b, v161
	v_exp_f32_e32 v0, v0
	v_pk_mul_f32 v[76:77], v[76:77], v[132:133]
	v_pk_add_f32 v[136:137], v[136:137], 1.0 op_sel_hi:[1,0]
	v_lshl_add_u64 v[132:133], s[96:97], 0, v[2:3]
	v_add_f32_e32 v0, 1.0, v0
	v_rcp_f32_e32 v177, v0
	v_lshl_add_u64 v[2:3], s[40:41], 0, v[2:3]
	v_pk_mul_f32 v[134:135], v[176:177], v[136:137]
	s_nop 0
	v_pk_mul_f32 v[78:79], v[78:79], v[134:135]
	s_waitcnt vmcnt(9)
; __device__ __forceinline__ void unpack8(const u32x4 w, float* f) { f[0] = bf_lo(w.x); f[1] = bf_hi(w.x); f[2] = bf_lo(w.y); f[3] = bf_hi(w.y); f[4] = bf_lo(w.z); f[5] = bf_hi(w.z); f[6] = bf_lo(w.w); f[7] = bf_hi(w.w); }
;     __device__ __forceinline__ void mid(f32x4 (&acc)[2][2][4][2], const Unit& u, int wr, int wc, int fr, int fq) const {
;         const int row0 = u.pm * BM + wr * 64 + fr, col0 = u.pn * BM + wc * 32 + 8 * fq;
; #pragma unroll
;         for (int ai = 0; ai < 2; ++ai)
; #pragma unroll
;             for (int m = 0; m < 4; ++m) { int row = row0 + ai * HALF + m * 16; asm volatile("" : "+v"(row));
; #pragma unroll
;                 for (int bj = 0; bj < 2; ++bj) { const size_t off = (size_t)row * NPROJ + col0 + bj * HALF;
;                     float fa[8], fb[8]; unpack8(*(const u32x4*)(ga + off), fa); unpack8(*(const u32x4*)(gr + off), fb);
; #pragma unroll
;                     for (int j = 0; j < 8; ++j) { const float rt = (1.0f + __builtin_amdgcn_exp2f(fb[j] * -1.4426950408889634f)) * __builtin_amdgcn_rcpf(1.0f + __builtin_amdgcn_exp2f(fa[j] * -1.4426950408889634f));
;                         if (j < 4) acc[ai][bj][m][0][j] *= rt; else acc[ai][bj][m][1][j - 4] *= rt; } }
;                 asm volatile("" ::: "memory"); }
;     }
	v_mov_b64_e32 v[132:133], v[190:191]
	v_mov_b64_e32 v[134:135], v[192:193]
	v_lshlrev_b32_e32 v155, 16, v134
	v_and_b32_e32 v157, 0xffff0000, v134
	v_lshlrev_b32_e32 v159, 16, v135
	v_and_b32_e32 v161, 0xffff0000, v135
	s_waitcnt vmcnt(8)
	v_mov_b64_e32 v[134:135], v[194:195]
	v_mov_b64_e32 v[136:137], v[196:197]
	v_mad_i64_i32 v[230:231], s[98:99], v152, s57, v[164:165]
	v_lshlrev_b64 v[230:231], 1, v[230:231]
	v_lshl_add_u64 v[236:237], s[96:97], 0, v[230:231]
	v_lshl_add_u64 v[238:239], s[40:41], 0, v[230:231]
	global_load_dwordx4 v[182:185], v[236:237], off
	global_load_dwordx4 v[186:189], v[238:239], off
	global_load_dwordx4 v[190:193], v[236:237], off offset:256
	global_load_dwordx4 v[194:197], v[238:239], off offset:256
	v_and_b32_e32 v0, 0xffff0000, v132
	v_mul_f32_e32 v0, 0xbfb8aa3b, v0
	v_exp_f32_e32 v0, v0
	v_lshlrev_b32_e32 v151, 16, v133
	v_and_b32_e32 v153, 0xffff0000, v133
	v_lshlrev_b32_e32 v132, 16, v132
	v_add_f32_e32 v0, 1.0, v0
	v_rcp_f32_e32 v133, v0
	v_mul_f32_e32 v132, 0xbfb8aa3b, v132
	v_exp_f32_e32 v132, v132
	v_lshlrev_b32_e32 v163, 16, v135
	v_mul_f32_e32 v0, 0xbfb8aa3b, v163
	v_and_b32_e32 v3, 0xffff0000, v134
	v_lshlrev_b32_e32 v2, 16, v134
	v_exp_f32_e32 v134, v0
	v_mul_f32_e32 v0, 0xbfb8aa3b, v151
	v_exp_f32_e32 v0, v0
	v_and_b32_e32 v135, 0xffff0000, v135
	v_lshlrev_b32_e32 v167, 16, v136
	v_and_b32_e32 v176, 0xffff0000, v136
	v_add_f32_e32 v0, 1.0, v0
	v_rcp_f32_e32 v136, v0
	v_mul_f32_e32 v0, 0xbfb8aa3b, v135
	v_mul_f32_e32 v2, 0xbfb8aa3b, v2
	v_mul_f32_e32 v3, 0xbfb8aa3b, v3
	v_exp_f32_e32 v135, v0
	v_mul_f32_e32 v0, 0xbfb8aa3b, v153
	v_exp_f32_e32 v2, v2
	v_add_f32_e32 v132, 1.0, v132
	v_exp_f32_e32 v3, v3
	v_exp_f32_e32 v0, v0
	v_rcp_f32_e32 v132, v132
	v_lshlrev_b32_e32 v177, 16, v137
	v_pk_add_f32 v[2:3], v[2:3], 1.0 op_sel_hi:[1,0]
	v_add_f32_e32 v0, 1.0, v0
	v_and_b32_e32 v178, 0xffff0000, v137
	v_rcp_f32_e32 v137, v0
	v_pk_mul_f32 v[2:3], v[2:3], v[132:133]
	v_mul_f32_e32 v0, 0xbfb8aa3b, v167
	v_pk_mul_f32 v[72:73], v[72:73], v[2:3]
	v_exp_f32_e32 v2, v0
	v_mul_f32_e32 v0, 0xbfb8aa3b, v155
	v_exp_f32_e32 v0, v0
	v_pk_add_f32 v[134:135], v[134:135], 1.0 op_sel_hi:[1,0]
	v_add_f32_e32 v0, 1.0, v0
	v_pk_mul_f32 v[132:133], v[134:135], v[136:137]
	s_nop 0
	v_pk_mul_f32 v[74:75], v[74:75], v[132:133]
	v_rcp_f32_e32 v132, v0
	v_mul_f32_e32 v0, 0xbfb8aa3b, v176
	v_exp_f32_e32 v3, v0
	v_mul_f32_e32 v0, 0xbfb8aa3b, v157
	v_exp_f32_e32 v0, v0
	v_pk_add_f32 v[2:3], v[2:3], 1.0 op_sel_hi:[1,0]
	v_add_f32_e32 v0, 1.0, v0
	v_rcp_f32_e32 v133, v0
	v_mul_f32_e32 v0, 0xbfb8aa3b, v177
	v_exp_f32_e32 v134, v0
	v_mul_f32_e32 v0, 0xbfb8aa3b, v159
	v_exp_f32_e32 v0, v0
	v_pk_mul_f32 v[2:3], v[2:3], v[132:133]
	v_add_f32_e32 v0, 1.0, v0
	v_rcp_f32_e32 v136, v0
	v_mul_f32_e32 v0, 0xbfb8aa3b, v178
	v_exp_f32_e32 v135, v0
	v_mul_f32_e32 v0, 0xbfb8aa3b, v161
	v_exp_f32_e32 v0, v0
	v_pk_mul_f32 v[68:69], v[68:69], v[2:3]
	v_pk_add_f32 v[134:135], v[134:135], 1.0 op_sel_hi:[1,0]
	v_add_f32_e32 v0, 1.0, v0
	v_rcp_f32_e32 v137, v0
	v_mov_b32_e32 v0, v156
	v_pk_mul_f32 v[132:133], v[134:135], v[136:137]
	v_mad_i64_i32 v[2:3], s[10:11], v0, s57, v[164:165]
	v_lshlrev_b64 v[2:3], 1, v[2:3]
	v_pk_mul_f32 v[70:71], v[70:71], v[132:133]
	v_lshl_add_u64 v[132:133], s[96:97], 0, v[2:3]
	s_waitcnt vmcnt(11)
	v_mov_b64_e32 v[132:133], v[198:199]
	v_mov_b64_e32 v[134:135], v[200:201]
	v_lshlrev_b32_e32 v155, 16, v134
	v_and_b32_e32 v157, 0xffff0000, v134
	v_lshlrev_b32_e32 v159, 16, v135
	v_and_b32_e32 v161, 0xffff0000, v135
	v_lshl_add_u64 v[134:135], s[40:41], 0, v[2:3]
	s_waitcnt vmcnt(10)
	v_mov_b64_e32 v[134:135], v[202:203]
	v_mov_b64_e32 v[136:137], v[204:205]
	v_and_b32_e32 v0, 0xffff0000, v132
	v_mul_f32_e32 v0, 0xbfb8aa3b, v0
	v_exp_f32_e32 v0, v0
	v_lshlrev_b32_e32 v151, 16, v133
	v_and_b32_e32 v153, 0xffff0000, v133
	v_or_b32_e32 v2, 0x100, v2
	v_add_f32_e32 v0, 1.0, v0
	v_lshlrev_b32_e32 v163, 16, v135
	v_and_b32_e32 v167, 0xffff0000, v135
	v_lshlrev_b32_e32 v135, 16, v132
	v_and_b32_e32 v133, 0xffff0000, v134
	v_lshlrev_b32_e32 v132, 16, v134
	v_mul_f32_e32 v134, 0xbfb8aa3b, v135
	v_rcp_f32_e32 v135, v0
	v_mul_f32_e32 v0, 0xbfb8aa3b, v163
	v_lshlrev_b32_e32 v178, 16, v136
	v_and_b32_e32 v179, 0xffff0000, v136
	v_exp_f32_e32 v136, v0
	v_mul_f32_e32 v0, 0xbfb8aa3b, v151
	v_exp_f32_e32 v0, v0
	v_exp_f32_e32 v134, v134
	v_lshlrev_b32_e32 v180, 16, v137
	v_and_b32_e32 v181, 0xffff0000, v137
	v_add_f32_e32 v0, 1.0, v0
	v_rcp_f32_e32 v176, v0
	v_mul_f32_e32 v0, 0xbfb8aa3b, v167
	v_mul_f32_e32 v132, 0xbfb8aa3b, v132
	v_mul_f32_e32 v133, 0xbfb8aa3b, v133
	v_exp_f32_e32 v137, v0
	v_mul_f32_e32 v0, 0xbfb8aa3b, v153
	v_exp_f32_e32 v132, v132
	v_add_f32_e32 v134, 1.0, v134
	v_exp_f32_e32 v133, v133
	v_exp_f32_e32 v0, v0
	v_rcp_f32_e32 v134, v134
	v_pk_add_f32 v[136:137], v[136:137], 1.0 op_sel_hi:[1,0]
	v_pk_add_f32 v[132:133], v[132:133], 1.0 op_sel_hi:[1,0]
	v_add_f32_e32 v0, 1.0, v0
	v_rcp_f32_e32 v177, v0
	v_pk_mul_f32 v[132:133], v[134:135], v[132:133]
	v_mul_f32_e32 v0, 0xbfb8aa3b, v178
	v_pk_mul_f32 v[64:65], v[64:65], v[132:133]
	v_exp_f32_e32 v132, v0
	v_mul_f32_e32 v0, 0xbfb8aa3b, v155
	v_exp_f32_e32 v0, v0
	v_pk_mul_f32 v[134:135], v[176:177], v[136:137]
	v_add_f32_e32 v0, 1.0, v0
	v_pk_mul_f32 v[66:67], v[66:67], v[134:135]
	v_rcp_f32_e32 v134, v0
	v_mul_f32_e32 v0, 0xbfb8aa3b, v179
	v_exp_f32_e32 v133, v0
	v_mul_f32_e32 v0, 0xbfb8aa3b, v157
	v_exp_f32_e32 v0, v0
	v_pk_add_f32 v[132:133], v[132:133], 1.0 op_sel_hi:[1,0]
	v_add_f32_e32 v0, 1.0, v0
	v_rcp_f32_e32 v135, v0
	v_mul_f32_e32 v0, 0xbfb8aa3b, v180
	v_exp_f32_e32 v136, v0
	v_mul_f32_e32 v0, 0xbfb8aa3b, v159
	v_exp_f32_e32 v0, v0
	v_pk_mul_f32 v[132:133], v[134:135], v[132:133]
	v_add_f32_e32 v0, 1.0, v0
	v_rcp_f32_e32 v176, v0
	v_mul_f32_e32 v0, 0xbfb8aa3b, v181
	v_exp_f32_e32 v137, v0
	v_mul_f32_e32 v0, 0xbfb8aa3b, v161
	v_exp_f32_e32 v0, v0
	v_pk_mul_f32 v[60:61], v[60:61], v[132:133]
	v_pk_add_f32 v[136:137], v[136:137], 1.0 op_sel_hi:[1,0]
	v_lshl_add_u64 v[132:133], s[96:97], 0, v[2:3]
	v_add_f32_e32 v0, 1.0, v0
	v_rcp_f32_e32 v177, v0
	v_lshl_add_u64 v[2:3], s[40:41], 0, v[2:3]
	v_pk_mul_f32 v[134:135], v[176:177], v[136:137]
	s_nop 0
	v_pk_mul_f32 v[62:63], v[62:63], v[134:135]
	s_waitcnt vmcnt(9)
; __device__ __forceinline__ void unpack8(const u32x4 w, float* f) { f[0] = bf_lo(w.x); f[1] = bf_hi(w.x); f[2] = bf_lo(w.y); f[3] = bf_hi(w.y); f[4] = bf_lo(w.z); f[5] = bf_hi(w.z); f[6] = bf_lo(w.w); f[7] = bf_hi(w.w); }
;     __device__ __forceinline__ void mid(f32x4 (&acc)[2][2][4][2], const Unit& u, int wr, int wc, int fr, int fq) const {
;         const int row0 = u.pm * BM + wr * 64 + fr, col0 = u.pn * BM + wc * 32 + 8 * fq;
; #pragma unroll
;         for (int ai = 0; ai < 2; ++ai)
; #pragma unroll
;             for (int m = 0; m < 4; ++m) { int row = row0 + ai * HALF + m * 16; asm volatile("" : "+v"(row));
; #pragma unroll
;                 for (int bj = 0; bj < 2; ++bj) { const size_t off = (size_t)row * NPROJ + col0 + bj * HALF;
;                     float fa[8], fb[8]; unpack8(*(const u32x4*)(ga + off), fa); unpack8(*(const u32x4*)(gr + off), fb);
; #pragma unroll
;                     for (int j = 0; j < 8; ++j) { const float rt = (1.0f + __builtin_amdgcn_exp2f(fb[j] * -1.4426950408889634f)) * __builtin_amdgcn_rcpf(1.0f + __builtin_amdgcn_exp2f(fa[j] * -1.4426950408889634f));
;                         if (j < 4) acc[ai][bj][m][0][j] *= rt; else acc[ai][bj][m][1][j - 4] *= rt; } }
;                 asm volatile("" ::: "memory"); }
;     }
	v_mov_b64_e32 v[132:133], v[206:207]
	v_mov_b64_e32 v[134:135], v[208:209]
	v_lshlrev_b32_e32 v155, 16, v134
	v_and_b32_e32 v157, 0xffff0000, v134
	v_lshlrev_b32_e32 v159, 16, v135
	v_and_b32_e32 v161, 0xffff0000, v135
	s_waitcnt vmcnt(8)
	v_mov_b64_e32 v[134:135], v[210:211]
	v_mov_b64_e32 v[136:137], v[212:213]
	v_mad_i64_i32 v[230:231], s[98:99], v150, s57, v[164:165]
	v_lshlrev_b64 v[230:231], 1, v[230:231]
	v_lshl_add_u64 v[236:237], s[96:97], 0, v[230:231]
	v_lshl_add_u64 v[238:239], s[40:41], 0, v[230:231]
	global_load_dwordx4 v[198:201], v[236:237], off
	global_load_dwordx4 v[202:205], v[238:239], off
	global_load_dwordx4 v[206:209], v[236:237], off offset:256
	global_load_dwordx4 v[210:213], v[238:239], off offset:256
	v_and_b32_e32 v0, 0xffff0000, v132
	v_mul_f32_e32 v0, 0xbfb8aa3b, v0
	v_exp_f32_e32 v0, v0
	v_lshlrev_b32_e32 v151, 16, v133
	v_and_b32_e32 v153, 0xffff0000, v133
	v_lshlrev_b32_e32 v132, 16, v132
	v_add_f32_e32 v0, 1.0, v0
	v_rcp_f32_e32 v133, v0
	v_mul_f32_e32 v132, 0xbfb8aa3b, v132
	v_exp_f32_e32 v132, v132
	v_lshlrev_b32_e32 v163, 16, v135
	v_mul_f32_e32 v0, 0xbfb8aa3b, v163
	v_and_b32_e32 v3, 0xffff0000, v134
	v_lshlrev_b32_e32 v2, 16, v134
	v_exp_f32_e32 v134, v0
	v_mul_f32_e32 v0, 0xbfb8aa3b, v151
	v_exp_f32_e32 v0, v0
	v_and_b32_e32 v135, 0xffff0000, v135
	v_lshlrev_b32_e32 v167, 16, v136
	v_and_b32_e32 v176, 0xffff0000, v136
	v_add_f32_e32 v0, 1.0, v0
	v_rcp_f32_e32 v136, v0
	v_mul_f32_e32 v0, 0xbfb8aa3b, v135
	v_mul_f32_e32 v2, 0xbfb8aa3b, v2
	v_mul_f32_e32 v3, 0xbfb8aa3b, v3
	v_exp_f32_e32 v135, v0
	v_mul_f32_e32 v0, 0xbfb8aa3b, v153
	v_exp_f32_e32 v2, v2
	v_add_f32_e32 v132, 1.0, v132
	v_exp_f32_e32 v3, v3
	v_exp_f32_e32 v0, v0
	v_rcp_f32_e32 v132, v132
	v_lshlrev_b32_e32 v177, 16, v137
	v_pk_add_f32 v[2:3], v[2:3], 1.0 op_sel_hi:[1,0]
	v_add_f32_e32 v0, 1.0, v0
	v_and_b32_e32 v178, 0xffff0000, v137
	v_rcp_f32_e32 v137, v0
	v_pk_mul_f32 v[2:3], v[2:3], v[132:133]
	v_mul_f32_e32 v0, 0xbfb8aa3b, v167
	v_pk_mul_f32 v[56:57], v[56:57], v[2:3]
	v_exp_f32_e32 v2, v0
	v_mul_f32_e32 v0, 0xbfb8aa3b, v155
	v_exp_f32_e32 v0, v0
	v_pk_add_f32 v[134:135], v[134:135], 1.0 op_sel_hi:[1,0]
	v_add_f32_e32 v0, 1.0, v0
	v_pk_mul_f32 v[132:133], v[134:135], v[136:137]
	s_nop 0
	v_pk_mul_f32 v[58:59], v[58:59], v[132:133]
	v_rcp_f32_e32 v132, v0
	v_mul_f32_e32 v0, 0xbfb8aa3b, v176
	v_exp_f32_e32 v3, v0
	v_mul_f32_e32 v0, 0xbfb8aa3b, v157
	v_exp_f32_e32 v0, v0
	v_pk_add_f32 v[2:3], v[2:3], 1.0 op_sel_hi:[1,0]
	v_add_f32_e32 v0, 1.0, v0
	v_rcp_f32_e32 v133, v0
	v_mul_f32_e32 v0, 0xbfb8aa3b, v177
	v_exp_f32_e32 v134, v0
	v_mul_f32_e32 v0, 0xbfb8aa3b, v159
	v_exp_f32_e32 v0, v0
	v_pk_mul_f32 v[2:3], v[2:3], v[132:133]
	v_add_f32_e32 v0, 1.0, v0
	v_rcp_f32_e32 v136, v0
	v_mul_f32_e32 v0, 0xbfb8aa3b, v178
	v_exp_f32_e32 v135, v0
	v_mul_f32_e32 v0, 0xbfb8aa3b, v161
	v_exp_f32_e32 v0, v0
	v_pk_mul_f32 v[52:53], v[52:53], v[2:3]
	v_pk_add_f32 v[134:135], v[134:135], 1.0 op_sel_hi:[1,0]
	v_add_f32_e32 v0, 1.0, v0
	v_rcp_f32_e32 v137, v0
	v_mov_b32_e32 v0, v154
	v_pk_mul_f32 v[132:133], v[134:135], v[136:137]
	v_mad_i64_i32 v[2:3], s[10:11], v0, s57, v[164:165]
	v_lshlrev_b64 v[2:3], 1, v[2:3]
	v_pk_mul_f32 v[54:55], v[54:55], v[132:133]
	v_lshl_add_u64 v[132:133], s[96:97], 0, v[2:3]
	s_waitcnt vmcnt(11)
	v_mov_b64_e32 v[132:133], v[214:215]
	v_mov_b64_e32 v[134:135], v[216:217]
	v_lshlrev_b32_e32 v155, 16, v134
	v_and_b32_e32 v157, 0xffff0000, v134
	v_lshlrev_b32_e32 v159, 16, v135
	v_and_b32_e32 v161, 0xffff0000, v135
	v_lshl_add_u64 v[134:135], s[40:41], 0, v[2:3]
	s_waitcnt vmcnt(10)
	v_mov_b64_e32 v[134:135], v[218:219]
	v_mov_b64_e32 v[136:137], v[220:221]
	v_and_b32_e32 v0, 0xffff0000, v132
	v_mul_f32_e32 v0, 0xbfb8aa3b, v0
	v_exp_f32_e32 v0, v0
	v_lshlrev_b32_e32 v151, 16, v133
	v_and_b32_e32 v153, 0xffff0000, v133
	v_or_b32_e32 v2, 0x100, v2
	v_add_f32_e32 v0, 1.0, v0
	v_lshlrev_b32_e32 v163, 16, v135
	v_and_b32_e32 v167, 0xffff0000, v135
	v_lshlrev_b32_e32 v135, 16, v132
	v_and_b32_e32 v133, 0xffff0000, v134
	v_lshlrev_b32_e32 v132, 16, v134
	v_mul_f32_e32 v134, 0xbfb8aa3b, v135
	v_rcp_f32_e32 v135, v0
	v_mul_f32_e32 v0, 0xbfb8aa3b, v163
	v_lshlrev_b32_e32 v178, 16, v136
	v_and_b32_e32 v179, 0xffff0000, v136
	v_exp_f32_e32 v136, v0
	v_mul_f32_e32 v0, 0xbfb8aa3b, v151
	v_exp_f32_e32 v0, v0
	v_exp_f32_e32 v134, v134
	v_lshlrev_b32_e32 v180, 16, v137
	v_and_b32_e32 v181, 0xffff0000, v137
	v_add_f32_e32 v0, 1.0, v0
	v_rcp_f32_e32 v176, v0
	v_mul_f32_e32 v0, 0xbfb8aa3b, v167
	v_mul_f32_e32 v132, 0xbfb8aa3b, v132
	v_mul_f32_e32 v133, 0xbfb8aa3b, v133
	v_exp_f32_e32 v137, v0
	v_mul_f32_e32 v0, 0xbfb8aa3b, v153
	v_exp_f32_e32 v132, v132
	v_add_f32_e32 v134, 1.0, v134
	v_exp_f32_e32 v133, v133
	v_exp_f32_e32 v0, v0
	v_rcp_f32_e32 v134, v134
	v_pk_add_f32 v[136:137], v[136:137], 1.0 op_sel_hi:[1,0]
	v_pk_add_f32 v[132:133], v[132:133], 1.0 op_sel_hi:[1,0]
	v_add_f32_e32 v0, 1.0, v0
	v_rcp_f32_e32 v177, v0
	v_pk_mul_f32 v[132:133], v[134:135], v[132:133]
	v_mul_f32_e32 v0, 0xbfb8aa3b, v178
	v_pk_mul_f32 v[48:49], v[48:49], v[132:133]
	v_exp_f32_e32 v132, v0
	v_mul_f32_e32 v0, 0xbfb8aa3b, v155
	v_exp_f32_e32 v0, v0
	v_pk_mul_f32 v[134:135], v[176:177], v[136:137]
	v_add_f32_e32 v0, 1.0, v0
	v_pk_mul_f32 v[50:51], v[50:51], v[134:135]
	v_rcp_f32_e32 v134, v0
	v_mul_f32_e32 v0, 0xbfb8aa3b, v179
	v_exp_f32_e32 v133, v0
	v_mul_f32_e32 v0, 0xbfb8aa3b, v157
	v_exp_f32_e32 v0, v0
	v_pk_add_f32 v[132:133], v[132:133], 1.0 op_sel_hi:[1,0]
	v_add_f32_e32 v0, 1.0, v0
	v_rcp_f32_e32 v135, v0
	v_mul_f32_e32 v0, 0xbfb8aa3b, v180
	v_exp_f32_e32 v136, v0
	v_mul_f32_e32 v0, 0xbfb8aa3b, v159
	v_exp_f32_e32 v0, v0
	v_pk_mul_f32 v[132:133], v[134:135], v[132:133]
	v_add_f32_e32 v0, 1.0, v0
	v_rcp_f32_e32 v176, v0
	v_mul_f32_e32 v0, 0xbfb8aa3b, v181
	v_exp_f32_e32 v137, v0
	v_mul_f32_e32 v0, 0xbfb8aa3b, v161
	v_exp_f32_e32 v0, v0
	v_pk_mul_f32 v[44:45], v[44:45], v[132:133]
	v_pk_add_f32 v[136:137], v[136:137], 1.0 op_sel_hi:[1,0]
	v_lshl_add_u64 v[132:133], s[96:97], 0, v[2:3]
	v_add_f32_e32 v0, 1.0, v0
	v_rcp_f32_e32 v177, v0
	v_lshl_add_u64 v[2:3], s[40:41], 0, v[2:3]
	v_pk_mul_f32 v[134:135], v[176:177], v[136:137]
	s_nop 0
	v_pk_mul_f32 v[46:47], v[46:47], v[134:135]
	s_waitcnt vmcnt(9)
; __device__ __forceinline__ void unpack8(const u32x4 w, float* f) { f[0] = bf_lo(w.x); f[1] = bf_hi(w.x); f[2] = bf_lo(w.y); f[3] = bf_hi(w.y); f[4] = bf_lo(w.z); f[5] = bf_hi(w.z); f[6] = bf_lo(w.w); f[7] = bf_hi(w.w); }
;     __device__ __forceinline__ void mid(f32x4 (&acc)[2][2][4][2], const Unit& u, int wr, int wc, int fr, int fq) const {
;         const int row0 = u.pm * BM + wr * 64 + fr, col0 = u.pn * BM + wc * 32 + 8 * fq;
; #pragma unroll
;         for (int ai = 0; ai < 2; ++ai)
; #pragma unroll
;             for (int m = 0; m < 4; ++m) { int row = row0 + ai * HALF + m * 16; asm volatile("" : "+v"(row));
; #pragma unroll
;                 for (int bj = 0; bj < 2; ++bj) { const size_t off = (size_t)row * NPROJ + col0 + bj * HALF;
;                     float fa[8], fb[8]; unpack8(*(const u32x4*)(ga + off), fa); unpack8(*(const u32x4*)(gr + off), fb);
; #pragma unroll
;                     for (int j = 0; j < 8; ++j) { const float rt = (1.0f + __builtin_amdgcn_exp2f(fb[j] * -1.4426950408889634f)) * __builtin_amdgcn_rcpf(1.0f + __builtin_amdgcn_exp2f(fa[j] * -1.4426950408889634f));
;                         if (j < 4) acc[ai][bj][m][0][j] *= rt; else acc[ai][bj][m][1][j - 4] *= rt; } }
;                 asm volatile("" ::: "memory"); }
;     }
	v_mov_b64_e32 v[132:133], v[222:223]
	v_mov_b64_e32 v[134:135], v[224:225]
	v_lshlrev_b32_e32 v155, 16, v134
	v_and_b32_e32 v157, 0xffff0000, v134
	v_lshlrev_b32_e32 v159, 16, v135
	v_and_b32_e32 v161, 0xffff0000, v135
	s_waitcnt vmcnt(8)
	v_mov_b64_e32 v[134:135], v[226:227]
	v_mov_b64_e32 v[136:137], v[228:229]
	v_and_b32_e32 v0, 0xffff0000, v132
	v_mul_f32_e32 v0, 0xbfb8aa3b, v0
	v_exp_f32_e32 v0, v0
	v_lshlrev_b32_e32 v151, 16, v133
	v_and_b32_e32 v153, 0xffff0000, v133
	v_lshlrev_b32_e32 v132, 16, v132
	v_add_f32_e32 v0, 1.0, v0
	v_rcp_f32_e32 v133, v0
	v_mul_f32_e32 v132, 0xbfb8aa3b, v132
	v_exp_f32_e32 v132, v132
	v_lshlrev_b32_e32 v163, 16, v135
	v_mul_f32_e32 v0, 0xbfb8aa3b, v163
	v_and_b32_e32 v3, 0xffff0000, v134
	v_lshlrev_b32_e32 v2, 16, v134
	v_exp_f32_e32 v134, v0
	v_mul_f32_e32 v0, 0xbfb8aa3b, v151
	v_exp_f32_e32 v0, v0
	v_and_b32_e32 v135, 0xffff0000, v135
	v_lshlrev_b32_e32 v167, 16, v136
	v_and_b32_e32 v176, 0xffff0000, v136
	v_add_f32_e32 v0, 1.0, v0
	v_rcp_f32_e32 v136, v0
	v_mul_f32_e32 v0, 0xbfb8aa3b, v135
	v_mul_f32_e32 v2, 0xbfb8aa3b, v2
	v_mul_f32_e32 v3, 0xbfb8aa3b, v3
	v_exp_f32_e32 v135, v0
	v_mul_f32_e32 v0, 0xbfb8aa3b, v153
	v_exp_f32_e32 v2, v2
	v_add_f32_e32 v132, 1.0, v132
	v_exp_f32_e32 v3, v3
	v_exp_f32_e32 v0, v0
	v_rcp_f32_e32 v132, v132
	v_lshlrev_b32_e32 v177, 16, v137
	v_pk_add_f32 v[2:3], v[2:3], 1.0 op_sel_hi:[1,0]
	v_add_f32_e32 v0, 1.0, v0
	v_and_b32_e32 v178, 0xffff0000, v137
	v_rcp_f32_e32 v137, v0
	v_pk_mul_f32 v[2:3], v[2:3], v[132:133]
	v_mul_f32_e32 v0, 0xbfb8aa3b, v167
	v_pk_mul_f32 v[40:41], v[40:41], v[2:3]
	v_exp_f32_e32 v2, v0
	v_mul_f32_e32 v0, 0xbfb8aa3b, v155
	v_exp_f32_e32 v0, v0
	v_pk_add_f32 v[134:135], v[134:135], 1.0 op_sel_hi:[1,0]
	v_add_f32_e32 v0, 1.0, v0
	v_pk_mul_f32 v[132:133], v[134:135], v[136:137]
	s_nop 0
	v_pk_mul_f32 v[42:43], v[42:43], v[132:133]
	v_rcp_f32_e32 v132, v0
	v_mul_f32_e32 v0, 0xbfb8aa3b, v176
	v_exp_f32_e32 v3, v0
	v_mul_f32_e32 v0, 0xbfb8aa3b, v157
	v_exp_f32_e32 v0, v0
	v_pk_add_f32 v[2:3], v[2:3], 1.0 op_sel_hi:[1,0]
	v_add_f32_e32 v0, 1.0, v0
	v_rcp_f32_e32 v133, v0
	v_mul_f32_e32 v0, 0xbfb8aa3b, v177
	v_exp_f32_e32 v134, v0
	v_mul_f32_e32 v0, 0xbfb8aa3b, v159
	v_exp_f32_e32 v0, v0
	v_pk_mul_f32 v[2:3], v[2:3], v[132:133]
	v_add_f32_e32 v0, 1.0, v0
	v_rcp_f32_e32 v136, v0
	v_mul_f32_e32 v0, 0xbfb8aa3b, v178
	v_exp_f32_e32 v135, v0
	v_mul_f32_e32 v0, 0xbfb8aa3b, v161
	v_exp_f32_e32 v0, v0
	v_pk_mul_f32 v[36:37], v[36:37], v[2:3]
	v_pk_add_f32 v[134:135], v[134:135], 1.0 op_sel_hi:[1,0]
	v_add_f32_e32 v0, 1.0, v0
	v_rcp_f32_e32 v137, v0
	v_mov_b32_e32 v0, v152
	v_pk_mul_f32 v[132:133], v[134:135], v[136:137]
	v_mad_i64_i32 v[2:3], s[10:11], v0, s57, v[164:165]
	v_lshlrev_b64 v[2:3], 1, v[2:3]
	v_pk_mul_f32 v[38:39], v[38:39], v[132:133]
	v_lshl_add_u64 v[132:133], s[96:97], 0, v[2:3]
	s_waitcnt vmcnt(7)
	v_mov_b64_e32 v[132:133], v[182:183]
	v_mov_b64_e32 v[134:135], v[184:185]
	v_lshlrev_b32_e32 v155, 16, v134
	v_and_b32_e32 v157, 0xffff0000, v134
	v_lshlrev_b32_e32 v159, 16, v135
	v_and_b32_e32 v161, 0xffff0000, v135
	v_lshl_add_u64 v[134:135], s[40:41], 0, v[2:3]
	s_waitcnt vmcnt(6)
	v_mov_b64_e32 v[134:135], v[186:187]
	v_mov_b64_e32 v[136:137], v[188:189]
	v_and_b32_e32 v0, 0xffff0000, v132
	v_mul_f32_e32 v0, 0xbfb8aa3b, v0
	v_exp_f32_e32 v0, v0
	v_lshlrev_b32_e32 v151, 16, v133
	v_and_b32_e32 v153, 0xffff0000, v133
	v_or_b32_e32 v2, 0x100, v2
	v_add_f32_e32 v0, 1.0, v0
	v_lshlrev_b32_e32 v163, 16, v135
	v_and_b32_e32 v167, 0xffff0000, v135
	v_lshlrev_b32_e32 v135, 16, v132
	v_and_b32_e32 v133, 0xffff0000, v134
	v_lshlrev_b32_e32 v132, 16, v134
	v_mul_f32_e32 v134, 0xbfb8aa3b, v135
	v_rcp_f32_e32 v135, v0
	v_mul_f32_e32 v0, 0xbfb8aa3b, v163
	v_lshlrev_b32_e32 v178, 16, v136
	v_and_b32_e32 v179, 0xffff0000, v136
	v_exp_f32_e32 v136, v0
	v_mul_f32_e32 v0, 0xbfb8aa3b, v151
	v_exp_f32_e32 v0, v0
	v_exp_f32_e32 v134, v134
	v_lshlrev_b32_e32 v180, 16, v137
	v_and_b32_e32 v181, 0xffff0000, v137
	v_add_f32_e32 v0, 1.0, v0
	v_rcp_f32_e32 v176, v0
	v_mul_f32_e32 v0, 0xbfb8aa3b, v167
	v_mul_f32_e32 v132, 0xbfb8aa3b, v132
	v_mul_f32_e32 v133, 0xbfb8aa3b, v133
	v_exp_f32_e32 v137, v0
	v_mul_f32_e32 v0, 0xbfb8aa3b, v153
	v_exp_f32_e32 v132, v132
	v_add_f32_e32 v134, 1.0, v134
	v_exp_f32_e32 v133, v133
	v_exp_f32_e32 v0, v0
	v_rcp_f32_e32 v134, v134
	v_pk_add_f32 v[136:137], v[136:137], 1.0 op_sel_hi:[1,0]
	v_pk_add_f32 v[132:133], v[132:133], 1.0 op_sel_hi:[1,0]
	v_add_f32_e32 v0, 1.0, v0
	v_rcp_f32_e32 v177, v0
	v_pk_mul_f32 v[132:133], v[134:135], v[132:133]
	v_mul_f32_e32 v0, 0xbfb8aa3b, v178
	v_pk_mul_f32 v[32:33], v[32:33], v[132:133]
	v_exp_f32_e32 v132, v0
	v_mul_f32_e32 v0, 0xbfb8aa3b, v155
	v_exp_f32_e32 v0, v0
	v_pk_mul_f32 v[134:135], v[176:177], v[136:137]
	v_add_f32_e32 v0, 1.0, v0
	v_pk_mul_f32 v[34:35], v[34:35], v[134:135]
	v_rcp_f32_e32 v134, v0
	v_mul_f32_e32 v0, 0xbfb8aa3b, v179
	v_exp_f32_e32 v133, v0
	v_mul_f32_e32 v0, 0xbfb8aa3b, v157
	v_exp_f32_e32 v0, v0
	v_pk_add_f32 v[132:133], v[132:133], 1.0 op_sel_hi:[1,0]
	v_add_f32_e32 v0, 1.0, v0
	v_rcp_f32_e32 v135, v0
	v_mul_f32_e32 v0, 0xbfb8aa3b, v180
	v_exp_f32_e32 v136, v0
	v_mul_f32_e32 v0, 0xbfb8aa3b, v159
	v_exp_f32_e32 v0, v0
	v_pk_mul_f32 v[132:133], v[134:135], v[132:133]
	v_add_f32_e32 v0, 1.0, v0
	v_rcp_f32_e32 v176, v0
	v_mul_f32_e32 v0, 0xbfb8aa3b, v181
	v_exp_f32_e32 v137, v0
	v_mul_f32_e32 v0, 0xbfb8aa3b, v161
	v_exp_f32_e32 v0, v0
	v_pk_mul_f32 v[28:29], v[28:29], v[132:133]
	v_pk_add_f32 v[136:137], v[136:137], 1.0 op_sel_hi:[1,0]
	v_lshl_add_u64 v[132:133], s[96:97], 0, v[2:3]
	v_add_f32_e32 v0, 1.0, v0
	v_rcp_f32_e32 v177, v0
	v_lshl_add_u64 v[2:3], s[40:41], 0, v[2:3]
	v_pk_mul_f32 v[134:135], v[176:177], v[136:137]
	s_nop 0
	v_pk_mul_f32 v[30:31], v[30:31], v[134:135]
	s_waitcnt vmcnt(5)
; __device__ __forceinline__ void unpack8(const u32x4 w, float* f) { f[0] = bf_lo(w.x); f[1] = bf_hi(w.x); f[2] = bf_lo(w.y); f[3] = bf_hi(w.y); f[4] = bf_lo(w.z); f[5] = bf_hi(w.z); f[6] = bf_lo(w.w); f[7] = bf_hi(w.w); }
;     __device__ __forceinline__ void mid(f32x4 (&acc)[2][2][4][2], const Unit& u, int wr, int wc, int fr, int fq) const {
;         const int row0 = u.pm * BM + wr * 64 + fr, col0 = u.pn * BM + wc * 32 + 8 * fq;
; #pragma unroll
;         for (int ai = 0; ai < 2; ++ai)
; #pragma unroll
;             for (int m = 0; m < 4; ++m) { int row = row0 + ai * HALF + m * 16; asm volatile("" : "+v"(row));
; #pragma unroll
;                 for (int bj = 0; bj < 2; ++bj) { const size_t off = (size_t)row * NPROJ + col0 + bj * HALF;
;                     float fa[8], fb[8]; unpack8(*(const u32x4*)(ga + off), fa); unpack8(*(const u32x4*)(gr + off), fb);
; #pragma unroll
;                     for (int j = 0; j < 8; ++j) { const float rt = (1.0f + __builtin_amdgcn_exp2f(fb[j] * -1.4426950408889634f)) * __builtin_amdgcn_rcpf(1.0f + __builtin_amdgcn_exp2f(fa[j] * -1.4426950408889634f));
;                         if (j < 4) acc[ai][bj][m][0][j] *= rt; else acc[ai][bj][m][1][j - 4] *= rt; } }
;                 asm volatile("" ::: "memory"); }
;     }
	v_mov_b64_e32 v[132:133], v[190:191]
	v_mov_b64_e32 v[134:135], v[192:193]
	v_lshlrev_b32_e32 v155, 16, v134
	v_and_b32_e32 v157, 0xffff0000, v134
	v_lshlrev_b32_e32 v159, 16, v135
	v_and_b32_e32 v161, 0xffff0000, v135
	s_waitcnt vmcnt(4)
	v_mov_b64_e32 v[134:135], v[194:195]
	v_mov_b64_e32 v[136:137], v[196:197]
	v_and_b32_e32 v0, 0xffff0000, v132
	v_mul_f32_e32 v0, 0xbfb8aa3b, v0
	v_exp_f32_e32 v0, v0
	v_lshlrev_b32_e32 v151, 16, v133
	v_and_b32_e32 v153, 0xffff0000, v133
	v_lshlrev_b32_e32 v132, 16, v132
	v_add_f32_e32 v0, 1.0, v0
	v_rcp_f32_e32 v133, v0
	v_mul_f32_e32 v132, 0xbfb8aa3b, v132
	v_exp_f32_e32 v132, v132
	v_lshlrev_b32_e32 v163, 16, v135
	v_mul_f32_e32 v0, 0xbfb8aa3b, v163
	v_and_b32_e32 v3, 0xffff0000, v134
	v_lshlrev_b32_e32 v2, 16, v134
	v_exp_f32_e32 v134, v0
	v_mul_f32_e32 v0, 0xbfb8aa3b, v151
	v_exp_f32_e32 v0, v0
	v_and_b32_e32 v135, 0xffff0000, v135
	v_lshlrev_b32_e32 v167, 16, v136
	v_and_b32_e32 v176, 0xffff0000, v136
	v_add_f32_e32 v0, 1.0, v0
	v_rcp_f32_e32 v136, v0
	v_mul_f32_e32 v0, 0xbfb8aa3b, v135
	v_mul_f32_e32 v2, 0xbfb8aa3b, v2
	v_mul_f32_e32 v3, 0xbfb8aa3b, v3
	v_exp_f32_e32 v135, v0
	v_mul_f32_e32 v0, 0xbfb8aa3b, v153
	v_exp_f32_e32 v2, v2
	v_add_f32_e32 v132, 1.0, v132
	v_exp_f32_e32 v3, v3
	v_exp_f32_e32 v0, v0
	v_rcp_f32_e32 v132, v132
	v_lshlrev_b32_e32 v177, 16, v137
	v_pk_add_f32 v[2:3], v[2:3], 1.0 op_sel_hi:[1,0]
	v_add_f32_e32 v0, 1.0, v0
	v_and_b32_e32 v178, 0xffff0000, v137
	v_rcp_f32_e32 v137, v0
	v_pk_mul_f32 v[2:3], v[2:3], v[132:133]
	v_mul_f32_e32 v0, 0xbfb8aa3b, v167
	v_pk_mul_f32 v[24:25], v[24:25], v[2:3]
	v_exp_f32_e32 v2, v0
	v_mul_f32_e32 v0, 0xbfb8aa3b, v155
	v_exp_f32_e32 v0, v0
	v_pk_add_f32 v[134:135], v[134:135], 1.0 op_sel_hi:[1,0]
	v_add_f32_e32 v0, 1.0, v0
	v_pk_mul_f32 v[132:133], v[134:135], v[136:137]
	s_nop 0
	v_pk_mul_f32 v[26:27], v[26:27], v[132:133]
	v_rcp_f32_e32 v132, v0
	v_mul_f32_e32 v0, 0xbfb8aa3b, v176
	v_exp_f32_e32 v3, v0
	v_mul_f32_e32 v0, 0xbfb8aa3b, v157
	v_exp_f32_e32 v0, v0
	v_pk_add_f32 v[2:3], v[2:3], 1.0 op_sel_hi:[1,0]
	v_add_f32_e32 v0, 1.0, v0
	v_rcp_f32_e32 v133, v0
	v_mul_f32_e32 v0, 0xbfb8aa3b, v177
	v_exp_f32_e32 v134, v0
	v_mul_f32_e32 v0, 0xbfb8aa3b, v159
	v_exp_f32_e32 v0, v0
	v_pk_mul_f32 v[2:3], v[2:3], v[132:133]
	v_add_f32_e32 v0, 1.0, v0
	v_rcp_f32_e32 v136, v0
	v_mul_f32_e32 v0, 0xbfb8aa3b, v178
	v_exp_f32_e32 v135, v0
	v_mul_f32_e32 v0, 0xbfb8aa3b, v161
	v_exp_f32_e32 v0, v0
	v_pk_mul_f32 v[20:21], v[20:21], v[2:3]
	v_pk_add_f32 v[134:135], v[134:135], 1.0 op_sel_hi:[1,0]
	v_add_f32_e32 v0, 1.0, v0
	v_rcp_f32_e32 v137, v0
	v_mov_b32_e32 v0, v150
	v_pk_mul_f32 v[132:133], v[134:135], v[136:137]
	v_mad_i64_i32 v[2:3], s[10:11], v0, s57, v[164:165]
	v_lshlrev_b64 v[2:3], 1, v[2:3]
	v_pk_mul_f32 v[22:23], v[22:23], v[132:133]
	v_lshl_add_u64 v[132:133], s[96:97], 0, v[2:3]
	s_waitcnt vmcnt(3)
	v_mov_b64_e32 v[132:133], v[198:199]
	v_mov_b64_e32 v[134:135], v[200:201]
	v_lshlrev_b32_e32 v155, 16, v134
	v_and_b32_e32 v157, 0xffff0000, v134
	v_lshlrev_b32_e32 v159, 16, v135
	v_and_b32_e32 v161, 0xffff0000, v135
	v_lshl_add_u64 v[134:135], s[40:41], 0, v[2:3]
	s_waitcnt vmcnt(2)
; __device__ __forceinline__ void unpack8(const u32x4 w, float* f) { f[0] = bf_lo(w.x); f[1] = bf_hi(w.x); f[2] = bf_lo(w.y); f[3] = bf_hi(w.y); f[4] = bf_lo(w.z); f[5] = bf_hi(w.z); f[6] = bf_lo(w.w); f[7] = bf_hi(w.w); }
;     __device__ __forceinline__ void mid(f32x4 (&acc)[2][2][4][2], const Unit& u, int wr, int wc, int fr, int fq) const {
;         const int row0 = u.pm * BM + wr * 64 + fr, col0 = u.pn * BM + wc * 32 + 8 * fq;
; #pragma unroll
;         for (int ai = 0; ai < 2; ++ai)
; #pragma unroll
;             for (int m = 0; m < 4; ++m) { int row = row0 + ai * HALF + m * 16; asm volatile("" : "+v"(row));
; #pragma unroll
;                 for (int bj = 0; bj < 2; ++bj) { const size_t off = (size_t)row * NPROJ + col0 + bj * HALF;
;                     float fa[8], fb[8]; unpack8(*(const u32x4*)(ga + off), fa); unpack8(*(const u32x4*)(gr + off), fb);
; #pragma unroll
;                     for (int j = 0; j < 8; ++j) { const float rt = (1.0f + __builtin_amdgcn_exp2f(fb[j] * -1.4426950408889634f)) * __builtin_amdgcn_rcpf(1.0f + __builtin_amdgcn_exp2f(fa[j] * -1.4426950408889634f));
;                         if (j < 4) acc[ai][bj][m][0][j] *= rt; else acc[ai][bj][m][1][j - 4] *= rt; } }
;                 asm volatile("" ::: "memory"); }
;     }
	v_mov_b64_e32 v[134:135], v[202:203]
	v_mov_b64_e32 v[136:137], v[204:205]
	v_and_b32_e32 v0, 0xffff0000, v132
	v_mul_f32_e32 v0, 0xbfb8aa3b, v0
	v_exp_f32_e32 v0, v0
	v_lshlrev_b32_e32 v151, 16, v133
	v_and_b32_e32 v153, 0xffff0000, v133
	v_or_b32_e32 v2, 0x100, v2
	v_add_f32_e32 v0, 1.0, v0
	v_lshlrev_b32_e32 v163, 16, v135
	v_and_b32_e32 v167, 0xffff0000, v135
	v_lshlrev_b32_e32 v135, 16, v132
	v_and_b32_e32 v133, 0xffff0000, v134
	v_lshlrev_b32_e32 v132, 16, v134
	v_mul_f32_e32 v134, 0xbfb8aa3b, v135
	v_rcp_f32_e32 v135, v0
	v_mul_f32_e32 v0, 0xbfb8aa3b, v163
	v_lshlrev_b32_e32 v178, 16, v136
	v_and_b32_e32 v179, 0xffff0000, v136
	v_exp_f32_e32 v136, v0
	v_mul_f32_e32 v0, 0xbfb8aa3b, v151
	v_exp_f32_e32 v0, v0
	v_exp_f32_e32 v134, v134
	v_lshlrev_b32_e32 v180, 16, v137
	v_and_b32_e32 v181, 0xffff0000, v137
	v_add_f32_e32 v0, 1.0, v0
	v_rcp_f32_e32 v176, v0
	v_mul_f32_e32 v0, 0xbfb8aa3b, v167
	v_mul_f32_e32 v132, 0xbfb8aa3b, v132
	v_mul_f32_e32 v133, 0xbfb8aa3b, v133
	v_exp_f32_e32 v137, v0
	v_mul_f32_e32 v0, 0xbfb8aa3b, v153
	v_exp_f32_e32 v132, v132
	v_add_f32_e32 v134, 1.0, v134
	v_exp_f32_e32 v133, v133
	v_exp_f32_e32 v0, v0
	v_rcp_f32_e32 v134, v134
	v_pk_add_f32 v[136:137], v[136:137], 1.0 op_sel_hi:[1,0]
	v_pk_add_f32 v[132:133], v[132:133], 1.0 op_sel_hi:[1,0]
	v_add_f32_e32 v0, 1.0, v0
	v_rcp_f32_e32 v177, v0
	v_pk_mul_f32 v[132:133], v[134:135], v[132:133]
	v_mul_f32_e32 v0, 0xbfb8aa3b, v178
	v_pk_mul_f32 v[16:17], v[16:17], v[132:133]
	v_exp_f32_e32 v132, v0
	v_mul_f32_e32 v0, 0xbfb8aa3b, v155
	v_exp_f32_e32 v0, v0
	v_pk_mul_f32 v[134:135], v[176:177], v[136:137]
	v_add_f32_e32 v0, 1.0, v0
	v_pk_mul_f32 v[18:19], v[18:19], v[134:135]
	v_rcp_f32_e32 v134, v0
	v_mul_f32_e32 v0, 0xbfb8aa3b, v179
	v_exp_f32_e32 v133, v0
	v_mul_f32_e32 v0, 0xbfb8aa3b, v157
	v_exp_f32_e32 v0, v0
	v_pk_add_f32 v[132:133], v[132:133], 1.0 op_sel_hi:[1,0]
	v_add_f32_e32 v0, 1.0, v0
	v_rcp_f32_e32 v135, v0
	v_mul_f32_e32 v0, 0xbfb8aa3b, v180
	v_exp_f32_e32 v136, v0
	v_mul_f32_e32 v0, 0xbfb8aa3b, v159
	v_exp_f32_e32 v0, v0
	v_pk_mul_f32 v[132:133], v[134:135], v[132:133]
	v_add_f32_e32 v0, 1.0, v0
	v_rcp_f32_e32 v176, v0
	v_mul_f32_e32 v0, 0xbfb8aa3b, v181
	v_exp_f32_e32 v137, v0
	v_mul_f32_e32 v0, 0xbfb8aa3b, v161
	v_exp_f32_e32 v0, v0
	v_pk_mul_f32 v[12:13], v[12:13], v[132:133]
	v_pk_add_f32 v[136:137], v[136:137], 1.0 op_sel_hi:[1,0]
	v_lshl_add_u64 v[132:133], s[96:97], 0, v[2:3]
	v_add_f32_e32 v0, 1.0, v0
	v_rcp_f32_e32 v177, v0
	v_lshl_add_u64 v[2:3], s[40:41], 0, v[2:3]
	v_pk_mul_f32 v[134:135], v[176:177], v[136:137]
	s_nop 0
	v_pk_mul_f32 v[14:15], v[14:15], v[134:135]
	s_waitcnt vmcnt(1)
	v_mov_b64_e32 v[132:133], v[206:207]
	v_mov_b64_e32 v[134:135], v[208:209]
	v_lshlrev_b32_e32 v157, 16, v133
	v_and_b32_e32 v159, 0xffff0000, v133
	v_lshlrev_b32_e32 v153, 16, v134
	v_and_b32_e32 v151, 0xffff0000, v134
	v_lshlrev_b32_e32 v133, 16, v135
	v_and_b32_e32 v0, 0xffff0000, v135
	s_waitcnt vmcnt(0)
	v_mov_b64_e32 v[134:135], v[210:211]
	v_mov_b64_e32 v[136:137], v[212:213]
	v_and_b32_e32 v155, 0xffff0000, v132
	v_lshlrev_b32_e32 v132, 16, v132
	v_mul_f32_e32 v132, 0xbfb8aa3b, v132
	v_exp_f32_e32 v132, v132
	v_mul_f32_e32 v133, 0xbfb8aa3b, v133
	v_exp_f32_e32 v133, v133
	v_mul_f32_e32 v0, 0xbfb8aa3b, v0
	v_add_f32_e32 v132, 1.0, v132
	v_exp_f32_e32 v0, v0
	v_add_f32_e32 v133, 1.0, v133
	v_add_f32_e32 v0, 1.0, v0
	v_and_b32_e32 v3, 0xffff0000, v134
	v_lshlrev_b32_e32 v2, 16, v134
	v_rcp_f32_e32 v134, v132
	v_mul_f32_e32 v132, 0xbfb8aa3b, v155
	v_exp_f32_e32 v132, v132
	v_lshlrev_b32_e32 v161, 16, v135
	v_and_b32_e32 v163, 0xffff0000, v135
	v_lshlrev_b32_e32 v167, 16, v136
	v_add_f32_e32 v132, 1.0, v132
	v_rcp_f32_e32 v135, v132
	v_mul_f32_e32 v132, 0xbfb8aa3b, v161
	v_and_b32_e32 v178, 0xffff0000, v136
	v_exp_f32_e32 v136, v132
	v_mul_f32_e32 v132, 0xbfb8aa3b, v157
	v_exp_f32_e32 v132, v132
	v_mul_f32_e32 v2, 0xbfb8aa3b, v2
	v_mul_f32_e32 v3, 0xbfb8aa3b, v3
	v_lshlrev_b32_e32 v179, 16, v137
	v_add_f32_e32 v132, 1.0, v132
	v_rcp_f32_e32 v176, v132
	v_mul_f32_e32 v132, 0xbfb8aa3b, v163
	v_and_b32_e32 v180, 0xffff0000, v137
	v_exp_f32_e32 v2, v2
	v_exp_f32_e32 v3, v3
	v_exp_f32_e32 v137, v132
	v_mul_f32_e32 v132, 0xbfb8aa3b, v159
	v_exp_f32_e32 v132, v132
	v_pk_add_f32 v[2:3], v[2:3], 1.0 op_sel_hi:[1,0]
	v_pk_add_f32 v[136:137], v[136:137], 1.0 op_sel_hi:[1,0]
	v_pk_mul_f32 v[2:3], v[2:3], v[134:135]
	v_add_f32_e32 v132, 1.0, v132
	v_rcp_f32_e32 v177, v132
	v_pk_mul_f32 v[8:9], v[8:9], v[2:3]
	v_mul_f32_e32 v3, 0xbfb8aa3b, v153
	v_mul_f32_e32 v132, 0xbfb8aa3b, v151
	v_exp_f32_e32 v3, v3
	v_exp_f32_e32 v132, v132
	v_pk_mul_f32 v[134:135], v[136:137], v[176:177]
	v_mul_f32_e32 v2, 0xbfb8aa3b, v167
	v_add_f32_e32 v3, 1.0, v3
	v_add_f32_e32 v132, 1.0, v132
	v_pk_mul_f32 v[10:11], v[10:11], v[134:135]
	v_rcp_f32_e32 v134, v3
	v_mul_f32_e32 v3, 0xbfb8aa3b, v178
	v_rcp_f32_e32 v135, v132
	v_mul_f32_e32 v132, 0xbfb8aa3b, v179
	v_rcp_f32_e32 v136, v133
	v_mul_f32_e32 v133, 0xbfb8aa3b, v180
	v_exp_f32_e32 v2, v2
	v_exp_f32_e32 v3, v3
	v_exp_f32_e32 v132, v132
	v_exp_f32_e32 v133, v133
	v_rcp_f32_e32 v137, v0
	v_pk_add_f32 v[2:3], v[2:3], 1.0 op_sel_hi:[1,0]
	v_pk_add_f32 v[132:133], v[132:133], 1.0 op_sel_hi:[1,0]
	v_pk_mul_f32 v[2:3], v[2:3], v[134:135]
	v_pk_mul_f32 v[132:133], v[132:133], v[136:137]
	v_pk_mul_f32 v[4:5], v[4:5], v[2:3]
	v_pk_mul_f32 v[6:7], v[6:7], v[132:133]
	s_branch .LBB0_560

; #define PG8_STAGE(bufoff, gbase, voff) do { _Pragma("unroll") for (int _i = 0; _i < 2; ++_i) \
;         __builtin_amdgcn_global_load_lds((const unsigned*)((const char*)(gbase) + (voff)[_i]), (LAS unsigned*)(lds + (bufoff) + ldsw + _i * 8192), 16, 0, 0); } while (0)
; #define PG8_LDA(dst, b, h) do { _Pragma("unroll") for (int m = 0; m < 4; ++m) _Pragma("unroll") for (int k = 0; k < 2; ++k) dst[m][k] = *(const LAS bf16x8*)(lds + PG8_SA(b, h) + aoff + m * 2048 + k * 1024); } while (0)
; #define PG8_LDB(dst, b, h) do { _Pragma("unroll") for (int n = 0; n < 2; ++n) _Pragma("unroll") for (int k = 0; k < 2; ++k) dst[n][k] = *(const LAS bf16x8*)(lds + PG8_SB(b, h) + boff + n * 2048 + k * 1024); } while (0)
; #define PG8_WAIT_V(n) asm volatile("s_waitcnt vmcnt(" #n ")" ::: "memory")
; #define PG8_WAIT_L(n) asm volatile("s_waitcnt lgkmcnt(" #n ")" ::: "memory")
; #define PG8_BAR __builtin_amdgcn_s_barrier()
; #define PG8_SCHED __builtin_amdgcn_sched_barrier(0)
; template <class Epi, class Sched>
; __device__ __forceinline__ void gemm_phase(LAS unsigned char* lds, const Gemm g, const Sched& S, const Epi& E) {
;     ...
;             PG8_LDB(B0, 0, 0); PG8_SCHED; PG8_LDA(At, 0, 0); PG8_STAGE(PG8_SA(1, 1), a1 + hstep, voffA);
;             PG8_WAIT_L(8); PG8_BAR; PG8_WAIT_L(0); PG8_MMA(0, 0, At, B0); PG8_BAR; PG8_SCHED;
;             PG8_LDB(B1, 0, 1); PG8_STAGE(PG8_SB(0, 0), b2, voffB);
;             PG8_BAR; PG8_WAIT_L(0); PG8_MMA(0, 1, At, B1); PG8_BAR;
;             PG8_LDA(At, 0, 1); PG8_STAGE(PG8_SA(0, 0), a2, voffA);
;             PG8_BAR; PG8_WAIT_L(0); PG8_MMA(1, 0, At, B0); PG8_BAR; PG8_SCHED;
;             PG8_STAGE(PG8_SB(0, 1), b2 + hstep, voffB);
;             PG8_WAIT_V(6); PG8_BAR; PG8_MMA(1, 1, At, B1); PG8_BAR;
;             PG8_LDB(B0, 1, 0); PG8_SCHED; PG8_LDA(At, 1, 0); PG8_STAGE(PG8_SA(0, 1), a2 + hstep, voffA);
;             PG8_WAIT_L(8); PG8_BAR; PG8_WAIT_L(0); PG8_MMA(0, 0, At, B0); PG8_BAR; PG8_SCHED;
;             PG8_LDB(B1, 1, 1); PG8_STAGE(PG8_SB(1, 0), b3, voffB);
;             PG8_BAR; PG8_WAIT_L(0); PG8_MMA(0, 1, At, B1); PG8_BAR;
;             PG8_LDA(At, 1, 1); PG8_STAGE(PG8_SA(1, 0), a3, voffA);
;             PG8_BAR; PG8_WAIT_L(0); PG8_MMA(1, 0, At, B0); PG8_BAR; PG8_SCHED;
;             PG8_STAGE(PG8_SB(1, 1), b3 + hstep, voffB);
;             PG8_WAIT_V(6); PG8_BAR; PG8_MMA(1, 1, At, B1); PG8_BAR;
.LBB0_631:
	s_add_u32 s38, s44, 0xfffc0080
	s_addc_u32 s39, s45, -1
	s_add_i32 s47, 0, 0x10000
	v_add_u32_e32 v144, s47, v147
	ds_read_b128 v[140:143], v144
	ds_read_b128 v[152:155], v144 offset:1024
	ds_read_b128 v[156:159], v144 offset:2048
	ds_read_b128 v[160:163], v144 offset:3072
	s_cmp_eq_u32 s17, 12
	s_cselect_b32 s79, s10, s39
	s_cselect_b32 s78, s11, s38
	s_cselect_b32 s69, s16, s51
	s_cselect_b32 s68, s29, s34
	v_lshl_add_u64 v[144:145], s[44:45], 0, v[136:137]
	s_add_i32 m0, s1, 0xc000
	ds_read_b128 v[164:167], v151
	ds_read_b128 v[168:171], v151 offset:1024
	ds_read_b128 v[172:175], v151 offset:2048
	ds_read_b128 v[176:179], v151 offset:3072
	ds_read_b128 v[180:183], v151 offset:4096
	ds_read_b128 v[184:187], v151 offset:5120
	ds_read_b128 v[188:191], v151 offset:6144
	ds_read_b128 v[192:195], v151 offset:7168
	global_load_lds_dwordx4 v[144:145], off
	v_lshl_add_u64 v[144:145], s[44:45], 0, v[138:139]
	s_add_i32 m0, s1, 0xe000
	s_nop 0
	global_load_lds_dwordx4 v[144:145], off
	s_waitcnt lgkmcnt(8)
	s_barrier
	s_waitcnt lgkmcnt(0)
	s_setprio 1
	s_waitcnt lgkmcnt(0)
	v_mfma_f32_16x16x32_bf16 v[126:129], v[140:143], v[164:167], v[126:129]
	v_mfma_f32_16x16x32_bf16 v[122:125], v[156:159], v[164:167], v[122:125]
	v_mfma_f32_16x16x32_bf16 v[110:113], v[140:143], v[172:175], v[110:113]
	v_mfma_f32_16x16x32_bf16 v[106:109], v[156:159], v[172:175], v[106:109]
	v_mfma_f32_16x16x32_bf16 v[94:97], v[140:143], v[180:183], v[94:97]
	v_mfma_f32_16x16x32_bf16 v[90:93], v[156:159], v[180:183], v[90:93]
	v_mfma_f32_16x16x32_bf16 v[78:81], v[140:143], v[188:191], v[78:81]
	v_mfma_f32_16x16x32_bf16 v[74:77], v[156:159], v[188:191], v[74:77]
	v_mfma_f32_16x16x32_bf16 v[126:129], v[152:155], v[168:171], v[126:129]
	v_mfma_f32_16x16x32_bf16 v[122:125], v[160:163], v[168:171], v[122:125]
	v_mfma_f32_16x16x32_bf16 v[110:113], v[152:155], v[176:179], v[110:113]
	v_mfma_f32_16x16x32_bf16 v[106:109], v[160:163], v[176:179], v[106:109]
	v_mfma_f32_16x16x32_bf16 v[94:97], v[152:155], v[184:187], v[94:97]
	v_mfma_f32_16x16x32_bf16 v[90:93], v[160:163], v[184:187], v[90:93]
	v_mfma_f32_16x16x32_bf16 v[78:81], v[152:155], v[192:195], v[78:81]
	v_mfma_f32_16x16x32_bf16 v[74:77], v[160:163], v[192:195], v[74:77]
	s_setprio 0
	s_barrier
	s_add_i32 s38, 0, 0x14000
	v_add_u32_e32 v144, s38, v147
	s_add_i32 s39, s47, s46
	ds_read_b128 v[196:199], v144
	ds_read_b128 v[200:203], v144 offset:1024
	ds_read_b128 v[204:207], v144 offset:2048
	ds_read_b128 v[208:211], v144 offset:3072
	v_lshl_add_u64 v[144:145], s[68:69], 0, v[0:1]
	s_mov_b32 m0, s39
	v_lshl_add_u64 v[212:213], s[68:69], 0, v[134:135]
	global_load_lds_dwordx4 v[144:145], off
	s_add_i32 m0, s39, 0x2000
	s_nop 0
	global_load_lds_dwordx4 v[212:213], off
	s_barrier
	s_waitcnt lgkmcnt(0)
	s_setprio 1
	s_waitcnt lgkmcnt(0)
	v_mfma_f32_16x16x32_bf16 v[118:121], v[196:199], v[164:167], v[118:121]
	v_mfma_f32_16x16x32_bf16 v[114:117], v[204:207], v[164:167], v[114:117]
	v_mfma_f32_16x16x32_bf16 v[102:105], v[196:199], v[172:175], v[102:105]
	v_mfma_f32_16x16x32_bf16 v[98:101], v[204:207], v[172:175], v[98:101]
	v_mfma_f32_16x16x32_bf16 v[86:89], v[196:199], v[180:183], v[86:89]
	v_mfma_f32_16x16x32_bf16 v[82:85], v[204:207], v[180:183], v[82:85]
	v_mfma_f32_16x16x32_bf16 v[70:73], v[196:199], v[188:191], v[70:73]
	v_mfma_f32_16x16x32_bf16 v[66:69], v[204:207], v[188:191], v[66:69]
	v_mfma_f32_16x16x32_bf16 v[118:121], v[200:203], v[168:171], v[118:121]
	v_mfma_f32_16x16x32_bf16 v[114:117], v[208:211], v[168:171], v[114:117]
	v_mfma_f32_16x16x32_bf16 v[102:105], v[200:203], v[176:179], v[102:105]
	v_mfma_f32_16x16x32_bf16 v[98:101], v[208:211], v[176:179], v[98:101]
	v_mfma_f32_16x16x32_bf16 v[86:89], v[200:203], v[184:187], v[86:89]
	v_mfma_f32_16x16x32_bf16 v[82:85], v[208:211], v[184:187], v[82:85]
	v_mfma_f32_16x16x32_bf16 v[70:73], v[200:203], v[192:195], v[70:73]
	v_mfma_f32_16x16x32_bf16 v[66:69], v[208:211], v[192:195], v[66:69]
	s_setprio 0
	s_mov_b32 m0, s1
	v_lshl_add_u64 v[214:215], s[78:79], 0, v[130:131]
	s_barrier
	ds_read_b128 v[164:167], v151 offset:16384
	ds_read_b128 v[168:171], v151 offset:17408
	ds_read_b128 v[172:175], v151 offset:18432
	ds_read_b128 v[176:179], v151 offset:19456
	ds_read_b128 v[180:183], v151 offset:20480
	ds_read_b128 v[184:187], v151 offset:21504
	ds_read_b128 v[188:191], v151 offset:22528
	ds_read_b128 v[192:195], v151 offset:23552
	global_load_lds_dwordx4 v[214:215], off
	v_lshl_add_u64 v[216:217], s[78:79], 0, v[132:133]
	s_mov_b32 m0, s72
	s_nop 0
	global_load_lds_dwordx4 v[216:217], off
	s_barrier
	s_waitcnt lgkmcnt(0)
	s_setprio 1
	s_waitcnt lgkmcnt(0)
	v_mfma_f32_16x16x32_bf16 v[62:65], v[140:143], v[164:167], v[62:65]
	v_mfma_f32_16x16x32_bf16 v[58:61], v[156:159], v[164:167], v[58:61]
	v_mfma_f32_16x16x32_bf16 v[46:49], v[140:143], v[172:175], v[46:49]
	v_mfma_f32_16x16x32_bf16 v[42:45], v[156:159], v[172:175], v[42:45]
	v_mfma_f32_16x16x32_bf16 v[30:33], v[140:143], v[180:183], v[30:33]
	v_mfma_f32_16x16x32_bf16 v[26:29], v[156:159], v[180:183], v[26:29]
	v_mfma_f32_16x16x32_bf16 v[14:17], v[140:143], v[188:191], v[14:17]
	v_mfma_f32_16x16x32_bf16 v[10:13], v[156:159], v[188:191], v[10:13]
	v_mfma_f32_16x16x32_bf16 v[62:65], v[152:155], v[168:171], v[62:65]
	v_mfma_f32_16x16x32_bf16 v[58:61], v[160:163], v[168:171], v[58:61]
	v_mfma_f32_16x16x32_bf16 v[46:49], v[152:155], v[176:179], v[46:49]
	v_mfma_f32_16x16x32_bf16 v[42:45], v[160:163], v[176:179], v[42:45]
	v_mfma_f32_16x16x32_bf16 v[30:33], v[152:155], v[184:187], v[30:33]
	v_mfma_f32_16x16x32_bf16 v[26:29], v[160:163], v[184:187], v[26:29]
	v_mfma_f32_16x16x32_bf16 v[14:17], v[152:155], v[192:195], v[14:17]
	v_mfma_f32_16x16x32_bf16 v[10:13], v[160:163], v[192:195], v[10:13]
	s_setprio 0
	s_barrier
; #define PG8_STAGE(bufoff, gbase, voff) do { _Pragma("unroll") for (int _i = 0; _i < 2; ++_i) \
;         __builtin_amdgcn_global_load_lds((const unsigned*)((const char*)(gbase) + (voff)[_i]), (LAS unsigned*)(lds + (bufoff) + ldsw + _i * 8192), 16, 0, 0); } while (0)
; #define PG8_LDA(dst, b, h) do { _Pragma("unroll") for (int m = 0; m < 4; ++m) _Pragma("unroll") for (int k = 0; k < 2; ++k) dst[m][k] = *(const LAS bf16x8*)(lds + PG8_SA(b, h) + aoff + m * 2048 + k * 1024); } while (0)
; #define PG8_LDB(dst, b, h) do { _Pragma("unroll") for (int n = 0; n < 2; ++n) _Pragma("unroll") for (int k = 0; k < 2; ++k) dst[n][k] = *(const LAS bf16x8*)(lds + PG8_SB(b, h) + boff + n * 2048 + k * 1024); } while (0)
; #define PG8_WAIT_V(n) asm volatile("s_waitcnt vmcnt(" #n ")" ::: "memory")
; #define PG8_WAIT_L(n) asm volatile("s_waitcnt lgkmcnt(" #n ")" ::: "memory")
; #define PG8_BAR __builtin_amdgcn_s_barrier()
; #define PG8_SCHED __builtin_amdgcn_sched_barrier(0)
; template <class Epi, class Sched>
; __device__ __forceinline__ void gemm_phase(LAS unsigned char* lds, const Gemm g, const Sched& S, const Epi& E) {
;     ...
;             PG8_LDB(B0, 0, 0); PG8_SCHED; PG8_LDA(At, 0, 0); PG8_STAGE(PG8_SA(1, 1), a1 + hstep, voffA);
;             PG8_WAIT_L(8); PG8_BAR; PG8_WAIT_L(0); PG8_MMA(0, 0, At, B0); PG8_BAR; PG8_SCHED;
;             PG8_LDB(B1, 0, 1); PG8_STAGE(PG8_SB(0, 0), b2, voffB);
;             PG8_BAR; PG8_WAIT_L(0); PG8_MMA(0, 1, At, B1); PG8_BAR;
;             PG8_LDA(At, 0, 1); PG8_STAGE(PG8_SA(0, 0), a2, voffA);
;             PG8_BAR; PG8_WAIT_L(0); PG8_MMA(1, 0, At, B0); PG8_BAR; PG8_SCHED;
;             PG8_STAGE(PG8_SB(0, 1), b2 + hstep, voffB);
;             PG8_WAIT_V(6); PG8_BAR; PG8_MMA(1, 1, At, B1); PG8_BAR;
;             PG8_LDB(B0, 1, 0); PG8_SCHED; PG8_LDA(At, 1, 0); PG8_STAGE(PG8_SA(0, 1), a2 + hstep, voffA);
;             PG8_WAIT_L(8); PG8_BAR; PG8_WAIT_L(0); PG8_MMA(0, 0, At, B0); PG8_BAR; PG8_SCHED;
;             PG8_LDB(B1, 1, 1); PG8_STAGE(PG8_SB(1, 0), b3, voffB);
;             PG8_BAR; PG8_WAIT_L(0); PG8_MMA(0, 1, At, B1); PG8_BAR;
;             PG8_LDA(At, 1, 1); PG8_STAGE(PG8_SA(1, 0), a3, voffA);
;             PG8_BAR; PG8_WAIT_L(0); PG8_MMA(1, 0, At, B0); PG8_BAR; PG8_SCHED;
;             PG8_STAGE(PG8_SB(1, 1), b3 + hstep, voffB);
;             PG8_WAIT_V(6); PG8_BAR; PG8_MMA(1, 1, At, B1); PG8_BAR;
	s_add_u32 s82, s68, 0x40000
	s_addc_u32 s83, s69, 0
	s_add_i32 s38, s38, s46
	v_lshl_add_u64 v[140:141], s[82:83], 0, v[0:1]
	s_mov_b32 m0, s38
	s_nop 0
	global_load_lds_dwordx4 v[140:141], off
	v_lshl_add_u64 v[140:141], s[82:83], 0, v[134:135]
	s_add_i32 m0, s38, 0x2000
	s_nop 0
	global_load_lds_dwordx4 v[140:141], off
	s_waitcnt vmcnt(6)
	s_barrier
	s_setprio 1
	v_mfma_f32_16x16x32_bf16 v[54:57], v[196:199], v[164:167], v[54:57]
	v_mfma_f32_16x16x32_bf16 v[50:53], v[204:207], v[164:167], v[50:53]
	v_mfma_f32_16x16x32_bf16 v[38:41], v[196:199], v[172:175], v[38:41]
	v_mfma_f32_16x16x32_bf16 v[34:37], v[204:207], v[172:175], v[34:37]
	v_mfma_f32_16x16x32_bf16 v[22:25], v[196:199], v[180:183], v[22:25]
	v_mfma_f32_16x16x32_bf16 v[18:21], v[204:207], v[180:183], v[18:21]
	v_mfma_f32_16x16x32_bf16 v[6:9], v[196:199], v[188:191], v[6:9]
	v_mfma_f32_16x16x32_bf16 v[2:5], v[204:207], v[188:191], v[2:5]
	v_mfma_f32_16x16x32_bf16 v[54:57], v[200:203], v[168:171], v[54:57]
	v_mfma_f32_16x16x32_bf16 v[50:53], v[208:211], v[168:171], v[50:53]
	v_mfma_f32_16x16x32_bf16 v[38:41], v[200:203], v[176:179], v[38:41]
	v_mfma_f32_16x16x32_bf16 v[34:37], v[208:211], v[176:179], v[34:37]
	v_mfma_f32_16x16x32_bf16 v[22:25], v[200:203], v[184:187], v[22:25]
	v_mfma_f32_16x16x32_bf16 v[18:21], v[208:211], v[184:187], v[18:21]
	v_mfma_f32_16x16x32_bf16 v[6:9], v[200:203], v[192:195], v[6:9]
	v_mfma_f32_16x16x32_bf16 v[2:5], v[208:211], v[192:195], v[2:5]
	s_setprio 0
	s_add_i32 s38, 0, 0x18000
	v_add_u32_e32 v160, s38, v147
	s_barrier
	ds_read_b128 v[140:143], v160
	ds_read_b128 v[152:155], v160 offset:1024
	ds_read_b128 v[156:159], v160 offset:2048
	ds_read_b128 v[160:163], v160 offset:3072
	s_add_u32 s78, s78, 0x40000
	s_addc_u32 s79, s79, 0
	s_mov_b32 m0, s73
	v_lshl_add_u64 v[196:197], s[78:79], 0, v[130:131]
	ds_read_b128 v[164:167], v151 offset:32768
	ds_read_b128 v[168:171], v151 offset:33792
	ds_read_b128 v[172:175], v151 offset:34816
	ds_read_b128 v[176:179], v151 offset:35840
	ds_read_b128 v[180:183], v151 offset:36864
	ds_read_b128 v[184:187], v151 offset:37888
	ds_read_b128 v[188:191], v151 offset:38912
	ds_read_b128 v[192:195], v151 offset:39936
	global_load_lds_dwordx4 v[196:197], off
	v_lshl_add_u64 v[196:197], s[78:79], 0, v[132:133]
	s_mov_b32 m0, s76
	s_nop 0
	global_load_lds_dwordx4 v[196:197], off
	s_waitcnt lgkmcnt(8)
	s_barrier
	s_waitcnt lgkmcnt(0)
	s_setprio 1
	s_waitcnt lgkmcnt(0)
	v_mfma_f32_16x16x32_bf16 v[126:129], v[140:143], v[164:167], v[126:129]
	v_mfma_f32_16x16x32_bf16 v[122:125], v[156:159], v[164:167], v[122:125]
	v_mfma_f32_16x16x32_bf16 v[110:113], v[140:143], v[172:175], v[110:113]
	v_mfma_f32_16x16x32_bf16 v[106:109], v[156:159], v[172:175], v[106:109]
	v_mfma_f32_16x16x32_bf16 v[94:97], v[140:143], v[180:183], v[94:97]
	v_mfma_f32_16x16x32_bf16 v[90:93], v[156:159], v[180:183], v[90:93]
	v_mfma_f32_16x16x32_bf16 v[78:81], v[140:143], v[188:191], v[78:81]
	v_mfma_f32_16x16x32_bf16 v[74:77], v[156:159], v[188:191], v[74:77]
	v_mfma_f32_16x16x32_bf16 v[126:129], v[152:155], v[168:171], v[126:129]
	v_mfma_f32_16x16x32_bf16 v[122:125], v[160:163], v[168:171], v[122:125]
	v_mfma_f32_16x16x32_bf16 v[110:113], v[152:155], v[176:179], v[110:113]
	v_mfma_f32_16x16x32_bf16 v[106:109], v[160:163], v[176:179], v[106:109]
	v_mfma_f32_16x16x32_bf16 v[94:97], v[152:155], v[184:187], v[94:97]
	v_mfma_f32_16x16x32_bf16 v[90:93], v[160:163], v[184:187], v[90:93]
	v_mfma_f32_16x16x32_bf16 v[78:81], v[152:155], v[192:195], v[78:81]
	v_mfma_f32_16x16x32_bf16 v[74:77], v[160:163], v[192:195], v[74:77]
	s_setprio 0
	s_barrier
	s_add_i32 s39, 0, 0x1c000
	s_add_i32 s38, s38, s46
	v_add_u32_e32 v208, s39, v147
	v_lshl_add_u64 v[144:145], v[144:145], 0, s[62:63]
	s_mov_b32 m0, s38
	ds_read_b128 v[196:199], v208
	ds_read_b128 v[200:203], v208 offset:1024
	ds_read_b128 v[204:207], v208 offset:2048
	ds_read_b128 v[208:211], v208 offset:3072
	global_load_lds_dwordx4 v[144:145], off
	v_lshl_add_u64 v[144:145], v[212:213], 0, s[62:63]
	s_add_i32 m0, s38, 0x2000
	s_nop 0
	global_load_lds_dwordx4 v[144:145], off
	s_barrier
	s_waitcnt lgkmcnt(0)
	s_setprio 1
	s_waitcnt lgkmcnt(0)
	v_mfma_f32_16x16x32_bf16 v[118:121], v[196:199], v[164:167], v[118:121]
	v_mfma_f32_16x16x32_bf16 v[114:117], v[204:207], v[164:167], v[114:117]
	v_mfma_f32_16x16x32_bf16 v[102:105], v[196:199], v[172:175], v[102:105]
	v_mfma_f32_16x16x32_bf16 v[98:101], v[204:207], v[172:175], v[98:101]
	v_mfma_f32_16x16x32_bf16 v[86:89], v[196:199], v[180:183], v[86:89]
	v_mfma_f32_16x16x32_bf16 v[82:85], v[204:207], v[180:183], v[82:85]
	v_mfma_f32_16x16x32_bf16 v[70:73], v[196:199], v[188:191], v[70:73]
	v_mfma_f32_16x16x32_bf16 v[66:69], v[204:207], v[188:191], v[66:69]
	v_mfma_f32_16x16x32_bf16 v[118:121], v[200:203], v[168:171], v[118:121]
	v_mfma_f32_16x16x32_bf16 v[114:117], v[208:211], v[168:171], v[114:117]
	v_mfma_f32_16x16x32_bf16 v[102:105], v[200:203], v[176:179], v[102:105]
	v_mfma_f32_16x16x32_bf16 v[98:101], v[208:211], v[176:179], v[98:101]
	v_mfma_f32_16x16x32_bf16 v[86:89], v[200:203], v[184:187], v[86:89]
	v_mfma_f32_16x16x32_bf16 v[82:85], v[208:211], v[184:187], v[82:85]
	v_mfma_f32_16x16x32_bf16 v[70:73], v[200:203], v[192:195], v[70:73]
	v_mfma_f32_16x16x32_bf16 v[66:69], v[208:211], v[192:195], v[66:69]
	s_setprio 0
	s_mov_b32 m0, s84
	v_lshl_add_u64 v[144:145], v[214:215], 0, s[62:63]
	s_barrier
	ds_read_b128 v[164:167], v151 offset:49152
	ds_read_b128 v[168:171], v151 offset:50176
	ds_read_b128 v[172:175], v151 offset:51200
	ds_read_b128 v[176:179], v151 offset:52224
	ds_read_b128 v[180:183], v151 offset:53248
	ds_read_b128 v[184:187], v151 offset:54272
	ds_read_b128 v[188:191], v151 offset:55296
	ds_read_b128 v[192:195], v151 offset:56320
	global_load_lds_dwordx4 v[144:145], off
	v_lshl_add_u64 v[144:145], v[216:217], 0, s[62:63]
	s_mov_b32 m0, s85
	s_nop 0
	global_load_lds_dwordx4 v[144:145], off
	s_barrier
; __device__ __forceinline__ void unpack8(const u32x4 w, float* f) { f[0] = bf_lo(w.x); f[1] = bf_hi(w.x); f[2] = bf_lo(w.y); f[3] = bf_hi(w.y); f[4] = bf_lo(w.z); f[5] = bf_hi(w.z); f[6] = bf_lo(w.w); f[7] = bf_hi(w.w); }
; __device__ __forceinline__ u32x4 pack8(const float* f) { u32x4 w; w.x = cvt_pk_bf16(f[0], f[1]); w.y = cvt_pk_bf16(f[2], f[3]); w.z = cvt_pk_bf16(f[4], f[5]); w.w = cvt_pk_bf16(f[6], f[7]); return w; }
; #define PG8_WAIT_V(n) asm volatile("s_waitcnt vmcnt(" #n ")" ::: "memory")
; template <class Epi, class Sched>
; __device__ __forceinline__ void gemm_phase(LAS unsigned char* lds, const Gemm g, const Sched& S, const Epi& E) {
;     ...
;             PG8_WAIT_L(8); PG8_BAR; PG8_WAIT_L(0); PG8_MMA(0, 0, At, B0); PG8_BAR; PG8_SCHED;
;             PG8_LDB(B1, 1, 1); PG8_STAGE(PG8_SB(1, 0), b3, voffB);
;             PG8_BAR; PG8_WAIT_L(0); PG8_MMA(0, 1, At, B1); PG8_BAR;
;             PG8_LDA(At, 1, 1); PG8_STAGE(PG8_SA(1, 0), a3, voffA);
;             PG8_BAR; PG8_WAIT_L(0); PG8_MMA(1, 0, At, B0); PG8_BAR; PG8_SCHED;
;             PG8_STAGE(PG8_SB(1, 1), b3 + hstep, voffB);
;             PG8_WAIT_V(6); PG8_BAR; PG8_MMA(1, 1, At, B1); PG8_BAR;
;         }
;     __device__ __forceinline__ void operator()(const f32x4 (&acc)[2][2][4][2], const Unit& u, int wr, int wc, int fr, int fq) const {
;         const int row0 = u.pm * BM + wr * 64 + fr, col0 = u.pn * BM + wc * 32 + 8 * fq;
; #pragma unroll
;         for (int ai = 0; ai < 2; ++ai)
; #pragma unroll
;             for (int m = 0; m < 4; ++m) { const int row = row0 + ai * HALF + m * 16; float ss = 0.f;
; #pragma unroll
;                 for (int bj = 0; bj < 2; ++bj) { const size_t off = (size_t)row * D + col0 + bj * HALF;
;                     float b[8], r[8]; unpack8(*(const u32x4*)(xb + off), b);
;                     const f32x4 v0 = acc[ai][bj][m][0], v1 = acc[ai][bj][m][1];
; #pragma unroll
;                     for (int j = 0; j < 4; ++j) { b[j] += v0[j]; b[4 + j] += v1[j]; }
;                     const u32x4 w = pack8(b);
;                     *(u32x4*)(xb + off) = w;
;                     unpack8(w, r);
; #pragma unroll
;                     for (int j = 0; j < 8; ++j) ss += r[j] * r[j]; }
;                 { const int ln = fr + 16 * fq; ss += shx(ss, 16, ln); ss += shx(ss, 32, ln); }
;                 if (fq == 0) rowss[(size_t)row * 16 + u.pn * 4 + wc] = ss; }
;     }
	s_waitcnt lgkmcnt(0)
	s_setprio 1
	s_waitcnt lgkmcnt(0)
	v_mfma_f32_16x16x32_bf16 v[62:65], v[140:143], v[164:167], v[62:65]
	v_mfma_f32_16x16x32_bf16 v[58:61], v[156:159], v[164:167], v[58:61]
	v_mfma_f32_16x16x32_bf16 v[46:49], v[140:143], v[172:175], v[46:49]
	v_mfma_f32_16x16x32_bf16 v[42:45], v[156:159], v[172:175], v[42:45]
	v_mfma_f32_16x16x32_bf16 v[30:33], v[140:143], v[180:183], v[30:33]
	v_mfma_f32_16x16x32_bf16 v[26:29], v[156:159], v[180:183], v[26:29]
	v_mfma_f32_16x16x32_bf16 v[14:17], v[140:143], v[188:191], v[14:17]
	v_mfma_f32_16x16x32_bf16 v[10:13], v[156:159], v[188:191], v[10:13]
	v_mfma_f32_16x16x32_bf16 v[62:65], v[152:155], v[168:171], v[62:65]
	v_mfma_f32_16x16x32_bf16 v[58:61], v[160:163], v[168:171], v[58:61]
	v_mfma_f32_16x16x32_bf16 v[46:49], v[152:155], v[176:179], v[46:49]
	v_mfma_f32_16x16x32_bf16 v[42:45], v[160:163], v[176:179], v[42:45]
	v_mfma_f32_16x16x32_bf16 v[30:33], v[152:155], v[184:187], v[30:33]
	v_mfma_f32_16x16x32_bf16 v[26:29], v[160:163], v[184:187], v[26:29]
	v_mfma_f32_16x16x32_bf16 v[14:17], v[152:155], v[192:195], v[14:17]
	v_mfma_f32_16x16x32_bf16 v[10:13], v[160:163], v[192:195], v[10:13]
	s_setprio 0
	s_barrier
	s_add_u32 s68, s68, 0x40080
	s_addc_u32 s69, s69, 0
	s_add_i32 s38, s39, s46
	v_lshl_add_u64 v[140:141], s[68:69], 0, v[0:1]
	s_mov_b32 m0, s38
	s_nop 0
	global_load_lds_dwordx4 v[140:141], off
	v_lshl_add_u64 v[140:141], s[68:69], 0, v[134:135]
	s_add_i32 m0, s38, 0x2000
	s_nop 0
	global_load_lds_dwordx4 v[140:141], off
	s_waitcnt vmcnt(6)
	s_barrier
	s_setprio 1
	v_mfma_f32_16x16x32_bf16 v[54:57], v[196:199], v[164:167], v[54:57]
	v_mfma_f32_16x16x32_bf16 v[50:53], v[204:207], v[164:167], v[50:53]
	v_mfma_f32_16x16x32_bf16 v[38:41], v[196:199], v[172:175], v[38:41]
	v_mfma_f32_16x16x32_bf16 v[34:37], v[204:207], v[172:175], v[34:37]
	v_mfma_f32_16x16x32_bf16 v[22:25], v[196:199], v[180:183], v[22:25]
	v_mfma_f32_16x16x32_bf16 v[18:21], v[204:207], v[180:183], v[18:21]
	v_mfma_f32_16x16x32_bf16 v[6:9], v[196:199], v[188:191], v[6:9]
	v_mfma_f32_16x16x32_bf16 v[2:5], v[204:207], v[188:191], v[2:5]
	v_mfma_f32_16x16x32_bf16 v[54:57], v[200:203], v[168:171], v[54:57]
	v_mfma_f32_16x16x32_bf16 v[50:53], v[208:211], v[168:171], v[50:53]
	v_mfma_f32_16x16x32_bf16 v[38:41], v[200:203], v[176:179], v[38:41]
	v_mfma_f32_16x16x32_bf16 v[34:37], v[208:211], v[176:179], v[34:37]
	v_mfma_f32_16x16x32_bf16 v[22:25], v[200:203], v[184:187], v[22:25]
	v_mfma_f32_16x16x32_bf16 v[18:21], v[208:211], v[184:187], v[18:21]
	v_mfma_f32_16x16x32_bf16 v[6:9], v[200:203], v[192:195], v[6:9]
	v_mfma_f32_16x16x32_bf16 v[2:5], v[208:211], v[192:195], v[2:5]
	s_setprio 0
	s_add_i32 s17, s17, 2
	s_add_u32 s44, s44, 0x100
	s_addc_u32 s45, s45, 0
	s_add_u32 s34, s34, 0x100
	s_addc_u32 s51, s51, 0
	s_cmp_gt_u32 s17, 13
	s_barrier
	s_cbranch_scc0 .LBB0_631
	v_lshl_add_u32 v142, s28, 8, v146
	v_ashrrev_i32_e32 v143, 31, v142
	v_lshl_or_b32 v140, s0, 8, v148
	v_lshlrev_b64 v[144:145], 11, v[142:143]
	v_ashrrev_i32_e32 v141, 31, v140
	v_lshl_add_u64 v[144:145], s[40:41], 0, v[144:145]
	v_lshl_add_u64 v[144:145], v[140:141], 1, v[144:145]
	global_load_dwordx4 v[158:161], v[144:145], off
	global_load_dwordx4 v[162:165], v[144:145], off offset:256
	s_mov_b32 s100, 0x8000
	s_mov_b32 s101, 0
	v_lshl_add_u64 v[230:231], v[144:145], 0, s[100:101]
	global_load_dwordx4 v[166:169], v[230:231], off
	global_load_dwordx4 v[170:173], v[230:231], off offset:256
	v_lshl_add_u64 v[230:231], v[230:231], 0, s[100:101]
	global_load_dwordx4 v[190:193], v[230:231], off
	global_load_dwordx4 v[194:197], v[230:231], off offset:256
	v_lshl_add_u64 v[230:231], v[230:231], 0, s[100:101]
	global_load_dwordx4 v[198:201], v[230:231], off
	global_load_dwordx4 v[202:205], v[230:231], off offset:256
	s_mov_b32 s100, 0x28000
	v_lshl_add_u64 v[230:231], v[230:231], 0, s[100:101]
	global_load_dwordx4 v[206:209], v[230:231], off
	global_load_dwordx4 v[210:213], v[230:231], off offset:256
	s_mov_b32 s100, 0x8000
	v_lshl_add_u64 v[230:231], v[230:231], 0, s[100:101]
	global_load_dwordx4 v[214:217], v[230:231], off
	global_load_dwordx4 v[218:221], v[230:231], off offset:256
	v_lshl_add_u64 v[230:231], v[230:231], 0, s[100:101]
	global_load_dwordx4 v[222:225], v[230:231], off
	global_load_dwordx4 v[226:229], v[230:231], off offset:256
	v_lshl_add_u64 v[230:231], v[230:231], 0, s[100:101]
	global_load_dwordx4 v[236:239], v[230:231], off
	global_load_dwordx4 v[248:251], v[230:231], off offset:256
	s_waitcnt vmcnt(15)
	v_mov_b64_e32 v[152:153], v[158:159]
	v_mov_b64_e32 v[154:155], v[160:161]
	v_lshlrev_b32_e32 v156, 16, v152
	v_and_b32_e32 v157, 0xffff0000, v152
	v_pk_add_f32 v[126:127], v[126:127], v[156:157]
	v_lshlrev_b32_e32 v156, 16, v154
	v_and_b32_e32 v157, 0xffff0000, v154
	v_pk_add_f32 v[156:157], v[122:123], v[156:157]
	v_lshlrev_b32_e32 v122, 16, v153
	v_and_b32_e32 v123, 0xffff0000, v153
	v_pk_add_f32 v[128:129], v[128:129], v[122:123]
	v_lshlrev_b32_e32 v122, 16, v155
	v_and_b32_e32 v123, 0xffff0000, v155
	v_pk_add_f32 v[152:153], v[124:125], v[122:123]
	v_cvt_pk_bf16_f32 v122, v126, v127
	v_cvt_pk_bf16_f32 v123, v128, v129
	v_cvt_pk_bf16_f32 v124, v156, v157
	v_cvt_pk_bf16_f32 v125, v152, v153
	global_store_dwordx4 v[144:145], v[122:125], off
	v_lshlrev_b32_e32 v126, 16, v122
	v_lshlrev_b32_e32 v127, 16, v123
	v_and_b32_e32 v122, 0xffff0000, v122
	v_mul_f32_e32 v152, v122, v122
	v_fmac_f32_e32 v152, v126, v126
	v_and_b32_e32 v123, 0xffff0000, v123
	v_fmac_f32_e32 v152, v127, v127
	v_lshlrev_b32_e32 v128, 16, v124
	v_fmac_f32_e32 v152, v123, v123
	v_and_b32_e32 v124, 0xffff0000, v124
	v_fmac_f32_e32 v152, v128, v128
	v_lshlrev_b32_e32 v129, 16, v125
	v_fmac_f32_e32 v152, v124, v124
	v_and_b32_e32 v125, 0xffff0000, v125
	v_fmac_f32_e32 v152, v129, v129
	v_fmac_f32_e32 v152, v125, v125
	s_waitcnt vmcnt(14)
; __device__ __forceinline__ void unpack8(const u32x4 w, float* f) { f[0] = bf_lo(w.x); f[1] = bf_hi(w.x); f[2] = bf_lo(w.y); f[3] = bf_hi(w.y); f[4] = bf_lo(w.z); f[5] = bf_hi(w.z); f[6] = bf_lo(w.w); f[7] = bf_hi(w.w); }
; __device__ __forceinline__ u32x4 pack8(const float* f) { u32x4 w; w.x = cvt_pk_bf16(f[0], f[1]); w.y = cvt_pk_bf16(f[2], f[3]); w.z = cvt_pk_bf16(f[4], f[5]); w.w = cvt_pk_bf16(f[6], f[7]); return w; }
; __device__ __forceinline__ float shx(float v, int m, int lane) { return __int_as_float(__builtin_amdgcn_ds_bpermute((lane ^ m) << 2, __float_as_int(v))); }
;     __device__ __forceinline__ void operator()(const f32x4 (&acc)[2][2][4][2], const Unit& u, int wr, int wc, int fr, int fq) const { if (u.kind == 0) e0(acc, u, wr, wc, fr, fq); else e1(acc, u, wr, wc, fr, fq); }
;     __device__ __forceinline__ void operator()(const f32x4 (&acc)[2][2][4][2], const Unit& u, int wr, int wc, int fr, int fq) const {
;         const int row0 = u.pm * BM + wr * 64 + fr, col0 = u.pn * BM + wc * 32 + 8 * fq;
; #pragma unroll
;         for (int ai = 0; ai < 2; ++ai)
; #pragma unroll
;             for (int m = 0; m < 4; ++m) { const int row = row0 + ai * HALF + m * 16; float ss = 0.f;
; #pragma unroll
;                 for (int bj = 0; bj < 2; ++bj) { const size_t off = (size_t)row * D + col0 + bj * HALF;
;                     float b[8], r[8]; unpack8(*(const u32x4*)(xb + off), b);
;                     const f32x4 v0 = acc[ai][bj][m][0], v1 = acc[ai][bj][m][1];
; #pragma unroll
;                     for (int j = 0; j < 4; ++j) { b[j] += v0[j]; b[4 + j] += v1[j]; }
;                     const u32x4 w = pack8(b);
;                     *(u32x4*)(xb + off) = w;
;                     unpack8(w, r);
; #pragma unroll
;                     for (int j = 0; j < 8; ++j) ss += r[j] * r[j]; }
;                 { const int ln = fr + 16 * fq; ss += shx(ss, 16, ln); ss += shx(ss, 32, ln); }
;                 if (fq == 0) rowss[(size_t)row * 16 + u.pn * 4 + wc] = ss; }
;     }
	v_mov_b64_e32 v[122:123], v[162:163]
	v_mov_b64_e32 v[124:125], v[164:165]
	v_lshlrev_b32_e32 v126, 16, v122
	v_and_b32_e32 v127, 0xffff0000, v122
	v_pk_add_f32 v[118:119], v[118:119], v[126:127]
	v_lshlrev_b32_e32 v126, 16, v124
	v_and_b32_e32 v127, 0xffff0000, v124
	v_pk_add_f32 v[126:127], v[114:115], v[126:127]
	v_lshlrev_b32_e32 v114, 16, v123
	v_and_b32_e32 v115, 0xffff0000, v123
	v_pk_add_f32 v[120:121], v[120:121], v[114:115]
	v_lshlrev_b32_e32 v114, 16, v125
	v_and_b32_e32 v115, 0xffff0000, v125
	v_pk_add_f32 v[122:123], v[116:117], v[114:115]
	v_cvt_pk_bf16_f32 v114, v118, v119
	v_cvt_pk_bf16_f32 v115, v120, v121
	v_cvt_pk_bf16_f32 v116, v126, v127
	v_cvt_pk_bf16_f32 v117, v122, v123
	v_lshlrev_b32_e32 v118, 16, v114
	global_store_dwordx4 v[144:145], v[114:117], off offset:256
	v_fmac_f32_e32 v152, v118, v118
	v_lshlrev_b32_e32 v119, 16, v115
	v_and_b32_e32 v114, 0xffff0000, v114
	v_fmac_f32_e32 v152, v114, v114
	v_and_b32_e32 v115, 0xffff0000, v115
	v_fmac_f32_e32 v152, v119, v119
	v_lshlrev_b32_e32 v120, 16, v116
	v_fmac_f32_e32 v152, v115, v115
	v_and_b32_e32 v116, 0xffff0000, v116
	v_fmac_f32_e32 v152, v120, v120
	v_lshlrev_b32_e32 v121, 16, v117
	v_fmac_f32_e32 v152, v116, v116
	v_and_b32_e32 v117, 0xffff0000, v117
	v_fmac_f32_e32 v152, v121, v121
	v_fmac_f32_e32 v152, v117, v117
	ds_bpermute_b32 v114, v149, v152
	s_waitcnt lgkmcnt(0)
	v_add_f32_e32 v114, v152, v114
	ds_bpermute_b32 v115, v150, v114
	s_and_saveexec_b64 s[28:29], s[6:7]
	s_cbranch_execz .LBB0_634
	s_waitcnt lgkmcnt(0)
	v_add_f32_e32 v116, v114, v115
	s_lshl_b32 s10, s0, 2
	v_lshlrev_b64 v[114:115], 6, v[142:143]
	s_ashr_i32 s11, s10, 31
	v_lshl_add_u64 v[114:115], s[42:43], 0, v[114:115]
	v_lshl_add_u64 v[114:115], s[10:11], 2, v[114:115]
	s_lshl_b32 s58, s77, 2
	v_lshl_add_u64 v[114:115], v[114:115], 0, s[58:59]
	global_store_dword v[114:115], v116, off
.LBB0_634:
	s_or_b64 exec, exec, s[28:29]
	v_or_b32_e32 v114, 16, v142
	s_waitcnt lgkmcnt(0)
	v_ashrrev_i32_e32 v115, 31, v114
	v_lshlrev_b64 v[116:117], 11, v[114:115]
	v_lshl_add_u64 v[116:117], s[40:41], 0, v[116:117]
	v_lshl_add_u64 v[116:117], v[140:141], 1, v[116:117]
	s_waitcnt vmcnt(13)
	v_mov_b64_e32 v[118:119], v[166:167]
	v_mov_b64_e32 v[120:121], v[168:169]
	v_lshlrev_b32_e32 v122, 16, v118
	v_and_b32_e32 v123, 0xffff0000, v118
	v_pk_add_f32 v[110:111], v[110:111], v[122:123]
	v_lshlrev_b32_e32 v122, 16, v120
	v_and_b32_e32 v123, 0xffff0000, v120
	v_pk_add_f32 v[122:123], v[106:107], v[122:123]
	v_lshlrev_b32_e32 v106, 16, v119
	v_and_b32_e32 v107, 0xffff0000, v119
	v_pk_add_f32 v[112:113], v[112:113], v[106:107]
	v_lshlrev_b32_e32 v106, 16, v121
	v_and_b32_e32 v107, 0xffff0000, v121
	v_pk_add_f32 v[118:119], v[108:109], v[106:107]
	v_cvt_pk_bf16_f32 v106, v110, v111
	v_cvt_pk_bf16_f32 v107, v112, v113
	v_cvt_pk_bf16_f32 v108, v122, v123
	v_cvt_pk_bf16_f32 v109, v118, v119
	global_store_dwordx4 v[116:117], v[106:109], off
	v_lshlrev_b32_e32 v110, 16, v106
	v_lshlrev_b32_e32 v111, 16, v107
	v_and_b32_e32 v106, 0xffff0000, v106
	v_mul_f32_e32 v118, v106, v106
	v_fmac_f32_e32 v118, v110, v110
	v_and_b32_e32 v107, 0xffff0000, v107
	v_fmac_f32_e32 v118, v111, v111
	v_lshlrev_b32_e32 v112, 16, v108
	v_fmac_f32_e32 v118, v107, v107
	v_and_b32_e32 v108, 0xffff0000, v108
	v_fmac_f32_e32 v118, v112, v112
	v_lshlrev_b32_e32 v113, 16, v109
	v_fmac_f32_e32 v118, v108, v108
	v_and_b32_e32 v109, 0xffff0000, v109
	v_fmac_f32_e32 v118, v113, v113
	v_fmac_f32_e32 v118, v109, v109
	s_waitcnt vmcnt(12)
	v_mov_b64_e32 v[106:107], v[170:171]
	v_mov_b64_e32 v[108:109], v[172:173]
	v_lshlrev_b32_e32 v110, 16, v106
	v_and_b32_e32 v111, 0xffff0000, v106
	v_pk_add_f32 v[102:103], v[102:103], v[110:111]
	v_lshlrev_b32_e32 v110, 16, v108
	v_and_b32_e32 v111, 0xffff0000, v108
	v_pk_add_f32 v[110:111], v[98:99], v[110:111]
	v_lshlrev_b32_e32 v98, 16, v107
	v_and_b32_e32 v99, 0xffff0000, v107
	v_pk_add_f32 v[104:105], v[104:105], v[98:99]
	v_lshlrev_b32_e32 v98, 16, v109
	v_and_b32_e32 v99, 0xffff0000, v109
	v_pk_add_f32 v[106:107], v[100:101], v[98:99]
	v_cvt_pk_bf16_f32 v98, v102, v103
	v_cvt_pk_bf16_f32 v99, v104, v105
	v_cvt_pk_bf16_f32 v100, v110, v111
	v_cvt_pk_bf16_f32 v101, v106, v107
	v_lshlrev_b32_e32 v102, 16, v98
	global_store_dwordx4 v[116:117], v[98:101], off offset:256
	v_fmac_f32_e32 v118, v102, v102
	v_lshlrev_b32_e32 v103, 16, v99
	v_and_b32_e32 v98, 0xffff0000, v98
	v_fmac_f32_e32 v118, v98, v98
	v_and_b32_e32 v99, 0xffff0000, v99
	v_fmac_f32_e32 v118, v103, v103
	v_lshlrev_b32_e32 v104, 16, v100
	v_fmac_f32_e32 v118, v99, v99
	v_and_b32_e32 v100, 0xffff0000, v100
	v_fmac_f32_e32 v118, v104, v104
	v_lshlrev_b32_e32 v105, 16, v101
	v_fmac_f32_e32 v118, v100, v100
	v_and_b32_e32 v101, 0xffff0000, v101
	v_fmac_f32_e32 v118, v105, v105
	v_fmac_f32_e32 v118, v101, v101
	ds_bpermute_b32 v98, v149, v118
	s_waitcnt lgkmcnt(0)
	v_add_f32_e32 v98, v118, v98
	ds_bpermute_b32 v99, v150, v98
	s_and_saveexec_b64 s[28:29], s[6:7]
	s_cbranch_execz .LBB0_636
	s_waitcnt lgkmcnt(0)
	v_add_f32_e32 v100, v98, v99
	s_lshl_b32 s10, s0, 2
	v_lshlrev_b64 v[98:99], 6, v[114:115]
	s_ashr_i32 s11, s10, 31
	v_lshl_add_u64 v[98:99], s[42:43], 0, v[98:99]
	v_lshl_add_u64 v[98:99], s[10:11], 2, v[98:99]
	s_lshl_b32 s58, s77, 2
	v_lshl_add_u64 v[98:99], v[98:99], 0, s[58:59]
	global_store_dword v[98:99], v100, off
; __device__ __forceinline__ void unpack8(const u32x4 w, float* f) { f[0] = bf_lo(w.x); f[1] = bf_hi(w.x); f[2] = bf_lo(w.y); f[3] = bf_hi(w.y); f[4] = bf_lo(w.z); f[5] = bf_hi(w.z); f[6] = bf_lo(w.w); f[7] = bf_hi(w.w); }
; __device__ __forceinline__ u32x4 pack8(const float* f) { u32x4 w; w.x = cvt_pk_bf16(f[0], f[1]); w.y = cvt_pk_bf16(f[2], f[3]); w.z = cvt_pk_bf16(f[4], f[5]); w.w = cvt_pk_bf16(f[6], f[7]); return w; }
; __device__ __forceinline__ float shx(float v, int m, int lane) { return __int_as_float(__builtin_amdgcn_ds_bpermute((lane ^ m) << 2, __float_as_int(v))); }
;     __device__ __forceinline__ void operator()(const f32x4 (&acc)[2][2][4][2], const Unit& u, int wr, int wc, int fr, int fq) const { if (u.kind == 0) e0(acc, u, wr, wc, fr, fq); else e1(acc, u, wr, wc, fr, fq); }
;     __device__ __forceinline__ void operator()(const f32x4 (&acc)[2][2][4][2], const Unit& u, int wr, int wc, int fr, int fq) const {
;         const int row0 = u.pm * BM + wr * 64 + fr, col0 = u.pn * BM + wc * 32 + 8 * fq;
; #pragma unroll
;         for (int ai = 0; ai < 2; ++ai)
; #pragma unroll
;             for (int m = 0; m < 4; ++m) { const int row = row0 + ai * HALF + m * 16; float ss = 0.f;
; #pragma unroll
;                 for (int bj = 0; bj < 2; ++bj) { const size_t off = (size_t)row * D + col0 + bj * HALF;
;                     float b[8], r[8]; unpack8(*(const u32x4*)(xb + off), b);
;                     const f32x4 v0 = acc[ai][bj][m][0], v1 = acc[ai][bj][m][1];
; #pragma unroll
;                     for (int j = 0; j < 4; ++j) { b[j] += v0[j]; b[4 + j] += v1[j]; }
;                     const u32x4 w = pack8(b);
;                     *(u32x4*)(xb + off) = w;
;                     unpack8(w, r);
; #pragma unroll
;                     for (int j = 0; j < 8; ++j) ss += r[j] * r[j]; }
;                 { const int ln = fr + 16 * fq; ss += shx(ss, 16, ln); ss += shx(ss, 32, ln); }
;                 if (fq == 0) rowss[(size_t)row * 16 + u.pn * 4 + wc] = ss; }
;     }
.LBB0_636:
	s_or_b64 exec, exec, s[28:29]
	v_or_b32_e32 v98, 32, v142
	s_waitcnt lgkmcnt(0)
	v_ashrrev_i32_e32 v99, 31, v98
	v_lshlrev_b64 v[100:101], 11, v[98:99]
	v_lshl_add_u64 v[100:101], s[40:41], 0, v[100:101]
	v_lshl_add_u64 v[100:101], v[140:141], 1, v[100:101]
	s_waitcnt vmcnt(11)
	v_mov_b64_e32 v[102:103], v[190:191]
	v_mov_b64_e32 v[104:105], v[192:193]
	v_lshlrev_b32_e32 v106, 16, v102
	v_and_b32_e32 v107, 0xffff0000, v102
	v_pk_add_f32 v[94:95], v[94:95], v[106:107]
	v_lshlrev_b32_e32 v106, 16, v104
	v_and_b32_e32 v107, 0xffff0000, v104
	v_pk_add_f32 v[106:107], v[90:91], v[106:107]
	v_lshlrev_b32_e32 v90, 16, v103
	v_and_b32_e32 v91, 0xffff0000, v103
	v_pk_add_f32 v[96:97], v[96:97], v[90:91]
	v_lshlrev_b32_e32 v90, 16, v105
	v_and_b32_e32 v91, 0xffff0000, v105
	v_pk_add_f32 v[102:103], v[92:93], v[90:91]
	v_cvt_pk_bf16_f32 v90, v94, v95
	v_cvt_pk_bf16_f32 v91, v96, v97
	v_cvt_pk_bf16_f32 v92, v106, v107
	v_cvt_pk_bf16_f32 v93, v102, v103
	global_store_dwordx4 v[100:101], v[90:93], off
	v_lshlrev_b32_e32 v94, 16, v90
	v_lshlrev_b32_e32 v95, 16, v91
	v_and_b32_e32 v90, 0xffff0000, v90
	v_mul_f32_e32 v102, v90, v90
	v_fmac_f32_e32 v102, v94, v94
	v_and_b32_e32 v91, 0xffff0000, v91
	v_fmac_f32_e32 v102, v95, v95
	v_lshlrev_b32_e32 v96, 16, v92
	v_fmac_f32_e32 v102, v91, v91
	v_and_b32_e32 v92, 0xffff0000, v92
	v_fmac_f32_e32 v102, v96, v96
	v_lshlrev_b32_e32 v97, 16, v93
	v_fmac_f32_e32 v102, v92, v92
	v_and_b32_e32 v93, 0xffff0000, v93
	v_fmac_f32_e32 v102, v97, v97
	v_fmac_f32_e32 v102, v93, v93
	s_waitcnt vmcnt(10)
	v_mov_b64_e32 v[90:91], v[194:195]
	v_mov_b64_e32 v[92:93], v[196:197]
	v_lshlrev_b32_e32 v94, 16, v90
	v_and_b32_e32 v95, 0xffff0000, v90
	v_pk_add_f32 v[86:87], v[86:87], v[94:95]
	v_lshlrev_b32_e32 v94, 16, v92
	v_and_b32_e32 v95, 0xffff0000, v92
	v_pk_add_f32 v[94:95], v[82:83], v[94:95]
	v_lshlrev_b32_e32 v82, 16, v91
	v_and_b32_e32 v83, 0xffff0000, v91
	v_pk_add_f32 v[88:89], v[88:89], v[82:83]
	v_lshlrev_b32_e32 v82, 16, v93
	v_and_b32_e32 v83, 0xffff0000, v93
	v_pk_add_f32 v[90:91], v[84:85], v[82:83]
	v_cvt_pk_bf16_f32 v82, v86, v87
	v_cvt_pk_bf16_f32 v83, v88, v89
	v_cvt_pk_bf16_f32 v84, v94, v95
	v_cvt_pk_bf16_f32 v85, v90, v91
	v_lshlrev_b32_e32 v86, 16, v82
	global_store_dwordx4 v[100:101], v[82:85], off offset:256
	v_fmac_f32_e32 v102, v86, v86
	v_lshlrev_b32_e32 v87, 16, v83
	v_and_b32_e32 v82, 0xffff0000, v82
	v_fmac_f32_e32 v102, v82, v82
	v_and_b32_e32 v83, 0xffff0000, v83
	v_fmac_f32_e32 v102, v87, v87
	v_lshlrev_b32_e32 v88, 16, v84
	v_fmac_f32_e32 v102, v83, v83
	v_and_b32_e32 v84, 0xffff0000, v84
	v_fmac_f32_e32 v102, v88, v88
	v_lshlrev_b32_e32 v89, 16, v85
	v_fmac_f32_e32 v102, v84, v84
	v_and_b32_e32 v85, 0xffff0000, v85
	v_fmac_f32_e32 v102, v89, v89
	v_fmac_f32_e32 v102, v85, v85
	ds_bpermute_b32 v82, v149, v102
	s_waitcnt lgkmcnt(0)
	v_add_f32_e32 v82, v102, v82
	ds_bpermute_b32 v83, v150, v82
	s_and_saveexec_b64 s[28:29], s[6:7]
	s_cbranch_execz .LBB0_638
	s_waitcnt lgkmcnt(0)
	v_add_f32_e32 v84, v82, v83
	s_lshl_b32 s10, s0, 2
	v_lshlrev_b64 v[82:83], 6, v[98:99]
	s_ashr_i32 s11, s10, 31
	v_lshl_add_u64 v[82:83], s[42:43], 0, v[82:83]
	v_lshl_add_u64 v[82:83], s[10:11], 2, v[82:83]
	s_lshl_b32 s58, s77, 2
	v_lshl_add_u64 v[82:83], v[82:83], 0, s[58:59]
	global_store_dword v[82:83], v84, off
.LBB0_638:
	s_or_b64 exec, exec, s[28:29]
	v_or_b32_e32 v82, 48, v142
	s_waitcnt lgkmcnt(0)
	v_ashrrev_i32_e32 v83, 31, v82
	v_lshlrev_b64 v[84:85], 11, v[82:83]
	v_lshl_add_u64 v[84:85], s[40:41], 0, v[84:85]
	v_lshl_add_u64 v[84:85], v[140:141], 1, v[84:85]
	s_waitcnt vmcnt(9)
	v_mov_b64_e32 v[86:87], v[198:199]
	v_mov_b64_e32 v[88:89], v[200:201]
	v_lshlrev_b32_e32 v90, 16, v86
	v_and_b32_e32 v91, 0xffff0000, v86
	v_pk_add_f32 v[78:79], v[78:79], v[90:91]
	v_lshlrev_b32_e32 v90, 16, v88
	v_and_b32_e32 v91, 0xffff0000, v88
	v_pk_add_f32 v[90:91], v[74:75], v[90:91]
	v_lshlrev_b32_e32 v74, 16, v87
	v_and_b32_e32 v75, 0xffff0000, v87
	v_pk_add_f32 v[80:81], v[80:81], v[74:75]
	v_lshlrev_b32_e32 v74, 16, v89
	v_and_b32_e32 v75, 0xffff0000, v89
	v_pk_add_f32 v[86:87], v[76:77], v[74:75]
	v_cvt_pk_bf16_f32 v74, v78, v79
	v_cvt_pk_bf16_f32 v75, v80, v81
	v_cvt_pk_bf16_f32 v76, v90, v91
	v_cvt_pk_bf16_f32 v77, v86, v87
	global_store_dwordx4 v[84:85], v[74:77], off
	v_lshlrev_b32_e32 v78, 16, v74
	v_lshlrev_b32_e32 v79, 16, v75
	v_and_b32_e32 v74, 0xffff0000, v74
	v_mul_f32_e32 v86, v74, v74
	v_fmac_f32_e32 v86, v78, v78
	v_and_b32_e32 v75, 0xffff0000, v75
	v_fmac_f32_e32 v86, v79, v79
	v_lshlrev_b32_e32 v80, 16, v76
	v_fmac_f32_e32 v86, v75, v75
	v_and_b32_e32 v76, 0xffff0000, v76
	v_fmac_f32_e32 v86, v80, v80
	v_lshlrev_b32_e32 v81, 16, v77
	v_fmac_f32_e32 v86, v76, v76
	v_and_b32_e32 v77, 0xffff0000, v77
	v_fmac_f32_e32 v86, v81, v81
	v_fmac_f32_e32 v86, v77, v77
	s_waitcnt vmcnt(8)
	v_mov_b64_e32 v[74:75], v[202:203]
	v_mov_b64_e32 v[76:77], v[204:205]
	v_lshlrev_b32_e32 v78, 16, v74
	v_and_b32_e32 v79, 0xffff0000, v74
	v_pk_add_f32 v[70:71], v[70:71], v[78:79]
	v_lshlrev_b32_e32 v78, 16, v76
	v_and_b32_e32 v79, 0xffff0000, v76
	v_pk_add_f32 v[78:79], v[66:67], v[78:79]
	v_lshlrev_b32_e32 v66, 16, v75
	v_and_b32_e32 v67, 0xffff0000, v75
	v_pk_add_f32 v[72:73], v[72:73], v[66:67]
	v_lshlrev_b32_e32 v66, 16, v77
	v_and_b32_e32 v67, 0xffff0000, v77
	v_pk_add_f32 v[74:75], v[68:69], v[66:67]
	v_cvt_pk_bf16_f32 v66, v70, v71
	v_cvt_pk_bf16_f32 v67, v72, v73
	v_cvt_pk_bf16_f32 v68, v78, v79
	v_cvt_pk_bf16_f32 v69, v74, v75
	v_lshlrev_b32_e32 v70, 16, v66
	global_store_dwordx4 v[84:85], v[66:69], off offset:256
	v_fmac_f32_e32 v86, v70, v70
	v_lshlrev_b32_e32 v71, 16, v67
	v_and_b32_e32 v66, 0xffff0000, v66
	v_fmac_f32_e32 v86, v66, v66
	v_and_b32_e32 v67, 0xffff0000, v67
	v_fmac_f32_e32 v86, v71, v71
	v_lshlrev_b32_e32 v72, 16, v68
	v_fmac_f32_e32 v86, v67, v67
	v_and_b32_e32 v68, 0xffff0000, v68
	v_fmac_f32_e32 v86, v72, v72
	v_lshlrev_b32_e32 v73, 16, v69
	v_fmac_f32_e32 v86, v68, v68
	v_and_b32_e32 v69, 0xffff0000, v69
	v_fmac_f32_e32 v86, v73, v73
	v_fmac_f32_e32 v86, v69, v69
	ds_bpermute_b32 v66, v149, v86
	s_waitcnt lgkmcnt(0)
	v_add_f32_e32 v66, v86, v66
	ds_bpermute_b32 v67, v150, v66
	s_and_saveexec_b64 s[28:29], s[6:7]
	s_cbranch_execz .LBB0_640
	s_waitcnt lgkmcnt(0)
	v_add_f32_e32 v68, v66, v67
	s_lshl_b32 s10, s0, 2
	v_lshlrev_b64 v[66:67], 6, v[82:83]
	s_ashr_i32 s11, s10, 31
	v_lshl_add_u64 v[66:67], s[42:43], 0, v[66:67]
	v_lshl_add_u64 v[66:67], s[10:11], 2, v[66:67]
	s_lshl_b32 s58, s77, 2
	v_lshl_add_u64 v[66:67], v[66:67], 0, s[58:59]
	global_store_dword v[66:67], v68, off
; __device__ __forceinline__ void unpack8(const u32x4 w, float* f) { f[0] = bf_lo(w.x); f[1] = bf_hi(w.x); f[2] = bf_lo(w.y); f[3] = bf_hi(w.y); f[4] = bf_lo(w.z); f[5] = bf_hi(w.z); f[6] = bf_lo(w.w); f[7] = bf_hi(w.w); }
; __device__ __forceinline__ u32x4 pack8(const float* f) { u32x4 w; w.x = cvt_pk_bf16(f[0], f[1]); w.y = cvt_pk_bf16(f[2], f[3]); w.z = cvt_pk_bf16(f[4], f[5]); w.w = cvt_pk_bf16(f[6], f[7]); return w; }
; __device__ __forceinline__ float shx(float v, int m, int lane) { return __int_as_float(__builtin_amdgcn_ds_bpermute((lane ^ m) << 2, __float_as_int(v))); }
;     __device__ __forceinline__ void operator()(const f32x4 (&acc)[2][2][4][2], const Unit& u, int wr, int wc, int fr, int fq) const { if (u.kind == 0) e0(acc, u, wr, wc, fr, fq); else e1(acc, u, wr, wc, fr, fq); }
;     __device__ __forceinline__ void operator()(const f32x4 (&acc)[2][2][4][2], const Unit& u, int wr, int wc, int fr, int fq) const {
;         const int row0 = u.pm * BM + wr * 64 + fr, col0 = u.pn * BM + wc * 32 + 8 * fq;
; #pragma unroll
;         for (int ai = 0; ai < 2; ++ai)
; #pragma unroll
;             for (int m = 0; m < 4; ++m) { const int row = row0 + ai * HALF + m * 16; float ss = 0.f;
; #pragma unroll
;                 for (int bj = 0; bj < 2; ++bj) { const size_t off = (size_t)row * D + col0 + bj * HALF;
;                     float b[8], r[8]; unpack8(*(const u32x4*)(xb + off), b);
;                     const f32x4 v0 = acc[ai][bj][m][0], v1 = acc[ai][bj][m][1];
; #pragma unroll
;                     for (int j = 0; j < 4; ++j) { b[j] += v0[j]; b[4 + j] += v1[j]; }
;                     const u32x4 w = pack8(b);
;                     *(u32x4*)(xb + off) = w;
;                     unpack8(w, r);
; #pragma unroll
;                     for (int j = 0; j < 8; ++j) ss += r[j] * r[j]; }
;                 { const int ln = fr + 16 * fq; ss += shx(ss, 16, ln); ss += shx(ss, 32, ln); }
;                 if (fq == 0) rowss[(size_t)row * 16 + u.pn * 4 + wc] = ss; }
;     }
.LBB0_640:
	s_or_b64 exec, exec, s[28:29]
	v_add_u32_e32 v66, 0x80, v142
	s_waitcnt lgkmcnt(0)
	v_ashrrev_i32_e32 v67, 31, v66
	v_lshlrev_b64 v[68:69], 11, v[66:67]
	v_lshl_add_u64 v[68:69], s[40:41], 0, v[68:69]
	v_lshl_add_u64 v[68:69], v[140:141], 1, v[68:69]
	s_waitcnt vmcnt(7)
	v_mov_b64_e32 v[70:71], v[206:207]
	v_mov_b64_e32 v[72:73], v[208:209]
	v_lshlrev_b32_e32 v74, 16, v70
	v_and_b32_e32 v75, 0xffff0000, v70
	v_pk_add_f32 v[62:63], v[62:63], v[74:75]
	v_lshlrev_b32_e32 v74, 16, v72
	v_and_b32_e32 v75, 0xffff0000, v72
	v_pk_add_f32 v[74:75], v[58:59], v[74:75]
	v_lshlrev_b32_e32 v58, 16, v71
	v_and_b32_e32 v59, 0xffff0000, v71
	v_pk_add_f32 v[64:65], v[64:65], v[58:59]
	v_lshlrev_b32_e32 v58, 16, v73
	v_and_b32_e32 v59, 0xffff0000, v73
	v_pk_add_f32 v[70:71], v[60:61], v[58:59]
	v_cvt_pk_bf16_f32 v58, v62, v63
	v_cvt_pk_bf16_f32 v59, v64, v65
	v_cvt_pk_bf16_f32 v60, v74, v75
	v_cvt_pk_bf16_f32 v61, v70, v71
	global_store_dwordx4 v[68:69], v[58:61], off
	v_lshlrev_b32_e32 v62, 16, v58
	v_lshlrev_b32_e32 v63, 16, v59
	v_and_b32_e32 v58, 0xffff0000, v58
	v_mul_f32_e32 v70, v58, v58
	v_fmac_f32_e32 v70, v62, v62
	v_and_b32_e32 v59, 0xffff0000, v59
	v_fmac_f32_e32 v70, v63, v63
	v_lshlrev_b32_e32 v64, 16, v60
	v_fmac_f32_e32 v70, v59, v59
	v_and_b32_e32 v60, 0xffff0000, v60
	v_fmac_f32_e32 v70, v64, v64
	v_lshlrev_b32_e32 v65, 16, v61
	v_fmac_f32_e32 v70, v60, v60
	v_and_b32_e32 v61, 0xffff0000, v61
	v_fmac_f32_e32 v70, v65, v65
	v_fmac_f32_e32 v70, v61, v61
	s_waitcnt vmcnt(6)
	v_mov_b64_e32 v[58:59], v[210:211]
	v_mov_b64_e32 v[60:61], v[212:213]
	v_lshlrev_b32_e32 v62, 16, v58
	v_and_b32_e32 v63, 0xffff0000, v58
	v_pk_add_f32 v[54:55], v[54:55], v[62:63]
	v_lshlrev_b32_e32 v62, 16, v60
	v_and_b32_e32 v63, 0xffff0000, v60
	v_pk_add_f32 v[62:63], v[50:51], v[62:63]
	v_lshlrev_b32_e32 v50, 16, v59
	v_and_b32_e32 v51, 0xffff0000, v59
	v_pk_add_f32 v[56:57], v[56:57], v[50:51]
	v_lshlrev_b32_e32 v50, 16, v61
	v_and_b32_e32 v51, 0xffff0000, v61
	v_pk_add_f32 v[58:59], v[52:53], v[50:51]
	v_cvt_pk_bf16_f32 v50, v54, v55
	v_cvt_pk_bf16_f32 v51, v56, v57
	v_cvt_pk_bf16_f32 v52, v62, v63
	v_cvt_pk_bf16_f32 v53, v58, v59
	v_lshlrev_b32_e32 v54, 16, v50
	global_store_dwordx4 v[68:69], v[50:53], off offset:256
	v_fmac_f32_e32 v70, v54, v54
	v_lshlrev_b32_e32 v55, 16, v51
	v_and_b32_e32 v50, 0xffff0000, v50
	v_fmac_f32_e32 v70, v50, v50
	v_and_b32_e32 v51, 0xffff0000, v51
	v_fmac_f32_e32 v70, v55, v55
	v_lshlrev_b32_e32 v56, 16, v52
	v_fmac_f32_e32 v70, v51, v51
	v_and_b32_e32 v52, 0xffff0000, v52
	v_fmac_f32_e32 v70, v56, v56
	v_lshlrev_b32_e32 v57, 16, v53
	v_fmac_f32_e32 v70, v52, v52
	v_and_b32_e32 v53, 0xffff0000, v53
	v_fmac_f32_e32 v70, v57, v57
	v_fmac_f32_e32 v70, v53, v53
	ds_bpermute_b32 v50, v149, v70
	s_waitcnt lgkmcnt(0)
	v_add_f32_e32 v50, v70, v50
	ds_bpermute_b32 v51, v150, v50
	s_and_saveexec_b64 s[28:29], s[6:7]
	s_cbranch_execz .LBB0_642
	s_waitcnt lgkmcnt(0)
	v_add_f32_e32 v52, v50, v51
	s_lshl_b32 s10, s0, 2
	v_lshlrev_b64 v[50:51], 6, v[66:67]
	s_ashr_i32 s11, s10, 31
	v_lshl_add_u64 v[50:51], s[42:43], 0, v[50:51]
	v_lshl_add_u64 v[50:51], s[10:11], 2, v[50:51]
	s_lshl_b32 s58, s77, 2
	v_lshl_add_u64 v[50:51], v[50:51], 0, s[58:59]
	global_store_dword v[50:51], v52, off
.LBB0_642:
	s_or_b64 exec, exec, s[28:29]
	v_add_u32_e32 v50, 0x90, v142
	s_waitcnt lgkmcnt(0)
	v_ashrrev_i32_e32 v51, 31, v50
	v_lshlrev_b64 v[52:53], 11, v[50:51]
	v_lshl_add_u64 v[52:53], s[40:41], 0, v[52:53]
	v_lshl_add_u64 v[52:53], v[140:141], 1, v[52:53]
	s_waitcnt vmcnt(5)
	v_mov_b64_e32 v[54:55], v[214:215]
	v_mov_b64_e32 v[56:57], v[216:217]
	v_lshlrev_b32_e32 v58, 16, v54
	v_and_b32_e32 v59, 0xffff0000, v54
	v_pk_add_f32 v[46:47], v[46:47], v[58:59]
	v_lshlrev_b32_e32 v58, 16, v56
	v_and_b32_e32 v59, 0xffff0000, v56
	v_pk_add_f32 v[58:59], v[42:43], v[58:59]
	v_lshlrev_b32_e32 v42, 16, v55
	v_and_b32_e32 v43, 0xffff0000, v55
	v_pk_add_f32 v[48:49], v[48:49], v[42:43]
	v_lshlrev_b32_e32 v42, 16, v57
	v_and_b32_e32 v43, 0xffff0000, v57
	v_pk_add_f32 v[54:55], v[44:45], v[42:43]
	v_cvt_pk_bf16_f32 v42, v46, v47
	v_cvt_pk_bf16_f32 v43, v48, v49
	v_cvt_pk_bf16_f32 v44, v58, v59
	v_cvt_pk_bf16_f32 v45, v54, v55
	global_store_dwordx4 v[52:53], v[42:45], off
	v_lshlrev_b32_e32 v46, 16, v42
	v_lshlrev_b32_e32 v47, 16, v43
	v_and_b32_e32 v42, 0xffff0000, v42
	v_mul_f32_e32 v54, v42, v42
	v_fmac_f32_e32 v54, v46, v46
	v_and_b32_e32 v43, 0xffff0000, v43
	v_fmac_f32_e32 v54, v47, v47
	v_lshlrev_b32_e32 v48, 16, v44
	v_fmac_f32_e32 v54, v43, v43
	v_and_b32_e32 v44, 0xffff0000, v44
	v_fmac_f32_e32 v54, v48, v48
	v_lshlrev_b32_e32 v49, 16, v45
	v_fmac_f32_e32 v54, v44, v44
	v_and_b32_e32 v45, 0xffff0000, v45
	v_fmac_f32_e32 v54, v49, v49
	v_fmac_f32_e32 v54, v45, v45
	s_waitcnt vmcnt(4)
	v_mov_b64_e32 v[42:43], v[218:219]
	v_mov_b64_e32 v[44:45], v[220:221]
	v_lshlrev_b32_e32 v46, 16, v42
	v_and_b32_e32 v47, 0xffff0000, v42
	v_pk_add_f32 v[38:39], v[38:39], v[46:47]
	v_lshlrev_b32_e32 v46, 16, v44
	v_and_b32_e32 v47, 0xffff0000, v44
	v_pk_add_f32 v[46:47], v[34:35], v[46:47]
	v_lshlrev_b32_e32 v34, 16, v43
	v_and_b32_e32 v35, 0xffff0000, v43
	v_pk_add_f32 v[40:41], v[40:41], v[34:35]
	v_lshlrev_b32_e32 v34, 16, v45
	v_and_b32_e32 v35, 0xffff0000, v45
	v_pk_add_f32 v[42:43], v[36:37], v[34:35]
	v_cvt_pk_bf16_f32 v34, v38, v39
	v_cvt_pk_bf16_f32 v35, v40, v41
	v_cvt_pk_bf16_f32 v36, v46, v47
	v_cvt_pk_bf16_f32 v37, v42, v43
	v_lshlrev_b32_e32 v38, 16, v34
	global_store_dwordx4 v[52:53], v[34:37], off offset:256
	v_fmac_f32_e32 v54, v38, v38
	v_lshlrev_b32_e32 v39, 16, v35
	v_and_b32_e32 v34, 0xffff0000, v34
	v_fmac_f32_e32 v54, v34, v34
	v_and_b32_e32 v35, 0xffff0000, v35
	v_fmac_f32_e32 v54, v39, v39
	v_lshlrev_b32_e32 v40, 16, v36
	v_fmac_f32_e32 v54, v35, v35
	v_and_b32_e32 v36, 0xffff0000, v36
	v_fmac_f32_e32 v54, v40, v40
	v_lshlrev_b32_e32 v41, 16, v37
	v_fmac_f32_e32 v54, v36, v36
	v_and_b32_e32 v37, 0xffff0000, v37
	v_fmac_f32_e32 v54, v41, v41
	v_fmac_f32_e32 v54, v37, v37
	ds_bpermute_b32 v34, v149, v54
	s_waitcnt lgkmcnt(0)
	v_add_f32_e32 v34, v54, v34
	ds_bpermute_b32 v35, v150, v34
	s_and_saveexec_b64 s[28:29], s[6:7]
	s_cbranch_execz .LBB0_644
	s_waitcnt lgkmcnt(0)
	v_add_f32_e32 v36, v34, v35
	s_lshl_b32 s10, s0, 2
	v_lshlrev_b64 v[34:35], 6, v[50:51]
	s_ashr_i32 s11, s10, 31
	v_lshl_add_u64 v[34:35], s[42:43], 0, v[34:35]
	v_lshl_add_u64 v[34:35], s[10:11], 2, v[34:35]
	s_lshl_b32 s58, s77, 2
	v_lshl_add_u64 v[34:35], v[34:35], 0, s[58:59]
	global_store_dword v[34:35], v36, off
; __device__ __forceinline__ void unpack8(const u32x4 w, float* f) { f[0] = bf_lo(w.x); f[1] = bf_hi(w.x); f[2] = bf_lo(w.y); f[3] = bf_hi(w.y); f[4] = bf_lo(w.z); f[5] = bf_hi(w.z); f[6] = bf_lo(w.w); f[7] = bf_hi(w.w); }
; __device__ __forceinline__ u32x4 pack8(const float* f) { u32x4 w; w.x = cvt_pk_bf16(f[0], f[1]); w.y = cvt_pk_bf16(f[2], f[3]); w.z = cvt_pk_bf16(f[4], f[5]); w.w = cvt_pk_bf16(f[6], f[7]); return w; }
; __device__ __forceinline__ float shx(float v, int m, int lane) { return __int_as_float(__builtin_amdgcn_ds_bpermute((lane ^ m) << 2, __float_as_int(v))); }
;     __device__ __forceinline__ void operator()(const f32x4 (&acc)[2][2][4][2], const Unit& u, int wr, int wc, int fr, int fq) const { if (u.kind == 0) e0(acc, u, wr, wc, fr, fq); else e1(acc, u, wr, wc, fr, fq); }
;     __device__ __forceinline__ void operator()(const f32x4 (&acc)[2][2][4][2], const Unit& u, int wr, int wc, int fr, int fq) const {
;         const int row0 = u.pm * BM + wr * 64 + fr, col0 = u.pn * BM + wc * 32 + 8 * fq;
; #pragma unroll
;         for (int ai = 0; ai < 2; ++ai)
; #pragma unroll
;             for (int m = 0; m < 4; ++m) { const int row = row0 + ai * HALF + m * 16; float ss = 0.f;
; #pragma unroll
;                 for (int bj = 0; bj < 2; ++bj) { const size_t off = (size_t)row * D + col0 + bj * HALF;
;                     float b[8], r[8]; unpack8(*(const u32x4*)(xb + off), b);
;                     const f32x4 v0 = acc[ai][bj][m][0], v1 = acc[ai][bj][m][1];
; #pragma unroll
;                     for (int j = 0; j < 4; ++j) { b[j] += v0[j]; b[4 + j] += v1[j]; }
;                     const u32x4 w = pack8(b);
;                     *(u32x4*)(xb + off) = w;
;                     unpack8(w, r);
; #pragma unroll
;                     for (int j = 0; j < 8; ++j) ss += r[j] * r[j]; }
;                 { const int ln = fr + 16 * fq; ss += shx(ss, 16, ln); ss += shx(ss, 32, ln); }
;                 if (fq == 0) rowss[(size_t)row * 16 + u.pn * 4 + wc] = ss; }
;     }
.LBB0_644:
	s_or_b64 exec, exec, s[28:29]
	v_add_u32_e32 v34, 0xa0, v142
	s_waitcnt lgkmcnt(0)
	v_ashrrev_i32_e32 v35, 31, v34
	v_lshlrev_b64 v[36:37], 11, v[34:35]
	v_lshl_add_u64 v[36:37], s[40:41], 0, v[36:37]
	v_lshl_add_u64 v[36:37], v[140:141], 1, v[36:37]
	s_waitcnt vmcnt(3)
	v_mov_b64_e32 v[38:39], v[222:223]
	v_mov_b64_e32 v[40:41], v[224:225]
	v_lshlrev_b32_e32 v42, 16, v38
	v_and_b32_e32 v43, 0xffff0000, v38
	v_pk_add_f32 v[30:31], v[30:31], v[42:43]
	v_lshlrev_b32_e32 v42, 16, v40
	v_and_b32_e32 v43, 0xffff0000, v40
	v_pk_add_f32 v[42:43], v[26:27], v[42:43]
	v_lshlrev_b32_e32 v26, 16, v39
	v_and_b32_e32 v27, 0xffff0000, v39
	v_pk_add_f32 v[32:33], v[32:33], v[26:27]
	v_lshlrev_b32_e32 v26, 16, v41
	v_and_b32_e32 v27, 0xffff0000, v41
	v_pk_add_f32 v[38:39], v[28:29], v[26:27]
	v_cvt_pk_bf16_f32 v26, v30, v31
	v_cvt_pk_bf16_f32 v27, v32, v33
	v_cvt_pk_bf16_f32 v28, v42, v43
	v_cvt_pk_bf16_f32 v29, v38, v39
	global_store_dwordx4 v[36:37], v[26:29], off
	v_lshlrev_b32_e32 v30, 16, v26
	v_lshlrev_b32_e32 v31, 16, v27
	v_and_b32_e32 v26, 0xffff0000, v26
	v_mul_f32_e32 v38, v26, v26
	v_fmac_f32_e32 v38, v30, v30
	v_and_b32_e32 v27, 0xffff0000, v27
	v_fmac_f32_e32 v38, v31, v31
	v_lshlrev_b32_e32 v32, 16, v28
	v_fmac_f32_e32 v38, v27, v27
	v_and_b32_e32 v28, 0xffff0000, v28
	v_fmac_f32_e32 v38, v32, v32
	v_lshlrev_b32_e32 v33, 16, v29
	v_fmac_f32_e32 v38, v28, v28
	v_and_b32_e32 v29, 0xffff0000, v29
	v_fmac_f32_e32 v38, v33, v33
	v_fmac_f32_e32 v38, v29, v29
	s_waitcnt vmcnt(2)
	v_mov_b64_e32 v[26:27], v[226:227]
	v_mov_b64_e32 v[28:29], v[228:229]
	v_lshlrev_b32_e32 v30, 16, v26
	v_and_b32_e32 v31, 0xffff0000, v26
	v_pk_add_f32 v[22:23], v[22:23], v[30:31]
	v_lshlrev_b32_e32 v30, 16, v28
	v_and_b32_e32 v31, 0xffff0000, v28
	v_pk_add_f32 v[30:31], v[18:19], v[30:31]
	v_lshlrev_b32_e32 v18, 16, v27
	v_and_b32_e32 v19, 0xffff0000, v27
	v_pk_add_f32 v[24:25], v[24:25], v[18:19]
	v_lshlrev_b32_e32 v18, 16, v29
	v_and_b32_e32 v19, 0xffff0000, v29
	v_pk_add_f32 v[26:27], v[20:21], v[18:19]
	v_cvt_pk_bf16_f32 v18, v22, v23
	v_cvt_pk_bf16_f32 v19, v24, v25
	v_cvt_pk_bf16_f32 v20, v30, v31
	v_cvt_pk_bf16_f32 v21, v26, v27
	v_lshlrev_b32_e32 v22, 16, v18
	global_store_dwordx4 v[36:37], v[18:21], off offset:256
	v_fmac_f32_e32 v38, v22, v22
	v_lshlrev_b32_e32 v23, 16, v19
	v_and_b32_e32 v18, 0xffff0000, v18
	v_fmac_f32_e32 v38, v18, v18
	v_and_b32_e32 v19, 0xffff0000, v19
	v_fmac_f32_e32 v38, v23, v23
	v_lshlrev_b32_e32 v24, 16, v20
	v_fmac_f32_e32 v38, v19, v19
	v_and_b32_e32 v20, 0xffff0000, v20
	v_fmac_f32_e32 v38, v24, v24
	v_lshlrev_b32_e32 v25, 16, v21
	v_fmac_f32_e32 v38, v20, v20
	v_and_b32_e32 v21, 0xffff0000, v21
	v_fmac_f32_e32 v38, v25, v25
	v_fmac_f32_e32 v38, v21, v21
	ds_bpermute_b32 v18, v149, v38
	s_waitcnt lgkmcnt(0)
	v_add_f32_e32 v18, v38, v18
	ds_bpermute_b32 v19, v150, v18
	s_and_saveexec_b64 s[28:29], s[6:7]
	s_cbranch_execz .LBB0_646
	s_waitcnt lgkmcnt(0)
	v_add_f32_e32 v20, v18, v19
	s_lshl_b32 s10, s0, 2
	v_lshlrev_b64 v[18:19], 6, v[34:35]
	s_ashr_i32 s11, s10, 31
	v_lshl_add_u64 v[18:19], s[42:43], 0, v[18:19]
	v_lshl_add_u64 v[18:19], s[10:11], 2, v[18:19]
	s_lshl_b32 s58, s77, 2
	v_lshl_add_u64 v[18:19], v[18:19], 0, s[58:59]
	global_store_dword v[18:19], v20, off
.LBB0_646:
	s_or_b64 exec, exec, s[28:29]
	v_add_u32_e32 v18, 0xb0, v142
	s_waitcnt lgkmcnt(0)
	v_ashrrev_i32_e32 v19, 31, v18
	v_lshlrev_b64 v[20:21], 11, v[18:19]
	v_lshl_add_u64 v[20:21], s[40:41], 0, v[20:21]
	v_lshl_add_u64 v[20:21], v[140:141], 1, v[20:21]
	s_waitcnt vmcnt(1)
	v_mov_b64_e32 v[22:23], v[236:237]
	v_mov_b64_e32 v[24:25], v[238:239]
	v_lshlrev_b32_e32 v26, 16, v22
	v_and_b32_e32 v27, 0xffff0000, v22
	v_pk_add_f32 v[14:15], v[14:15], v[26:27]
	v_lshlrev_b32_e32 v26, 16, v24
	v_and_b32_e32 v27, 0xffff0000, v24
	v_pk_add_f32 v[26:27], v[10:11], v[26:27]
	v_lshlrev_b32_e32 v10, 16, v23
	v_and_b32_e32 v11, 0xffff0000, v23
	v_pk_add_f32 v[16:17], v[16:17], v[10:11]
	v_lshlrev_b32_e32 v10, 16, v25
	v_and_b32_e32 v11, 0xffff0000, v25
	v_pk_add_f32 v[22:23], v[12:13], v[10:11]
	v_cvt_pk_bf16_f32 v10, v14, v15
	v_cvt_pk_bf16_f32 v11, v16, v17
	v_cvt_pk_bf16_f32 v12, v26, v27
	v_cvt_pk_bf16_f32 v13, v22, v23
	global_store_dwordx4 v[20:21], v[10:13], off
	v_lshlrev_b32_e32 v14, 16, v10
	v_lshlrev_b32_e32 v15, 16, v11
	v_and_b32_e32 v10, 0xffff0000, v10
	v_mul_f32_e32 v22, v10, v10
	v_fmac_f32_e32 v22, v14, v14
	v_and_b32_e32 v11, 0xffff0000, v11
	v_fmac_f32_e32 v22, v15, v15
	v_lshlrev_b32_e32 v16, 16, v12
	v_fmac_f32_e32 v22, v11, v11
	v_and_b32_e32 v12, 0xffff0000, v12
	v_fmac_f32_e32 v22, v16, v16
	v_lshlrev_b32_e32 v17, 16, v13
	v_fmac_f32_e32 v22, v12, v12
	v_and_b32_e32 v13, 0xffff0000, v13
	v_fmac_f32_e32 v22, v17, v17
	v_fmac_f32_e32 v22, v13, v13
	s_waitcnt vmcnt(0)
	v_mov_b64_e32 v[10:11], v[248:249]
	v_mov_b64_e32 v[12:13], v[250:251]
	v_lshlrev_b32_e32 v14, 16, v10
	v_and_b32_e32 v15, 0xffff0000, v10
	v_pk_add_f32 v[6:7], v[6:7], v[14:15]
	v_lshlrev_b32_e32 v14, 16, v12
	v_and_b32_e32 v15, 0xffff0000, v12
	v_pk_add_f32 v[14:15], v[2:3], v[14:15]
	v_lshlrev_b32_e32 v2, 16, v11
	v_and_b32_e32 v3, 0xffff0000, v11
	v_pk_add_f32 v[8:9], v[8:9], v[2:3]
	v_lshlrev_b32_e32 v2, 16, v13
	v_and_b32_e32 v3, 0xffff0000, v13
	v_pk_add_f32 v[10:11], v[4:5], v[2:3]
	v_cvt_pk_bf16_f32 v2, v6, v7
	v_cvt_pk_bf16_f32 v3, v8, v9
	v_cvt_pk_bf16_f32 v4, v14, v15
	v_cvt_pk_bf16_f32 v5, v10, v11
	v_lshlrev_b32_e32 v6, 16, v2
	global_store_dwordx4 v[20:21], v[2:5], off offset:256
	v_fmac_f32_e32 v22, v6, v6
	v_lshlrev_b32_e32 v7, 16, v3
	v_and_b32_e32 v2, 0xffff0000, v2
	v_fmac_f32_e32 v22, v2, v2
	v_and_b32_e32 v3, 0xffff0000, v3
	v_fmac_f32_e32 v22, v7, v7
	v_lshlrev_b32_e32 v8, 16, v4
	v_fmac_f32_e32 v22, v3, v3
	v_and_b32_e32 v4, 0xffff0000, v4
	v_fmac_f32_e32 v22, v8, v8
	v_lshlrev_b32_e32 v9, 16, v5
	v_fmac_f32_e32 v22, v4, v4
	v_and_b32_e32 v5, 0xffff0000, v5
	v_fmac_f32_e32 v22, v9, v9
	v_fmac_f32_e32 v22, v5, v5
	ds_bpermute_b32 v2, v149, v22
	s_waitcnt lgkmcnt(0)
	v_add_f32_e32 v2, v22, v2
	ds_bpermute_b32 v3, v150, v2
	s_and_saveexec_b64 s[28:29], s[6:7]
	s_cbranch_execz .LBB0_623
	s_waitcnt lgkmcnt(0)
	v_add_f32_e32 v4, v2, v3
	s_lshl_b32 s10, s0, 2
	v_lshlrev_b64 v[2:3], 6, v[18:19]
	s_ashr_i32 s11, s10, 31
	v_lshl_add_u64 v[2:3], s[42:43], 0, v[2:3]
	v_lshl_add_u64 v[2:3], s[10:11], 2, v[2:3]
	s_lshl_b32 s58, s77, 2
	v_lshl_add_u64 v[2:3], v[2:3], 0, s[58:59]
	global_store_dword v[2:3], v4, off
	s_branch .LBB0_623

; #define PG8_STAGE(bufoff, gbase, voff) do { _Pragma("unroll") for (int _i = 0; _i < 2; ++_i) \
;         __builtin_amdgcn_global_load_lds((const unsigned*)((const char*)(gbase) + (voff)[_i]), (LAS unsigned*)(lds + (bufoff) + ldsw + _i * 8192), 16, 0, 0); } while (0)
; #define PG8_LDA(dst, b, h) do { _Pragma("unroll") for (int m = 0; m < 4; ++m) _Pragma("unroll") for (int k = 0; k < 2; ++k) dst[m][k] = *(const LAS bf16x8*)(lds + PG8_SA(b, h) + aoff + m * 2048 + k * 1024); } while (0)
; #define PG8_LDB(dst, b, h) do { _Pragma("unroll") for (int n = 0; n < 2; ++n) _Pragma("unroll") for (int k = 0; k < 2; ++k) dst[n][k] = *(const LAS bf16x8*)(lds + PG8_SB(b, h) + boff + n * 2048 + k * 1024); } while (0)
; #define PG8_WAIT_V(n) asm volatile("s_waitcnt vmcnt(" #n ")" ::: "memory")
; #define PG8_WAIT_L(n) asm volatile("s_waitcnt lgkmcnt(" #n ")" ::: "memory")
; #define PG8_BAR __builtin_amdgcn_s_barrier()
; #define PG8_SCHED __builtin_amdgcn_sched_barrier(0)
; template <class Epi, class Sched>
; __device__ __forceinline__ void gemm_phase(LAS unsigned char* lds, const Gemm g, const Sched& S, const Epi& E) {
;     ...
;             PG8_LDB(B0, 0, 0); PG8_SCHED; PG8_LDA(At, 0, 0); PG8_STAGE(PG8_SA(1, 1), a1 + hstep, voffA);
;             PG8_WAIT_L(8); PG8_BAR; PG8_WAIT_L(0); PG8_MMA(0, 0, At, B0); PG8_BAR; PG8_SCHED;
;             PG8_LDB(B1, 0, 1); PG8_STAGE(PG8_SB(0, 0), b2, voffB);
;             PG8_BAR; PG8_WAIT_L(0); PG8_MMA(0, 1, At, B1); PG8_BAR;
;             PG8_LDA(At, 0, 1); PG8_STAGE(PG8_SA(0, 0), a2, voffA);
;             PG8_BAR; PG8_WAIT_L(0); PG8_MMA(1, 0, At, B0); PG8_BAR; PG8_SCHED;
;             PG8_STAGE(PG8_SB(0, 1), b2 + hstep, voffB);
;             PG8_WAIT_V(6); PG8_BAR; PG8_MMA(1, 1, At, B1); PG8_BAR;
;             PG8_LDB(B0, 1, 0); PG8_SCHED; PG8_LDA(At, 1, 0); PG8_STAGE(PG8_SA(0, 1), a2 + hstep, voffA);
;             PG8_WAIT_L(8); PG8_BAR; PG8_WAIT_L(0); PG8_MMA(0, 0, At, B0); PG8_BAR; PG8_SCHED;
;             PG8_LDB(B1, 1, 1); PG8_STAGE(PG8_SB(1, 0), b3, voffB);
;             PG8_BAR; PG8_WAIT_L(0); PG8_MMA(0, 1, At, B1); PG8_BAR;
;             PG8_LDA(At, 1, 1); PG8_STAGE(PG8_SA(1, 0), a3, voffA);
;             PG8_BAR; PG8_WAIT_L(0); PG8_MMA(1, 0, At, B0); PG8_BAR; PG8_SCHED;
;             PG8_STAGE(PG8_SB(1, 1), b3 + hstep, voffB);
;             PG8_WAIT_V(6); PG8_BAR; PG8_MMA(1, 1, At, B1); PG8_BAR;
.LBB0_851:
	s_add_u32 s44, s28, 0x100
	s_addc_u32 s45, s29, 0
	s_add_i32 s34, 0, 0x10000
	v_add_u32_e32 v144, s34, v147
	ds_read_b128 v[140:143], v144
	ds_read_b128 v[152:155], v144 offset:1024
	ds_read_b128 v[156:159], v144 offset:2048
	ds_read_b128 v[160:163], v144 offset:3072
	s_cmp_eq_u32 s17, 40
	s_cselect_b32 s79, s9, s45
	s_cselect_b32 s78, s8, s44
	s_cselect_b32 s69, s1, s16
	s_cselect_b32 s68, s0, s11
	v_lshl_add_u64 v[144:145], s[28:29], 0, v[136:137]
	s_add_i32 m0, s73, 0xc000
	ds_read_b128 v[164:167], v151
	ds_read_b128 v[168:171], v151 offset:1024
	ds_read_b128 v[172:175], v151 offset:2048
	ds_read_b128 v[176:179], v151 offset:3072
	ds_read_b128 v[180:183], v151 offset:4096
	ds_read_b128 v[184:187], v151 offset:5120
	ds_read_b128 v[188:191], v151 offset:6144
	ds_read_b128 v[192:195], v151 offset:7168
	global_load_lds_dwordx4 v[144:145], off
	v_lshl_add_u64 v[144:145], s[28:29], 0, v[138:139]
	s_add_i32 m0, s73, 0xe000
	s_nop 0
	global_load_lds_dwordx4 v[144:145], off
	s_waitcnt lgkmcnt(8)
	s_barrier
	s_waitcnt lgkmcnt(0)
	s_setprio 1
	s_waitcnt lgkmcnt(0)
	v_mfma_f32_16x16x32_bf16 v[126:129], v[140:143], v[164:167], v[126:129]
	v_mfma_f32_16x16x32_bf16 v[122:125], v[156:159], v[164:167], v[122:125]
	v_mfma_f32_16x16x32_bf16 v[110:113], v[140:143], v[172:175], v[110:113]
	v_mfma_f32_16x16x32_bf16 v[106:109], v[156:159], v[172:175], v[106:109]
	v_mfma_f32_16x16x32_bf16 v[94:97], v[140:143], v[180:183], v[94:97]
	v_mfma_f32_16x16x32_bf16 v[90:93], v[156:159], v[180:183], v[90:93]
	v_mfma_f32_16x16x32_bf16 v[78:81], v[140:143], v[188:191], v[78:81]
	v_mfma_f32_16x16x32_bf16 v[74:77], v[156:159], v[188:191], v[74:77]
	v_mfma_f32_16x16x32_bf16 v[126:129], v[152:155], v[168:171], v[126:129]
	v_mfma_f32_16x16x32_bf16 v[122:125], v[160:163], v[168:171], v[122:125]
	v_mfma_f32_16x16x32_bf16 v[110:113], v[152:155], v[176:179], v[110:113]
	v_mfma_f32_16x16x32_bf16 v[106:109], v[160:163], v[176:179], v[106:109]
	v_mfma_f32_16x16x32_bf16 v[94:97], v[152:155], v[184:187], v[94:97]
	v_mfma_f32_16x16x32_bf16 v[90:93], v[160:163], v[184:187], v[90:93]
	v_mfma_f32_16x16x32_bf16 v[78:81], v[152:155], v[192:195], v[78:81]
	v_mfma_f32_16x16x32_bf16 v[74:77], v[160:163], v[192:195], v[74:77]
	s_setprio 0
	s_barrier
	s_add_i32 s38, 0, 0x14000
	v_add_u32_e32 v144, s38, v147
	s_add_i32 s28, s34, s72
	ds_read_b128 v[196:199], v144
	ds_read_b128 v[200:203], v144 offset:1024
	ds_read_b128 v[204:207], v144 offset:2048
	ds_read_b128 v[208:211], v144 offset:3072
	v_lshl_add_u64 v[144:145], s[68:69], 0, v[0:1]
	s_mov_b32 m0, s28
	v_lshl_add_u64 v[212:213], s[68:69], 0, v[134:135]
	global_load_lds_dwordx4 v[144:145], off
	s_add_i32 m0, s28, 0x2000
	s_nop 0
	global_load_lds_dwordx4 v[212:213], off
	s_barrier
	s_waitcnt lgkmcnt(0)
	s_setprio 1
	s_waitcnt lgkmcnt(0)
	v_mfma_f32_16x16x32_bf16 v[118:121], v[196:199], v[164:167], v[118:121]
	v_mfma_f32_16x16x32_bf16 v[114:117], v[204:207], v[164:167], v[114:117]
	v_mfma_f32_16x16x32_bf16 v[102:105], v[196:199], v[172:175], v[102:105]
	v_mfma_f32_16x16x32_bf16 v[98:101], v[204:207], v[172:175], v[98:101]
	v_mfma_f32_16x16x32_bf16 v[86:89], v[196:199], v[180:183], v[86:89]
	v_mfma_f32_16x16x32_bf16 v[82:85], v[204:207], v[180:183], v[82:85]
	v_mfma_f32_16x16x32_bf16 v[70:73], v[196:199], v[188:191], v[70:73]
	v_mfma_f32_16x16x32_bf16 v[66:69], v[204:207], v[188:191], v[66:69]
	v_mfma_f32_16x16x32_bf16 v[118:121], v[200:203], v[168:171], v[118:121]
	v_mfma_f32_16x16x32_bf16 v[114:117], v[208:211], v[168:171], v[114:117]
	v_mfma_f32_16x16x32_bf16 v[102:105], v[200:203], v[176:179], v[102:105]
	v_mfma_f32_16x16x32_bf16 v[98:101], v[208:211], v[176:179], v[98:101]
	v_mfma_f32_16x16x32_bf16 v[86:89], v[200:203], v[184:187], v[86:89]
	v_mfma_f32_16x16x32_bf16 v[82:85], v[208:211], v[184:187], v[82:85]
	v_mfma_f32_16x16x32_bf16 v[70:73], v[200:203], v[192:195], v[70:73]
	v_mfma_f32_16x16x32_bf16 v[66:69], v[208:211], v[192:195], v[66:69]
	s_setprio 0
	s_mov_b32 m0, s73
	v_lshl_add_u64 v[214:215], s[78:79], 0, v[130:131]
	s_barrier
	ds_read_b128 v[164:167], v151 offset:16384
	ds_read_b128 v[168:171], v151 offset:17408
	ds_read_b128 v[172:175], v151 offset:18432
	ds_read_b128 v[176:179], v151 offset:19456
	ds_read_b128 v[180:183], v151 offset:20480
	ds_read_b128 v[184:187], v151 offset:21504
	ds_read_b128 v[188:191], v151 offset:22528
	ds_read_b128 v[192:195], v151 offset:23552
	global_load_lds_dwordx4 v[214:215], off
	v_lshl_add_u64 v[216:217], s[78:79], 0, v[132:133]
	s_mov_b32 m0, s76
	s_nop 0
	global_load_lds_dwordx4 v[216:217], off
	s_barrier
	s_waitcnt lgkmcnt(0)
	s_setprio 1
	s_waitcnt lgkmcnt(0)
	v_mfma_f32_16x16x32_bf16 v[62:65], v[140:143], v[164:167], v[62:65]
	v_mfma_f32_16x16x32_bf16 v[58:61], v[156:159], v[164:167], v[58:61]
	v_mfma_f32_16x16x32_bf16 v[46:49], v[140:143], v[172:175], v[46:49]
	v_mfma_f32_16x16x32_bf16 v[42:45], v[156:159], v[172:175], v[42:45]
	v_mfma_f32_16x16x32_bf16 v[30:33], v[140:143], v[180:183], v[30:33]
	v_mfma_f32_16x16x32_bf16 v[26:29], v[156:159], v[180:183], v[26:29]
	v_mfma_f32_16x16x32_bf16 v[14:17], v[140:143], v[188:191], v[14:17]
	v_mfma_f32_16x16x32_bf16 v[10:13], v[156:159], v[188:191], v[10:13]
	v_mfma_f32_16x16x32_bf16 v[62:65], v[152:155], v[168:171], v[62:65]
	v_mfma_f32_16x16x32_bf16 v[58:61], v[160:163], v[168:171], v[58:61]
	v_mfma_f32_16x16x32_bf16 v[46:49], v[152:155], v[176:179], v[46:49]
	v_mfma_f32_16x16x32_bf16 v[42:45], v[160:163], v[176:179], v[42:45]
	v_mfma_f32_16x16x32_bf16 v[30:33], v[152:155], v[184:187], v[30:33]
	v_mfma_f32_16x16x32_bf16 v[26:29], v[160:163], v[184:187], v[26:29]
	v_mfma_f32_16x16x32_bf16 v[14:17], v[152:155], v[192:195], v[14:17]
	v_mfma_f32_16x16x32_bf16 v[10:13], v[160:163], v[192:195], v[10:13]
	s_setprio 0
	s_barrier
; #define PG8_STAGE(bufoff, gbase, voff) do { _Pragma("unroll") for (int _i = 0; _i < 2; ++_i) \
;         __builtin_amdgcn_global_load_lds((const unsigned*)((const char*)(gbase) + (voff)[_i]), (LAS unsigned*)(lds + (bufoff) + ldsw + _i * 8192), 16, 0, 0); } while (0)
; #define PG8_LDA(dst, b, h) do { _Pragma("unroll") for (int m = 0; m < 4; ++m) _Pragma("unroll") for (int k = 0; k < 2; ++k) dst[m][k] = *(const LAS bf16x8*)(lds + PG8_SA(b, h) + aoff + m * 2048 + k * 1024); } while (0)
; #define PG8_LDB(dst, b, h) do { _Pragma("unroll") for (int n = 0; n < 2; ++n) _Pragma("unroll") for (int k = 0; k < 2; ++k) dst[n][k] = *(const LAS bf16x8*)(lds + PG8_SB(b, h) + boff + n * 2048 + k * 1024); } while (0)
; #define PG8_WAIT_V(n) asm volatile("s_waitcnt vmcnt(" #n ")" ::: "memory")
; #define PG8_WAIT_L(n) asm volatile("s_waitcnt lgkmcnt(" #n ")" ::: "memory")
; #define PG8_BAR __builtin_amdgcn_s_barrier()
; #define PG8_SCHED __builtin_amdgcn_sched_barrier(0)
; template <class Epi, class Sched>
; __device__ __forceinline__ void gemm_phase(LAS unsigned char* lds, const Gemm g, const Sched& S, const Epi& E) {
;     ...
;             PG8_LDB(B0, 0, 0); PG8_SCHED; PG8_LDA(At, 0, 0); PG8_STAGE(PG8_SA(1, 1), a1 + hstep, voffA);
;             PG8_WAIT_L(8); PG8_BAR; PG8_WAIT_L(0); PG8_MMA(0, 0, At, B0); PG8_BAR; PG8_SCHED;
;             PG8_LDB(B1, 0, 1); PG8_STAGE(PG8_SB(0, 0), b2, voffB);
;             PG8_BAR; PG8_WAIT_L(0); PG8_MMA(0, 1, At, B1); PG8_BAR;
;             PG8_LDA(At, 0, 1); PG8_STAGE(PG8_SA(0, 0), a2, voffA);
;             PG8_BAR; PG8_WAIT_L(0); PG8_MMA(1, 0, At, B0); PG8_BAR; PG8_SCHED;
;             PG8_STAGE(PG8_SB(0, 1), b2 + hstep, voffB);
;             PG8_WAIT_V(6); PG8_BAR; PG8_MMA(1, 1, At, B1); PG8_BAR;
;             PG8_LDB(B0, 1, 0); PG8_SCHED; PG8_LDA(At, 1, 0); PG8_STAGE(PG8_SA(0, 1), a2 + hstep, voffA);
;             PG8_WAIT_L(8); PG8_BAR; PG8_WAIT_L(0); PG8_MMA(0, 0, At, B0); PG8_BAR; PG8_SCHED;
;             PG8_LDB(B1, 1, 1); PG8_STAGE(PG8_SB(1, 0), b3, voffB);
;             PG8_BAR; PG8_WAIT_L(0); PG8_MMA(0, 1, At, B1); PG8_BAR;
;             PG8_LDA(At, 1, 1); PG8_STAGE(PG8_SA(1, 0), a3, voffA);
;             PG8_BAR; PG8_WAIT_L(0); PG8_MMA(1, 0, At, B0); PG8_BAR; PG8_SCHED;
;             PG8_STAGE(PG8_SB(1, 1), b3 + hstep, voffB);
;             PG8_WAIT_V(6); PG8_BAR; PG8_MMA(1, 1, At, B1); PG8_BAR;
	s_add_u32 s28, s68, 0xb0000
	s_addc_u32 s29, s69, 0
	s_add_i32 s34, s38, s72
	v_lshl_add_u64 v[140:141], s[28:29], 0, v[0:1]
	s_mov_b32 m0, s34
	s_nop 0
	global_load_lds_dwordx4 v[140:141], off
	v_lshl_add_u64 v[140:141], s[28:29], 0, v[134:135]
	s_add_i32 m0, s34, 0x2000
	s_nop 0
	global_load_lds_dwordx4 v[140:141], off
	s_waitcnt vmcnt(6)
	s_barrier
	s_setprio 1
	v_mfma_f32_16x16x32_bf16 v[54:57], v[196:199], v[164:167], v[54:57]
	v_mfma_f32_16x16x32_bf16 v[50:53], v[204:207], v[164:167], v[50:53]
	v_mfma_f32_16x16x32_bf16 v[38:41], v[196:199], v[172:175], v[38:41]
	v_mfma_f32_16x16x32_bf16 v[34:37], v[204:207], v[172:175], v[34:37]
	v_mfma_f32_16x16x32_bf16 v[22:25], v[196:199], v[180:183], v[22:25]
	v_mfma_f32_16x16x32_bf16 v[18:21], v[204:207], v[180:183], v[18:21]
	v_mfma_f32_16x16x32_bf16 v[6:9], v[196:199], v[188:191], v[6:9]
	v_mfma_f32_16x16x32_bf16 v[2:5], v[204:207], v[188:191], v[2:5]
	v_mfma_f32_16x16x32_bf16 v[54:57], v[200:203], v[168:171], v[54:57]
	v_mfma_f32_16x16x32_bf16 v[50:53], v[208:211], v[168:171], v[50:53]
	v_mfma_f32_16x16x32_bf16 v[38:41], v[200:203], v[176:179], v[38:41]
	v_mfma_f32_16x16x32_bf16 v[34:37], v[208:211], v[176:179], v[34:37]
	v_mfma_f32_16x16x32_bf16 v[22:25], v[200:203], v[184:187], v[22:25]
	v_mfma_f32_16x16x32_bf16 v[18:21], v[208:211], v[184:187], v[18:21]
	v_mfma_f32_16x16x32_bf16 v[6:9], v[200:203], v[192:195], v[6:9]
	v_mfma_f32_16x16x32_bf16 v[2:5], v[208:211], v[192:195], v[2:5]
	s_setprio 0
	s_add_i32 s34, 0, 0x18000
	v_add_u32_e32 v160, s34, v147
	s_barrier
	ds_read_b128 v[140:143], v160
	ds_read_b128 v[152:155], v160 offset:1024
	ds_read_b128 v[156:159], v160 offset:2048
	ds_read_b128 v[160:163], v160 offset:3072
	s_add_u32 s28, s78, 0xb0000
	s_addc_u32 s29, s79, 0
	s_mov_b32 m0, s77
	v_lshl_add_u64 v[196:197], s[28:29], 0, v[130:131]
	ds_read_b128 v[164:167], v151 offset:32768
	ds_read_b128 v[168:171], v151 offset:33792
	ds_read_b128 v[172:175], v151 offset:34816
	ds_read_b128 v[176:179], v151 offset:35840
	ds_read_b128 v[180:183], v151 offset:36864
	ds_read_b128 v[184:187], v151 offset:37888
	ds_read_b128 v[188:191], v151 offset:38912
	ds_read_b128 v[192:195], v151 offset:39936
	global_load_lds_dwordx4 v[196:197], off
	v_lshl_add_u64 v[196:197], s[28:29], 0, v[132:133]
	s_mov_b32 m0, s82
	s_nop 0
	global_load_lds_dwordx4 v[196:197], off
	s_waitcnt lgkmcnt(8)
	s_barrier
	s_waitcnt lgkmcnt(0)
	s_setprio 1
	s_waitcnt lgkmcnt(0)
	v_mfma_f32_16x16x32_bf16 v[126:129], v[140:143], v[164:167], v[126:129]
	v_mfma_f32_16x16x32_bf16 v[122:125], v[156:159], v[164:167], v[122:125]
	v_mfma_f32_16x16x32_bf16 v[110:113], v[140:143], v[172:175], v[110:113]
	v_mfma_f32_16x16x32_bf16 v[106:109], v[156:159], v[172:175], v[106:109]
	v_mfma_f32_16x16x32_bf16 v[94:97], v[140:143], v[180:183], v[94:97]
	v_mfma_f32_16x16x32_bf16 v[90:93], v[156:159], v[180:183], v[90:93]
	v_mfma_f32_16x16x32_bf16 v[78:81], v[140:143], v[188:191], v[78:81]
	v_mfma_f32_16x16x32_bf16 v[74:77], v[156:159], v[188:191], v[74:77]
	v_mfma_f32_16x16x32_bf16 v[126:129], v[152:155], v[168:171], v[126:129]
	v_mfma_f32_16x16x32_bf16 v[122:125], v[160:163], v[168:171], v[122:125]
	v_mfma_f32_16x16x32_bf16 v[110:113], v[152:155], v[176:179], v[110:113]
	v_mfma_f32_16x16x32_bf16 v[106:109], v[160:163], v[176:179], v[106:109]
	v_mfma_f32_16x16x32_bf16 v[94:97], v[152:155], v[184:187], v[94:97]
	v_mfma_f32_16x16x32_bf16 v[90:93], v[160:163], v[184:187], v[90:93]
	v_mfma_f32_16x16x32_bf16 v[78:81], v[152:155], v[192:195], v[78:81]
	v_mfma_f32_16x16x32_bf16 v[74:77], v[160:163], v[192:195], v[74:77]
	s_setprio 0
	s_barrier
	s_add_i32 s38, 0, 0x1c000
	s_add_i32 s28, s34, s72
	v_add_u32_e32 v208, s38, v147
	v_lshl_add_u64 v[144:145], v[144:145], 0, s[62:63]
	s_mov_b32 m0, s28
	ds_read_b128 v[196:199], v208
	ds_read_b128 v[200:203], v208 offset:1024
	ds_read_b128 v[204:207], v208 offset:2048
	ds_read_b128 v[208:211], v208 offset:3072
	global_load_lds_dwordx4 v[144:145], off
	v_lshl_add_u64 v[144:145], v[212:213], 0, s[62:63]
	s_add_i32 m0, s28, 0x2000
	s_nop 0
	global_load_lds_dwordx4 v[144:145], off
	s_barrier
	s_waitcnt lgkmcnt(0)
	s_setprio 1
	s_waitcnt lgkmcnt(0)
	v_mfma_f32_16x16x32_bf16 v[118:121], v[196:199], v[164:167], v[118:121]
	v_mfma_f32_16x16x32_bf16 v[114:117], v[204:207], v[164:167], v[114:117]
	v_mfma_f32_16x16x32_bf16 v[102:105], v[196:199], v[172:175], v[102:105]
	v_mfma_f32_16x16x32_bf16 v[98:101], v[204:207], v[172:175], v[98:101]
	v_mfma_f32_16x16x32_bf16 v[86:89], v[196:199], v[180:183], v[86:89]
	v_mfma_f32_16x16x32_bf16 v[82:85], v[204:207], v[180:183], v[82:85]
	v_mfma_f32_16x16x32_bf16 v[70:73], v[196:199], v[188:191], v[70:73]
	v_mfma_f32_16x16x32_bf16 v[66:69], v[204:207], v[188:191], v[66:69]
	v_mfma_f32_16x16x32_bf16 v[118:121], v[200:203], v[168:171], v[118:121]
	v_mfma_f32_16x16x32_bf16 v[114:117], v[208:211], v[168:171], v[114:117]
	v_mfma_f32_16x16x32_bf16 v[102:105], v[200:203], v[176:179], v[102:105]
	v_mfma_f32_16x16x32_bf16 v[98:101], v[208:211], v[176:179], v[98:101]
	v_mfma_f32_16x16x32_bf16 v[86:89], v[200:203], v[184:187], v[86:89]
	v_mfma_f32_16x16x32_bf16 v[82:85], v[208:211], v[184:187], v[82:85]
	v_mfma_f32_16x16x32_bf16 v[70:73], v[200:203], v[192:195], v[70:73]
	v_mfma_f32_16x16x32_bf16 v[66:69], v[208:211], v[192:195], v[66:69]
	s_setprio 0
	s_mov_b32 m0, s84
	v_lshl_add_u64 v[144:145], v[214:215], 0, s[62:63]
	s_barrier
	ds_read_b128 v[164:167], v151 offset:49152
	ds_read_b128 v[168:171], v151 offset:50176
	ds_read_b128 v[172:175], v151 offset:51200
	ds_read_b128 v[176:179], v151 offset:52224
	ds_read_b128 v[180:183], v151 offset:53248
	ds_read_b128 v[184:187], v151 offset:54272
	ds_read_b128 v[188:191], v151 offset:55296
	ds_read_b128 v[192:195], v151 offset:56320
	global_load_lds_dwordx4 v[144:145], off
	v_lshl_add_u64 v[144:145], v[216:217], 0, s[62:63]
	s_mov_b32 m0, s85
	s_nop 0
	global_load_lds_dwordx4 v[144:145], off
	s_barrier
; __device__ __forceinline__ void unpack8(const u32x4 w, float* f) { f[0] = bf_lo(w.x); f[1] = bf_hi(w.x); f[2] = bf_lo(w.y); f[3] = bf_hi(w.y); f[4] = bf_lo(w.z); f[5] = bf_hi(w.z); f[6] = bf_lo(w.w); f[7] = bf_hi(w.w); }
; __device__ __forceinline__ u32x4 pack8(const float* f) { u32x4 w; w.x = cvt_pk_bf16(f[0], f[1]); w.y = cvt_pk_bf16(f[2], f[3]); w.z = cvt_pk_bf16(f[4], f[5]); w.w = cvt_pk_bf16(f[6], f[7]); return w; }
; #define PG8_WAIT_V(n) asm volatile("s_waitcnt vmcnt(" #n ")" ::: "memory")
; template <class Epi, class Sched>
; __device__ __forceinline__ void gemm_phase(LAS unsigned char* lds, const Gemm g, const Sched& S, const Epi& E) {
;     ...
;             PG8_WAIT_L(8); PG8_BAR; PG8_WAIT_L(0); PG8_MMA(0, 0, At, B0); PG8_BAR; PG8_SCHED;
;             PG8_LDB(B1, 1, 1); PG8_STAGE(PG8_SB(1, 0), b3, voffB);
;             PG8_BAR; PG8_WAIT_L(0); PG8_MMA(0, 1, At, B1); PG8_BAR;
;             PG8_LDA(At, 1, 1); PG8_STAGE(PG8_SA(1, 0), a3, voffA);
;             PG8_BAR; PG8_WAIT_L(0); PG8_MMA(1, 0, At, B0); PG8_BAR; PG8_SCHED;
;             PG8_STAGE(PG8_SB(1, 1), b3 + hstep, voffB);
;             PG8_WAIT_V(6); PG8_BAR; PG8_MMA(1, 1, At, B1); PG8_BAR;
;         }
;     __device__ __forceinline__ void operator()(const f32x4 (&acc)[2][2][4][2], const Unit& u, int wr, int wc, int fr, int fq) const {
;         const int row0 = u.pm * BM + wr * 64 + fr, col0 = u.pn * BM + wc * 32 + 8 * fq;
; #pragma unroll
;         for (int ai = 0; ai < 2; ++ai)
; #pragma unroll
;             for (int m = 0; m < 4; ++m) { const int row = row0 + ai * HALF + m * 16; float ss = 0.f;
; #pragma unroll
;                 for (int bj = 0; bj < 2; ++bj) { const size_t off = (size_t)row * D + col0 + bj * HALF;
;                     float b[8], r[8]; unpack8(*(const u32x4*)(xb + off), b);
;                     const f32x4 v0 = acc[ai][bj][m][0], v1 = acc[ai][bj][m][1];
; #pragma unroll
;                     for (int j = 0; j < 4; ++j) { b[j] += v0[j]; b[4 + j] += v1[j]; }
;                     const u32x4 w = pack8(b);
;                     *(u32x4*)(xb + off) = w;
;                     unpack8(w, r);
; #pragma unroll
;                     for (int j = 0; j < 8; ++j) ss += r[j] * r[j]; }
;                 { const int ln = fr + 16 * fq; ss += shx(ss, 16, ln); ss += shx(ss, 32, ln); }
;                 if (fq == 0) rowss[(size_t)row * 16 + u.pn * 4 + wc] = ss; }
;     }
	s_waitcnt lgkmcnt(0)
	s_setprio 1
	s_waitcnt lgkmcnt(0)
	v_mfma_f32_16x16x32_bf16 v[62:65], v[140:143], v[164:167], v[62:65]
	v_mfma_f32_16x16x32_bf16 v[58:61], v[156:159], v[164:167], v[58:61]
	v_mfma_f32_16x16x32_bf16 v[46:49], v[140:143], v[172:175], v[46:49]
	v_mfma_f32_16x16x32_bf16 v[42:45], v[156:159], v[172:175], v[42:45]
	v_mfma_f32_16x16x32_bf16 v[30:33], v[140:143], v[180:183], v[30:33]
	v_mfma_f32_16x16x32_bf16 v[26:29], v[156:159], v[180:183], v[26:29]
	v_mfma_f32_16x16x32_bf16 v[14:17], v[140:143], v[188:191], v[14:17]
	v_mfma_f32_16x16x32_bf16 v[10:13], v[156:159], v[188:191], v[10:13]
	v_mfma_f32_16x16x32_bf16 v[62:65], v[152:155], v[168:171], v[62:65]
	v_mfma_f32_16x16x32_bf16 v[58:61], v[160:163], v[168:171], v[58:61]
	v_mfma_f32_16x16x32_bf16 v[46:49], v[152:155], v[176:179], v[46:49]
	v_mfma_f32_16x16x32_bf16 v[42:45], v[160:163], v[176:179], v[42:45]
	v_mfma_f32_16x16x32_bf16 v[30:33], v[152:155], v[184:187], v[30:33]
	v_mfma_f32_16x16x32_bf16 v[26:29], v[160:163], v[184:187], v[26:29]
	v_mfma_f32_16x16x32_bf16 v[14:17], v[152:155], v[192:195], v[14:17]
	v_mfma_f32_16x16x32_bf16 v[10:13], v[160:163], v[192:195], v[10:13]
	s_setprio 0
	s_barrier
	s_add_u32 s28, s68, 0xb0080
	s_addc_u32 s29, s69, 0
	s_add_i32 s34, s38, s72
	v_lshl_add_u64 v[140:141], s[28:29], 0, v[0:1]
	s_mov_b32 m0, s34
	s_nop 0
	global_load_lds_dwordx4 v[140:141], off
	v_lshl_add_u64 v[140:141], s[28:29], 0, v[134:135]
	s_add_i32 m0, s34, 0x2000
	s_nop 0
	global_load_lds_dwordx4 v[140:141], off
	s_waitcnt vmcnt(6)
	s_barrier
	s_setprio 1
	v_mfma_f32_16x16x32_bf16 v[54:57], v[196:199], v[164:167], v[54:57]
	v_mfma_f32_16x16x32_bf16 v[50:53], v[204:207], v[164:167], v[50:53]
	v_mfma_f32_16x16x32_bf16 v[38:41], v[196:199], v[172:175], v[38:41]
	v_mfma_f32_16x16x32_bf16 v[34:37], v[204:207], v[172:175], v[34:37]
	v_mfma_f32_16x16x32_bf16 v[22:25], v[196:199], v[180:183], v[22:25]
	v_mfma_f32_16x16x32_bf16 v[18:21], v[204:207], v[180:183], v[18:21]
	v_mfma_f32_16x16x32_bf16 v[6:9], v[196:199], v[188:191], v[6:9]
	v_mfma_f32_16x16x32_bf16 v[2:5], v[204:207], v[188:191], v[2:5]
	v_mfma_f32_16x16x32_bf16 v[54:57], v[200:203], v[168:171], v[54:57]
	v_mfma_f32_16x16x32_bf16 v[50:53], v[208:211], v[168:171], v[50:53]
	v_mfma_f32_16x16x32_bf16 v[38:41], v[200:203], v[176:179], v[38:41]
	v_mfma_f32_16x16x32_bf16 v[34:37], v[208:211], v[176:179], v[34:37]
	v_mfma_f32_16x16x32_bf16 v[22:25], v[200:203], v[184:187], v[22:25]
	v_mfma_f32_16x16x32_bf16 v[18:21], v[208:211], v[184:187], v[18:21]
	v_mfma_f32_16x16x32_bf16 v[6:9], v[200:203], v[192:195], v[6:9]
	v_mfma_f32_16x16x32_bf16 v[2:5], v[208:211], v[192:195], v[2:5]
	s_setprio 0
	s_add_i32 s17, s17, 2
	s_add_u32 s11, s11, 0x100
	s_addc_u32 s16, s16, 0
	s_cmp_gt_u32 s17, 41
	s_mov_b64 s[28:29], s[44:45]
	s_barrier
	s_cbranch_scc0 .LBB0_851
	v_lshl_add_u32 v142, s10, 8, v146
	v_ashrrev_i32_e32 v143, 31, v142
	v_lshl_or_b32 v140, s37, 8, v148
	v_lshlrev_b64 v[144:145], 11, v[142:143]
	v_ashrrev_i32_e32 v141, 31, v140
	v_lshl_add_u64 v[144:145], s[40:41], 0, v[144:145]
	v_lshl_add_u64 v[144:145], v[140:141], 1, v[144:145]
	global_load_dwordx4 v[158:161], v[144:145], off
	global_load_dwordx4 v[162:165], v[144:145], off offset:256
	s_mov_b32 s100, 0x8000
	s_mov_b32 s101, 0
	v_lshl_add_u64 v[230:231], v[144:145], 0, s[100:101]
	global_load_dwordx4 v[166:169], v[230:231], off
	global_load_dwordx4 v[170:173], v[230:231], off offset:256
	v_lshl_add_u64 v[230:231], v[230:231], 0, s[100:101]
	global_load_dwordx4 v[190:193], v[230:231], off
	global_load_dwordx4 v[194:197], v[230:231], off offset:256
	v_lshl_add_u64 v[230:231], v[230:231], 0, s[100:101]
	global_load_dwordx4 v[198:201], v[230:231], off
	global_load_dwordx4 v[202:205], v[230:231], off offset:256
	s_mov_b32 s100, 0x28000
	v_lshl_add_u64 v[230:231], v[230:231], 0, s[100:101]
	global_load_dwordx4 v[206:209], v[230:231], off
	global_load_dwordx4 v[210:213], v[230:231], off offset:256
	s_mov_b32 s100, 0x8000
	v_lshl_add_u64 v[230:231], v[230:231], 0, s[100:101]
	global_load_dwordx4 v[214:217], v[230:231], off
	global_load_dwordx4 v[218:221], v[230:231], off offset:256
	v_lshl_add_u64 v[230:231], v[230:231], 0, s[100:101]
	global_load_dwordx4 v[222:225], v[230:231], off
	global_load_dwordx4 v[226:229], v[230:231], off offset:256
	v_lshl_add_u64 v[230:231], v[230:231], 0, s[100:101]
	global_load_dwordx4 v[236:239], v[230:231], off
	global_load_dwordx4 v[248:251], v[230:231], off offset:256
	s_waitcnt vmcnt(15)
	v_mov_b64_e32 v[152:153], v[158:159]
	v_mov_b64_e32 v[154:155], v[160:161]
	v_lshlrev_b32_e32 v156, 16, v152
	v_and_b32_e32 v157, 0xffff0000, v152
	v_pk_add_f32 v[126:127], v[126:127], v[156:157]
	v_lshlrev_b32_e32 v156, 16, v154
	v_and_b32_e32 v157, 0xffff0000, v154
	v_pk_add_f32 v[156:157], v[122:123], v[156:157]
	v_lshlrev_b32_e32 v122, 16, v153
	v_and_b32_e32 v123, 0xffff0000, v153
	v_pk_add_f32 v[128:129], v[128:129], v[122:123]
	v_lshlrev_b32_e32 v122, 16, v155
	v_and_b32_e32 v123, 0xffff0000, v155
	v_pk_add_f32 v[152:153], v[124:125], v[122:123]
	v_cvt_pk_bf16_f32 v122, v126, v127
	v_cvt_pk_bf16_f32 v123, v128, v129
	v_cvt_pk_bf16_f32 v124, v156, v157
	v_cvt_pk_bf16_f32 v125, v152, v153
	global_store_dwordx4 v[144:145], v[122:125], off
	v_lshlrev_b32_e32 v126, 16, v122
	v_lshlrev_b32_e32 v127, 16, v123
	v_and_b32_e32 v122, 0xffff0000, v122
	v_mul_f32_e32 v152, v122, v122
	v_fmac_f32_e32 v152, v126, v126
	v_and_b32_e32 v123, 0xffff0000, v123
	v_fmac_f32_e32 v152, v127, v127
	v_lshlrev_b32_e32 v128, 16, v124
	v_fmac_f32_e32 v152, v123, v123
	v_and_b32_e32 v124, 0xffff0000, v124
	v_fmac_f32_e32 v152, v128, v128
	v_lshlrev_b32_e32 v129, 16, v125
	v_fmac_f32_e32 v152, v124, v124
	v_and_b32_e32 v125, 0xffff0000, v125
	v_fmac_f32_e32 v152, v129, v129
	v_fmac_f32_e32 v152, v125, v125
	s_waitcnt vmcnt(14)
; __device__ __forceinline__ void unpack8(const u32x4 w, float* f) { f[0] = bf_lo(w.x); f[1] = bf_hi(w.x); f[2] = bf_lo(w.y); f[3] = bf_hi(w.y); f[4] = bf_lo(w.z); f[5] = bf_hi(w.z); f[6] = bf_lo(w.w); f[7] = bf_hi(w.w); }
; __device__ __forceinline__ u32x4 pack8(const float* f) { u32x4 w; w.x = cvt_pk_bf16(f[0], f[1]); w.y = cvt_pk_bf16(f[2], f[3]); w.z = cvt_pk_bf16(f[4], f[5]); w.w = cvt_pk_bf16(f[6], f[7]); return w; }
; __device__ __forceinline__ float shx(float v, int m, int lane) { return __int_as_float(__builtin_amdgcn_ds_bpermute((lane ^ m) << 2, __float_as_int(v))); }
;     __device__ __forceinline__ void operator()(const f32x4 (&acc)[2][2][4][2], const Unit& u, int wr, int wc, int fr, int fq) const { if (u.kind == 0) e0(acc, u, wr, wc, fr, fq); else e1(acc, u, wr, wc, fr, fq); }
;     __device__ __forceinline__ void operator()(const f32x4 (&acc)[2][2][4][2], const Unit& u, int wr, int wc, int fr, int fq) const {
;         const int row0 = u.pm * BM + wr * 64 + fr, col0 = u.pn * BM + wc * 32 + 8 * fq;
; #pragma unroll
;         for (int ai = 0; ai < 2; ++ai)
; #pragma unroll
;             for (int m = 0; m < 4; ++m) { const int row = row0 + ai * HALF + m * 16; float ss = 0.f;
; #pragma unroll
;                 for (int bj = 0; bj < 2; ++bj) { const size_t off = (size_t)row * D + col0 + bj * HALF;
;                     float b[8], r[8]; unpack8(*(const u32x4*)(xb + off), b);
;                     const f32x4 v0 = acc[ai][bj][m][0], v1 = acc[ai][bj][m][1];
; #pragma unroll
;                     for (int j = 0; j < 4; ++j) { b[j] += v0[j]; b[4 + j] += v1[j]; }
;                     const u32x4 w = pack8(b);
;                     *(u32x4*)(xb + off) = w;
;                     unpack8(w, r);
; #pragma unroll
;                     for (int j = 0; j < 8; ++j) ss += r[j] * r[j]; }
;                 { const int ln = fr + 16 * fq; ss += shx(ss, 16, ln); ss += shx(ss, 32, ln); }
;                 if (fq == 0) rowss[(size_t)row * 16 + u.pn * 4 + wc] = ss; }
;     }
	v_mov_b64_e32 v[122:123], v[162:163]
	v_mov_b64_e32 v[124:125], v[164:165]
	v_lshlrev_b32_e32 v126, 16, v122
	v_and_b32_e32 v127, 0xffff0000, v122
	v_pk_add_f32 v[118:119], v[118:119], v[126:127]
	v_lshlrev_b32_e32 v126, 16, v124
	v_and_b32_e32 v127, 0xffff0000, v124
	v_pk_add_f32 v[126:127], v[114:115], v[126:127]
	v_lshlrev_b32_e32 v114, 16, v123
	v_and_b32_e32 v115, 0xffff0000, v123
	v_pk_add_f32 v[120:121], v[120:121], v[114:115]
	v_lshlrev_b32_e32 v114, 16, v125
	v_and_b32_e32 v115, 0xffff0000, v125
	v_pk_add_f32 v[122:123], v[116:117], v[114:115]
	v_cvt_pk_bf16_f32 v114, v118, v119
	v_cvt_pk_bf16_f32 v115, v120, v121
	v_cvt_pk_bf16_f32 v116, v126, v127
	v_cvt_pk_bf16_f32 v117, v122, v123
	v_lshlrev_b32_e32 v118, 16, v114
	global_store_dwordx4 v[144:145], v[114:117], off offset:256
	v_fmac_f32_e32 v152, v118, v118
	v_lshlrev_b32_e32 v119, 16, v115
	v_and_b32_e32 v114, 0xffff0000, v114
	v_fmac_f32_e32 v152, v114, v114
	v_and_b32_e32 v115, 0xffff0000, v115
	v_fmac_f32_e32 v152, v119, v119
	v_lshlrev_b32_e32 v120, 16, v116
	v_fmac_f32_e32 v152, v115, v115
	v_and_b32_e32 v116, 0xffff0000, v116
	v_fmac_f32_e32 v152, v120, v120
	v_lshlrev_b32_e32 v121, 16, v117
	v_fmac_f32_e32 v152, v116, v116
	v_and_b32_e32 v117, 0xffff0000, v117
	v_fmac_f32_e32 v152, v121, v121
	v_fmac_f32_e32 v152, v117, v117
	ds_bpermute_b32 v114, v149, v152
	s_waitcnt lgkmcnt(0)
	v_add_f32_e32 v114, v152, v114
	ds_bpermute_b32 v115, v150, v114
	s_and_saveexec_b64 s[28:29], s[4:5]
	s_cbranch_execz .LBB0_854
	s_waitcnt lgkmcnt(0)
	v_add_f32_e32 v116, v114, v115
	s_lshl_b32 s10, s37, 2
	v_lshlrev_b64 v[114:115], 6, v[142:143]
	s_ashr_i32 s11, s10, 31
	v_lshl_add_u64 v[114:115], s[42:43], 0, v[114:115]
	v_lshl_add_u64 v[114:115], s[10:11], 2, v[114:115]
	s_lshl_b32 s58, s83, 2
	v_lshl_add_u64 v[114:115], v[114:115], 0, s[58:59]
	global_store_dword v[114:115], v116, off
.LBB0_854:
	s_or_b64 exec, exec, s[28:29]
	v_or_b32_e32 v114, 16, v142
	s_waitcnt lgkmcnt(0)
	v_ashrrev_i32_e32 v115, 31, v114
	v_lshlrev_b64 v[116:117], 11, v[114:115]
	v_lshl_add_u64 v[116:117], s[40:41], 0, v[116:117]
	v_lshl_add_u64 v[116:117], v[140:141], 1, v[116:117]
	s_waitcnt vmcnt(13)
	v_mov_b64_e32 v[118:119], v[166:167]
	v_mov_b64_e32 v[120:121], v[168:169]
	v_lshlrev_b32_e32 v122, 16, v118
	v_and_b32_e32 v123, 0xffff0000, v118
	v_pk_add_f32 v[110:111], v[110:111], v[122:123]
	v_lshlrev_b32_e32 v122, 16, v120
	v_and_b32_e32 v123, 0xffff0000, v120
	v_pk_add_f32 v[122:123], v[106:107], v[122:123]
	v_lshlrev_b32_e32 v106, 16, v119
	v_and_b32_e32 v107, 0xffff0000, v119
	v_pk_add_f32 v[112:113], v[112:113], v[106:107]
	v_lshlrev_b32_e32 v106, 16, v121
	v_and_b32_e32 v107, 0xffff0000, v121
	v_pk_add_f32 v[118:119], v[108:109], v[106:107]
	v_cvt_pk_bf16_f32 v106, v110, v111
	v_cvt_pk_bf16_f32 v107, v112, v113
	v_cvt_pk_bf16_f32 v108, v122, v123
	v_cvt_pk_bf16_f32 v109, v118, v119
	global_store_dwordx4 v[116:117], v[106:109], off
	v_lshlrev_b32_e32 v110, 16, v106
	v_lshlrev_b32_e32 v111, 16, v107
	v_and_b32_e32 v106, 0xffff0000, v106
	v_mul_f32_e32 v118, v106, v106
	v_fmac_f32_e32 v118, v110, v110
	v_and_b32_e32 v107, 0xffff0000, v107
	v_fmac_f32_e32 v118, v111, v111
	v_lshlrev_b32_e32 v112, 16, v108
	v_fmac_f32_e32 v118, v107, v107
	v_and_b32_e32 v108, 0xffff0000, v108
	v_fmac_f32_e32 v118, v112, v112
	v_lshlrev_b32_e32 v113, 16, v109
	v_fmac_f32_e32 v118, v108, v108
	v_and_b32_e32 v109, 0xffff0000, v109
	v_fmac_f32_e32 v118, v113, v113
	v_fmac_f32_e32 v118, v109, v109
	s_waitcnt vmcnt(12)
	v_mov_b64_e32 v[106:107], v[170:171]
	v_mov_b64_e32 v[108:109], v[172:173]
	v_lshlrev_b32_e32 v110, 16, v106
	v_and_b32_e32 v111, 0xffff0000, v106
	v_pk_add_f32 v[102:103], v[102:103], v[110:111]
	v_lshlrev_b32_e32 v110, 16, v108
	v_and_b32_e32 v111, 0xffff0000, v108
	v_pk_add_f32 v[110:111], v[98:99], v[110:111]
	v_lshlrev_b32_e32 v98, 16, v107
	v_and_b32_e32 v99, 0xffff0000, v107
	v_pk_add_f32 v[104:105], v[104:105], v[98:99]
	v_lshlrev_b32_e32 v98, 16, v109
	v_and_b32_e32 v99, 0xffff0000, v109
	v_pk_add_f32 v[106:107], v[100:101], v[98:99]
	v_cvt_pk_bf16_f32 v98, v102, v103
	v_cvt_pk_bf16_f32 v99, v104, v105
	v_cvt_pk_bf16_f32 v100, v110, v111
	v_cvt_pk_bf16_f32 v101, v106, v107
	v_lshlrev_b32_e32 v102, 16, v98
	global_store_dwordx4 v[116:117], v[98:101], off offset:256
	v_fmac_f32_e32 v118, v102, v102
	v_lshlrev_b32_e32 v103, 16, v99
	v_and_b32_e32 v98, 0xffff0000, v98
	v_fmac_f32_e32 v118, v98, v98
	v_and_b32_e32 v99, 0xffff0000, v99
	v_fmac_f32_e32 v118, v103, v103
	v_lshlrev_b32_e32 v104, 16, v100
	v_fmac_f32_e32 v118, v99, v99
	v_and_b32_e32 v100, 0xffff0000, v100
	v_fmac_f32_e32 v118, v104, v104
	v_lshlrev_b32_e32 v105, 16, v101
	v_fmac_f32_e32 v118, v100, v100
	v_and_b32_e32 v101, 0xffff0000, v101
	v_fmac_f32_e32 v118, v105, v105
	v_fmac_f32_e32 v118, v101, v101
	ds_bpermute_b32 v98, v149, v118
	s_waitcnt lgkmcnt(0)
	v_add_f32_e32 v98, v118, v98
	ds_bpermute_b32 v99, v150, v98
	s_and_saveexec_b64 s[28:29], s[4:5]
	s_cbranch_execz .LBB0_856
	s_waitcnt lgkmcnt(0)
	v_add_f32_e32 v100, v98, v99
	s_lshl_b32 s10, s37, 2
	v_lshlrev_b64 v[98:99], 6, v[114:115]
	s_ashr_i32 s11, s10, 31
	v_lshl_add_u64 v[98:99], s[42:43], 0, v[98:99]
	v_lshl_add_u64 v[98:99], s[10:11], 2, v[98:99]
	s_lshl_b32 s58, s83, 2
	v_lshl_add_u64 v[98:99], v[98:99], 0, s[58:59]
	global_store_dword v[98:99], v100, off
; __device__ __forceinline__ void unpack8(const u32x4 w, float* f) { f[0] = bf_lo(w.x); f[1] = bf_hi(w.x); f[2] = bf_lo(w.y); f[3] = bf_hi(w.y); f[4] = bf_lo(w.z); f[5] = bf_hi(w.z); f[6] = bf_lo(w.w); f[7] = bf_hi(w.w); }
; __device__ __forceinline__ u32x4 pack8(const float* f) { u32x4 w; w.x = cvt_pk_bf16(f[0], f[1]); w.y = cvt_pk_bf16(f[2], f[3]); w.z = cvt_pk_bf16(f[4], f[5]); w.w = cvt_pk_bf16(f[6], f[7]); return w; }
; __device__ __forceinline__ float shx(float v, int m, int lane) { return __int_as_float(__builtin_amdgcn_ds_bpermute((lane ^ m) << 2, __float_as_int(v))); }
;     __device__ __forceinline__ void operator()(const f32x4 (&acc)[2][2][4][2], const Unit& u, int wr, int wc, int fr, int fq) const { if (u.kind == 0) e0(acc, u, wr, wc, fr, fq); else e1(acc, u, wr, wc, fr, fq); }
;     __device__ __forceinline__ void operator()(const f32x4 (&acc)[2][2][4][2], const Unit& u, int wr, int wc, int fr, int fq) const {
;         const int row0 = u.pm * BM + wr * 64 + fr, col0 = u.pn * BM + wc * 32 + 8 * fq;
; #pragma unroll
;         for (int ai = 0; ai < 2; ++ai)
; #pragma unroll
;             for (int m = 0; m < 4; ++m) { const int row = row0 + ai * HALF + m * 16; float ss = 0.f;
; #pragma unroll
;                 for (int bj = 0; bj < 2; ++bj) { const size_t off = (size_t)row * D + col0 + bj * HALF;
;                     float b[8], r[8]; unpack8(*(const u32x4*)(xb + off), b);
;                     const f32x4 v0 = acc[ai][bj][m][0], v1 = acc[ai][bj][m][1];
; #pragma unroll
;                     for (int j = 0; j < 4; ++j) { b[j] += v0[j]; b[4 + j] += v1[j]; }
;                     const u32x4 w = pack8(b);
;                     *(u32x4*)(xb + off) = w;
;                     unpack8(w, r);
; #pragma unroll
;                     for (int j = 0; j < 8; ++j) ss += r[j] * r[j]; }
;                 { const int ln = fr + 16 * fq; ss += shx(ss, 16, ln); ss += shx(ss, 32, ln); }
;                 if (fq == 0) rowss[(size_t)row * 16 + u.pn * 4 + wc] = ss; }
;     }
.LBB0_856:
	s_or_b64 exec, exec, s[28:29]
	v_or_b32_e32 v98, 32, v142
	s_waitcnt lgkmcnt(0)
	v_ashrrev_i32_e32 v99, 31, v98
	v_lshlrev_b64 v[100:101], 11, v[98:99]
	v_lshl_add_u64 v[100:101], s[40:41], 0, v[100:101]
	v_lshl_add_u64 v[100:101], v[140:141], 1, v[100:101]
	s_waitcnt vmcnt(11)
	v_mov_b64_e32 v[102:103], v[190:191]
	v_mov_b64_e32 v[104:105], v[192:193]
	v_lshlrev_b32_e32 v106, 16, v102
	v_and_b32_e32 v107, 0xffff0000, v102
	v_pk_add_f32 v[94:95], v[94:95], v[106:107]
	v_lshlrev_b32_e32 v106, 16, v104
	v_and_b32_e32 v107, 0xffff0000, v104
	v_pk_add_f32 v[106:107], v[90:91], v[106:107]
	v_lshlrev_b32_e32 v90, 16, v103
	v_and_b32_e32 v91, 0xffff0000, v103
	v_pk_add_f32 v[96:97], v[96:97], v[90:91]
	v_lshlrev_b32_e32 v90, 16, v105
	v_and_b32_e32 v91, 0xffff0000, v105
	v_pk_add_f32 v[102:103], v[92:93], v[90:91]
	v_cvt_pk_bf16_f32 v90, v94, v95
	v_cvt_pk_bf16_f32 v91, v96, v97
	v_cvt_pk_bf16_f32 v92, v106, v107
	v_cvt_pk_bf16_f32 v93, v102, v103
	global_store_dwordx4 v[100:101], v[90:93], off
	v_lshlrev_b32_e32 v94, 16, v90
	v_lshlrev_b32_e32 v95, 16, v91
	v_and_b32_e32 v90, 0xffff0000, v90
	v_mul_f32_e32 v102, v90, v90
	v_fmac_f32_e32 v102, v94, v94
	v_and_b32_e32 v91, 0xffff0000, v91
	v_fmac_f32_e32 v102, v95, v95
	v_lshlrev_b32_e32 v96, 16, v92
	v_fmac_f32_e32 v102, v91, v91
	v_and_b32_e32 v92, 0xffff0000, v92
	v_fmac_f32_e32 v102, v96, v96
	v_lshlrev_b32_e32 v97, 16, v93
	v_fmac_f32_e32 v102, v92, v92
	v_and_b32_e32 v93, 0xffff0000, v93
	v_fmac_f32_e32 v102, v97, v97
	v_fmac_f32_e32 v102, v93, v93
	s_waitcnt vmcnt(10)
	v_mov_b64_e32 v[90:91], v[194:195]
	v_mov_b64_e32 v[92:93], v[196:197]
	v_lshlrev_b32_e32 v94, 16, v90
	v_and_b32_e32 v95, 0xffff0000, v90
	v_pk_add_f32 v[86:87], v[86:87], v[94:95]
	v_lshlrev_b32_e32 v94, 16, v92
	v_and_b32_e32 v95, 0xffff0000, v92
	v_pk_add_f32 v[94:95], v[82:83], v[94:95]
	v_lshlrev_b32_e32 v82, 16, v91
	v_and_b32_e32 v83, 0xffff0000, v91
	v_pk_add_f32 v[88:89], v[88:89], v[82:83]
	v_lshlrev_b32_e32 v82, 16, v93
	v_and_b32_e32 v83, 0xffff0000, v93
	v_pk_add_f32 v[90:91], v[84:85], v[82:83]
	v_cvt_pk_bf16_f32 v82, v86, v87
	v_cvt_pk_bf16_f32 v83, v88, v89
	v_cvt_pk_bf16_f32 v84, v94, v95
	v_cvt_pk_bf16_f32 v85, v90, v91
	v_lshlrev_b32_e32 v86, 16, v82
	global_store_dwordx4 v[100:101], v[82:85], off offset:256
	v_fmac_f32_e32 v102, v86, v86
	v_lshlrev_b32_e32 v87, 16, v83
	v_and_b32_e32 v82, 0xffff0000, v82
	v_fmac_f32_e32 v102, v82, v82
	v_and_b32_e32 v83, 0xffff0000, v83
	v_fmac_f32_e32 v102, v87, v87
	v_lshlrev_b32_e32 v88, 16, v84
	v_fmac_f32_e32 v102, v83, v83
	v_and_b32_e32 v84, 0xffff0000, v84
	v_fmac_f32_e32 v102, v88, v88
	v_lshlrev_b32_e32 v89, 16, v85
	v_fmac_f32_e32 v102, v84, v84
	v_and_b32_e32 v85, 0xffff0000, v85
	v_fmac_f32_e32 v102, v89, v89
	v_fmac_f32_e32 v102, v85, v85
	ds_bpermute_b32 v82, v149, v102
	s_waitcnt lgkmcnt(0)
	v_add_f32_e32 v82, v102, v82
	ds_bpermute_b32 v83, v150, v82
	s_and_saveexec_b64 s[28:29], s[4:5]
	s_cbranch_execz .LBB0_858
	s_waitcnt lgkmcnt(0)
	v_add_f32_e32 v84, v82, v83
	s_lshl_b32 s10, s37, 2
	v_lshlrev_b64 v[82:83], 6, v[98:99]
	s_ashr_i32 s11, s10, 31
	v_lshl_add_u64 v[82:83], s[42:43], 0, v[82:83]
	v_lshl_add_u64 v[82:83], s[10:11], 2, v[82:83]
	s_lshl_b32 s58, s83, 2
	v_lshl_add_u64 v[82:83], v[82:83], 0, s[58:59]
	global_store_dword v[82:83], v84, off
.LBB0_858:
	s_or_b64 exec, exec, s[28:29]
	v_or_b32_e32 v82, 48, v142
	s_waitcnt lgkmcnt(0)
	v_ashrrev_i32_e32 v83, 31, v82
	v_lshlrev_b64 v[84:85], 11, v[82:83]
	v_lshl_add_u64 v[84:85], s[40:41], 0, v[84:85]
	v_lshl_add_u64 v[84:85], v[140:141], 1, v[84:85]
	s_waitcnt vmcnt(9)
	v_mov_b64_e32 v[86:87], v[198:199]
	v_mov_b64_e32 v[88:89], v[200:201]
	v_lshlrev_b32_e32 v90, 16, v86
	v_and_b32_e32 v91, 0xffff0000, v86
	v_pk_add_f32 v[78:79], v[78:79], v[90:91]
	v_lshlrev_b32_e32 v90, 16, v88
	v_and_b32_e32 v91, 0xffff0000, v88
	v_pk_add_f32 v[90:91], v[74:75], v[90:91]
	v_lshlrev_b32_e32 v74, 16, v87
	v_and_b32_e32 v75, 0xffff0000, v87
	v_pk_add_f32 v[80:81], v[80:81], v[74:75]
	v_lshlrev_b32_e32 v74, 16, v89
	v_and_b32_e32 v75, 0xffff0000, v89
	v_pk_add_f32 v[86:87], v[76:77], v[74:75]
	v_cvt_pk_bf16_f32 v74, v78, v79
	v_cvt_pk_bf16_f32 v75, v80, v81
	v_cvt_pk_bf16_f32 v76, v90, v91
	v_cvt_pk_bf16_f32 v77, v86, v87
	global_store_dwordx4 v[84:85], v[74:77], off
	v_lshlrev_b32_e32 v78, 16, v74
	v_lshlrev_b32_e32 v79, 16, v75
	v_and_b32_e32 v74, 0xffff0000, v74
	v_mul_f32_e32 v86, v74, v74
	v_fmac_f32_e32 v86, v78, v78
	v_and_b32_e32 v75, 0xffff0000, v75
	v_fmac_f32_e32 v86, v79, v79
	v_lshlrev_b32_e32 v80, 16, v76
	v_fmac_f32_e32 v86, v75, v75
	v_and_b32_e32 v76, 0xffff0000, v76
	v_fmac_f32_e32 v86, v80, v80
	v_lshlrev_b32_e32 v81, 16, v77
	v_fmac_f32_e32 v86, v76, v76
	v_and_b32_e32 v77, 0xffff0000, v77
	v_fmac_f32_e32 v86, v81, v81
	v_fmac_f32_e32 v86, v77, v77
	s_waitcnt vmcnt(8)
	v_mov_b64_e32 v[74:75], v[202:203]
	v_mov_b64_e32 v[76:77], v[204:205]
	v_lshlrev_b32_e32 v78, 16, v74
	v_and_b32_e32 v79, 0xffff0000, v74
	v_pk_add_f32 v[70:71], v[70:71], v[78:79]
	v_lshlrev_b32_e32 v78, 16, v76
	v_and_b32_e32 v79, 0xffff0000, v76
	v_pk_add_f32 v[78:79], v[66:67], v[78:79]
	v_lshlrev_b32_e32 v66, 16, v75
	v_and_b32_e32 v67, 0xffff0000, v75
	v_pk_add_f32 v[72:73], v[72:73], v[66:67]
	v_lshlrev_b32_e32 v66, 16, v77
	v_and_b32_e32 v67, 0xffff0000, v77
	v_pk_add_f32 v[74:75], v[68:69], v[66:67]
	v_cvt_pk_bf16_f32 v66, v70, v71
	v_cvt_pk_bf16_f32 v67, v72, v73
	v_cvt_pk_bf16_f32 v68, v78, v79
	v_cvt_pk_bf16_f32 v69, v74, v75
	v_lshlrev_b32_e32 v70, 16, v66
	global_store_dwordx4 v[84:85], v[66:69], off offset:256
	v_fmac_f32_e32 v86, v70, v70
	v_lshlrev_b32_e32 v71, 16, v67
	v_and_b32_e32 v66, 0xffff0000, v66
	v_fmac_f32_e32 v86, v66, v66
	v_and_b32_e32 v67, 0xffff0000, v67
	v_fmac_f32_e32 v86, v71, v71
	v_lshlrev_b32_e32 v72, 16, v68
	v_fmac_f32_e32 v86, v67, v67
	v_and_b32_e32 v68, 0xffff0000, v68
	v_fmac_f32_e32 v86, v72, v72
	v_lshlrev_b32_e32 v73, 16, v69
	v_fmac_f32_e32 v86, v68, v68
	v_and_b32_e32 v69, 0xffff0000, v69
	v_fmac_f32_e32 v86, v73, v73
	v_fmac_f32_e32 v86, v69, v69
	ds_bpermute_b32 v66, v149, v86
	s_waitcnt lgkmcnt(0)
	v_add_f32_e32 v66, v86, v66
	ds_bpermute_b32 v67, v150, v66
	s_and_saveexec_b64 s[28:29], s[4:5]
	s_cbranch_execz .LBB0_860
	s_waitcnt lgkmcnt(0)
	v_add_f32_e32 v68, v66, v67
	s_lshl_b32 s10, s37, 2
	v_lshlrev_b64 v[66:67], 6, v[82:83]
	s_ashr_i32 s11, s10, 31
	v_lshl_add_u64 v[66:67], s[42:43], 0, v[66:67]
	v_lshl_add_u64 v[66:67], s[10:11], 2, v[66:67]
	s_lshl_b32 s58, s83, 2
	v_lshl_add_u64 v[66:67], v[66:67], 0, s[58:59]
	global_store_dword v[66:67], v68, off
; __device__ __forceinline__ void unpack8(const u32x4 w, float* f) { f[0] = bf_lo(w.x); f[1] = bf_hi(w.x); f[2] = bf_lo(w.y); f[3] = bf_hi(w.y); f[4] = bf_lo(w.z); f[5] = bf_hi(w.z); f[6] = bf_lo(w.w); f[7] = bf_hi(w.w); }
; __device__ __forceinline__ u32x4 pack8(const float* f) { u32x4 w; w.x = cvt_pk_bf16(f[0], f[1]); w.y = cvt_pk_bf16(f[2], f[3]); w.z = cvt_pk_bf16(f[4], f[5]); w.w = cvt_pk_bf16(f[6], f[7]); return w; }
; __device__ __forceinline__ float shx(float v, int m, int lane) { return __int_as_float(__builtin_amdgcn_ds_bpermute((lane ^ m) << 2, __float_as_int(v))); }
;     __device__ __forceinline__ void operator()(const f32x4 (&acc)[2][2][4][2], const Unit& u, int wr, int wc, int fr, int fq) const {
;     ...
; #pragma unroll
;         for (int ai = 0; ai < 2; ++ai)
; #pragma unroll
;             for (int m = 0; m < 4; ++m) { const int row = row0 + ai * HALF + m * 16; float ss = 0.f;
; #pragma unroll
;                 for (int bj = 0; bj < 2; ++bj) { const size_t off = (size_t)row * D + col0 + bj * HALF;
;                     float b[8], r[8]; unpack8(*(const u32x4*)(xb + off), b);
;                     const f32x4 v0 = acc[ai][bj][m][0], v1 = acc[ai][bj][m][1];
; #pragma unroll
;                     for (int j = 0; j < 4; ++j) { b[j] += v0[j]; b[4 + j] += v1[j]; }
;                     const u32x4 w = pack8(b);
;                     *(u32x4*)(xb + off) = w;
;                     unpack8(w, r);
; #pragma unroll
;                     for (int j = 0; j < 8; ++j) ss += r[j] * r[j]; }
;                 { const int ln = fr + 16 * fq; ss += shx(ss, 16, ln); ss += shx(ss, 32, ln); }
;                 if (fq == 0) rowss[(size_t)row * 16 + u.pn * 4 + wc] = ss; }
.LBB0_860:
	s_or_b64 exec, exec, s[28:29]
	v_add_u32_e32 v66, 0x80, v142
	s_waitcnt lgkmcnt(0)
	v_ashrrev_i32_e32 v67, 31, v66
	v_lshlrev_b64 v[68:69], 11, v[66:67]
	v_lshl_add_u64 v[68:69], s[40:41], 0, v[68:69]
	v_lshl_add_u64 v[68:69], v[140:141], 1, v[68:69]
	s_waitcnt vmcnt(7)
	v_mov_b64_e32 v[70:71], v[206:207]
	v_mov_b64_e32 v[72:73], v[208:209]
	v_lshlrev_b32_e32 v74, 16, v70
	v_and_b32_e32 v75, 0xffff0000, v70
	v_pk_add_f32 v[62:63], v[62:63], v[74:75]
	v_lshlrev_b32_e32 v74, 16, v72
	v_and_b32_e32 v75, 0xffff0000, v72
	v_pk_add_f32 v[74:75], v[58:59], v[74:75]
	v_lshlrev_b32_e32 v58, 16, v71
	v_and_b32_e32 v59, 0xffff0000, v71
	v_pk_add_f32 v[64:65], v[64:65], v[58:59]
	v_lshlrev_b32_e32 v58, 16, v73
	v_and_b32_e32 v59, 0xffff0000, v73
	v_pk_add_f32 v[70:71], v[60:61], v[58:59]
	v_cvt_pk_bf16_f32 v58, v62, v63
	v_cvt_pk_bf16_f32 v59, v64, v65
	v_cvt_pk_bf16_f32 v60, v74, v75
	v_cvt_pk_bf16_f32 v61, v70, v71
	global_store_dwordx4 v[68:69], v[58:61], off
	v_lshlrev_b32_e32 v62, 16, v58
	v_lshlrev_b32_e32 v63, 16, v59
	v_and_b32_e32 v58, 0xffff0000, v58
	v_mul_f32_e32 v70, v58, v58
	v_fmac_f32_e32 v70, v62, v62
	v_and_b32_e32 v59, 0xffff0000, v59
	v_fmac_f32_e32 v70, v63, v63
	v_lshlrev_b32_e32 v64, 16, v60
	v_fmac_f32_e32 v70, v59, v59
	v_and_b32_e32 v60, 0xffff0000, v60
	v_fmac_f32_e32 v70, v64, v64
	v_lshlrev_b32_e32 v65, 16, v61
	v_fmac_f32_e32 v70, v60, v60
	v_and_b32_e32 v61, 0xffff0000, v61
	v_fmac_f32_e32 v70, v65, v65
	v_fmac_f32_e32 v70, v61, v61
	s_waitcnt vmcnt(6)
	v_mov_b64_e32 v[58:59], v[210:211]
	v_mov_b64_e32 v[60:61], v[212:213]
	v_lshlrev_b32_e32 v62, 16, v58
	v_and_b32_e32 v63, 0xffff0000, v58
	v_pk_add_f32 v[54:55], v[54:55], v[62:63]
	v_lshlrev_b32_e32 v62, 16, v60
	v_and_b32_e32 v63, 0xffff0000, v60
	v_pk_add_f32 v[62:63], v[50:51], v[62:63]
	v_lshlrev_b32_e32 v50, 16, v59
	v_and_b32_e32 v51, 0xffff0000, v59
	v_pk_add_f32 v[56:57], v[56:57], v[50:51]
	v_lshlrev_b32_e32 v50, 16, v61
	v_and_b32_e32 v51, 0xffff0000, v61
	v_pk_add_f32 v[58:59], v[52:53], v[50:51]
	v_cvt_pk_bf16_f32 v50, v54, v55
	v_cvt_pk_bf16_f32 v51, v56, v57
	v_cvt_pk_bf16_f32 v52, v62, v63
	v_cvt_pk_bf16_f32 v53, v58, v59
	v_lshlrev_b32_e32 v54, 16, v50
	global_store_dwordx4 v[68:69], v[50:53], off offset:256
	v_fmac_f32_e32 v70, v54, v54
	v_lshlrev_b32_e32 v55, 16, v51
	v_and_b32_e32 v50, 0xffff0000, v50
	v_fmac_f32_e32 v70, v50, v50
	v_and_b32_e32 v51, 0xffff0000, v51
	v_fmac_f32_e32 v70, v55, v55
	v_lshlrev_b32_e32 v56, 16, v52
	v_fmac_f32_e32 v70, v51, v51
	v_and_b32_e32 v52, 0xffff0000, v52
	v_fmac_f32_e32 v70, v56, v56
	v_lshlrev_b32_e32 v57, 16, v53
	v_fmac_f32_e32 v70, v52, v52
	v_and_b32_e32 v53, 0xffff0000, v53
	v_fmac_f32_e32 v70, v57, v57
	v_fmac_f32_e32 v70, v53, v53
	ds_bpermute_b32 v50, v149, v70
	s_waitcnt lgkmcnt(0)
	v_add_f32_e32 v50, v70, v50
	ds_bpermute_b32 v51, v150, v50
	s_and_saveexec_b64 s[28:29], s[4:5]
	s_cbranch_execz .LBB0_862
	s_waitcnt lgkmcnt(0)
	v_add_f32_e32 v52, v50, v51
	s_lshl_b32 s10, s37, 2
	v_lshlrev_b64 v[50:51], 6, v[66:67]
	s_ashr_i32 s11, s10, 31
	v_lshl_add_u64 v[50:51], s[42:43], 0, v[50:51]
	v_lshl_add_u64 v[50:51], s[10:11], 2, v[50:51]
	s_lshl_b32 s58, s83, 2
	v_lshl_add_u64 v[50:51], v[50:51], 0, s[58:59]
	global_store_dword v[50:51], v52, off
.LBB0_862:
	s_or_b64 exec, exec, s[28:29]
	v_add_u32_e32 v50, 0x90, v142
	s_waitcnt lgkmcnt(0)
	v_ashrrev_i32_e32 v51, 31, v50
	v_lshlrev_b64 v[52:53], 11, v[50:51]
	v_lshl_add_u64 v[52:53], s[40:41], 0, v[52:53]
	v_lshl_add_u64 v[52:53], v[140:141], 1, v[52:53]
	s_waitcnt vmcnt(5)
	v_mov_b64_e32 v[54:55], v[214:215]
	v_mov_b64_e32 v[56:57], v[216:217]
	v_lshlrev_b32_e32 v58, 16, v54
	v_and_b32_e32 v59, 0xffff0000, v54
	v_pk_add_f32 v[46:47], v[46:47], v[58:59]
	v_lshlrev_b32_e32 v58, 16, v56
	v_and_b32_e32 v59, 0xffff0000, v56
	v_pk_add_f32 v[58:59], v[42:43], v[58:59]
	v_lshlrev_b32_e32 v42, 16, v55
	v_and_b32_e32 v43, 0xffff0000, v55
	v_pk_add_f32 v[48:49], v[48:49], v[42:43]
	v_lshlrev_b32_e32 v42, 16, v57
	v_and_b32_e32 v43, 0xffff0000, v57
	v_pk_add_f32 v[54:55], v[44:45], v[42:43]
	v_cvt_pk_bf16_f32 v42, v46, v47
	v_cvt_pk_bf16_f32 v43, v48, v49
	v_cvt_pk_bf16_f32 v44, v58, v59
	v_cvt_pk_bf16_f32 v45, v54, v55
	global_store_dwordx4 v[52:53], v[42:45], off
	v_lshlrev_b32_e32 v46, 16, v42
	v_lshlrev_b32_e32 v47, 16, v43
	v_and_b32_e32 v42, 0xffff0000, v42
	v_mul_f32_e32 v54, v42, v42
	v_fmac_f32_e32 v54, v46, v46
	v_and_b32_e32 v43, 0xffff0000, v43
	v_fmac_f32_e32 v54, v47, v47
	v_lshlrev_b32_e32 v48, 16, v44
	v_fmac_f32_e32 v54, v43, v43
	v_and_b32_e32 v44, 0xffff0000, v44
	v_fmac_f32_e32 v54, v48, v48
	v_lshlrev_b32_e32 v49, 16, v45
	v_fmac_f32_e32 v54, v44, v44
	v_and_b32_e32 v45, 0xffff0000, v45
	v_fmac_f32_e32 v54, v49, v49
	v_fmac_f32_e32 v54, v45, v45
	s_waitcnt vmcnt(4)
	v_mov_b64_e32 v[42:43], v[218:219]
	v_mov_b64_e32 v[44:45], v[220:221]
	v_lshlrev_b32_e32 v46, 16, v42
	v_and_b32_e32 v47, 0xffff0000, v42
	v_pk_add_f32 v[38:39], v[38:39], v[46:47]
	v_lshlrev_b32_e32 v46, 16, v44
	v_and_b32_e32 v47, 0xffff0000, v44
	v_pk_add_f32 v[46:47], v[34:35], v[46:47]
	v_lshlrev_b32_e32 v34, 16, v43
	v_and_b32_e32 v35, 0xffff0000, v43
	v_pk_add_f32 v[40:41], v[40:41], v[34:35]
	v_lshlrev_b32_e32 v34, 16, v45
	v_and_b32_e32 v35, 0xffff0000, v45
	v_pk_add_f32 v[42:43], v[36:37], v[34:35]
	v_cvt_pk_bf16_f32 v34, v38, v39
	v_cvt_pk_bf16_f32 v35, v40, v41
	v_cvt_pk_bf16_f32 v36, v46, v47
	v_cvt_pk_bf16_f32 v37, v42, v43
	v_lshlrev_b32_e32 v38, 16, v34
	global_store_dwordx4 v[52:53], v[34:37], off offset:256
	v_fmac_f32_e32 v54, v38, v38
	v_lshlrev_b32_e32 v39, 16, v35
	v_and_b32_e32 v34, 0xffff0000, v34
	v_fmac_f32_e32 v54, v34, v34
	v_and_b32_e32 v35, 0xffff0000, v35
	v_fmac_f32_e32 v54, v39, v39
	v_lshlrev_b32_e32 v40, 16, v36
	v_fmac_f32_e32 v54, v35, v35
	v_and_b32_e32 v36, 0xffff0000, v36
	v_fmac_f32_e32 v54, v40, v40
	v_lshlrev_b32_e32 v41, 16, v37
	v_fmac_f32_e32 v54, v36, v36
	v_and_b32_e32 v37, 0xffff0000, v37
	v_fmac_f32_e32 v54, v41, v41
	v_fmac_f32_e32 v54, v37, v37
	ds_bpermute_b32 v34, v149, v54
	s_waitcnt lgkmcnt(0)
	v_add_f32_e32 v34, v54, v34
	ds_bpermute_b32 v35, v150, v34
	s_and_saveexec_b64 s[28:29], s[4:5]
	s_cbranch_execz .LBB0_864
	s_waitcnt lgkmcnt(0)
	v_add_f32_e32 v36, v34, v35
	s_lshl_b32 s10, s37, 2
	v_lshlrev_b64 v[34:35], 6, v[50:51]
	s_ashr_i32 s11, s10, 31
	v_lshl_add_u64 v[34:35], s[42:43], 0, v[34:35]
	v_lshl_add_u64 v[34:35], s[10:11], 2, v[34:35]
	s_lshl_b32 s58, s83, 2
	v_lshl_add_u64 v[34:35], v[34:35], 0, s[58:59]
	global_store_dword v[34:35], v36, off
; __device__ __forceinline__ void unpack8(const u32x4 w, float* f) { f[0] = bf_lo(w.x); f[1] = bf_hi(w.x); f[2] = bf_lo(w.y); f[3] = bf_hi(w.y); f[4] = bf_lo(w.z); f[5] = bf_hi(w.z); f[6] = bf_lo(w.w); f[7] = bf_hi(w.w); }
; __device__ __forceinline__ u32x4 pack8(const float* f) { u32x4 w; w.x = cvt_pk_bf16(f[0], f[1]); w.y = cvt_pk_bf16(f[2], f[3]); w.z = cvt_pk_bf16(f[4], f[5]); w.w = cvt_pk_bf16(f[6], f[7]); return w; }
; __device__ __forceinline__ float shx(float v, int m, int lane) { return __int_as_float(__builtin_amdgcn_ds_bpermute((lane ^ m) << 2, __float_as_int(v))); }
;     __device__ __forceinline__ void operator()(const f32x4 (&acc)[2][2][4][2], const Unit& u, int wr, int wc, int fr, int fq) const {
;     ...
; #pragma unroll
;         for (int ai = 0; ai < 2; ++ai)
; #pragma unroll
;             for (int m = 0; m < 4; ++m) { const int row = row0 + ai * HALF + m * 16; float ss = 0.f;
; #pragma unroll
;                 for (int bj = 0; bj < 2; ++bj) { const size_t off = (size_t)row * D + col0 + bj * HALF;
;                     float b[8], r[8]; unpack8(*(const u32x4*)(xb + off), b);
;                     const f32x4 v0 = acc[ai][bj][m][0], v1 = acc[ai][bj][m][1];
; #pragma unroll
;                     for (int j = 0; j < 4; ++j) { b[j] += v0[j]; b[4 + j] += v1[j]; }
;                     const u32x4 w = pack8(b);
;                     *(u32x4*)(xb + off) = w;
;                     unpack8(w, r);
; #pragma unroll
;                     for (int j = 0; j < 8; ++j) ss += r[j] * r[j]; }
;                 { const int ln = fr + 16 * fq; ss += shx(ss, 16, ln); ss += shx(ss, 32, ln); }
;                 if (fq == 0) rowss[(size_t)row * 16 + u.pn * 4 + wc] = ss; }
.LBB0_864:
	s_or_b64 exec, exec, s[28:29]
	v_add_u32_e32 v34, 0xa0, v142
	s_waitcnt lgkmcnt(0)
	v_ashrrev_i32_e32 v35, 31, v34
	v_lshlrev_b64 v[36:37], 11, v[34:35]
	v_lshl_add_u64 v[36:37], s[40:41], 0, v[36:37]
	v_lshl_add_u64 v[36:37], v[140:141], 1, v[36:37]
	s_waitcnt vmcnt(3)
	v_mov_b64_e32 v[38:39], v[222:223]
	v_mov_b64_e32 v[40:41], v[224:225]
	v_lshlrev_b32_e32 v42, 16, v38
	v_and_b32_e32 v43, 0xffff0000, v38
	v_pk_add_f32 v[30:31], v[30:31], v[42:43]
	v_lshlrev_b32_e32 v42, 16, v40
	v_and_b32_e32 v43, 0xffff0000, v40
	v_pk_add_f32 v[42:43], v[26:27], v[42:43]
	v_lshlrev_b32_e32 v26, 16, v39
	v_and_b32_e32 v27, 0xffff0000, v39
	v_pk_add_f32 v[32:33], v[32:33], v[26:27]
	v_lshlrev_b32_e32 v26, 16, v41
	v_and_b32_e32 v27, 0xffff0000, v41
	v_pk_add_f32 v[38:39], v[28:29], v[26:27]
	v_cvt_pk_bf16_f32 v26, v30, v31
	v_cvt_pk_bf16_f32 v27, v32, v33
	v_cvt_pk_bf16_f32 v28, v42, v43
	v_cvt_pk_bf16_f32 v29, v38, v39
	global_store_dwordx4 v[36:37], v[26:29], off
	v_lshlrev_b32_e32 v30, 16, v26
	v_lshlrev_b32_e32 v31, 16, v27
	v_and_b32_e32 v26, 0xffff0000, v26
	v_mul_f32_e32 v38, v26, v26
	v_fmac_f32_e32 v38, v30, v30
	v_and_b32_e32 v27, 0xffff0000, v27
	v_fmac_f32_e32 v38, v31, v31
	v_lshlrev_b32_e32 v32, 16, v28
	v_fmac_f32_e32 v38, v27, v27
	v_and_b32_e32 v28, 0xffff0000, v28
	v_fmac_f32_e32 v38, v32, v32
	v_lshlrev_b32_e32 v33, 16, v29
	v_fmac_f32_e32 v38, v28, v28
	v_and_b32_e32 v29, 0xffff0000, v29
	v_fmac_f32_e32 v38, v33, v33
	v_fmac_f32_e32 v38, v29, v29
	s_waitcnt vmcnt(2)
	v_mov_b64_e32 v[26:27], v[226:227]
	v_mov_b64_e32 v[28:29], v[228:229]
	v_lshlrev_b32_e32 v30, 16, v26
	v_and_b32_e32 v31, 0xffff0000, v26
	v_pk_add_f32 v[22:23], v[22:23], v[30:31]
	v_lshlrev_b32_e32 v30, 16, v28
	v_and_b32_e32 v31, 0xffff0000, v28
	v_pk_add_f32 v[30:31], v[18:19], v[30:31]
	v_lshlrev_b32_e32 v18, 16, v27
	v_and_b32_e32 v19, 0xffff0000, v27
	v_pk_add_f32 v[24:25], v[24:25], v[18:19]
	v_lshlrev_b32_e32 v18, 16, v29
	v_and_b32_e32 v19, 0xffff0000, v29
	v_pk_add_f32 v[26:27], v[20:21], v[18:19]
	v_cvt_pk_bf16_f32 v18, v22, v23
	v_cvt_pk_bf16_f32 v19, v24, v25
	v_cvt_pk_bf16_f32 v20, v30, v31
	v_cvt_pk_bf16_f32 v21, v26, v27
	v_lshlrev_b32_e32 v22, 16, v18
	global_store_dwordx4 v[36:37], v[18:21], off offset:256
	v_fmac_f32_e32 v38, v22, v22
	v_lshlrev_b32_e32 v23, 16, v19
	v_and_b32_e32 v18, 0xffff0000, v18
	v_fmac_f32_e32 v38, v18, v18
	v_and_b32_e32 v19, 0xffff0000, v19
	v_fmac_f32_e32 v38, v23, v23
	v_lshlrev_b32_e32 v24, 16, v20
	v_fmac_f32_e32 v38, v19, v19
	v_and_b32_e32 v20, 0xffff0000, v20
	v_fmac_f32_e32 v38, v24, v24
	v_lshlrev_b32_e32 v25, 16, v21
	v_fmac_f32_e32 v38, v20, v20
	v_and_b32_e32 v21, 0xffff0000, v21
	v_fmac_f32_e32 v38, v25, v25
	v_fmac_f32_e32 v38, v21, v21
	ds_bpermute_b32 v18, v149, v38
	s_waitcnt lgkmcnt(0)
	v_add_f32_e32 v18, v38, v18
	ds_bpermute_b32 v19, v150, v18
	s_and_saveexec_b64 s[28:29], s[4:5]
	s_cbranch_execz .LBB0_866
	s_waitcnt lgkmcnt(0)
	v_add_f32_e32 v20, v18, v19
	s_lshl_b32 s10, s37, 2
	v_lshlrev_b64 v[18:19], 6, v[34:35]
	s_ashr_i32 s11, s10, 31
	v_lshl_add_u64 v[18:19], s[42:43], 0, v[18:19]
	v_lshl_add_u64 v[18:19], s[10:11], 2, v[18:19]
	s_lshl_b32 s58, s83, 2
	v_lshl_add_u64 v[18:19], v[18:19], 0, s[58:59]
	global_store_dword v[18:19], v20, off
.LBB0_866:
	s_or_b64 exec, exec, s[28:29]
	v_add_u32_e32 v18, 0xb0, v142
	s_waitcnt lgkmcnt(0)
	v_ashrrev_i32_e32 v19, 31, v18
	v_lshlrev_b64 v[20:21], 11, v[18:19]
	v_lshl_add_u64 v[20:21], s[40:41], 0, v[20:21]
	v_lshl_add_u64 v[20:21], v[140:141], 1, v[20:21]
	s_waitcnt vmcnt(1)
	v_mov_b64_e32 v[22:23], v[236:237]
	v_mov_b64_e32 v[24:25], v[238:239]
	v_lshlrev_b32_e32 v26, 16, v22
	v_and_b32_e32 v27, 0xffff0000, v22
	v_pk_add_f32 v[14:15], v[14:15], v[26:27]
	v_lshlrev_b32_e32 v26, 16, v24
	v_and_b32_e32 v27, 0xffff0000, v24
	v_pk_add_f32 v[26:27], v[10:11], v[26:27]
	v_lshlrev_b32_e32 v10, 16, v23
	v_and_b32_e32 v11, 0xffff0000, v23
	v_pk_add_f32 v[16:17], v[16:17], v[10:11]
	v_lshlrev_b32_e32 v10, 16, v25
	v_and_b32_e32 v11, 0xffff0000, v25
	v_pk_add_f32 v[22:23], v[12:13], v[10:11]
	v_cvt_pk_bf16_f32 v10, v14, v15
	v_cvt_pk_bf16_f32 v11, v16, v17
	v_cvt_pk_bf16_f32 v12, v26, v27
	v_cvt_pk_bf16_f32 v13, v22, v23
	global_store_dwordx4 v[20:21], v[10:13], off
	v_lshlrev_b32_e32 v14, 16, v10
	v_lshlrev_b32_e32 v15, 16, v11
	v_and_b32_e32 v10, 0xffff0000, v10
	v_mul_f32_e32 v22, v10, v10
	v_fmac_f32_e32 v22, v14, v14
	v_and_b32_e32 v11, 0xffff0000, v11
	v_fmac_f32_e32 v22, v15, v15
	v_lshlrev_b32_e32 v16, 16, v12
	v_fmac_f32_e32 v22, v11, v11
	v_and_b32_e32 v12, 0xffff0000, v12
	v_fmac_f32_e32 v22, v16, v16
	v_lshlrev_b32_e32 v17, 16, v13
	v_fmac_f32_e32 v22, v12, v12
	v_and_b32_e32 v13, 0xffff0000, v13
	v_fmac_f32_e32 v22, v17, v17
	v_fmac_f32_e32 v22, v13, v13
	s_waitcnt vmcnt(0)
	v_mov_b64_e32 v[10:11], v[248:249]
	v_mov_b64_e32 v[12:13], v[250:251]
	v_lshlrev_b32_e32 v14, 16, v10
	v_and_b32_e32 v15, 0xffff0000, v10
	v_pk_add_f32 v[6:7], v[6:7], v[14:15]
	v_lshlrev_b32_e32 v14, 16, v12
	v_and_b32_e32 v15, 0xffff0000, v12
	v_pk_add_f32 v[14:15], v[2:3], v[14:15]
	v_lshlrev_b32_e32 v2, 16, v11
	v_and_b32_e32 v3, 0xffff0000, v11
	v_pk_add_f32 v[8:9], v[8:9], v[2:3]
	v_lshlrev_b32_e32 v2, 16, v13
	v_and_b32_e32 v3, 0xffff0000, v13
	v_pk_add_f32 v[10:11], v[4:5], v[2:3]
	v_cvt_pk_bf16_f32 v2, v6, v7
	v_cvt_pk_bf16_f32 v3, v8, v9
	v_cvt_pk_bf16_f32 v4, v14, v15
	v_cvt_pk_bf16_f32 v5, v10, v11
	v_lshlrev_b32_e32 v6, 16, v2
	global_store_dwordx4 v[20:21], v[2:5], off offset:256
	v_fmac_f32_e32 v22, v6, v6
	v_lshlrev_b32_e32 v7, 16, v3
	v_and_b32_e32 v2, 0xffff0000, v2
	v_fmac_f32_e32 v22, v2, v2
	v_and_b32_e32 v3, 0xffff0000, v3
	v_fmac_f32_e32 v22, v7, v7
	v_lshlrev_b32_e32 v8, 16, v4
	v_fmac_f32_e32 v22, v3, v3
	v_and_b32_e32 v4, 0xffff0000, v4
	v_fmac_f32_e32 v22, v8, v8
	v_lshlrev_b32_e32 v9, 16, v5
	v_fmac_f32_e32 v22, v4, v4
	v_and_b32_e32 v5, 0xffff0000, v5
	v_fmac_f32_e32 v22, v9, v9
	v_fmac_f32_e32 v22, v5, v5
	ds_bpermute_b32 v2, v149, v22
	s_waitcnt lgkmcnt(0)
	v_add_f32_e32 v2, v22, v2
	ds_bpermute_b32 v3, v150, v2
	s_and_saveexec_b64 s[28:29], s[4:5]
	s_cbranch_execz .LBB0_839
	s_waitcnt lgkmcnt(0)
	v_add_f32_e32 v4, v2, v3
	s_lshl_b32 s10, s37, 2
	v_lshlrev_b64 v[2:3], 6, v[18:19]
	s_ashr_i32 s11, s10, 31
	v_lshl_add_u64 v[2:3], s[42:43], 0, v[2:3]
	v_lshl_add_u64 v[2:3], s[10:11], 2, v[2:3]
	s_lshl_b32 s58, s83, 2
	v_lshl_add_u64 v[2:3], v[2:3], 0, s[58:59]
	global_store_dword v[2:3], v4, off
	s_branch .LBB0_839

; __global__ void __launch_bounds__(NTHREADS, 2) fwd_megakernel(Params P) {
;     extern __shared__ __attribute__((aligned(16))) unsigned char lds_raw[];
	.amdhsa_kernel _Z14fwd_megakernel6Params
		.amdhsa_group_segment_fixed_size 0
		.amdhsa_private_segment_fixed_size 0
		.amdhsa_kernarg_size 400
		.amdhsa_user_sgpr_count 2
		.amdhsa_user_sgpr_dispatch_ptr 0
		.amdhsa_user_sgpr_queue_ptr 0
		.amdhsa_user_sgpr_kernarg_segment_ptr 1
		.amdhsa_user_sgpr_dispatch_id 0
		.amdhsa_user_sgpr_kernarg_preload_length 0
		.amdhsa_user_sgpr_kernarg_preload_offset 0
		.amdhsa_user_sgpr_private_segment_size 0
		.amdhsa_uses_dynamic_stack 0
		.amdhsa_enable_private_segment 0
		.amdhsa_system_sgpr_workgroup_id_x 1
		.amdhsa_system_sgpr_workgroup_id_y 0
		.amdhsa_system_sgpr_workgroup_id_z 0
		.amdhsa_system_sgpr_workgroup_info 0
		.amdhsa_system_vgpr_workitem_id 2
		.amdhsa_next_free_vgpr 256
		.amdhsa_next_free_sgpr 102
		.amdhsa_accum_offset 256
		.amdhsa_reserve_vcc 1
		.amdhsa_float_round_mode_32 0
		.amdhsa_float_round_mode_16_64 0
		.amdhsa_float_denorm_mode_32 3
		.amdhsa_float_denorm_mode_16_64 3
		.amdhsa_dx10_clamp 1
		.amdhsa_ieee_mode 1
		.amdhsa_fp16_overflow 0
		.amdhsa_tg_split 0
		.amdhsa_exception_fp_ieee_invalid_op 0
		.amdhsa_exception_fp_denorm_src 0
		.amdhsa_exception_fp_ieee_div_zero 0
		.amdhsa_exception_fp_ieee_overflow 0
		.amdhsa_exception_fp_ieee_underflow 0
		.amdhsa_exception_fp_ieee_inexact 0
		.amdhsa_exception_int_div_zero 0
	.end_amdhsa_kernel

; __global__ void __launch_bounds__(NTHREADS, 2) fwd_megakernel(Params P) {
amdhsa.kernels:
  - .agpr_count:     0
    .args:
      - .offset:         0
        .size:           144
        .value_kind:     by_value
      - .offset:         144
        .size:           4
        .value_kind:     hidden_block_count_x
      - .offset:         148
        .size:           4
        .value_kind:     hidden_block_count_y
      - .offset:         152
        .size:           4
        .value_kind:     hidden_block_count_z
      - .offset:         156
        .size:           2
        .value_kind:     hidden_group_size_x
      - .offset:         158
        .size:           2
        .value_kind:     hidden_group_size_y
      - .offset:         160
        .size:           2
        .value_kind:     hidden_group_size_z
      - .offset:         162
        .size:           2
        .value_kind:     hidden_remainder_x
      - .offset:         164
        .size:           2
        .value_kind:     hidden_remainder_y
      - .offset:         166
        .size:           2
        .value_kind:     hidden_remainder_z
      - .offset:         184
        .size:           8
        .value_kind:     hidden_global_offset_x
      - .offset:         192
        .size:           8
        .value_kind:     hidden_global_offset_y
      - .offset:         200
        .size:           8
        .value_kind:     hidden_global_offset_z
      - .offset:         208
        .size:           2
        .value_kind:     hidden_grid_dims
      - .offset:         232
        .size:           8
        .value_kind:     hidden_multigrid_sync_arg
      - .offset:         264
        .size:           4
        .value_kind:     hidden_dynamic_lds_size
    .group_segment_fixed_size: 0
    .kernarg_segment_align: 8
    .kernarg_segment_size: 400
    .language:       OpenCL C
    .language_version:
      - 2
      - 0
    .max_flat_workgroup_size: 512
    .name:           _Z14fwd_megakernel6Params
    .private_segment_fixed_size: 0
    .sgpr_count:     108
    .sgpr_spill_count: 110
    .symbol:         _Z14fwd_megakernel6Params.kd
    .uniform_work_group_size: 1
    .uses_dynamic_stack: false
    .vgpr_count:     256
    .vgpr_spill_count: 0
    .wavefront_size: 64
